# hand-off version with the replay-rule s_nop 0 pads between back-to-back global loads removed (194 sites)
# baseline (speedup 1.0000x reference)
; #define LAS __attribute__((address_space(3)))
; __device__ __forceinline__ void transpose_item(const float* W, int ldw, int k0, int n0, bf16_t* WT, int ldt, int drow0, int dk0, LAS float* scr, int lane) {
;     float tv[32];
; #pragma unroll
;     for (int i = 0; i < 32; ++i) { const int kk = 2 * i + (lane >> 5); tv[i] = W[(size_t)(k0 + kk) * ldw + n0 + (lane & 31)]; }
; __device__ __forceinline__ void prep_weights(const Params& P, LAS unsigned char* lds, int lay, int bid, int G, int sel) {
;     ...
;           if (r < 2 * I_GU) { if (!((sel >> (r / I_GU)) & 1)) continue; const int mat = lay * 2 + r / I_GU, ii = r % I_GU, kb = ii / 176, nb = ii % 176, n0 = nb * 32;
;               const int drow = n0 < DFF ? (n0 >> 7) * 256 + (n0 & 127) : ((n0 - DFF) >> 7) * 256 + 128 + ((n0 - DFF) & 127);
;               transpose_item(P.w_gu + (size_t)mat * 1024 * 5632, 5632, kb * 64, n0, (bf16_t*)(ws + OFF_WGU + mat * SZ_WGU1), 1024, drow, kb * 64, scr, lane); continue; }
.LBB0_24:
	s_or_b64 exec, exec, s[16:17]
	v_mov_b64_e32 v[32:33], s[78:79]
	v_lshlrev_b32_sdwa v38, v29, sext(v9) dst_sel:DWORD dst_unused:UNUSED_PAD src0_sel:DWORD src1_sel:WORD_0
	v_mad_i64_i32 v[32:33], s[16:17], v7, s13, v[32:33]
	v_or_b32_e32 v31, v38, v12
	v_ashrrev_i32_e32 v9, 31, v8
	v_lshl_add_u64 v[8:9], v[8:9], 2, v[32:33]
	v_mul_i32_i24_e32 v32, 0x1600, v31
	v_lshl_add_u64 v[8:9], v[8:9], 0, v[0:1]
	v_ashrrev_i32_e32 v33, 31, v32
	v_lshl_add_u64 v[8:9], v[32:33], 2, v[8:9]
	v_add_co_u32_e32 v32, vcc, s15, v8
	s_mov_b32 s16, 0x16000
	s_nop 0
	v_addc_co_u32_e32 v33, vcc, 0, v9, vcc
	v_add_co_u32_e32 v34, vcc, s16, v8
	s_mov_b32 s16, 0x2c000
	s_nop 0
	v_addc_co_u32_e32 v35, vcc, 0, v9, vcc
	v_add_co_u32_e32 v40, vcc, s18, v8
	s_nop 1
	v_addc_co_u32_e32 v41, vcc, 0, v9, vcc
	v_add_co_u32_e32 v42, vcc, s16, v8
	s_nop 1
	v_addc_co_u32_e32 v43, vcc, 0, v9, vcc
	v_add_co_u32_e32 v44, vcc, s19, v8
	s_nop 1
	v_addc_co_u32_e32 v45, vcc, 0, v9, vcc
	v_add_co_u32_e32 v46, vcc, s20, v8
	s_nop 1
	v_addc_co_u32_e32 v47, vcc, 0, v9, vcc
	v_add_co_u32_e32 v48, vcc, s21, v8
	s_nop 1
	v_addc_co_u32_e32 v49, vcc, 0, v9, vcc
	global_load_dword v31, v[8:9], off
	global_load_dword v37, v[32:33], off
	global_load_dword v39, v[34:35], off
	global_load_dword v52, v[40:41], off
	global_load_dword v53, v[42:43], off
	global_load_dword v54, v[44:45], off
	global_load_dword v55, v[46:47], off
	global_load_dword v56, v[48:49], off
	v_add_co_u32_e32 v32, vcc, s22, v8
	s_nop 1
	v_addc_co_u32_e32 v33, vcc, 0, v9, vcc
	v_add_co_u32_e32 v34, vcc, s23, v8
	s_nop 1
	v_addc_co_u32_e32 v35, vcc, 0, v9, vcc
	v_add_co_u32_e32 v40, vcc, s24, v8
	s_nop 1
	v_addc_co_u32_e32 v41, vcc, 0, v9, vcc
	v_add_co_u32_e32 v42, vcc, s25, v8
	s_nop 1
	v_addc_co_u32_e32 v43, vcc, 0, v9, vcc
	v_add_co_u32_e32 v44, vcc, s26, v8
	s_nop 1
	v_addc_co_u32_e32 v45, vcc, 0, v9, vcc
	v_add_co_u32_e32 v46, vcc, s27, v8
	s_nop 1
	v_addc_co_u32_e32 v47, vcc, 0, v9, vcc
	v_add_co_u32_e32 v48, vcc, s28, v8
	s_nop 1
	v_addc_co_u32_e32 v49, vcc, 0, v9, vcc
	v_add_co_u32_e32 v50, vcc, s29, v8
	s_nop 1
	v_addc_co_u32_e32 v51, vcc, 0, v9, vcc
	global_load_dword v57, v[32:33], off
	global_load_dword v58, v[34:35], off
	global_load_dword v59, v[40:41], off
	global_load_dword v60, v[42:43], off
	global_load_dword v61, v[44:45], off
	global_load_dword v62, v[46:47], off
	global_load_dword v63, v[48:49], off
	global_load_dword v64, v[50:51], off
	v_add_co_u32_e32 v32, vcc, s30, v8
	s_nop 1
	v_addc_co_u32_e32 v33, vcc, 0, v9, vcc
	v_add_co_u32_e32 v34, vcc, s31, v8
	s_nop 1
	v_addc_co_u32_e32 v35, vcc, 0, v9, vcc
	v_add_co_u32_e32 v40, vcc, s34, v8
	s_nop 1
	v_addc_co_u32_e32 v41, vcc, 0, v9, vcc
	v_add_co_u32_e32 v42, vcc, s35, v8
	s_nop 1
	v_addc_co_u32_e32 v43, vcc, 0, v9, vcc
	v_add_co_u32_e32 v44, vcc, s36, v8
	s_nop 1
	v_addc_co_u32_e32 v45, vcc, 0, v9, vcc
	v_add_co_u32_e32 v46, vcc, s37, v8
	s_nop 1
	v_addc_co_u32_e32 v47, vcc, 0, v9, vcc
	v_add_co_u32_e32 v48, vcc, s38, v8
	s_nop 1
	v_addc_co_u32_e32 v49, vcc, 0, v9, vcc
	v_add_co_u32_e32 v50, vcc, s39, v8
	s_nop 1
	v_addc_co_u32_e32 v51, vcc, 0, v9, vcc
	global_load_dword v65, v[32:33], off
	global_load_dword v66, v[34:35], off
	global_load_dword v67, v[40:41], off
	global_load_dword v68, v[42:43], off
	global_load_dword v69, v[44:45], off
	global_load_dword v70, v[46:47], off
	global_load_dword v71, v[48:49], off
	global_load_dword v50, v[50:51], off
	v_add_co_u32_e32 v32, vcc, s40, v8
	s_nop 1
	v_addc_co_u32_e32 v33, vcc, 0, v9, vcc
	v_add_co_u32_e32 v34, vcc, s41, v8
	s_nop 1
	v_addc_co_u32_e32 v35, vcc, 0, v9, vcc
	v_add_co_u32_e32 v40, vcc, s42, v8
	s_nop 1
	v_addc_co_u32_e32 v41, vcc, 0, v9, vcc
	v_add_co_u32_e32 v42, vcc, s43, v8
	s_nop 1
	v_addc_co_u32_e32 v43, vcc, 0, v9, vcc
	v_add_co_u32_e32 v44, vcc, s44, v8
	s_nop 1
	v_addc_co_u32_e32 v45, vcc, 0, v9, vcc
	v_add_co_u32_e32 v46, vcc, s45, v8
	s_nop 1
	v_addc_co_u32_e32 v47, vcc, 0, v9, vcc
	v_add_co_u32_e32 v48, vcc, s46, v8
	s_nop 1
	v_addc_co_u32_e32 v49, vcc, 0, v9, vcc
	v_add_co_u32_e32 v8, vcc, s47, v8
	s_nop 1
	v_addc_co_u32_e32 v9, vcc, 0, v9, vcc
	global_load_dword v32, v[32:33], off
	global_load_dword v33, v[34:35], off
	global_load_dword v34, v[40:41], off
	global_load_dword v35, v[42:43], off
	global_load_dword v40, v[44:45], off
	global_load_dword v41, v[46:47], off
	global_load_dword v42, v[48:49], off
	global_load_dword v8, v[8:9], off
	s_waitcnt vmcnt(30)
; #define LAS __attribute__((address_space(3)))
; #define GAS __attribute__((address_space(1)))
; __device__ __forceinline__ unsigned cvt_pk_bf16(float lo, float hi) { unsigned r; asm volatile("v_cvt_pk_bf16_f32 %0, %1, %2" : "=v"(r) : "v"(lo), "v"(hi)); return r; }
; __device__ __forceinline__ void transpose_item(const float* W, int ldw, int k0, int n0, bf16_t* WT, int ldt, int drow0, int dk0, LAS float* scr, int lane) {
;     ...
; #pragma unroll
;     for (int i = 0; i < 32; ++i) { const int kk = 2 * i + (lane >> 5); scr[kk * 33 + (lane & 31)] = tv[i]; }
;     asm volatile("s_waitcnt lgkmcnt(0)" ::: "memory");
;     const int c = lane & 7;
; #pragma unroll
;     for (int j = 0; j < 4; ++j) { const int n = (lane >> 3) + 8 * j; const LAS float* s = scr + (8 * c) * 33 + n;
;         u32x4 o; o.x = cvt_pk_bf16(s[0 * 33], s[1 * 33]); o.y = cvt_pk_bf16(s[2 * 33], s[3 * 33]); o.z = cvt_pk_bf16(s[4 * 33], s[5 * 33]); o.w = cvt_pk_bf16(s[6 * 33], s[7 * 33]);
;         *(GAS u32x4*)((GAS bf16_t*)WT + (size_t)(drow0 + n) * ldt + dk0 + 8 * c) = o; }
;     asm volatile("s_waitcnt lgkmcnt(0)" ::: "memory");
	ds_write2_b32 v20, v31, v37 offset1:66
	s_waitcnt vmcnt(28)
	ds_write2_b32 v20, v39, v52 offset0:132 offset1:198
	s_waitcnt vmcnt(26)
	ds_write2_b32 v21, v53, v54 offset0:8 offset1:74
	s_waitcnt vmcnt(24)
	ds_write2_b32 v21, v55, v56 offset0:140 offset1:206
	s_waitcnt vmcnt(22)
	ds_write2_b32 v22, v57, v58 offset0:16 offset1:82
	s_waitcnt vmcnt(20)
	ds_write2_b32 v22, v59, v60 offset0:148 offset1:214
	s_waitcnt vmcnt(18)
	ds_write2_b32 v23, v61, v62 offset0:24 offset1:90
	s_waitcnt vmcnt(16)
	ds_write2_b32 v23, v63, v64 offset0:156 offset1:222
	s_waitcnt vmcnt(14)
	ds_write2_b32 v24, v65, v66 offset0:32 offset1:98
	s_waitcnt vmcnt(12)
	ds_write2_b32 v24, v67, v68 offset0:164 offset1:230
	s_waitcnt vmcnt(10)
	ds_write2_b32 v25, v69, v70 offset0:40 offset1:106
	s_waitcnt vmcnt(8)
	ds_write2_b32 v25, v71, v50 offset0:172 offset1:238
	s_waitcnt vmcnt(6)
	ds_write2_b32 v26, v32, v33 offset0:48 offset1:114
	s_waitcnt vmcnt(4)
	ds_write2_b32 v26, v34, v35 offset0:180 offset1:246
	s_waitcnt vmcnt(2)
	ds_write2_b32 v27, v40, v41 offset0:56 offset1:122
	s_waitcnt vmcnt(0)
	ds_write2_b32 v27, v42, v8 offset0:188 offset1:254
	s_waitcnt lgkmcnt(0)
	ds_read2_b32 v[8:9], v14 offset1:33
	s_waitcnt lgkmcnt(0)
	v_cvt_pk_bf16_f32 v32, v8, v9
	ds_read2_b32 v[8:9], v14 offset0:66 offset1:99
	s_waitcnt lgkmcnt(0)
	v_cvt_pk_bf16_f32 v33, v8, v9
	ds_read2_b32 v[8:9], v14 offset0:132 offset1:165
	v_mov_b64_e32 v[34:35], s[92:93]
	v_mad_i64_i32 v[40:41], s[16:17], v7, s14, v[34:35]
	s_waitcnt lgkmcnt(0)
	v_cvt_pk_bf16_f32 v34, v8, v9
	ds_read2_b32 v[8:9], v14 offset0:198 offset1:231
	v_ashrrev_i32_e32 v39, 31, v38
	s_waitcnt lgkmcnt(0)
	v_cvt_pk_bf16_f32 v35, v8, v9
	v_add_u32_e32 v8, v30, v13
	v_lshl_add_u64 v[38:39], v[38:39], 1, v[40:41]
	v_mov_b32_e32 v7, v1
	v_ashrrev_i32_e32 v9, 31, v8
	v_lshl_add_u64 v[38:39], v[38:39], 0, v[6:7]
	v_lshlrev_b64 v[8:9], 11, v[8:9]
	v_lshl_add_u64 v[8:9], v[38:39], 0, v[8:9]
	ds_read2_b32 v[40:41], v14 offset0:8 offset1:41
	global_store_dwordx4 v[8:9], v[32:35], off
	s_waitcnt lgkmcnt(0)
	s_nop 0
	v_cvt_pk_bf16_f32 v32, v40, v41
	ds_read2_b32 v[8:9], v14 offset0:74 offset1:107
	s_waitcnt lgkmcnt(0)
	v_cvt_pk_bf16_f32 v33, v8, v9
	ds_read2_b32 v[8:9], v14 offset0:140 offset1:173
	s_waitcnt lgkmcnt(0)
	v_cvt_pk_bf16_f32 v34, v8, v9
	ds_read2_b32 v[8:9], v14 offset0:206 offset1:239
	s_waitcnt lgkmcnt(0)
	v_cvt_pk_bf16_f32 v35, v8, v9
	v_add_u32_e32 v8, v30, v15
	v_ashrrev_i32_e32 v9, 31, v8
	v_lshlrev_b64 v[8:9], 11, v[8:9]
	v_lshl_add_u64 v[8:9], v[38:39], 0, v[8:9]
	ds_read2_b32 v[40:41], v14 offset0:16 offset1:49
	global_store_dwordx4 v[8:9], v[32:35], off
	s_waitcnt lgkmcnt(0)
	s_nop 0
	v_cvt_pk_bf16_f32 v32, v40, v41
	ds_read2_b32 v[8:9], v14 offset0:82 offset1:115
	s_waitcnt lgkmcnt(0)
	v_cvt_pk_bf16_f32 v33, v8, v9
	ds_read2_b32 v[8:9], v14 offset0:148 offset1:181
	s_waitcnt lgkmcnt(0)
	v_cvt_pk_bf16_f32 v34, v8, v9
	ds_read2_b32 v[8:9], v14 offset0:214 offset1:247
	s_waitcnt lgkmcnt(0)
	v_cvt_pk_bf16_f32 v35, v8, v9
	v_add_u32_e32 v8, v30, v16
	v_ashrrev_i32_e32 v9, 31, v8
	v_lshlrev_b64 v[8:9], 11, v[8:9]
	v_lshl_add_u64 v[8:9], v[38:39], 0, v[8:9]
	ds_read2_b32 v[40:41], v14 offset0:24 offset1:57
	global_store_dwordx4 v[8:9], v[32:35], off
	s_waitcnt lgkmcnt(0)
	s_nop 0
	v_cvt_pk_bf16_f32 v32, v40, v41
	ds_read2_b32 v[8:9], v14 offset0:90 offset1:123
	s_waitcnt lgkmcnt(0)
	v_cvt_pk_bf16_f32 v33, v8, v9
	ds_read2_b32 v[8:9], v14 offset0:156 offset1:189
	s_waitcnt lgkmcnt(0)
	v_cvt_pk_bf16_f32 v34, v8, v9
	ds_read2_b32 v[8:9], v14 offset0:222 offset1:255
	s_waitcnt lgkmcnt(0)
	v_cvt_pk_bf16_f32 v35, v8, v9
	v_add_u32_e32 v8, v30, v17
	v_ashrrev_i32_e32 v9, 31, v8
	v_lshlrev_b64 v[8:9], 11, v[8:9]
	v_lshl_add_u64 v[8:9], v[38:39], 0, v[8:9]
	global_store_dwordx4 v[8:9], v[32:35], off
	s_waitcnt lgkmcnt(0)

; #define LAS __attribute__((address_space(3)))
; __device__ __forceinline__ void transpose_item(const float* W, int ldw, int k0, int n0, bf16_t* WT, int ldt, int drow0, int dk0, LAS float* scr, int lane) {
;     float tv[32];
; #pragma unroll
;     for (int i = 0; i < 32; ++i) { const int kk = 2 * i + (lane >> 5); tv[i] = W[(size_t)(k0 + kk) * ldw + n0 + (lane & 31)]; }
; __device__ __forceinline__ void prep_weights(const Params& P, LAS unsigned char* lds, int lay, int bid, int G, int sel) {
;     ...
;           if (r < 2 * I_DN) { if (!((sel >> (2 + r / I_DN)) & 1)) continue; const int mat = lay * 2 + r / I_DN, ii = r % I_DN, kb = ii / 32, nb = ii % 32;
;               transpose_item(P.w_down + (size_t)mat * DFF * 1024, 1024, kb * 64, nb * 32, (bf16_t*)(ws + OFF_WDN + mat * SZ_WDN1), DFF, nb * 32, kb * 64, scr, lane); continue; }
.LBB0_27:
	s_movk_i32 s8, 0x15ff
	v_cmp_lt_i32_e32 vcc, s8, v11
	s_and_saveexec_b64 s[8:9], vcc
	s_xor_b64 s[8:9], exec, s[8:9]
	s_cbranch_execz .LBB0_31
	v_add_u32_e32 v7, 0xffffe480, v11
	s_movk_i32 s10, 0xfa7f
	v_cmp_lt_u32_e32 vcc, s10, v7
	s_and_saveexec_b64 s[10:11], vcc
	s_cbranch_execz .LBB0_30
	v_and_b32_e32 v7, 0xfc0, v19
	v_and_b32_e32 v37, 0x3e0, v18
	v_or_b32_e32 v30, v7, v12
	v_lshlrev_b32_e32 v8, 2, v37
	v_mov_b32_e32 v9, v1
	v_lshl_add_u64 v[8:9], v[4:5], 0, v[8:9]
	v_lshlrev_b32_e32 v30, 12, v30
	v_mov_b32_e32 v31, v1
	v_lshl_add_u64 v[8:9], v[8:9], 0, v[30:31]
	v_add_co_u32_e32 v30, vcc, 0x2000, v8
	s_nop 1
	v_addc_co_u32_e32 v31, vcc, 0, v9, vcc
	v_add_co_u32_e32 v32, vcc, 0x4000, v8
	s_nop 1
	v_addc_co_u32_e32 v33, vcc, 0, v9, vcc
	v_add_co_u32_e32 v34, vcc, 0x6000, v8
	s_nop 1
	v_addc_co_u32_e32 v35, vcc, 0, v9, vcc
	v_add_co_u32_e32 v38, vcc, 0x8000, v8
	s_nop 1
	v_addc_co_u32_e32 v39, vcc, 0, v9, vcc
	v_add_co_u32_e32 v40, vcc, 0xa000, v8
	s_nop 1
	v_addc_co_u32_e32 v41, vcc, 0, v9, vcc
	v_add_co_u32_e32 v42, vcc, 0xc000, v8
	s_nop 1
	v_addc_co_u32_e32 v43, vcc, 0, v9, vcc
	v_add_co_u32_e32 v44, vcc, 0xe000, v8
	s_nop 1
	v_addc_co_u32_e32 v45, vcc, 0, v9, vcc
	global_load_dword v48, v[8:9], off
	global_load_dword v49, v[30:31], off
	global_load_dword v50, v[32:33], off
	global_load_dword v51, v[34:35], off
	global_load_dword v52, v[38:39], off
	global_load_dword v53, v[40:41], off
	global_load_dword v54, v[42:43], off
	global_load_dword v55, v[44:45], off
	v_add_co_u32_e32 v30, vcc, 0x10000, v8
	s_nop 1
	v_addc_co_u32_e32 v31, vcc, 0, v9, vcc
	v_add_co_u32_e32 v32, vcc, 0x12000, v8
	s_nop 1
	v_addc_co_u32_e32 v33, vcc, 0, v9, vcc
	v_add_co_u32_e32 v34, vcc, 0x14000, v8
	s_nop 1
	v_addc_co_u32_e32 v35, vcc, 0, v9, vcc
	v_add_co_u32_e32 v38, vcc, 0x16000, v8
	s_nop 1
	v_addc_co_u32_e32 v39, vcc, 0, v9, vcc
	v_add_co_u32_e32 v40, vcc, 0x18000, v8
	s_nop 1
	v_addc_co_u32_e32 v41, vcc, 0, v9, vcc
	v_add_co_u32_e32 v42, vcc, 0x1a000, v8
	s_nop 1
	v_addc_co_u32_e32 v43, vcc, 0, v9, vcc
	v_add_co_u32_e32 v44, vcc, 0x1c000, v8
	s_nop 1
	v_addc_co_u32_e32 v45, vcc, 0, v9, vcc
	v_add_co_u32_e32 v46, vcc, 0x1e000, v8
	s_nop 1
	v_addc_co_u32_e32 v47, vcc, 0, v9, vcc
	global_load_dword v56, v[30:31], off
	global_load_dword v57, v[32:33], off
	global_load_dword v58, v[34:35], off
	global_load_dword v59, v[38:39], off
	global_load_dword v60, v[40:41], off
	global_load_dword v61, v[42:43], off
	global_load_dword v62, v[44:45], off
	global_load_dword v63, v[46:47], off
	v_add_co_u32_e32 v30, vcc, 0x20000, v8
	s_nop 1
	v_addc_co_u32_e32 v31, vcc, 0, v9, vcc
	v_add_co_u32_e32 v32, vcc, 0x22000, v8
	s_nop 1
	v_addc_co_u32_e32 v33, vcc, 0, v9, vcc
	v_add_co_u32_e32 v34, vcc, 0x24000, v8
	s_nop 1
	v_addc_co_u32_e32 v35, vcc, 0, v9, vcc
	v_add_co_u32_e32 v38, vcc, 0x26000, v8
	s_nop 1
	v_addc_co_u32_e32 v39, vcc, 0, v9, vcc
	v_add_co_u32_e32 v40, vcc, 0x28000, v8
	s_nop 1
	v_addc_co_u32_e32 v41, vcc, 0, v9, vcc
	v_add_co_u32_e32 v42, vcc, 0x2a000, v8
	s_nop 1
	v_addc_co_u32_e32 v43, vcc, 0, v9, vcc
	v_add_co_u32_e32 v44, vcc, 0x2c000, v8
	s_nop 1
	v_addc_co_u32_e32 v45, vcc, 0, v9, vcc
	v_add_co_u32_e32 v46, vcc, 0x2e000, v8
	s_nop 1
	v_addc_co_u32_e32 v47, vcc, 0, v9, vcc
	global_load_dword v64, v[30:31], off
	global_load_dword v65, v[32:33], off
	global_load_dword v66, v[34:35], off
	global_load_dword v67, v[38:39], off
	global_load_dword v68, v[40:41], off
	global_load_dword v69, v[42:43], off
	global_load_dword v70, v[44:45], off
	global_load_dword v46, v[46:47], off
	v_add_co_u32_e32 v30, vcc, 0x30000, v8
	s_nop 1
	v_addc_co_u32_e32 v31, vcc, 0, v9, vcc
	v_add_co_u32_e32 v32, vcc, 0x32000, v8
	s_nop 1
	v_addc_co_u32_e32 v33, vcc, 0, v9, vcc
	v_add_co_u32_e32 v34, vcc, 0x34000, v8
	s_nop 1
	v_addc_co_u32_e32 v35, vcc, 0, v9, vcc
	v_add_co_u32_e32 v38, vcc, 0x36000, v8
	s_nop 1
	v_addc_co_u32_e32 v39, vcc, 0, v9, vcc
	v_add_co_u32_e32 v40, vcc, 0x38000, v8
	s_nop 1
	v_addc_co_u32_e32 v41, vcc, 0, v9, vcc
	v_add_co_u32_e32 v42, vcc, 0x3a000, v8
	s_nop 1
	v_addc_co_u32_e32 v43, vcc, 0, v9, vcc
	v_add_co_u32_e32 v44, vcc, 0x3c000, v8
	s_nop 1
	v_addc_co_u32_e32 v45, vcc, 0, v9, vcc
	v_add_co_u32_e32 v8, vcc, 0x3e000, v8
	s_nop 1
	v_addc_co_u32_e32 v9, vcc, 0, v9, vcc
	global_load_dword v30, v[30:31], off
	global_load_dword v31, v[32:33], off
	global_load_dword v32, v[34:35], off
	global_load_dword v33, v[38:39], off
	global_load_dword v34, v[40:41], off
	global_load_dword v35, v[42:43], off
	global_load_dword v38, v[44:45], off
	global_load_dword v8, v[8:9], off
	s_waitcnt vmcnt(30)
; #define LAS __attribute__((address_space(3)))
; #define GAS __attribute__((address_space(1)))
; __device__ __forceinline__ unsigned cvt_pk_bf16(float lo, float hi) { unsigned r; asm volatile("v_cvt_pk_bf16_f32 %0, %1, %2" : "=v"(r) : "v"(lo), "v"(hi)); return r; }
; __device__ __forceinline__ void transpose_item(const float* W, int ldw, int k0, int n0, bf16_t* WT, int ldt, int drow0, int dk0, LAS float* scr, int lane) {
;     ...
; #pragma unroll
;     for (int i = 0; i < 32; ++i) { const int kk = 2 * i + (lane >> 5); scr[kk * 33 + (lane & 31)] = tv[i]; }
;     asm volatile("s_waitcnt lgkmcnt(0)" ::: "memory");
;     const int c = lane & 7;
; #pragma unroll
;     for (int j = 0; j < 4; ++j) { const int n = (lane >> 3) + 8 * j; const LAS float* s = scr + (8 * c) * 33 + n;
;         u32x4 o; o.x = cvt_pk_bf16(s[0 * 33], s[1 * 33]); o.y = cvt_pk_bf16(s[2 * 33], s[3 * 33]); o.z = cvt_pk_bf16(s[4 * 33], s[5 * 33]); o.w = cvt_pk_bf16(s[6 * 33], s[7 * 33]);
;         *(GAS u32x4*)((GAS bf16_t*)WT + (size_t)(drow0 + n) * ldt + dk0 + 8 * c) = o; }
;     asm volatile("s_waitcnt lgkmcnt(0)" ::: "memory");
	ds_write2_b32 v20, v48, v49 offset1:66
	s_waitcnt vmcnt(28)
	ds_write2_b32 v20, v50, v51 offset0:132 offset1:198
	s_waitcnt vmcnt(26)
	ds_write2_b32 v21, v52, v53 offset0:8 offset1:74
	s_waitcnt vmcnt(24)
	ds_write2_b32 v21, v54, v55 offset0:140 offset1:206
	s_waitcnt vmcnt(22)
	ds_write2_b32 v22, v56, v57 offset0:16 offset1:82
	s_waitcnt vmcnt(20)
	ds_write2_b32 v22, v58, v59 offset0:148 offset1:214
	s_waitcnt vmcnt(18)
	ds_write2_b32 v23, v60, v61 offset0:24 offset1:90
	s_waitcnt vmcnt(16)
	ds_write2_b32 v23, v62, v63 offset0:156 offset1:222
	s_waitcnt vmcnt(14)
	ds_write2_b32 v24, v64, v65 offset0:32 offset1:98
	s_waitcnt vmcnt(12)
	ds_write2_b32 v24, v66, v67 offset0:164 offset1:230
	s_waitcnt vmcnt(10)
	ds_write2_b32 v25, v68, v69 offset0:40 offset1:106
	s_waitcnt vmcnt(8)
	ds_write2_b32 v25, v70, v46 offset0:172 offset1:238
	s_waitcnt vmcnt(6)
	ds_write2_b32 v26, v30, v31 offset0:48 offset1:114
	s_waitcnt vmcnt(4)
	ds_write2_b32 v26, v32, v33 offset0:180 offset1:246
	s_waitcnt vmcnt(2)
	ds_write2_b32 v27, v34, v35 offset0:56 offset1:122
	s_waitcnt vmcnt(0)
	ds_write2_b32 v27, v38, v8 offset0:188 offset1:254
	s_waitcnt lgkmcnt(0)
	ds_read2_b32 v[8:9], v14 offset1:33
	s_waitcnt lgkmcnt(0)
	v_cvt_pk_bf16_f32 v30, v8, v9
	ds_read2_b32 v[8:9], v14 offset0:66 offset1:99
	v_lshlrev_b32_e32 v34, 1, v7
	v_or_b32_e32 v7, v37, v13
	s_waitcnt lgkmcnt(0)
	v_cvt_pk_bf16_f32 v31, v8, v9
	ds_read2_b32 v[8:9], v14 offset0:132 offset1:165
	v_mov_b32_e32 v35, v1
	v_mul_u32_u24_e32 v7, 0xb00, v7
	s_waitcnt lgkmcnt(0)
	v_cvt_pk_bf16_f32 v32, v8, v9
	ds_read2_b32 v[8:9], v14 offset0:198 offset1:231
	v_lshl_add_u64 v[34:35], v[2:3], 0, v[34:35]
	v_lshlrev_b32_e32 v38, 1, v7
	v_mov_b32_e32 v39, v1
	s_waitcnt lgkmcnt(0)
	v_cvt_pk_bf16_f32 v33, v8, v9
	ds_read2_b32 v[8:9], v14 offset0:8 offset1:41
	v_lshl_add_u64 v[38:39], v[34:35], 0, v[38:39]
	global_store_dwordx4 v[38:39], v[30:33], off
	v_or_b32_e32 v7, v37, v15
	v_mul_u32_u24_e32 v7, 0xb00, v7
	s_waitcnt lgkmcnt(0)
	v_cvt_pk_bf16_f32 v30, v8, v9
	ds_read2_b32 v[8:9], v14 offset0:74 offset1:107
	s_waitcnt lgkmcnt(0)
	v_cvt_pk_bf16_f32 v31, v8, v9
	ds_read2_b32 v[8:9], v14 offset0:140 offset1:173
	s_waitcnt lgkmcnt(0)
	v_cvt_pk_bf16_f32 v32, v8, v9
	ds_read2_b32 v[8:9], v14 offset0:206 offset1:239
	v_lshlrev_b32_e32 v38, 1, v7
	v_mov_b32_e32 v39, v1
	s_waitcnt lgkmcnt(0)
	v_cvt_pk_bf16_f32 v33, v8, v9
	ds_read2_b32 v[8:9], v14 offset0:16 offset1:49
	v_lshl_add_u64 v[38:39], v[34:35], 0, v[38:39]
	global_store_dwordx4 v[38:39], v[30:33], off
	v_or_b32_e32 v7, v37, v16
	v_mul_u32_u24_e32 v7, 0xb00, v7
	s_waitcnt lgkmcnt(0)
	v_cvt_pk_bf16_f32 v30, v8, v9
	ds_read2_b32 v[8:9], v14 offset0:82 offset1:115
	s_waitcnt lgkmcnt(0)
	v_cvt_pk_bf16_f32 v31, v8, v9
	ds_read2_b32 v[8:9], v14 offset0:148 offset1:181
	s_waitcnt lgkmcnt(0)
	v_cvt_pk_bf16_f32 v32, v8, v9
	ds_read2_b32 v[8:9], v14 offset0:214 offset1:247
	v_lshlrev_b32_e32 v38, 1, v7
	v_mov_b32_e32 v39, v1
	s_waitcnt lgkmcnt(0)
	v_cvt_pk_bf16_f32 v33, v8, v9
	ds_read2_b32 v[8:9], v14 offset0:24 offset1:57
	v_lshl_add_u64 v[38:39], v[34:35], 0, v[38:39]
	global_store_dwordx4 v[38:39], v[30:33], off
	v_or_b32_e32 v7, v37, v17
	v_mul_u32_u24_e32 v7, 0xb00, v7
	s_waitcnt lgkmcnt(0)
	v_cvt_pk_bf16_f32 v30, v8, v9
	ds_read2_b32 v[8:9], v14 offset0:90 offset1:123
	s_waitcnt lgkmcnt(0)
	v_cvt_pk_bf16_f32 v31, v8, v9
	ds_read2_b32 v[8:9], v14 offset0:156 offset1:189
	s_waitcnt lgkmcnt(0)
	v_cvt_pk_bf16_f32 v32, v8, v9
	ds_read2_b32 v[8:9], v14 offset0:222 offset1:255
	s_waitcnt lgkmcnt(0)
	v_cvt_pk_bf16_f32 v33, v8, v9
	v_lshlrev_b32_e32 v8, 1, v7
	v_mov_b32_e32 v9, v1
	v_lshl_add_u64 v[8:9], v[34:35], 0, v[8:9]
	global_store_dwordx4 v[8:9], v[30:33], off
	s_waitcnt lgkmcnt(0)

; __device__ __forceinline__ void prep_weights(const Params& P, LAS unsigned char* lds, int lay, int bid, int G, int sel) {
;     ...
;       for (int idx = gt; idx < ((sel & 32) ? 256 * 1024 : 0); idx += NGT) { const int n = idx & 1023, gj = (idx >> 10) & 255, g = gj >> 6, j = gj & 63;
;           const float* wp = P.w_out + (size_t)l * 1024 * 1024 + (size_t)(768 + g * 64) * 1024 + n; float cs = 0.f, sn = 0.f;
; #pragma unroll 1
;           for (int m0 = 0; m0 < 64; m0 += 32) { float wv[32];
; #pragma unroll
;               for (int m = 0; m < 32; ++m) wv[m] = wp[(size_t)(m0 + m) * 1024];
; #pragma unroll
;               for (int m = 0; m < 32; ++m) { const int t = ((m0 + m) * j) & 63; cs += tab64[t] * wv[m]; sn += tab64[(t + 48) & 63] * wv[m]; } }
.LBB0_40:
	s_lshl_b32 s10, s13, 10
	v_lshl_add_u64 v[22:23], s[10:11], 2, v[4:5]
	v_mul_u32_u24_e32 v2, s13, v19
	v_mad_u32_u24 v8, s13, v19, 48
	v_mad_u32_u24 v9, s13, v19, v19
	v_add_co_u32_e32 v14, vcc, 0x1000, v22
	v_and_b32_e32 v10, 32, v2
	v_and_b32_e32 v8, 48, v8
	v_and_b32_e32 v11, 63, v9
	v_add_u32_e32 v12, 48, v9
	v_add_u32_e32 v9, v9, v19
	v_addc_co_u32_e32 v15, vcc, 0, v23, vcc
	v_lshl_add_u32 v10, v10, 2, s3
	v_lshl_add_u32 v16, v8, 2, s3
	v_and_b32_e32 v17, 62, v9
	v_add_u32_e32 v18, 48, v9
	v_add_u32_e32 v21, v9, v19
	v_add_co_u32_e32 v20, vcc, 0x2000, v22
	global_load_dword v2, v[22:23], off
	v_lshl_add_u32 v11, v11, 2, s3
	ds_read_b32 v8, v10
	ds_read_b32 v9, v16
	ds_read_b32 v10, v11
	v_lshl_add_u32 v16, v17, 2, s3
	v_and_b32_e32 v17, 62, v18
	v_and_b32_e32 v18, 63, v21
	v_add_u32_e32 v25, 48, v21
	v_add_u32_e32 v26, v21, v19
	v_addc_co_u32_e32 v21, vcc, 0, v23, vcc
	v_and_b32_e32 v12, 63, v12
	v_add_co_u32_e32 v24, vcc, 0x3000, v22
	v_lshl_add_u32 v11, v12, 2, s3
	global_load_dword v12, v[14:15], off
	v_lshl_add_u32 v15, v17, 2, s3
	v_and_b32_e32 v17, 63, v25
	v_addc_co_u32_e32 v25, vcc, 0, v23, vcc
	v_add_co_u32_e32 v28, vcc, 0x4000, v22
	ds_read_b32 v11, v11
	ds_read_b32 v14, v16
	v_lshl_add_u32 v16, v18, 2, s3
	v_and_b32_e32 v18, 60, v26
	v_addc_co_u32_e32 v29, vcc, 0, v23, vcc
	v_lshl_add_u32 v17, v17, 2, s3
	v_lshl_add_u32 v31, v18, 2, s3
	v_add_co_u32_e32 v30, vcc, 0x5000, v22
	ds_read_b32 v15, v15
	ds_read_b32 v16, v16
	global_load_dword v18, v[20:21], off
	global_load_dword v20, v[24:25], off
	ds_read_b32 v17, v17
	ds_read_b32 v24, v31
	v_addc_co_u32_e32 v31, vcc, 0, v23, vcc
	v_add_co_u32_e32 v38, vcc, 0x6000, v22
	v_add_u32_e32 v27, 48, v26
	s_nop 0
	v_addc_co_u32_e32 v39, vcc, 0, v23, vcc
	v_add_co_u32_e32 v40, vcc, 0x7000, v22
	v_add_u32_e32 v26, v26, v19
	s_nop 0
	v_addc_co_u32_e32 v41, vcc, 0, v23, vcc
	v_add_co_u32_e32 v46, vcc, 0x8000, v22
	v_and_b32_e32 v27, 60, v27
	s_nop 0
	v_addc_co_u32_e32 v47, vcc, 0, v23, vcc
	v_add_co_u32_e32 v48, vcc, 0x9000, v22
	v_and_b32_e32 v32, 63, v26
	s_nop 0
	v_addc_co_u32_e32 v49, vcc, 0, v23, vcc
	v_add_co_u32_e32 v54, vcc, 0xa000, v22
	v_add_u32_e32 v33, 48, v26
	s_nop 0
	v_addc_co_u32_e32 v55, vcc, 0, v23, vcc
	v_add_co_u32_e32 v56, vcc, 0xb000, v22
	v_add_u32_e32 v26, v26, v19
	s_nop 0
	v_addc_co_u32_e32 v57, vcc, 0, v23, vcc
	v_add_co_u32_e32 v62, vcc, 0xc000, v22
	v_lshl_add_u32 v21, v27, 2, s3
	s_nop 0
	v_addc_co_u32_e32 v63, vcc, 0, v23, vcc
	v_add_co_u32_e32 v64, vcc, 0xd000, v22
	v_lshl_add_u32 v27, v32, 2, s3
	s_nop 0
	v_addc_co_u32_e32 v65, vcc, 0, v23, vcc
	v_add_co_u32_e32 v70, vcc, 0xe000, v22
	v_and_b32_e32 v32, 63, v33
	s_nop 0
	v_addc_co_u32_e32 v71, vcc, 0, v23, vcc
	v_add_co_u32_e32 v72, vcc, 0xf000, v22
	v_and_b32_e32 v33, 62, v26
	s_nop 0
	v_addc_co_u32_e32 v73, vcc, 0, v23, vcc
	v_add_co_u32_e32 v74, vcc, 0x10000, v22
	v_add_u32_e32 v34, 48, v26
	s_nop 0
	v_addc_co_u32_e32 v75, vcc, 0, v23, vcc
	v_add_co_u32_e32 v76, vcc, 0x11000, v22
	v_add_u32_e32 v35, v26, v19
	s_nop 0
	v_addc_co_u32_e32 v77, vcc, 0, v23, vcc
	v_add_co_u32_e32 v80, vcc, 0x12000, v22
	ds_read_b32 v25, v21
	ds_read_b32 v26, v27
	v_lshl_add_u32 v21, v32, 2, s3
	v_lshl_add_u32 v32, v33, 2, s3
	v_and_b32_e32 v33, 62, v34
	v_and_b32_e32 v34, 63, v35
	v_add_u32_e32 v37, 48, v35
	v_add_u32_e32 v35, v35, v19
	global_load_dword v28, v[28:29], off
	global_load_dword v30, v[30:31], off
	v_addc_co_u32_e32 v81, vcc, 0, v23, vcc
	ds_read_b32 v27, v21
	ds_read_b32 v32, v32
	v_lshl_add_u32 v21, v33, 2, s3
	v_lshl_add_u32 v29, v34, 2, s3
	v_and_b32_e32 v31, 63, v37
	v_and_b32_e32 v37, 56, v35
	v_add_u32_e32 v42, 48, v35
	v_add_u32_e32 v35, v35, v19
	v_add_co_u32_e32 v84, vcc, 0x13000, v22
	ds_read_b32 v33, v21
	ds_read_b32 v34, v29
	v_lshl_add_u32 v21, v31, 2, s3
	v_lshl_add_u32 v29, v37, 2, s3
	v_and_b32_e32 v31, 56, v42
	v_and_b32_e32 v37, 63, v35
	v_add_u32_e32 v43, 48, v35
	v_add_u32_e32 v44, v35, v19
	global_load_dword v38, v[38:39], off
	global_load_dword v40, v[40:41], off
	v_addc_co_u32_e32 v85, vcc, 0, v23, vcc
	ds_read_b32 v35, v21
	ds_read_b32 v42, v29
	v_lshl_add_u32 v21, v31, 2, s3
	v_lshl_add_u32 v29, v37, 2, s3
	v_and_b32_e32 v31, 63, v43
	v_and_b32_e32 v37, 62, v44
	v_add_u32_e32 v39, 48, v44
	v_add_u32_e32 v41, v44, v19
	v_add_co_u32_e32 v88, vcc, 0x14000, v22
	ds_read_b32 v43, v21
	ds_read_b32 v44, v29
	v_lshl_add_u32 v21, v31, 2, s3
	v_lshl_add_u32 v29, v37, 2, s3
	v_and_b32_e32 v31, 62, v39
	v_and_b32_e32 v37, 63, v41
	v_add_u32_e32 v39, 48, v41
	v_add_u32_e32 v41, v41, v19
	global_load_dword v46, v[46:47], off
	global_load_dword v48, v[48:49], off
	v_addc_co_u32_e32 v89, vcc, 0, v23, vcc
	ds_read_b32 v45, v21
	ds_read_b32 v50, v29
	v_lshl_add_u32 v21, v31, 2, s3
	v_lshl_add_u32 v29, v37, 2, s3
	v_and_b32_e32 v31, 63, v39
	v_and_b32_e32 v37, 60, v41
	v_add_u32_e32 v39, 48, v41
	v_add_u32_e32 v41, v41, v19
	v_add_co_u32_e32 v92, vcc, 0x15000, v22
	ds_read_b32 v51, v21
	ds_read_b32 v52, v29
	v_lshl_add_u32 v21, v31, 2, s3
	v_lshl_add_u32 v29, v37, 2, s3
	v_and_b32_e32 v31, 60, v39
	v_and_b32_e32 v37, 63, v41
	v_add_u32_e32 v39, 48, v41
	v_add_u32_e32 v41, v41, v19
	global_load_dword v54, v[54:55], off
	global_load_dword v56, v[56:57], off
	v_addc_co_u32_e32 v93, vcc, 0, v23, vcc
	ds_read_b32 v53, v21
	ds_read_b32 v58, v29
	v_lshl_add_u32 v21, v31, 2, s3
	v_lshl_add_u32 v29, v37, 2, s3
	v_and_b32_e32 v31, 63, v39
	v_and_b32_e32 v37, 62, v41
	v_add_u32_e32 v39, 48, v41
	v_add_u32_e32 v41, v41, v19
	v_add_co_u32_e32 v96, vcc, 0x16000, v22
	ds_read_b32 v59, v21
	ds_read_b32 v60, v29
	v_lshl_add_u32 v21, v31, 2, s3
	v_lshl_add_u32 v29, v37, 2, s3
	v_and_b32_e32 v31, 62, v39
; __device__ __forceinline__ void prep_weights(const Params& P, LAS unsigned char* lds, int lay, int bid, int G, int sel) {
;     ...
;           for (int m0 = 0; m0 < 64; m0 += 32) { float wv[32];
; #pragma unroll
;               for (int m = 0; m < 32; ++m) wv[m] = wp[(size_t)(m0 + m) * 1024];
; #pragma unroll
;               for (int m = 0; m < 32; ++m) { const int t = ((m0 + m) * j) & 63; cs += tab64[t] * wv[m]; sn += tab64[(t + 48) & 63] * wv[m]; } }
	v_and_b32_e32 v37, 63, v41
	v_add_u32_e32 v39, 48, v41
	v_add_u32_e32 v41, v41, v19
	global_load_dword v62, v[62:63], off
	global_load_dword v64, v[64:65], off
	v_addc_co_u32_e32 v97, vcc, 0, v23, vcc
	ds_read_b32 v61, v21
	ds_read_b32 v66, v29
	v_lshl_add_u32 v21, v31, 2, s3
	v_lshl_add_u32 v29, v37, 2, s3
	v_and_b32_e32 v31, 63, v39
	v_and_b32_e32 v37, 48, v41
	v_add_u32_e32 v39, 48, v41
	v_add_u32_e32 v41, v41, v19
	v_add_co_u32_e32 v100, vcc, 0x17000, v22
	ds_read_b32 v67, v21
	ds_read_b32 v68, v29
	v_lshl_add_u32 v21, v31, 2, s3
	v_lshl_add_u32 v29, v37, 2, s3
	v_and_b32_e32 v31, 48, v39
	v_and_b32_e32 v37, 63, v41
	v_add_u32_e32 v39, 48, v41
	v_add_u32_e32 v41, v41, v19
	global_load_dword v70, v[70:71], off
	global_load_dword v72, v[72:73], off
	v_addc_co_u32_e32 v101, vcc, 0, v23, vcc
	ds_read_b32 v69, v21
	ds_read_b32 v78, v29
	v_lshl_add_u32 v21, v31, 2, s3
	v_lshl_add_u32 v29, v37, 2, s3
	v_and_b32_e32 v31, 63, v39
	v_and_b32_e32 v37, 62, v41
	v_add_u32_e32 v39, 48, v41
	v_add_u32_e32 v41, v41, v19
	v_add_co_u32_e32 v104, vcc, 0x18000, v22
	ds_read_b32 v79, v21
	ds_read_b32 v82, v29
	v_lshl_add_u32 v21, v31, 2, s3
	v_lshl_add_u32 v29, v37, 2, s3
	v_and_b32_e32 v31, 62, v39
	v_and_b32_e32 v37, 63, v41
	v_add_u32_e32 v39, 48, v41
	v_add_u32_e32 v41, v41, v19
	global_load_dword v74, v[74:75], off
	global_load_dword v76, v[76:77], off
	v_addc_co_u32_e32 v105, vcc, 0, v23, vcc
	ds_read_b32 v83, v21
	ds_read_b32 v86, v29
	v_lshl_add_u32 v21, v31, 2, s3
	v_lshl_add_u32 v29, v37, 2, s3
	v_and_b32_e32 v31, 63, v39
	v_and_b32_e32 v37, 60, v41
	v_add_u32_e32 v39, 48, v41
	v_add_u32_e32 v41, v41, v19
	v_add_co_u32_e32 v108, vcc, 0x19000, v22
	ds_read_b32 v87, v21
	ds_read_b32 v90, v29
	v_lshl_add_u32 v21, v31, 2, s3
	v_lshl_add_u32 v29, v37, 2, s3
	v_and_b32_e32 v31, 60, v39
	v_and_b32_e32 v37, 63, v41
	v_add_u32_e32 v39, 48, v41
	v_add_u32_e32 v41, v41, v19
	global_load_dword v80, v[80:81], off
	global_load_dword v84, v[84:85], off
	v_addc_co_u32_e32 v109, vcc, 0, v23, vcc
	ds_read_b32 v91, v21
	ds_read_b32 v94, v29
	v_lshl_add_u32 v21, v31, 2, s3
	v_lshl_add_u32 v29, v37, 2, s3
	v_and_b32_e32 v31, 63, v39
	v_and_b32_e32 v37, 62, v41
	v_add_u32_e32 v39, 48, v41
	v_add_u32_e32 v41, v41, v19
	v_add_co_u32_e32 v112, vcc, 0x1a000, v22
	ds_read_b32 v95, v21
	ds_read_b32 v98, v29
	v_lshl_add_u32 v21, v31, 2, s3
	v_and_b32_e32 v31, 62, v39
	v_add_u32_e32 v39, 48, v41
	global_load_dword v88, v[88:89], off
	global_load_dword v92, v[92:93], off
	v_addc_co_u32_e32 v113, vcc, 0, v23, vcc
	v_lshl_add_u32 v29, v37, 2, s3
	v_and_b32_e32 v37, 63, v41
	v_add_u32_e32 v41, v41, v19
	ds_read_b32 v99, v21
	ds_read_b32 v102, v29
	v_lshl_add_u32 v21, v31, 2, s3
	v_and_b32_e32 v31, 63, v39
	global_load_dword v96, v[96:97], off
	v_add_co_u32_e32 v114, vcc, 0x1b000, v22
	v_lshl_add_u32 v29, v37, 2, s3
	v_and_b32_e32 v37, 56, v41
	v_lshl_add_u32 v31, v31, 2, s3
	ds_read_b32 v103, v21
	ds_read_b32 v106, v29
	global_load_dword v100, v[100:101], off
	v_addc_co_u32_e32 v115, vcc, 0, v23, vcc
	v_lshl_add_u32 v37, v37, 2, s3
	ds_read_b32 v107, v31
	ds_read_b32 v110, v37
	global_load_dword v104, v[104:105], off
	v_add_co_u32_e32 v116, vcc, 0x1c000, v22
	global_load_dword v108, v[108:109], off
	s_nop 0
	v_addc_co_u32_e32 v117, vcc, 0, v23, vcc
	global_load_dword v112, v[112:113], off
	v_add_co_u32_e32 v118, vcc, 0x1d000, v22
	global_load_dword v114, v[114:115], off
	s_nop 0
	v_addc_co_u32_e32 v119, vcc, 0, v23, vcc
	v_add_co_u32_e32 v120, vcc, 0x1e000, v22
	global_load_dword v116, v[116:117], off
	s_nop 0
	v_addc_co_u32_e32 v121, vcc, 0, v23, vcc
	global_load_dword v118, v[118:119], off
	v_add_co_u32_e32 v22, vcc, 0x1f000, v22
	v_add_u32_e32 v39, 48, v41
	s_nop 0
	v_addc_co_u32_e32 v23, vcc, 0, v23, vcc
	global_load_dword v120, v[120:121], off
	global_load_dword v22, v[22:23], off
	v_add_u32_e32 v41, v41, v19
	v_and_b32_e32 v39, 56, v39
	v_and_b32_e32 v47, 63, v41
	v_add_u32_e32 v49, 48, v41
	v_add_u32_e32 v41, v41, v19
	v_lshl_add_u32 v21, v39, 2, s3
	v_and_b32_e32 v31, 63, v49
	v_and_b32_e32 v37, 62, v41
	v_add_u32_e32 v39, 48, v41
	v_add_u32_e32 v41, v41, v19
	v_lshl_add_u32 v29, v47, 2, s3
	v_lshl_add_u32 v31, v31, 2, s3
	v_lshl_add_u32 v37, v37, 2, s3
	v_and_b32_e32 v23, 62, v39
	v_and_b32_e32 v39, 63, v41
	v_add_u32_e32 v47, 48, v41
	v_add_u32_e32 v41, v41, v19
	ds_read_b32 v111, v21
	ds_read_b32 v122, v29
	ds_read_b32 v123, v31
	ds_read_b32 v124, v37
	v_lshl_add_u32 v21, v23, 2, s3
	v_lshl_add_u32 v23, v39, 2, s3
	v_and_b32_e32 v29, 63, v47
	v_and_b32_e32 v31, 60, v41
	v_add_u32_e32 v37, 48, v41
	v_add_u32_e32 v39, v41, v19
	v_lshl_add_u32 v29, v29, 2, s3
	v_lshl_add_u32 v31, v31, 2, s3
	v_and_b32_e32 v37, 60, v37
	v_and_b32_e32 v41, 63, v39
	v_add_u32_e32 v47, 48, v39
	v_add_u32_e32 v39, v39, v19
	ds_read_b32 v125, v21
	ds_read_b32 v126, v23
	ds_read_b32 v127, v29
	ds_read_b32 v128, v31
	v_lshl_add_u32 v21, v37, 2, s3
	v_and_b32_e32 v29, 63, v47
	v_and_b32_e32 v31, 62, v39
	v_add_u32_e32 v37, 48, v39
	v_add_u32_e32 v39, v39, v19
	s_waitcnt vmcnt(31) lgkmcnt(14)
	v_pk_fma_f32 v[6:7], v[2:3], v[8:9], v[6:7] op_sel_hi:[0,1,1]
	v_lshl_add_u32 v23, v41, 2, s3
	v_lshl_add_u32 v29, v29, 2, s3
	v_and_b32_e32 v37, 62, v37
	v_and_b32_e32 v41, 63, v39
	v_add_u32_e32 v39, 48, v39
	s_waitcnt vmcnt(30)
; __device__ __forceinline__ unsigned f2bf(float f) { unsigned u = __float_as_uint(f); return (u + 0x7fffu + ((u >> 16) & 1u)) >> 16; }
; __device__ __forceinline__ void prep_weights(const Params& P, LAS unsigned char* lds, int lay, int bid, int G, int sel) {
;     ...
;           for (int m0 = 0; m0 < 64; m0 += 32) { float wv[32];
; #pragma unroll
;               for (int m = 0; m < 32; ++m) wv[m] = wp[(size_t)(m0 + m) * 1024];
; #pragma unroll
;               for (int m = 0; m < 32; ++m) { const int t = ((m0 + m) * j) & 63; cs += tab64[t] * wv[m]; sn += tab64[(t + 48) & 63] * wv[m]; } }
;           bf16_t* o = (bf16_t*)(ws + OFF_WOUT + l * SZ_WOUT1) + (size_t)n * 1280; o[768 + gj] = (bf16_t)f2bf(cs); o[1024 + gj] = (bf16_t)f2bf(-sn); }
;       for (int i0 = gt; i0 < ((sel & 64) ? 131072 : 0); i0 += NGT) { const int idx = l * 131072 + i0; const int i = idx & 63, j = (idx >> 6) & 63, hi = idx >> 12;
;           ((bf16_t*)(ws + OFF_WGT))[idx] = (bf16_t)f2bf(P.lru_wg[(size_t)hi * 4096 + i * 64 + j]); }
	v_pk_fma_f32 v[6:7], v[12:13], v[10:11], v[6:7] op_sel_hi:[0,1,1]
	v_lshl_add_u32 v31, v31, 2, s3
	ds_read_b32 v129, v21
	ds_read_b32 v130, v23
	ds_read_b32 v131, v29
	ds_read_b32 v132, v31
	v_lshl_add_u32 v21, v37, 2, s3
	v_and_b32_e32 v29, 63, v39
	s_waitcnt vmcnt(29)
	v_pk_fma_f32 v[6:7], v[18:19], v[14:15], v[6:7] op_sel_hi:[0,1,1]
	v_lshl_add_u32 v29, v29, 2, s3
	s_waitcnt vmcnt(28)
	v_pk_fma_f32 v[6:7], v[20:21], v[16:17], v[6:7] op_sel_hi:[0,1,1]
	s_waitcnt vmcnt(27)
	v_pk_fma_f32 v[6:7], v[28:29], v[24:25], v[6:7] op_sel_hi:[0,1,1]
	s_waitcnt vmcnt(26)
	v_pk_fma_f32 v[6:7], v[30:31], v[26:27], v[6:7] op_sel_hi:[0,1,1]
	s_waitcnt vmcnt(25)
	v_pk_fma_f32 v[6:7], v[38:39], v[32:33], v[6:7] op_sel_hi:[0,1,1]
	s_waitcnt vmcnt(24)
	v_pk_fma_f32 v[6:7], v[40:41], v[34:35], v[6:7] op_sel_hi:[0,1,1]
	s_waitcnt vmcnt(23)
	v_pk_fma_f32 v[6:7], v[46:47], v[42:43], v[6:7] op_sel_hi:[0,1,1]
	s_waitcnt vmcnt(22)
	v_pk_fma_f32 v[6:7], v[48:49], v[44:45], v[6:7] op_sel_hi:[0,1,1]
	s_waitcnt vmcnt(21)
	v_pk_fma_f32 v[6:7], v[54:55], v[50:51], v[6:7] op_sel_hi:[0,1,1]
	s_waitcnt vmcnt(20)
	v_pk_fma_f32 v[6:7], v[56:57], v[52:53], v[6:7] op_sel_hi:[0,1,1]
	s_waitcnt vmcnt(19)
	v_pk_fma_f32 v[6:7], v[62:63], v[58:59], v[6:7] op_sel_hi:[0,1,1]
	s_waitcnt vmcnt(18)
	v_pk_fma_f32 v[6:7], v[64:65], v[60:61], v[6:7] op_sel_hi:[0,1,1]
	s_waitcnt vmcnt(17)
	v_pk_fma_f32 v[6:7], v[70:71], v[66:67], v[6:7] op_sel_hi:[0,1,1]
	s_waitcnt vmcnt(16)
	v_pk_fma_f32 v[6:7], v[72:73], v[68:69], v[6:7] op_sel_hi:[0,1,1]
	s_waitcnt vmcnt(15)
	v_pk_fma_f32 v[6:7], v[74:75], v[78:79], v[6:7] op_sel_hi:[0,1,1]
	s_waitcnt vmcnt(14)
	v_pk_fma_f32 v[6:7], v[76:77], v[82:83], v[6:7] op_sel_hi:[0,1,1]
	s_waitcnt vmcnt(13)
	v_pk_fma_f32 v[6:7], v[80:81], v[86:87], v[6:7] op_sel_hi:[0,1,1]
	s_waitcnt vmcnt(12)
	v_pk_fma_f32 v[6:7], v[84:85], v[90:91], v[6:7] op_sel_hi:[0,1,1]
	s_waitcnt vmcnt(11)
	v_pk_fma_f32 v[6:7], v[88:89], v[94:95], v[6:7] op_sel_hi:[0,1,1]
	s_waitcnt vmcnt(10) lgkmcnt(14)
	v_pk_fma_f32 v[6:7], v[92:93], v[98:99], v[6:7] op_sel_hi:[0,1,1]
	s_waitcnt vmcnt(9)
	v_pk_fma_f32 v[6:7], v[96:97], v[102:103], v[6:7] op_sel_hi:[0,1,1]
	s_waitcnt vmcnt(8) lgkmcnt(13)
	v_pk_fma_f32 v[6:7], v[100:101], v[106:107], v[6:7] op_sel_hi:[0,1,1]
	s_waitcnt vmcnt(7) lgkmcnt(11)
	v_pk_fma_f32 v[6:7], v[104:105], v[110:111], v[6:7] op_sel_hi:[0,1,1]
	s_waitcnt vmcnt(6) lgkmcnt(9)
	v_pk_fma_f32 v[6:7], v[108:109], v[122:123], v[6:7] op_sel_hi:[0,1,1]
	v_lshl_add_u32 v23, v41, 2, s3
	ds_read_b32 v133, v21
	ds_read_b32 v134, v23
	ds_read_b32 v135, v29
	s_waitcnt vmcnt(5) lgkmcnt(10)
	v_pk_fma_f32 v[6:7], v[112:113], v[124:125], v[6:7] op_sel_hi:[0,1,1]
	s_waitcnt vmcnt(4) lgkmcnt(8)
	v_pk_fma_f32 v[6:7], v[114:115], v[126:127], v[6:7] op_sel_hi:[0,1,1]
	s_waitcnt vmcnt(3) lgkmcnt(6)
	v_pk_fma_f32 v[6:7], v[116:117], v[128:129], v[6:7] op_sel_hi:[0,1,1]
	s_waitcnt vmcnt(2) lgkmcnt(4)
	v_pk_fma_f32 v[6:7], v[118:119], v[130:131], v[6:7] op_sel_hi:[0,1,1]
	s_and_b64 s[4:5], exec, s[22:23]
	s_waitcnt vmcnt(1) lgkmcnt(2)
	v_pk_fma_f32 v[6:7], v[120:121], v[132:133], v[6:7] op_sel_hi:[0,1,1]
	s_mov_b64 s[22:23], 0
	s_mov_b32 s13, 32
	s_waitcnt vmcnt(0) lgkmcnt(0)
	v_pk_fma_f32 v[6:7], v[22:23], v[134:135], v[6:7] op_sel_hi:[0,1,1]
	s_mov_b64 vcc, s[4:5]
	s_cbranch_vccnz .LBB0_40
	v_bfe_u32 v2, v6, 16, 1
	v_mov_b64_e32 v[4:5], s[16:17]
	v_add3_u32 v6, v6, v2, s12
	v_lshrrev_b32_e32 v2, 9, v1
	v_mad_u64_u32 v[4:5], s[4:5], v13, s7, v[4:5]
	v_and_b32_e32 v2, 0x1fe, v2
	v_lshl_add_u64 v[4:5], v[4:5], 0, v[2:3]
	v_xor_b32_e32 v2, 0x80000000, v7
	v_add_u32_e32 v1, s6, v1
	global_store_short_d16_hi v[4:5], v6, off offset:1536
	v_bfe_u32 v6, v2, 16, 1
	v_cmp_lt_i32_e32 vcc, -1, v1
	v_add3_u32 v2, v2, v6, s12
	s_or_b64 s[18:19], vcc, s[18:19]
	global_store_short_d16_hi v[4:5], v2, off offset:2048
	s_andn2_b64 exec, exec, s[18:19]
	s_cbranch_execnz .LBB0_39
	s_or_b64 exec, exec, s[18:19]
	v_cvt_f32_u32_e32 v1, s6
	s_sub_i32 s3, 0, s6
	s_mov_b64 s[4:5], -1
	v_rcp_iflag_f32_e32 v2, v1
	v_add_u32_e32 v1, s6, v0
	v_lshrrev_b32_e32 v4, 31, v1
	v_max_i32_e32 v3, 0, v1
	v_mul_f32_e32 v2, 0x4f7ffffe, v2
	v_cvt_u32_f32_e32 v2, v2
	v_add_u32_e32 v5, v4, v1
	v_sub_u32_e32 v3, v3, v5
	v_mul_lo_u32 v5, s3, v2
	v_mul_hi_u32 v5, v2, v5
	v_add_u32_e32 v2, v2, v5
	v_mul_hi_u32 v2, v3, v2
	v_mul_lo_u32 v5, v2, s6
	v_sub_u32_e32 v3, v3, v5
	v_add_u32_e32 v6, 1, v2
	v_cmp_le_u32_e32 vcc, s6, v3
	v_subrev_u32_e32 v5, s6, v3
	s_nop 0
	v_cndmask_b32_e32 v2, v2, v6, vcc
	v_cndmask_b32_e32 v3, v3, v5, vcc
	v_add_u32_e32 v5, 1, v2
	v_cmp_le_u32_e32 vcc, s6, v3
	s_nop 1
	v_cndmask_b32_e32 v2, v2, v5, vcc
	v_add3_u32 v8, v4, v2, 1
	v_cmp_lt_u32_e32 vcc, 1, v8
	v_and_b32_e32 v9, -2, v8
	v_mov_b32_e32 v2, v0
	s_and_saveexec_b64 s[10:11], vcc
	s_cbranch_execz .LBB0_46
	s_add_u32 s16, s92, 0x4e00000
	s_addc_u32 s17, s93, 0
	v_and_b32_e32 v6, -2, v8
	s_lshl_b32 s3, s90, 10
	v_readlane_b32 s36, v250, 0
	s_mov_b32 s7, s3
	s_mov_b64 s[18:19], 0
	v_mov_b32_e32 v3, 0
	s_movk_i32 s12, 0x7fff
	v_mov_b32_e32 v7, 1
	v_mov_b32_e32 v10, v6
	v_mov_b64_e32 v[4:5], v[0:1]
	v_readlane_b32 s46, v250, 10
	v_readlane_b32 s47, v250, 11
	v_readlane_b32 s37, v250, 1
	v_readlane_b32 s38, v250, 2
	v_readlane_b32 s39, v250, 3
	v_readlane_b32 s40, v250, 4
	v_readlane_b32 s41, v250, 5
	v_readlane_b32 s42, v250, 6
	v_readlane_b32 s43, v250, 7
	v_readlane_b32 s44, v250, 8
	v_readlane_b32 s45, v250, 9
	v_readlane_b32 s48, v250, 12
	v_readlane_b32 s49, v250, 13
	v_readlane_b32 s50, v250, 14
	v_readlane_b32 s51, v250, 15

; __device__ __forceinline__ unsigned f2bf(float f) { unsigned u = __float_as_uint(f); return (u + 0x7fffu + ((u >> 16) & 1u)) >> 16; }
; __device__ __forceinline__ void prep_weights(const Params& P, LAS unsigned char* lds, int lay, int bid, int G, int sel) {
;     ...
;       for (int i0 = gt; i0 < ((sel & 64) ? 65536 : 0); i0 += NGT) { const int idx = l * 65536 + i0; ((bf16_t*)(ws + OFF_GWS))[idx] = (bf16_t)f2bf(P.gmlp_ws[idx]); } }
.LBB0_51:
	v_ashrrev_i32_e32 v7, 31, v3
	v_mov_b32_e32 v6, v3
	v_ashrrev_i32_e32 v11, 31, v2
	v_mov_b32_e32 v10, v2
	v_lshl_add_u64 v[12:13], v[10:11], 2, s[80:81]
	v_lshl_add_u64 v[14:15], v[6:7], 2, s[80:81]
	global_load_dword v1, v[14:15], off
	global_load_dword v12, v[12:13], off
	v_add_u32_e32 v5, -2, v5
	v_cmp_eq_u32_e32 vcc, 0, v5
	v_add_u32_e32 v3, s7, v3
	v_add_u32_e32 v2, s3, v2
	v_lshl_add_u64 v[10:11], v[10:11], 1, s[10:11]
	s_or_b64 s[16:17], vcc, s[16:17]
	v_lshl_add_u64 v[6:7], v[6:7], 1, s[10:11]
	s_waitcnt vmcnt(1)
	v_and_b32_sdwa v13, v1, v4 dst_sel:DWORD dst_unused:UNUSED_PAD src0_sel:WORD_1 src1_sel:DWORD
	s_waitcnt vmcnt(0)
	v_and_b32_sdwa v14, v12, v4 dst_sel:DWORD dst_unused:UNUSED_PAD src0_sel:WORD_1 src1_sel:DWORD
	v_add3_u32 v12, v12, v14, s12
	v_add3_u32 v1, v1, v13, s12
	global_store_short_d16_hi v[10:11], v12, off
	global_store_short_d16_hi v[6:7], v1, off
	s_andn2_b64 exec, exec, s[16:17]
	s_cbranch_execnz .LBB0_51
	s_or_b64 exec, exec, s[16:17]
	v_mad_u64_u32 v[0:1], s[10:11], v9, s6, v[0:1]
	v_cmp_ne_u32_e32 vcc, v8, v9
	s_orn2_b64 s[10:11], vcc, exec

; __device__ __forceinline__ void phase_prep(const Params& P, LAS unsigned char* lds) {
;     ...
;       for (int i = tid; i < 9 * 1024; i += 512) { const int v = i >> 10, k = i & 1023; const float cv = v < 8 ? P.c[v * 1024 + k] : P.c_ctx[k]; sc[i] = cv / (1.0f + expf(-cv)); }
.LBB0_63:
	v_and_b32_e32 v2, 0x3ff, v0
	v_ashrrev_i32_e32 v13, 31, v0
	v_mov_b32_e32 v12, v0
	v_add_u32_e32 v16, 0x400, v0
	v_lshlrev_b32_e32 v2, 2, v2
	v_and_b32_e32 v20, 0x3ff, v1
	v_add_u32_e32 v14, 0x400, v1
	v_add_u32_e32 v6, -2, v6
	v_lshl_add_u64 v[12:13], v[12:13], 2, s[66:67]
	v_ashrrev_i32_e32 v17, 31, v16
	v_lshl_add_u64 v[18:19], s[70:71], 0, v[2:3]
	v_cmp_gt_i32_e64 s[4:5], s3, v0
	v_ashrrev_i32_e32 v11, 31, v1
	v_mov_b32_e32 v10, v1
	s_add_i32 s2, s2, 4
	v_ashrrev_i32_e32 v15, 31, v14
	v_cmp_eq_u32_e32 vcc, 0, v6
	v_lshlrev_b32_e32 v2, 2, v20
	v_lshl_add_u64 v[20:21], v[16:17], 2, s[66:67]
	v_cmp_gt_i32_e64 s[6:7], s3, v16
	v_cndmask_b32_e64 v13, v19, v13, s[4:5]
	v_cndmask_b32_e64 v12, v18, v12, s[4:5]
	v_lshl_add_u64 v[10:11], v[10:11], 2, s[66:67]
	v_lshl_add_u64 v[16:17], v[14:15], 2, s[66:67]
	s_or_b64 s[20:21], vcc, s[20:21]
	v_lshl_add_u64 v[22:23], s[70:71], 0, v[2:3]
	v_cmp_gt_i32_e32 vcc, s3, v1
	v_cmp_gt_i32_e64 s[4:5], s3, v14
	v_cndmask_b32_e64 v15, v19, v21, s[6:7]
	v_cndmask_b32_e64 v14, v18, v20, s[6:7]
	global_load_dword v2, v[12:13], off
	v_cndmask_b32_e32 v11, v23, v11, vcc
	v_cndmask_b32_e32 v10, v22, v10, vcc
	v_cndmask_b32_e64 v13, v23, v17, s[4:5]
	v_cndmask_b32_e64 v12, v22, v16, s[4:5]
	global_load_dword v14, v[14:15], off
	global_load_dword v15, v[10:11], off
	global_load_dword v16, v[12:13], off
	v_mov_b32_e32 v9, s2
	v_add_u32_e32 v0, 0x800, v0
	v_add_u32_e32 v1, 0x800, v1
	s_waitcnt vmcnt(3)
	v_mul_f32_e32 v10, 0xbfb8aa3b, v2
	v_fma_f32 v13, v2, s12, -v10
	v_rndne_f32_e32 v17, v10
	s_waitcnt vmcnt(2)
	v_mul_f32_e32 v11, 0xbfb8aa3b, v14
	s_waitcnt vmcnt(1)
	v_mul_f32_e32 v12, 0xbfb8aa3b, v15
	v_fma_f32 v19, v14, s12, -v11
	v_rndne_f32_e32 v20, v11
	v_fma_f32 v21, v15, s12, -v12
	v_rndne_f32_e32 v22, v12
	v_fmac_f32_e32 v19, 0xb2a5705f, v14
	v_sub_f32_e32 v11, v11, v20
	s_waitcnt vmcnt(0)
	v_mul_f32_e32 v18, 0xbfb8aa3b, v16
	v_fmac_f32_e32 v13, 0xb2a5705f, v2
	v_sub_f32_e32 v10, v10, v17
	v_fmac_f32_e32 v21, 0xb2a5705f, v15
	v_sub_f32_e32 v12, v12, v22
	v_add_f32_e32 v11, v11, v19
	v_fma_f32 v23, v16, s12, -v18
	v_rndne_f32_e32 v24, v18
	v_cvt_i32_f32_e32 v20, v20
	v_add_f32_e32 v10, v10, v13
	v_add_f32_e32 v12, v12, v21
	v_exp_f32_e32 v11, v11
	v_cvt_i32_f32_e32 v17, v17
	v_cvt_i32_f32_e32 v22, v22
	v_fmac_f32_e32 v23, 0xb2a5705f, v16
	v_sub_f32_e32 v13, v18, v24
	v_exp_f32_e32 v10, v10
	v_exp_f32_e32 v12, v12
	v_add_f32_e32 v13, v13, v23
	v_cvt_i32_f32_e32 v18, v24
	v_exp_f32_e32 v13, v13
	v_ldexp_f32 v11, v11, v20
	v_cmp_nlt_f32_e64 s[4:5], s13, v14
	v_ldexp_f32 v10, v10, v17
	v_cmp_nlt_f32_e32 vcc, s13, v2
	v_ldexp_f32 v12, v12, v22
	v_cndmask_b32_e64 v11, 0, v11, s[4:5]
	v_cmp_ngt_f32_e64 s[4:5], s14, v14
	v_cmp_nlt_f32_e64 s[8:9], s13, v15
	v_cndmask_b32_e32 v10, 0, v10, vcc
	v_cmp_ngt_f32_e32 vcc, s14, v2
	v_cndmask_b32_e64 v17, 0, v12, s[8:9]
	v_cndmask_b32_e64 v12, v8, v11, s[4:5]
	v_cmp_ngt_f32_e64 s[4:5], s14, v15
	v_ldexp_f32 v13, v13, v18
	v_cmp_nlt_f32_e64 s[6:7], s13, v16
	v_cndmask_b32_e32 v10, v8, v10, vcc
	v_cndmask_b32_e64 v11, v8, v17, s[4:5]
	v_cndmask_b32_e64 v13, 0, v13, s[6:7]
	v_cmp_ngt_f32_e32 vcc, s14, v16
	v_pk_add_f32 v[10:11], v[10:11], 1.0 op_sel_hi:[1,0]
	s_nop 0
	v_cndmask_b32_e32 v13, v8, v13, vcc
	v_div_scale_f32 v17, s[4:5], v11, v11, v15
	v_pk_add_f32 v[12:13], v[12:13], 1.0 op_sel_hi:[1,0]
	v_div_scale_f32 v19, s[4:5], v10, v10, v2
	v_rcp_f32_e32 v25, v17
	v_div_scale_f32 v21, s[6:7], v13, v13, v16
	v_rcp_f32_e32 v26, v19
	v_div_scale_f32 v23, s[8:9], v12, v12, v14
	v_rcp_f32_e32 v27, v21
	v_rcp_f32_e32 v28, v23
	v_fma_f32 v29, -v17, v25, 1.0
	v_div_scale_f32 v18, vcc, v15, v11, v15
	v_fma_f32 v30, -v19, v26, 1.0
	v_fmac_f32_e32 v25, v29, v25
	v_div_scale_f32 v20, s[4:5], v2, v10, v2
	v_fma_f32 v31, -v21, v27, 1.0
	v_fmac_f32_e32 v26, v30, v26
	v_mul_f32_e32 v29, v18, v25
	v_div_scale_f32 v22, s[6:7], v16, v13, v16
	v_fma_f32 v32, -v23, v28, 1.0
	v_fmac_f32_e32 v27, v31, v27
	v_mul_f32_e32 v30, v20, v26
	v_fma_f32 v33, -v17, v29, v18
	v_div_scale_f32 v24, s[8:9], v14, v12, v14
	v_fmac_f32_e32 v28, v32, v28
	v_mul_f32_e32 v31, v22, v27
	v_fma_f32 v34, -v19, v30, v20
	v_fmac_f32_e32 v29, v33, v25
	v_mul_f32_e32 v32, v24, v28
	v_fma_f32 v35, -v21, v31, v22
	v_fmac_f32_e32 v30, v34, v26
	v_fma_f32 v17, -v17, v29, v18
	v_fma_f32 v37, -v23, v32, v24
	v_fmac_f32_e32 v31, v35, v27
	v_fma_f32 v18, -v19, v30, v20
	v_div_fmas_f32 v17, v17, v25, v29
	s_mov_b64 vcc, s[4:5]
	v_fmac_f32_e32 v32, v37, v28
	v_fma_f32 v19, -v21, v31, v22
	v_div_fixup_f32 v11, v17, v11, v15
	v_div_fmas_f32 v15, v18, v26, v30
	s_mov_b64 vcc, s[6:7]
	v_fma_f32 v20, -v23, v32, v24
	v_div_fixup_f32 v2, v15, v10, v2
	v_div_fmas_f32 v10, v19, v27, v31
	s_mov_b64 vcc, s[8:9]
	ds_write2st64_b32 v7, v2, v11 offset1:8
	v_div_fixup_f32 v2, v10, v13, v16
	v_div_fmas_f32 v10, v20, v28, v32
	v_div_fixup_f32 v10, v10, v12, v14
	ds_write2st64_b32 v7, v10, v2 offset0:16 offset1:24
	v_add_u32_e32 v7, 0x2000, v7
	s_andn2_b64 exec, exec, s[20:21]
	s_cbranch_execnz .LBB0_63
	s_or_b64 exec, exec, s[20:21]
	v_lshlrev_b32_e32 v2, 9, v9

; __device__ __forceinline__ void phase_prep(const Params& P, LAS unsigned char* lds) {
;     ...
;           const float* wp = P.w_mod + (size_t)l * 1024 * 9216 + (size_t)(kc * 32) * 9216 + col0 + 4 * cq;
; #pragma unroll 1
;           for (int k0 = 0; k0 < 32; k0 += 16) { f32x4 wv[16];
; #pragma unroll
;               for (int k = 0; k < 16; ++k) wv[k] = *(const f32x4*)(wp + (size_t)(k0 + k) * 9216);
; #pragma unroll
;               for (int k = 0; k < 16; ++k) {
; #pragma unroll
;                   for (int v = 0; v < 9; ++v) a[v] += wv[k] * sc[v * 1024 + kc * 32 + k0 + k]; } }
.LBB0_75:
	s_mul_i32 s6, s2, 0x2400
	v_lshl_add_u32 v73, s2, 2, v37
	v_lshl_add_u64 v[46:47], s[6:7], 2, v[44:45]
	ds_read_b128 v[60:63], v73
	ds_read_b128 v[64:67], v73 offset:16
	ds_read_b128 v[68:71], v73 offset:4096
	ds_read_b128 v[74:77], v73 offset:4112
	ds_read_b128 v[78:81], v73 offset:8192
	ds_read_b128 v[82:85], v73 offset:8208
	global_load_dwordx4 v[86:89], v[46:47], off
	v_add_co_u32_e32 v48, vcc, s16, v46
	s_mov_b32 s2, 16
	s_nop 0
	v_addc_co_u32_e32 v49, vcc, 0, v47, vcc
	global_load_dwordx4 v[90:93], v[48:49], off
	s_waitcnt lgkmcnt(0)
	v_mov_b32_e32 v58, v85
	s_waitcnt vmcnt(1)
	v_pk_fma_f32 v[48:49], v[88:89], v[60:61], v[2:3] op_sel_hi:[1,0,1]
	v_pk_fma_f32 v[52:53], v[86:87], v[60:61], v[0:1] op_sel_hi:[1,0,1]
	v_pk_fma_f32 v[56:57], v[88:89], v[68:69], v[6:7] op_sel_hi:[1,0,1]
	v_pk_fma_f32 v[110:111], v[86:87], v[68:69], v[4:5] op_sel_hi:[1,0,1]
	ds_read_b128 v[0:3], v73 offset:12288
	ds_read_b128 v[4:7], v73 offset:12304
	v_pk_fma_f32 v[112:113], v[88:89], v[78:79], v[14:15] op_sel_hi:[1,0,1]
	v_pk_fma_f32 v[114:115], v[86:87], v[78:79], v[12:13] op_sel_hi:[1,0,1]
	s_waitcnt vmcnt(0)
	v_pk_fma_f32 v[48:49], v[92:93], v[60:61], v[48:49] op_sel:[0,1,0]
	s_waitcnt lgkmcnt(1)
	v_pk_fma_f32 v[116:117], v[88:89], v[0:1], v[18:19] op_sel_hi:[1,0,1]
	v_pk_fma_f32 v[118:119], v[86:87], v[0:1], v[16:17] op_sel_hi:[1,0,1]
	ds_read_b128 v[12:15], v73 offset:16384
	ds_read_b128 v[16:19], v73 offset:16400
	v_pk_fma_f32 v[52:53], v[90:91], v[60:61], v[52:53] op_sel:[0,1,0]
	v_pk_fma_f32 v[56:57], v[92:93], v[68:69], v[56:57] op_sel:[0,1,0]
	v_pk_fma_f32 v[60:61], v[90:91], v[68:69], v[110:111] op_sel:[0,1,0]
	s_waitcnt lgkmcnt(1)
	v_pk_fma_f32 v[120:121], v[88:89], v[12:13], v[22:23] op_sel_hi:[1,0,1]
	v_pk_fma_f32 v[122:123], v[86:87], v[12:13], v[20:21] op_sel_hi:[1,0,1]
	ds_read_b128 v[20:23], v73 offset:20480
	ds_read_b128 v[94:97], v73 offset:20496
	v_pk_fma_f32 v[68:69], v[92:93], v[78:79], v[112:113] op_sel:[0,1,0]
	v_pk_fma_f32 v[78:79], v[90:91], v[78:79], v[114:115] op_sel:[0,1,0]
	v_pk_fma_f32 v[110:111], v[92:93], v[0:1], v[116:117] op_sel:[0,1,0]
	s_waitcnt lgkmcnt(1)
	v_pk_fma_f32 v[124:125], v[88:89], v[20:21], v[26:27] op_sel_hi:[1,0,1]
	v_pk_fma_f32 v[126:127], v[86:87], v[20:21], v[24:25] op_sel_hi:[1,0,1]
	ds_read_b128 v[24:27], v73 offset:24576
	ds_read_b128 v[98:101], v73 offset:24592
	v_pk_fma_f32 v[0:1], v[90:91], v[0:1], v[118:119] op_sel:[0,1,0]
	v_pk_fma_f32 v[112:113], v[92:93], v[12:13], v[120:121] op_sel:[0,1,0]
	v_pk_fma_f32 v[114:115], v[92:93], v[20:21], v[124:125] op_sel:[0,1,0]
	s_waitcnt lgkmcnt(1)
	v_pk_fma_f32 v[128:129], v[88:89], v[24:25], v[30:31] op_sel_hi:[1,0,1]
	v_pk_fma_f32 v[130:131], v[86:87], v[24:25], v[28:29] op_sel_hi:[1,0,1]
	ds_read_b128 v[28:31], v73 offset:28672
	ds_read_b128 v[102:105], v73 offset:28688
	v_pk_fma_f32 v[116:117], v[92:93], v[24:25], v[128:129] op_sel:[0,1,0]
	v_pk_fma_f32 v[24:25], v[90:91], v[24:25], v[130:131] op_sel:[0,1,0]
	v_pk_fma_f32 v[12:13], v[90:91], v[12:13], v[122:123] op_sel:[0,1,0]
	s_waitcnt lgkmcnt(1)
	v_pk_fma_f32 v[132:133], v[88:89], v[28:29], v[34:35] op_sel_hi:[1,0,1]
	v_pk_fma_f32 v[134:135], v[86:87], v[28:29], v[32:33] op_sel_hi:[1,0,1]
	ds_read_b128 v[32:35], v73 offset:32768
	ds_read_b128 v[106:109], v73 offset:32784
	v_pk_fma_f32 v[118:119], v[92:93], v[28:29], v[132:133] op_sel:[0,1,0]
	v_pk_fma_f32 v[20:21], v[90:91], v[20:21], v[126:127] op_sel:[0,1,0]
	v_pk_fma_f32 v[28:29], v[90:91], v[28:29], v[134:135] op_sel:[0,1,0]
	s_waitcnt lgkmcnt(1)
	v_pk_fma_f32 v[10:11], v[88:89], v[32:33], v[10:11] op_sel_hi:[1,0,1]
	v_pk_fma_f32 v[8:9], v[86:87], v[32:33], v[8:9] op_sel_hi:[1,0,1]
	v_pk_fma_f32 v[92:93], v[92:93], v[32:33], v[10:11] op_sel:[0,1,0]
	v_pk_fma_f32 v[32:33], v[90:91], v[32:33], v[8:9] op_sel:[0,1,0]
	v_add_co_u32_e32 v8, vcc, s17, v46
	v_mov_b32_e32 v54, v35
	s_nop 0
	v_addc_co_u32_e32 v9, vcc, 0, v47, vcc
	v_add_co_u32_e32 v86, vcc, s18, v46
	v_mov_b32_e32 v50, v31
	s_nop 0
	v_addc_co_u32_e32 v87, vcc, 0, v47, vcc
	global_load_dwordx4 v[8:11], v[8:9], off
	global_load_dwordx4 v[86:89], v[86:87], off
	s_waitcnt vmcnt(1)
	v_pk_fma_f32 v[0:1], v[8:9], v[2:3], v[0:1] op_sel_hi:[1,0,1]
	v_pk_fma_f32 v[90:91], v[10:11], v[2:3], v[110:111] op_sel_hi:[1,0,1]
	v_pk_fma_f32 v[110:111], v[10:11], v[14:15], v[112:113] op_sel_hi:[1,0,1]
	v_pk_fma_f32 v[112:113], v[10:11], v[22:23], v[114:115] op_sel_hi:[1,0,1]
	v_pk_fma_f32 v[24:25], v[8:9], v[26:27], v[24:25] op_sel_hi:[1,0,1]
	v_pk_fma_f32 v[114:115], v[10:11], v[26:27], v[116:117] op_sel_hi:[1,0,1]
	v_mov_b32_e32 v26, v3
	v_pk_fma_f32 v[52:53], v[8:9], v[62:63], v[52:53] op_sel_hi:[1,0,1]
	v_pk_fma_f32 v[48:49], v[10:11], v[62:63], v[48:49] op_sel_hi:[1,0,1]
	v_pk_fma_f32 v[60:61], v[8:9], v[70:71], v[60:61] op_sel_hi:[1,0,1]
	v_pk_fma_f32 v[56:57], v[10:11], v[70:71], v[56:57] op_sel_hi:[1,0,1]
	v_pk_fma_f32 v[78:79], v[8:9], v[80:81], v[78:79] op_sel_hi:[1,0,1]
	v_pk_fma_f32 v[68:69], v[10:11], v[80:81], v[68:69] op_sel_hi:[1,0,1]
	v_pk_fma_f32 v[12:13], v[8:9], v[14:15], v[12:13] op_sel_hi:[1,0,1]
	v_pk_fma_f32 v[20:21], v[8:9], v[22:23], v[20:21] op_sel_hi:[1,0,1]
	v_pk_fma_f32 v[28:29], v[8:9], v[30:31], v[28:29] op_sel_hi:[1,0,1]
	v_pk_fma_f32 v[116:117], v[10:11], v[30:31], v[118:119] op_sel_hi:[1,0,1]
	v_pk_fma_f32 v[8:9], v[8:9], v[34:35], v[32:33] op_sel_hi:[1,0,1]
	v_pk_fma_f32 v[10:11], v[10:11], v[34:35], v[92:93] op_sel_hi:[1,0,1]
	v_mov_b32_e32 v2, v63
	v_mov_b32_e32 v34, v27
	s_waitcnt vmcnt(0)
; __device__ __forceinline__ void phase_prep(const Params& P, LAS unsigned char* lds) {
;     ...
;           for (int k0 = 0; k0 < 32; k0 += 16) { f32x4 wv[16];
; #pragma unroll
;               for (int k = 0; k < 16; ++k) wv[k] = *(const f32x4*)(wp + (size_t)(k0 + k) * 9216);
; #pragma unroll
;               for (int k = 0; k < 16; ++k) {
; #pragma unroll
;                   for (int v = 0; v < 9; ++v) a[v] += wv[k] * sc[v * 1024 + kc * 32 + k0 + k]; } }
	v_pk_fma_f32 v[62:63], v[88:89], v[26:27], v[90:91] op_sel_hi:[1,0,1]
	v_pk_fma_f32 v[26:27], v[86:87], v[26:27], v[0:1] op_sel_hi:[1,0,1]
	v_add_co_u32_e32 v0, vcc, s19, v46
	v_mov_b32_e32 v14, v71
	v_mov_b32_e32 v22, v81
	v_addc_co_u32_e32 v1, vcc, 0, v47, vcc
	v_mov_b32_e32 v30, v15
	v_mov_b32_e32 v32, v23
	v_pk_fma_f32 v[56:57], v[88:89], v[14:15], v[56:57] op_sel_hi:[1,0,1]
	v_pk_fma_f32 v[14:15], v[86:87], v[14:15], v[60:61] op_sel_hi:[1,0,1]
	v_pk_fma_f32 v[60:61], v[88:89], v[22:23], v[68:69] op_sel_hi:[1,0,1]
	v_pk_fma_f32 v[22:23], v[86:87], v[22:23], v[78:79] op_sel_hi:[1,0,1]
	v_pk_fma_f32 v[78:79], v[86:87], v[54:55], v[8:9] op_sel_hi:[1,0,1]
	v_add_co_u32_e32 v8, vcc, s20, v46
	v_pk_fma_f32 v[48:49], v[88:89], v[2:3], v[48:49] op_sel_hi:[1,0,1]
	s_nop 0
	v_addc_co_u32_e32 v9, vcc, 0, v47, vcc
	v_pk_fma_f32 v[52:53], v[86:87], v[2:3], v[52:53] op_sel_hi:[1,0,1]
	v_pk_fma_f32 v[70:71], v[88:89], v[54:55], v[10:11] op_sel_hi:[1,0,1]
	global_load_dwordx4 v[0:3], v[0:1], off
	global_load_dwordx4 v[8:11], v[8:9], off
	v_pk_fma_f32 v[68:69], v[88:89], v[30:31], v[110:111] op_sel_hi:[1,0,1]
	v_pk_fma_f32 v[12:13], v[86:87], v[30:31], v[12:13] op_sel_hi:[1,0,1]
	v_pk_fma_f32 v[20:21], v[86:87], v[32:33], v[20:21] op_sel_hi:[1,0,1]
	v_pk_fma_f32 v[24:25], v[86:87], v[34:35], v[24:25] op_sel_hi:[1,0,1]
	v_pk_fma_f32 v[28:29], v[86:87], v[50:51], v[28:29] op_sel_hi:[1,0,1]
	v_pk_fma_f32 v[30:31], v[88:89], v[32:33], v[112:113] op_sel_hi:[1,0,1]
	v_pk_fma_f32 v[32:33], v[88:89], v[34:35], v[114:115] op_sel_hi:[1,0,1]
	v_pk_fma_f32 v[34:35], v[88:89], v[50:51], v[116:117] op_sel_hi:[1,0,1]
	v_mov_b32_e32 v80, v97
	v_mov_b32_e32 v50, v67
	v_mov_b32_e32 v54, v77
	s_waitcnt lgkmcnt(0)
	v_mov_b32_e32 v88, v109
	s_waitcnt vmcnt(1)
	v_pk_fma_f32 v[52:53], v[0:1], v[64:65], v[52:53] op_sel_hi:[1,0,1]
	v_pk_fma_f32 v[14:15], v[0:1], v[74:75], v[14:15] op_sel_hi:[1,0,1]
	v_pk_fma_f32 v[22:23], v[0:1], v[82:83], v[22:23] op_sel_hi:[1,0,1]
	v_pk_fma_f32 v[26:27], v[0:1], v[4:5], v[26:27] op_sel_hi:[1,0,1]
	v_pk_fma_f32 v[62:63], v[2:3], v[4:5], v[62:63] op_sel_hi:[1,0,1]
	v_pk_fma_f32 v[12:13], v[0:1], v[16:17], v[12:13] op_sel_hi:[1,0,1]
	v_pk_fma_f32 v[68:69], v[2:3], v[16:17], v[68:69] op_sel_hi:[1,0,1]
	v_pk_fma_f32 v[20:21], v[0:1], v[94:95], v[20:21] op_sel_hi:[1,0,1]
	v_pk_fma_f32 v[24:25], v[0:1], v[98:99], v[24:25] op_sel_hi:[1,0,1]
	v_pk_fma_f32 v[28:29], v[0:1], v[102:103], v[28:29] op_sel_hi:[1,0,1]
	v_pk_fma_f32 v[0:1], v[0:1], v[106:107], v[78:79] op_sel_hi:[1,0,1]
	s_waitcnt vmcnt(0)
	v_pk_fma_f32 v[62:63], v[10:11], v[4:5], v[62:63] op_sel:[0,1,0]
	v_pk_fma_f32 v[4:5], v[8:9], v[4:5], v[26:27] op_sel:[0,1,0]
	v_pk_fma_f32 v[26:27], v[10:11], v[16:17], v[68:69] op_sel:[0,1,0]
	v_pk_fma_f32 v[68:69], v[8:9], v[106:107], v[0:1] op_sel:[0,1,0]
	v_add_co_u32_e32 v0, vcc, s21, v46
	v_pk_fma_f32 v[30:31], v[2:3], v[94:95], v[30:31] op_sel_hi:[1,0,1]
	v_pk_fma_f32 v[32:33], v[2:3], v[98:99], v[32:33] op_sel_hi:[1,0,1]
	v_pk_fma_f32 v[34:35], v[2:3], v[102:103], v[34:35] op_sel_hi:[1,0,1]
	v_addc_co_u32_e32 v1, vcc, 0, v47, vcc
	v_pk_fma_f32 v[52:53], v[8:9], v[64:65], v[52:53] op_sel:[0,1,0]
	v_pk_fma_f32 v[14:15], v[8:9], v[74:75], v[14:15] op_sel:[0,1,0]
	v_pk_fma_f32 v[22:23], v[8:9], v[82:83], v[22:23] op_sel:[0,1,0]
	v_pk_fma_f32 v[12:13], v[8:9], v[16:17], v[12:13] op_sel:[0,1,0]
	v_pk_fma_f32 v[16:17], v[10:11], v[94:95], v[30:31] op_sel:[0,1,0]
	v_pk_fma_f32 v[20:21], v[8:9], v[94:95], v[20:21] op_sel:[0,1,0]
	v_pk_fma_f32 v[30:31], v[10:11], v[98:99], v[32:33] op_sel:[0,1,0]
	v_pk_fma_f32 v[24:25], v[8:9], v[98:99], v[24:25] op_sel:[0,1,0]
	v_pk_fma_f32 v[32:33], v[10:11], v[102:103], v[34:35] op_sel:[0,1,0]
	v_pk_fma_f32 v[34:35], v[8:9], v[102:103], v[28:29] op_sel:[0,1,0]
	v_add_co_u32_e32 v8, vcc, s22, v46
	v_pk_fma_f32 v[48:49], v[2:3], v[64:65], v[48:49] op_sel_hi:[1,0,1]
	v_pk_fma_f32 v[56:57], v[2:3], v[74:75], v[56:57] op_sel_hi:[1,0,1]
	v_pk_fma_f32 v[60:61], v[2:3], v[82:83], v[60:61] op_sel_hi:[1,0,1]
	v_pk_fma_f32 v[2:3], v[2:3], v[106:107], v[70:71] op_sel_hi:[1,0,1]
	v_addc_co_u32_e32 v9, vcc, 0, v47, vcc
	v_pk_fma_f32 v[48:49], v[10:11], v[64:65], v[48:49] op_sel:[0,1,0]
	v_pk_fma_f32 v[56:57], v[10:11], v[74:75], v[56:57] op_sel:[0,1,0]
	v_pk_fma_f32 v[60:61], v[10:11], v[82:83], v[60:61] op_sel:[0,1,0]
	v_pk_fma_f32 v[64:65], v[10:11], v[106:107], v[2:3] op_sel:[0,1,0]
	global_load_dwordx4 v[0:3], v[0:1], off
	global_load_dwordx4 v[8:11], v[8:9], off
	v_mov_b32_e32 v82, v101
	s_waitcnt vmcnt(1)
	v_pk_fma_f32 v[4:5], v[0:1], v[6:7], v[4:5] op_sel_hi:[1,0,1]
	v_pk_fma_f32 v[74:75], v[2:3], v[6:7], v[62:63] op_sel_hi:[1,0,1]
	v_mov_b32_e32 v6, v7
	v_pk_fma_f32 v[12:13], v[0:1], v[18:19], v[12:13] op_sel_hi:[1,0,1]
	v_pk_fma_f32 v[78:79], v[2:3], v[18:19], v[26:27] op_sel_hi:[1,0,1]
	v_mov_b32_e32 v18, v19
	s_waitcnt vmcnt(0)
; __device__ __forceinline__ void phase_prep(const Params& P, LAS unsigned char* lds) {
;     ...
;           for (int k0 = 0; k0 < 32; k0 += 16) { f32x4 wv[16];
; #pragma unroll
;               for (int k = 0; k < 16; ++k) wv[k] = *(const f32x4*)(wp + (size_t)(k0 + k) * 9216);
; #pragma unroll
;               for (int k = 0; k < 16; ++k) {
; #pragma unroll
;                   for (int v = 0; v < 9; ++v) a[v] += wv[k] * sc[v * 1024 + kc * 32 + k0 + k]; } }
	v_pk_fma_f32 v[92:93], v[10:11], v[6:7], v[74:75] op_sel_hi:[1,0,1]
	v_pk_fma_f32 v[4:5], v[8:9], v[6:7], v[4:5] op_sel_hi:[1,0,1]
	v_pk_fma_f32 v[6:7], v[10:11], v[18:19], v[78:79] op_sel_hi:[1,0,1]
	v_pk_fma_f32 v[12:13], v[8:9], v[18:19], v[12:13] op_sel_hi:[1,0,1]
	v_add_co_u32_e32 v18, vcc, s23, v46
	v_pk_fma_f32 v[20:21], v[0:1], v[96:97], v[20:21] op_sel_hi:[1,0,1]
	s_nop 0
	v_addc_co_u32_e32 v19, vcc, 0, v47, vcc
	v_pk_fma_f32 v[52:53], v[0:1], v[66:67], v[52:53] op_sel_hi:[1,0,1]
	v_pk_fma_f32 v[48:49], v[2:3], v[66:67], v[48:49] op_sel_hi:[1,0,1]
	v_pk_fma_f32 v[14:15], v[0:1], v[76:77], v[14:15] op_sel_hi:[1,0,1]
	v_pk_fma_f32 v[56:57], v[2:3], v[76:77], v[56:57] op_sel_hi:[1,0,1]
	v_pk_fma_f32 v[22:23], v[0:1], v[84:85], v[22:23] op_sel_hi:[1,0,1]
	v_pk_fma_f32 v[70:71], v[2:3], v[84:85], v[60:61] op_sel_hi:[1,0,1]
	v_pk_fma_f32 v[16:17], v[2:3], v[96:97], v[16:17] op_sel_hi:[1,0,1]
	v_pk_fma_f32 v[24:25], v[0:1], v[100:101], v[24:25] op_sel_hi:[1,0,1]
	v_pk_fma_f32 v[84:85], v[2:3], v[100:101], v[30:31] op_sel_hi:[1,0,1]
	v_pk_fma_f32 v[34:35], v[0:1], v[104:105], v[34:35] op_sel_hi:[1,0,1]
	v_pk_fma_f32 v[86:87], v[2:3], v[104:105], v[32:33] op_sel_hi:[1,0,1]
	v_pk_fma_f32 v[0:1], v[0:1], v[108:109], v[68:69] op_sel_hi:[1,0,1]
	v_pk_fma_f32 v[2:3], v[2:3], v[108:109], v[64:65] op_sel_hi:[1,0,1]
	v_mov_b32_e32 v68, v105
	v_pk_fma_f32 v[98:99], v[8:9], v[80:81], v[20:21] op_sel_hi:[1,0,1]
	v_add_co_u32_e32 v20, vcc, s24, v46
	ds_read_b128 v[26:29], v73 offset:32
	ds_read_b128 v[30:33], v73 offset:48
	ds_read_b128 v[60:63], v73 offset:4128
	ds_read_b128 v[74:77], v73 offset:4144
	v_pk_fma_f32 v[48:49], v[10:11], v[50:51], v[48:49] op_sel_hi:[1,0,1]
	v_pk_fma_f32 v[52:53], v[8:9], v[50:51], v[52:53] op_sel_hi:[1,0,1]
	v_pk_fma_f32 v[56:57], v[10:11], v[54:55], v[56:57] op_sel_hi:[1,0,1]
	v_pk_fma_f32 v[14:15], v[8:9], v[54:55], v[14:15] op_sel_hi:[1,0,1]
	ds_read_b128 v[64:67], v73 offset:8224
	v_pk_fma_f32 v[90:91], v[10:11], v[58:59], v[70:71] op_sel_hi:[1,0,1]
	v_pk_fma_f32 v[22:23], v[8:9], v[58:59], v[22:23] op_sel_hi:[1,0,1]
	v_pk_fma_f32 v[16:17], v[10:11], v[80:81], v[16:17] op_sel_hi:[1,0,1]
	ds_read_b128 v[78:81], v73 offset:8240
	v_pk_fma_f32 v[102:103], v[10:11], v[82:83], v[84:85] op_sel_hi:[1,0,1]
	v_pk_fma_f32 v[104:105], v[8:9], v[82:83], v[24:25] op_sel_hi:[1,0,1]
	v_pk_fma_f32 v[106:107], v[10:11], v[68:69], v[86:87] op_sel_hi:[1,0,1]
	v_pk_fma_f32 v[34:35], v[8:9], v[68:69], v[34:35] op_sel_hi:[1,0,1]
	v_addc_co_u32_e32 v21, vcc, 0, v47, vcc
	v_pk_fma_f32 v[110:111], v[10:11], v[88:89], v[2:3] op_sel_hi:[1,0,1]
	v_pk_fma_f32 v[112:113], v[8:9], v[88:89], v[0:1] op_sel_hi:[1,0,1]
	global_load_dwordx4 v[8:11], v[18:19], off
	global_load_dwordx4 v[68:71], v[20:21], off
	ds_read_b128 v[82:85], v73 offset:12320
	ds_read_b128 v[86:89], v73 offset:12336
	s_waitcnt lgkmcnt(5)
	v_mov_b32_e32 v50, v63
	s_waitcnt lgkmcnt(3)
	v_mov_b32_e32 v54, v67
	s_waitcnt lgkmcnt(1)
	v_mov_b32_e32 v58, v85
	s_waitcnt vmcnt(1)
	v_pk_fma_f32 v[116:117], v[8:9], v[64:65], v[22:23] op_sel_hi:[1,0,1]
	v_pk_fma_f32 v[118:119], v[10:11], v[64:65], v[90:91] op_sel_hi:[1,0,1]
	v_pk_fma_f32 v[122:123], v[10:11], v[82:83], v[92:93] op_sel_hi:[1,0,1]
	ds_read_b128 v[90:93], v73 offset:16416
	ds_read_b128 v[22:25], v73 offset:16432
	ds_read_b128 v[94:97], v73 offset:20512
	ds_read_b128 v[18:21], v73 offset:20528
	v_pk_fma_f32 v[114:115], v[8:9], v[60:61], v[14:15] op_sel_hi:[1,0,1]
	v_pk_fma_f32 v[120:121], v[8:9], v[82:83], v[4:5] op_sel_hi:[1,0,1]
	s_waitcnt lgkmcnt(3)
	v_pk_fma_f32 v[124:125], v[10:11], v[90:91], v[6:7] op_sel_hi:[1,0,1]
	s_waitcnt lgkmcnt(1)
	v_pk_fma_f32 v[126:127], v[8:9], v[94:95], v[98:99] op_sel_hi:[1,0,1]
	v_pk_fma_f32 v[128:129], v[10:11], v[94:95], v[16:17] op_sel_hi:[1,0,1]
	ds_read_b128 v[98:101], v73 offset:24608
	ds_read_b128 v[14:17], v73 offset:24624
	v_pk_fma_f32 v[52:53], v[8:9], v[26:27], v[52:53] op_sel_hi:[1,0,1]
	v_pk_fma_f32 v[48:49], v[10:11], v[26:27], v[48:49] op_sel_hi:[1,0,1]
	v_pk_fma_f32 v[56:57], v[10:11], v[60:61], v[56:57] op_sel_hi:[1,0,1]
	s_waitcnt lgkmcnt(1)
	v_pk_fma_f32 v[130:131], v[8:9], v[98:99], v[104:105] op_sel_hi:[1,0,1]
	v_pk_fma_f32 v[132:133], v[10:11], v[98:99], v[102:103] op_sel_hi:[1,0,1]
	ds_read_b128 v[102:105], v73 offset:28704
	ds_read_b128 v[0:3], v73 offset:28720
	v_pk_fma_f32 v[12:13], v[8:9], v[90:91], v[12:13] op_sel_hi:[1,0,1]
	s_waitcnt vmcnt(0)
	v_pk_fma_f32 v[48:49], v[70:71], v[26:27], v[48:49] op_sel:[0,1,0]
	v_pk_fma_f32 v[26:27], v[68:69], v[26:27], v[52:53] op_sel:[0,1,0]
	s_waitcnt lgkmcnt(1)
	v_pk_fma_f32 v[134:135], v[10:11], v[102:103], v[106:107] op_sel_hi:[1,0,1]
	ds_read_b128 v[106:109], v73 offset:32800
	ds_read_b128 v[4:7], v73 offset:32816
	v_pk_fma_f32 v[34:35], v[8:9], v[102:103], v[34:35] op_sel_hi:[1,0,1]
	v_pk_fma_f32 v[52:53], v[70:71], v[60:61], v[56:57] op_sel:[0,1,0]
	v_pk_fma_f32 v[56:57], v[68:69], v[60:61], v[114:115] op_sel:[0,1,0]
	s_waitcnt lgkmcnt(1)
; __device__ __forceinline__ void phase_prep(const Params& P, LAS unsigned char* lds) {
;     ...
;           for (int k0 = 0; k0 < 32; k0 += 16) { f32x4 wv[16];
; #pragma unroll
;               for (int k = 0; k < 16; ++k) wv[k] = *(const f32x4*)(wp + (size_t)(k0 + k) * 9216);
; #pragma unroll
;               for (int k = 0; k < 16; ++k) {
; #pragma unroll
;                   for (int v = 0; v < 9; ++v) a[v] += wv[k] * sc[v * 1024 + kc * 32 + k0 + k]; } }
	v_pk_fma_f32 v[8:9], v[8:9], v[106:107], v[112:113] op_sel_hi:[1,0,1]
	v_pk_fma_f32 v[10:11], v[10:11], v[106:107], v[110:111] op_sel_hi:[1,0,1]
	v_pk_fma_f32 v[60:61], v[70:71], v[64:65], v[118:119] op_sel:[0,1,0]
	v_pk_fma_f32 v[64:65], v[68:69], v[64:65], v[116:117] op_sel:[0,1,0]
	v_pk_fma_f32 v[116:117], v[70:71], v[102:103], v[134:135] op_sel:[0,1,0]
	v_pk_fma_f32 v[34:35], v[68:69], v[102:103], v[34:35] op_sel:[0,1,0]
	v_pk_fma_f32 v[102:103], v[70:71], v[106:107], v[10:11] op_sel:[0,1,0]
	v_pk_fma_f32 v[106:107], v[68:69], v[106:107], v[8:9] op_sel:[0,1,0]
	v_add_co_u32_e32 v8, vcc, s25, v46
	v_pk_fma_f32 v[110:111], v[70:71], v[82:83], v[122:123] op_sel:[0,1,0]
	s_nop 0
	v_addc_co_u32_e32 v9, vcc, 0, v47, vcc
	v_pk_fma_f32 v[82:83], v[68:69], v[82:83], v[120:121] op_sel:[0,1,0]
	v_pk_fma_f32 v[112:113], v[70:71], v[90:91], v[124:125] op_sel:[0,1,0]
	v_pk_fma_f32 v[12:13], v[68:69], v[90:91], v[12:13] op_sel:[0,1,0]
	v_pk_fma_f32 v[90:91], v[70:71], v[94:95], v[128:129] op_sel:[0,1,0]
	v_pk_fma_f32 v[94:95], v[68:69], v[94:95], v[126:127] op_sel:[0,1,0]
	v_pk_fma_f32 v[114:115], v[70:71], v[98:99], v[132:133] op_sel:[0,1,0]
	v_pk_fma_f32 v[98:99], v[68:69], v[98:99], v[130:131] op_sel:[0,1,0]
	v_add_co_u32_e32 v68, vcc, s26, v46
	s_nop 1
	v_addc_co_u32_e32 v69, vcc, 0, v47, vcc
	global_load_dwordx4 v[8:11], v[8:9], off
	global_load_dwordx4 v[68:71], v[68:69], off
	s_waitcnt vmcnt(1)
	v_pk_fma_f32 v[26:27], v[8:9], v[28:29], v[26:27] op_sel_hi:[1,0,1]
	v_pk_fma_f32 v[48:49], v[10:11], v[28:29], v[48:49] op_sel_hi:[1,0,1]
	v_pk_fma_f32 v[56:57], v[8:9], v[62:63], v[56:57] op_sel_hi:[1,0,1]
	v_pk_fma_f32 v[52:53], v[10:11], v[62:63], v[52:53] op_sel_hi:[1,0,1]
	v_pk_fma_f32 v[64:65], v[8:9], v[66:67], v[64:65] op_sel_hi:[1,0,1]
	v_pk_fma_f32 v[60:61], v[10:11], v[66:67], v[60:61] op_sel_hi:[1,0,1]
	v_pk_fma_f32 v[82:83], v[8:9], v[84:85], v[82:83] op_sel_hi:[1,0,1]
	v_pk_fma_f32 v[110:111], v[10:11], v[84:85], v[110:111] op_sel_hi:[1,0,1]
	v_pk_fma_f32 v[12:13], v[8:9], v[92:93], v[12:13] op_sel_hi:[1,0,1]
	v_pk_fma_f32 v[112:113], v[10:11], v[92:93], v[112:113] op_sel_hi:[1,0,1]
	v_pk_fma_f32 v[94:95], v[8:9], v[96:97], v[94:95] op_sel_hi:[1,0,1]
	v_pk_fma_f32 v[90:91], v[10:11], v[96:97], v[90:91] op_sel_hi:[1,0,1]
	v_pk_fma_f32 v[98:99], v[8:9], v[100:101], v[98:99] op_sel_hi:[1,0,1]
	v_pk_fma_f32 v[114:115], v[10:11], v[100:101], v[114:115] op_sel_hi:[1,0,1]
	v_pk_fma_f32 v[34:35], v[8:9], v[104:105], v[34:35] op_sel_hi:[1,0,1]
	v_pk_fma_f32 v[8:9], v[8:9], v[108:109], v[106:107] op_sel_hi:[1,0,1]
	v_mov_b32_e32 v28, v29
	v_mov_b32_e32 v62, v93
	v_mov_b32_e32 v66, v97
	v_mov_b32_e32 v84, v101
	v_mov_b32_e32 v92, v105
	v_mov_b32_e32 v96, v109
	v_pk_fma_f32 v[116:117], v[10:11], v[104:105], v[116:117] op_sel_hi:[1,0,1]
	s_waitcnt vmcnt(0)
	v_pk_fma_f32 v[100:101], v[68:69], v[28:29], v[26:27] op_sel_hi:[1,0,1]
	v_pk_fma_f32 v[56:57], v[68:69], v[50:51], v[56:57] op_sel_hi:[1,0,1]
	v_pk_fma_f32 v[64:65], v[68:69], v[54:55], v[64:65] op_sel_hi:[1,0,1]
	v_pk_fma_f32 v[82:83], v[68:69], v[58:59], v[82:83] op_sel_hi:[1,0,1]
	v_pk_fma_f32 v[104:105], v[70:71], v[62:63], v[112:113] op_sel_hi:[1,0,1]
	v_pk_fma_f32 v[12:13], v[68:69], v[62:63], v[12:13] op_sel_hi:[1,0,1]
	v_pk_fma_f32 v[62:63], v[70:71], v[66:67], v[90:91] op_sel_hi:[1,0,1]
	v_pk_fma_f32 v[66:67], v[68:69], v[66:67], v[94:95] op_sel_hi:[1,0,1]
	v_pk_fma_f32 v[90:91], v[70:71], v[84:85], v[114:115] op_sel_hi:[1,0,1]
	v_pk_fma_f32 v[84:85], v[68:69], v[84:85], v[98:99] op_sel_hi:[1,0,1]
	v_pk_fma_f32 v[34:35], v[68:69], v[92:93], v[34:35] op_sel_hi:[1,0,1]
	v_pk_fma_f32 v[68:69], v[68:69], v[96:97], v[8:9] op_sel_hi:[1,0,1]
	v_add_co_u32_e32 v8, vcc, s27, v46
	v_pk_fma_f32 v[10:11], v[10:11], v[108:109], v[102:103] op_sel_hi:[1,0,1]
	s_nop 0
	v_addc_co_u32_e32 v9, vcc, 0, v47, vcc
	v_add_co_u32_e32 v26, vcc, s28, v46
	v_pk_fma_f32 v[48:49], v[70:71], v[28:29], v[48:49] op_sel_hi:[1,0,1]
	s_nop 0
	v_addc_co_u32_e32 v27, vcc, 0, v47, vcc
	v_pk_fma_f32 v[52:53], v[70:71], v[50:51], v[52:53] op_sel_hi:[1,0,1]
	v_pk_fma_f32 v[60:61], v[70:71], v[54:55], v[60:61] op_sel_hi:[1,0,1]
	v_pk_fma_f32 v[102:103], v[70:71], v[58:59], v[110:111] op_sel_hi:[1,0,1]
	v_pk_fma_f32 v[94:95], v[70:71], v[92:93], v[116:117] op_sel_hi:[1,0,1]
	v_pk_fma_f32 v[70:71], v[70:71], v[96:97], v[10:11] op_sel_hi:[1,0,1]
	global_load_dwordx4 v[8:11], v[8:9], off
	global_load_dwordx4 v[26:29], v[26:27], off
	v_mov_b32_e32 v50, v77
	v_mov_b32_e32 v54, v81
	v_mov_b32_e32 v58, v89
	s_waitcnt vmcnt(1)
	v_pk_fma_f32 v[92:93], v[8:9], v[30:31], v[100:101] op_sel_hi:[1,0,1]
	v_pk_fma_f32 v[48:49], v[10:11], v[30:31], v[48:49] op_sel_hi:[1,0,1]
	v_pk_fma_f32 v[56:57], v[8:9], v[74:75], v[56:57] op_sel_hi:[1,0,1]
	v_pk_fma_f32 v[52:53], v[10:11], v[74:75], v[52:53] op_sel_hi:[1,0,1]
	v_pk_fma_f32 v[64:65], v[8:9], v[78:79], v[64:65] op_sel_hi:[1,0,1]
	v_pk_fma_f32 v[60:61], v[10:11], v[78:79], v[60:61] op_sel_hi:[1,0,1]
	v_pk_fma_f32 v[82:83], v[8:9], v[86:87], v[82:83] op_sel_hi:[1,0,1]
	v_pk_fma_f32 v[96:97], v[10:11], v[86:87], v[102:103] op_sel_hi:[1,0,1]
	v_pk_fma_f32 v[12:13], v[8:9], v[22:23], v[12:13] op_sel_hi:[1,0,1]
	v_pk_fma_f32 v[98:99], v[10:11], v[22:23], v[104:105] op_sel_hi:[1,0,1]
	v_pk_fma_f32 v[66:67], v[8:9], v[18:19], v[66:67] op_sel_hi:[1,0,1]
	v_pk_fma_f32 v[62:63], v[10:11], v[18:19], v[62:63] op_sel_hi:[1,0,1]
	v_pk_fma_f32 v[84:85], v[8:9], v[14:15], v[84:85] op_sel_hi:[1,0,1]
	v_pk_fma_f32 v[90:91], v[10:11], v[14:15], v[90:91] op_sel_hi:[1,0,1]
	v_pk_fma_f32 v[34:35], v[8:9], v[0:1], v[34:35] op_sel_hi:[1,0,1]
	v_pk_fma_f32 v[94:95], v[10:11], v[0:1], v[94:95] op_sel_hi:[1,0,1]
	s_waitcnt lgkmcnt(0)
; #define LAS __attribute__((address_space(3)))
; __device__ __forceinline__ void phase_prep(const Params& P, LAS unsigned char* lds) {
;     ...
;           for (int k0 = 0; k0 < 32; k0 += 16) { f32x4 wv[16];
; #pragma unroll
;               for (int k = 0; k < 16; ++k) wv[k] = *(const f32x4*)(wp + (size_t)(k0 + k) * 9216);
; #pragma unroll
;               for (int k = 0; k < 16; ++k) {
; #pragma unroll
;                   for (int v = 0; v < 9; ++v) a[v] += wv[k] * sc[v * 1024 + kc * 32 + k0 + k]; } }
; #pragma unroll
;           for (int v = 0; v < 9; ++v) *(LAS f32x4*)(red + (kc * 9 + v) * 64 + 4 * cq) = a[v];
;           __syncthreads();
;           for (int o = tid; o < 9 * 64; o += 512) { const int v = o >> 6, cc = o & 63; float s = P.b_mod[l * 9216 + col0 + cc];
	v_pk_fma_f32 v[8:9], v[8:9], v[4:5], v[68:69] op_sel_hi:[1,0,1]
	v_pk_fma_f32 v[10:11], v[10:11], v[4:5], v[70:71] op_sel_hi:[1,0,1]
	s_waitcnt vmcnt(0)
	v_pk_fma_f32 v[52:53], v[28:29], v[74:75], v[52:53] op_sel:[0,1,0]
	v_pk_fma_f32 v[56:57], v[26:27], v[74:75], v[56:57] op_sel:[0,1,0]
	v_pk_fma_f32 v[74:75], v[28:29], v[78:79], v[60:61] op_sel:[0,1,0]
	v_pk_fma_f32 v[78:79], v[26:27], v[78:79], v[64:65] op_sel:[0,1,0]
	v_pk_fma_f32 v[68:69], v[28:29], v[22:23], v[98:99] op_sel:[0,1,0]
	v_pk_fma_f32 v[70:71], v[26:27], v[22:23], v[12:13] op_sel:[0,1,0]
	v_pk_fma_f32 v[64:65], v[28:29], v[18:19], v[62:63] op_sel:[0,1,0]
	v_pk_fma_f32 v[66:67], v[26:27], v[18:19], v[66:67] op_sel:[0,1,0]
	v_pk_fma_f32 v[18:19], v[28:29], v[0:1], v[94:95] op_sel:[0,1,0]
	v_pk_fma_f32 v[22:23], v[26:27], v[0:1], v[34:35] op_sel:[0,1,0]
	v_pk_fma_f32 v[0:1], v[28:29], v[4:5], v[10:11] op_sel:[0,1,0]
	v_pk_fma_f32 v[4:5], v[26:27], v[4:5], v[8:9] op_sel:[0,1,0]
	v_add_co_u32_e32 v8, vcc, s29, v46
	v_pk_fma_f32 v[60:61], v[28:29], v[14:15], v[90:91] op_sel:[0,1,0]
	s_nop 0
	v_addc_co_u32_e32 v9, vcc, 0, v47, vcc
	v_add_co_u32_e32 v10, vcc, s30, v46
	v_pk_fma_f32 v[62:63], v[26:27], v[14:15], v[84:85] op_sel:[0,1,0]
	s_nop 0
	v_addc_co_u32_e32 v11, vcc, 0, v47, vcc
	global_load_dwordx4 v[12:15], v[8:9], off
	global_load_dwordx4 v[8:11], v[10:11], off
	v_pk_fma_f32 v[48:49], v[28:29], v[30:31], v[48:49] op_sel:[0,1,0]
	v_pk_fma_f32 v[30:31], v[26:27], v[30:31], v[92:93] op_sel:[0,1,0]
	v_pk_fma_f32 v[92:93], v[28:29], v[86:87], v[96:97] op_sel:[0,1,0]
	v_pk_fma_f32 v[82:83], v[26:27], v[86:87], v[82:83] op_sel:[0,1,0]
	v_mov_b32_e32 v34, v33
	s_and_b64 vcc, exec, s[10:11]
	s_mov_b64 s[10:11], 0
	s_waitcnt vmcnt(1)
	v_pk_fma_f32 v[26:27], v[12:13], v[32:33], v[30:31] op_sel_hi:[1,0,1]
	v_pk_fma_f32 v[30:31], v[14:15], v[32:33], v[48:49] op_sel_hi:[1,0,1]
	v_pk_fma_f32 v[28:29], v[12:13], v[76:77], v[56:57] op_sel_hi:[1,0,1]
	v_pk_fma_f32 v[46:47], v[14:15], v[76:77], v[52:53] op_sel_hi:[1,0,1]
	v_pk_fma_f32 v[32:33], v[12:13], v[80:81], v[78:79] op_sel_hi:[1,0,1]
	v_pk_fma_f32 v[52:53], v[14:15], v[80:81], v[74:75] op_sel_hi:[1,0,1]
	v_pk_fma_f32 v[48:49], v[12:13], v[88:89], v[82:83] op_sel_hi:[1,0,1]
	v_pk_fma_f32 v[56:57], v[14:15], v[88:89], v[92:93] op_sel_hi:[1,0,1]
	v_pk_fma_f32 v[70:71], v[12:13], v[24:25], v[70:71] op_sel_hi:[1,0,1]
	v_pk_fma_f32 v[68:69], v[14:15], v[24:25], v[68:69] op_sel_hi:[1,0,1]
	v_mov_b32_e32 v24, v25
	v_mov_b32_e32 v74, v21
	v_pk_fma_f32 v[66:67], v[12:13], v[20:21], v[66:67] op_sel_hi:[1,0,1]
	v_pk_fma_f32 v[64:65], v[14:15], v[20:21], v[64:65] op_sel_hi:[1,0,1]
	v_mov_b32_e32 v76, v17
	v_mov_b32_e32 v78, v3
	v_pk_fma_f32 v[62:63], v[12:13], v[16:17], v[62:63] op_sel_hi:[1,0,1]
	v_pk_fma_f32 v[60:61], v[14:15], v[16:17], v[60:61] op_sel_hi:[1,0,1]
	v_mov_b32_e32 v80, v7
	v_pk_fma_f32 v[82:83], v[12:13], v[2:3], v[22:23] op_sel_hi:[1,0,1]
	v_pk_fma_f32 v[84:85], v[14:15], v[2:3], v[18:19] op_sel_hi:[1,0,1]
	v_pk_fma_f32 v[86:87], v[12:13], v[6:7], v[4:5] op_sel_hi:[1,0,1]
	v_pk_fma_f32 v[88:89], v[14:15], v[6:7], v[0:1] op_sel_hi:[1,0,1]
	s_waitcnt vmcnt(0)
	v_pk_fma_f32 v[2:3], v[10:11], v[34:35], v[30:31] op_sel_hi:[1,0,1]
	v_pk_fma_f32 v[0:1], v[8:9], v[34:35], v[26:27] op_sel_hi:[1,0,1]
	v_pk_fma_f32 v[6:7], v[10:11], v[50:51], v[46:47] op_sel_hi:[1,0,1]
	v_pk_fma_f32 v[4:5], v[8:9], v[50:51], v[28:29] op_sel_hi:[1,0,1]
	v_pk_fma_f32 v[14:15], v[10:11], v[54:55], v[52:53] op_sel_hi:[1,0,1]
	v_pk_fma_f32 v[12:13], v[8:9], v[54:55], v[32:33] op_sel_hi:[1,0,1]
	v_pk_fma_f32 v[18:19], v[10:11], v[58:59], v[56:57] op_sel_hi:[1,0,1]
	v_pk_fma_f32 v[16:17], v[8:9], v[58:59], v[48:49] op_sel_hi:[1,0,1]
	v_pk_fma_f32 v[22:23], v[10:11], v[24:25], v[68:69] op_sel_hi:[1,0,1]
	v_pk_fma_f32 v[20:21], v[8:9], v[24:25], v[70:71] op_sel_hi:[1,0,1]
	v_pk_fma_f32 v[26:27], v[10:11], v[74:75], v[64:65] op_sel_hi:[1,0,1]
	v_pk_fma_f32 v[24:25], v[8:9], v[74:75], v[66:67] op_sel_hi:[1,0,1]
	v_pk_fma_f32 v[30:31], v[10:11], v[76:77], v[60:61] op_sel_hi:[1,0,1]
	v_pk_fma_f32 v[28:29], v[8:9], v[76:77], v[62:63] op_sel_hi:[1,0,1]
	v_pk_fma_f32 v[34:35], v[10:11], v[78:79], v[84:85] op_sel_hi:[1,0,1]
	v_pk_fma_f32 v[32:33], v[8:9], v[78:79], v[82:83] op_sel_hi:[1,0,1]
	v_pk_fma_f32 v[10:11], v[10:11], v[80:81], v[88:89] op_sel_hi:[1,0,1]
	v_pk_fma_f32 v[8:9], v[8:9], v[80:81], v[86:87] op_sel_hi:[1,0,1]
	s_cbranch_vccnz .LBB0_75
	ds_write_b128 v72, v[0:3] offset:36864
	ds_write_b128 v72, v[4:7] offset:37120
	ds_write_b128 v72, v[12:15] offset:37376
	ds_write_b128 v72, v[16:19] offset:37632
	ds_write_b128 v72, v[20:23] offset:37888
	ds_write_b128 v72, v[24:27] offset:38144
	ds_write_b128 v72, v[28:31] offset:38400
	ds_write_b128 v72, v[32:35] offset:38656
	ds_write_b128 v72, v[8:11] offset:38912
	s_waitcnt lgkmcnt(0)
	s_barrier
	s_and_saveexec_b64 s[10:11], s[4:5]
	s_cbranch_execz .LBB0_73
	s_mul_i32 s2, s34, 0x2400
	s_add_i32 s2, s2, s8
	v_or_b32_e32 v0, s2, v51
	v_ashrrev_i32_e32 v1, 31, v0
	s_mul_i32 s34, s34, 9
	v_lshl_add_u64 v[0:1], v[0:1], 2, s[74:75]
	v_lshl_add_u64 v[2:3], s[8:9], 2, v[40:41]
	s_mov_b64 s[8:9], 0
	v_mov_b32_e32 v4, v36

; __device__ __forceinline__ void phase_norm(const Params& P, int l, int sub, int addpart) {
;     int tid = threadIdx.x; asm volatile("" : "+v"(tid)); const int lane = tid & 63, wave = tid >> 6; const int rbeg = blockIdx.x * 8 + wave, rstride = gridDim.x * 8, rend = T;
;     const float* Hc = (const float*)(P.ws + OFF_HC); bf16_t* XN = (bf16_t*)(P.ws + OFF_XN); const float* MOD = (const float*)(P.ws + OFF_MOD) + (size_t)l * 9 * 9216;
;     const float* g = P.norm_g + (l * 3 + sub) * 1024; f32x4 gg[4];
; #pragma unroll
;     for (int j = 0; j < 4; ++j) gg[j] = *(const f32x4*)(g + 4 * lane + 256 * j);
;     f32x4 v[4], sc[4], sh[4];
;     if (rbeg < rend) NR_LOAD(rbeg, v, sc, sh);
.LBB0_200:
	s_or_b64 exec, exec, s[4:5]
	v_lshlrev_b32_e32 v116, 2, v90
	global_load_dwordx4 v[32:35], v116, s[76:77]
	global_load_dwordx4 v[36:39], v116, s[76:77] offset:1024
	global_load_dwordx4 v[40:43], v116, s[76:77] offset:2048
	global_load_dwordx4 v[44:47], v116, s[76:77] offset:3072
	v_mov_b32_e32 v0, 0
	s_add_u32 s16, s92, 0x4ec0000
	s_mov_b32 s2, 0x8800
	s_addc_u32 s17, s93, 0
	v_cmp_gt_i32_e32 vcc, s2, v112
	v_mov_b32_e32 v1, v0
	v_mov_b32_e32 v2, v0
	v_mov_b32_e32 v3, v0
	v_mov_b32_e32 v4, v0
	v_mov_b32_e32 v5, v0
	v_mov_b32_e32 v6, v0
	v_mov_b32_e32 v7, v0
	v_mov_b32_e32 v8, v0
	v_mov_b32_e32 v9, v0
	v_mov_b32_e32 v10, v0
	v_mov_b32_e32 v11, v0
	v_mov_b32_e32 v12, v0
	v_mov_b32_e32 v13, v0
	v_mov_b32_e32 v14, v0
	v_mov_b32_e32 v15, v0
	v_ashrrev_i32_e32 v113, 31, v112
	s_and_saveexec_b64 s[6:7], vcc
	s_cbranch_execz .LBB0_202
	s_mov_b32 s2, 0x8000
	v_add_u32_e32 v1, 0xffff8000, v112
	v_cmp_gt_i32_e64 s[4:5], s2, v112
	v_mov_b32_e32 v4, s65
	s_mov_b64 s[2:3], 0x1000
	v_cndmask_b32_e64 v2, v1, v112, s[4:5]
	v_mov_b32_e32 v1, s69
	v_cndmask_b32_e64 v5, v1, v4, s[4:5]
	v_mov_b32_e32 v1, s68
	v_mov_b32_e32 v4, s64
	v_cndmask_b32_e64 v3, 0, v113, s[4:5]
	v_cndmask_b32_e64 v4, v1, v4, s[4:5]
	v_min_i32_e32 v1, 0x8000, v112
	v_lshlrev_b64 v[2:3], 12, v[2:3]
	v_ashrrev_i32_e32 v1, 12, v1
	v_lshl_add_u64 v[2:3], v[4:5], 0, v[2:3]
	v_mul_hi_i32_i24_e32 v5, 0x9000, v1
	v_mul_i32_i24_e32 v4, 0x9000, v1
	v_lshl_add_u64 v[4:5], s[16:17], 0, v[4:5]
	v_lshl_add_u64 v[64:65], v[4:5], 0, s[2:3]
	v_or_b32_e32 v10, 0x400, v116
	v_mov_b32_e32 v11, v0
	v_mov_b32_e32 v117, v0
	v_lshl_add_u64 v[72:73], v[64:65], 0, v[10:11]
	v_or_b32_e32 v10, 0x800, v116
	v_lshl_add_u64 v[14:15], v[2:3], 0, v[116:117]
	v_lshl_add_u64 v[2:3], v[64:65], 0, v[116:117]
	v_lshl_add_u64 v[76:77], v[4:5], 0, v[116:117]
	v_lshl_add_u64 v[66:67], v[64:65], 0, v[10:11]
	v_or_b32_e32 v68, 0xc00, v116
	v_mov_b32_e32 v69, v0
	global_load_dwordx4 v[48:51], v[2:3], off
	global_load_dwordx4 v[52:55], v[76:77], off
	global_load_dwordx4 v[2:5], v[14:15], off
	global_load_dwordx4 v[6:9], v[14:15], off offset:1024
	global_load_dwordx4 v[60:63], v[76:77], off offset:1024
	global_load_dwordx4 v[56:59], v[76:77], off offset:2048
	global_load_dwordx4 v[10:13], v[14:15], off offset:2048
	global_load_dwordx4 v[14:17], v[14:15], off offset:3072
	v_lshl_add_u64 v[0:1], v[64:65], 0, v[68:69]
	global_load_dwordx4 v[68:71], v[66:67], off
	global_load_dwordx4 v[64:67], v[0:1], off
	global_load_dwordx4 v[72:75], v[72:73], off
	global_load_dwordx4 v[76:79], v[76:77], off offset:3072
	s_waitcnt vmcnt(4)
	v_mov_b64_e32 v[0:1], v[2:3]
	v_mov_b64_e32 v[2:3], v[4:5]
	v_mov_b64_e32 v[4:5], v[6:7]
	v_mov_b64_e32 v[6:7], v[8:9]
	v_mov_b64_e32 v[8:9], v[10:11]
	v_mov_b64_e32 v[10:11], v[12:13]
	v_mov_b64_e32 v[12:13], v[14:15]
	v_mov_b64_e32 v[14:15], v[16:17]

; __device__ __forceinline__ void phase_norm(const Params& P, int l, int sub, int addpart) {
;     ...
;     for (int r = rbeg; r < rend; r += rstride) { const int rn = r + rstride; f32x4 vn[4], scn[4], shn[4];
;         if (rn < rend) NR_LOAD(rn, vn, scn, shn);
.LBB0_205:
	v_add_u32_e32 v184, s96, v160
	v_cmp_gt_i32_e64 s[4:5], s44, v184
	v_cmp_lt_i32_e32 vcc, s45, v184
	s_and_saveexec_b64 s[8:9], s[4:5]
	s_cbranch_execz .LBB0_207
	v_add_u32_e32 v18, 0xffff8000, v184
	v_lshl_add_u64 v[16:17], v[114:115], 0, s[28:29]
	v_cmp_gt_i32_e64 s[6:7], s46, v184
	v_mov_b32_e32 v19, s65
	v_mov_b32_e32 v20, s64
	v_cndmask_b32_e64 v16, v18, v16, s[6:7]
	v_mov_b32_e32 v18, s69
	v_cndmask_b32_e64 v17, 0, v17, s[6:7]
	v_cndmask_b32_e64 v19, v18, v19, s[6:7]
	v_mov_b32_e32 v18, s68
	v_cndmask_b32_e64 v18, v18, v20, s[6:7]
	v_lshlrev_b64 v[16:17], 12, v[16:17]
	v_lshl_add_u64 v[16:17], v[18:19], 0, v[16:17]
	v_min_i32_e32 v18, 0x8000, v184
	v_ashrrev_i32_e32 v18, 12, v18
	v_mul_hi_i32_i24_e32 v19, 0x9000, v18
	v_mul_i32_i24_e32 v18, 0x9000, v18
	v_lshl_add_u64 v[18:19], s[16:17], 0, v[18:19]
	v_lshl_add_u64 v[96:97], v[18:19], 0, s[26:27]
	v_mov_b32_e32 v155, v117
	v_mov_b32_e32 v157, v117
	v_mov_b32_e32 v159, v117
	v_lshl_add_u64 v[28:29], v[16:17], 0, v[116:117]
	v_lshl_add_u64 v[16:17], v[96:97], 0, v[116:117]
	v_lshl_add_u64 v[108:109], v[18:19], 0, v[116:117]
	v_lshl_add_u64 v[104:105], v[96:97], 0, v[154:155]
	v_lshl_add_u64 v[98:99], v[96:97], 0, v[156:157]
	v_lshl_add_u64 v[96:97], v[96:97], 0, v[158:159]
	global_load_dwordx4 v[80:83], v[16:17], off
	global_load_dwordx4 v[84:87], v[108:109], off
	global_load_dwordx4 v[16:19], v[28:29], off
	global_load_dwordx4 v[20:23], v[28:29], off offset:1024
	global_load_dwordx4 v[88:91], v[108:109], off offset:1024
	global_load_dwordx4 v[92:95], v[108:109], off offset:2048
	global_load_dwordx4 v[24:27], v[28:29], off offset:2048
	global_load_dwordx4 v[28:31], v[28:29], off offset:3072
	global_load_dwordx4 v[100:103], v[98:99], off
	global_load_dwordx4 v[96:99], v[96:97], off
	global_load_dwordx4 v[104:107], v[104:105], off
	global_load_dwordx4 v[108:111], v[108:109], off offset:3072

; __device__ __forceinline__ void phase_norm(const Params& P, int l, int sub, int addpart) {
;     int tid = threadIdx.x; asm volatile("" : "+v"(tid)); const int lane = tid & 63, wave = tid >> 6; const int rbeg = blockIdx.x * 8 + wave, rstride = gridDim.x * 8, rend = T;
;     const float* Hc = (const float*)(P.ws + OFF_HC); bf16_t* XN = (bf16_t*)(P.ws + OFF_XN); const float* MOD = (const float*)(P.ws + OFF_MOD) + (size_t)l * 9 * 9216;
;     const float* g = P.norm_g + (l * 3 + sub) * 1024; f32x4 gg[4];
; #pragma unroll
;     for (int j = 0; j < 4; ++j) gg[j] = *(const f32x4*)(g + 4 * lane + 256 * j);
;     f32x4 v[4], sc[4], sh[4];
;     if (rbeg < rend) NR_LOAD(rbeg, v, sc, sh);
.LBB0_313:
	s_andn2_b64 vcc, exec, s[8:9]
	s_cbranch_vccnz .LBB0_384
	s_waitcnt vmcnt(0)
	v_mov_b32_e32 v66, v168
	v_readlane_b32 s0, v250, 18
	v_ashrrev_i32_e32 v67, 6, v66
	s_nop 0
	v_add_u32_e32 v64, s0, v67
	s_mov_b32 s0, 0x8800
	v_cmp_gt_i32_e32 vcc, s0, v64
	s_and_saveexec_b64 s[40:41], vcc
	s_cbranch_execz .LBB0_330
	v_add_u32_e32 v128, 0xffff8000, v64
	v_ashrrev_i32_e32 v65, 31, v64
	v_cmp_gt_i32_e32 vcc, s25, v64
	v_mov_b32_e32 v18, s31
	v_mov_b32_e32 v19, s87
	v_lshlrev_b32_e32 v0, 2, v66
	v_cndmask_b32_e32 v17, 0, v65, vcc
	v_cndmask_b32_e32 v16, v128, v64, vcc
	v_cndmask_b32_e32 v19, v18, v19, vcc
	v_mov_b32_e32 v18, s30
	v_mov_b32_e32 v20, s86
	s_waitcnt vmcnt(0)
	v_and_b32_e32 v40, 0xfc, v0
	v_readlane_b32 s0, v254, 40
	v_cndmask_b32_e32 v18, v18, v20, vcc
	v_lshlrev_b64 v[16:17], 12, v[16:17]
	v_lshlrev_b32_e32 v112, 2, v40
	v_readlane_b32 s1, v254, 41
	v_lshl_add_u64 v[16:17], v[18:19], 0, v[16:17]
	v_min_i32_e32 v18, 0x8000, v64
	s_waitcnt lgkmcnt(0)
	s_nop 1
	global_load_dwordx4 v[0:3], v112, s[0:1]
	global_load_dwordx4 v[4:7], v112, s[0:1] offset:1024
	global_load_dwordx4 v[8:11], v112, s[0:1] offset:2048
	global_load_dwordx4 v[12:15], v112, s[0:1] offset:3072
	v_ashrrev_i32_e32 v18, 12, v18
	v_readlane_b32 s0, v255, 12
	v_mul_hi_i32_i24_e32 v19, 0x9000, v18
	v_mul_i32_i24_e32 v18, 0x9000, v18
	v_readlane_b32 s1, v255, 13
	v_mov_b32_e32 v113, v129
	v_mov_b32_e32 v115, v129
	v_lshl_add_u64 v[18:19], s[0:1], 0, v[18:19]
	s_mov_b64 s[0:1], 0x3000
	v_lshl_add_u64 v[20:21], v[18:19], 0, s[0:1]
	s_mov_b64 s[0:1], 0x4000
	v_lshl_add_u64 v[18:19], v[18:19], 0, s[0:1]
	v_lshl_add_u64 v[22:23], v[18:19], 0, v[112:113]
	v_lshl_add_u64 v[24:25], v[20:21], 0, v[112:113]
	global_load_dwordx4 v[44:47], v[22:23], off
	global_load_dwordx4 v[48:51], v[24:25], off
	v_or_b32_e32 v22, 0x100, v40
	v_lshlrev_b32_e32 v114, 2, v22
	v_lshl_add_u64 v[16:17], v[16:17], 0, v[112:113]
	v_lshl_add_u64 v[22:23], v[18:19], 0, v[114:115]
	global_load_dwordx4 v[60:63], v[16:17], off
	global_load_dwordx4 v[56:59], v[16:17], off offset:1024
	v_lshl_add_u64 v[24:25], v[20:21], 0, v[114:115]
	global_load_dwordx4 v[32:35], v[22:23], off
	global_load_dwordx4 v[36:39], v[24:25], off
	v_or_b32_e32 v22, 0x200, v40
	v_lshlrev_b32_e32 v116, 2, v22
	v_mov_b32_e32 v117, v129
	v_lshl_add_u64 v[22:23], v[18:19], 0, v[116:117]
	v_lshl_add_u64 v[28:29], v[20:21], 0, v[116:117]
	global_load_dwordx4 v[24:27], v[22:23], off
	global_load_dwordx4 v[28:31], v[28:29], off
	v_or_b32_e32 v22, 0x300, v40
	v_lshlrev_b32_e32 v118, 2, v22
	v_mov_b32_e32 v119, v129
	global_load_dwordx4 v[52:55], v[16:17], off offset:2048
	global_load_dwordx4 v[40:43], v[16:17], off offset:3072
	v_lshl_add_u64 v[16:17], v[18:19], 0, v[118:119]
	v_lshl_add_u64 v[20:21], v[20:21], 0, v[118:119]
	global_load_dwordx4 v[16:19], v[16:17], off
	global_load_dwordx4 v[20:23], v[20:21], off
	v_cmp_lt_i32_e32 vcc, s19, v64
	s_and_saveexec_b64 s[8:9], vcc
	s_cbranch_execz .LBB0_318
	v_readlane_b32 s0, v250, 21
	v_lshlrev_b64 v[68:69], 12, v[128:129]
	v_readlane_b32 s1, v250, 22
	s_nop 1
	v_lshl_add_u64 v[68:69], s[0:1], 0, v[68:69]
	v_lshl_add_u64 v[72:73], v[68:69], 0, v[112:113]
	global_load_dwordx4 v[68:71], v[72:73], off
	v_readlane_b32 s0, v254, 61
	v_readlane_b32 s1, v254, 62
	s_andn2_b64 vcc, exec, s[0:1]
	s_waitcnt vmcnt(0)
	v_pk_add_f32 v[62:63], v[62:63], v[70:71]
	v_pk_add_f32 v[60:61], v[60:61], v[68:69]
	global_load_dwordx4 v[68:71], v[72:73], off offset:1024
	s_waitcnt vmcnt(0)
	v_pk_add_f32 v[58:59], v[58:59], v[70:71]
	v_pk_add_f32 v[56:57], v[56:57], v[68:69]
	global_load_dwordx4 v[68:71], v[72:73], off offset:2048
	s_waitcnt vmcnt(0)
	v_pk_add_f32 v[54:55], v[54:55], v[70:71]
	v_pk_add_f32 v[52:53], v[52:53], v[68:69]
	global_load_dwordx4 v[68:71], v[72:73], off offset:3072
	s_waitcnt vmcnt(0)
	v_pk_add_f32 v[42:43], v[42:43], v[70:71]
	v_pk_add_f32 v[40:41], v[40:41], v[68:69]
	s_cbranch_vccnz .LBB0_318
	v_lshlrev_b64 v[68:69], 10, v[128:129]
	v_readlane_b32 s0, v251, 61
	v_lshlrev_b64 v[68:69], 2, v[68:69]
	v_readlane_b32 s1, v251, 62
	v_mov_b32_e32 v128, v112
	s_nop 0
	v_lshl_add_u64 v[70:71], s[0:1], 0, v[68:69]
	v_readlane_b32 s0, v250, 23
	v_readlane_b32 s1, v250, 24
	v_lshl_add_u64 v[92:93], v[70:71], 0, v[128:129]
	s_nop 0
	v_lshl_add_u64 v[68:69], s[0:1], 0, v[68:69]
	v_lshl_add_u64 v[96:97], v[68:69], 0, v[128:129]
	global_load_dwordx4 v[68:71], v[96:97], off
	global_load_dwordx4 v[72:75], v[92:93], off
	global_load_dwordx4 v[76:79], v[92:93], off offset:1024
	global_load_dwordx4 v[80:83], v[96:97], off offset:1024
	global_load_dwordx4 v[84:87], v[96:97], off offset:2048
	global_load_dwordx4 v[88:91], v[92:93], off offset:2048
	global_load_dwordx4 v[92:95], v[92:93], off offset:3072
	global_load_dwordx4 v[96:99], v[96:97], off offset:3072
	s_waitcnt vmcnt(6)
	v_pk_add_f32 v[70:71], v[74:75], v[70:71]
	v_pk_add_f32 v[68:69], v[72:73], v[68:69]
	s_waitcnt vmcnt(4)
	v_pk_add_f32 v[72:73], v[78:79], v[82:83]
	v_pk_add_f32 v[74:75], v[76:77], v[80:81]
	s_waitcnt vmcnt(2)
	v_pk_add_f32 v[76:77], v[90:91], v[86:87]
	v_pk_add_f32 v[78:79], v[88:89], v[84:85]
	s_waitcnt vmcnt(0)
	v_pk_add_f32 v[80:81], v[94:95], v[98:99]
	v_pk_add_f32 v[82:83], v[92:93], v[96:97]
	v_pk_add_f32 v[62:63], v[62:63], v[70:71]
	v_pk_add_f32 v[60:61], v[60:61], v[68:69]
	v_pk_add_f32 v[58:59], v[58:59], v[72:73]
	v_pk_add_f32 v[56:57], v[56:57], v[74:75]
	v_pk_add_f32 v[54:55], v[54:55], v[76:77]
	v_pk_add_f32 v[52:53], v[52:53], v[78:79]
	v_pk_add_f32 v[42:43], v[42:43], v[80:81]
	v_pk_add_f32 v[40:41], v[40:41], v[82:83]

; __device__ __forceinline__ void phase_norm(const Params& P, int l, int sub, int addpart) {
;     int tid = threadIdx.x; asm volatile("" : "+v"(tid)); const int lane = tid & 63, wave = tid >> 6; const int rbeg = blockIdx.x * 8 + wave, rstride = gridDim.x * 8, rend = T;
;     const float* Hc = (const float*)(P.ws + OFF_HC); bf16_t* XN = (bf16_t*)(P.ws + OFF_XN); const float* MOD = (const float*)(P.ws + OFF_MOD) + (size_t)l * 9 * 9216;
;     const float* g = P.norm_g + (l * 3 + sub) * 1024; f32x4 gg[4];
; #pragma unroll
;     for (int j = 0; j < 4; ++j) gg[j] = *(const f32x4*)(g + 4 * lane + 256 * j);
;     f32x4 v[4], sc[4], sh[4];
;     if (rbeg < rend) NR_LOAD(rbeg, v, sc, sh);
;     for (int r = rbeg; r < rend; r += rstride) { const int rn = r + rstride; f32x4 vn[4], scn[4], shn[4];
;         if (rn < rend) NR_LOAD(rn, vn, scn, shn);
.LBB0_320:
	v_add_u32_e32 v128, s96, v142
	v_add_u32_e32 v43, 0x8000, v128
	s_mov_b32 s0, 0x8800
	v_cmp_gt_i32_e32 vcc, s0, v43
	s_mov_b32 s0, 0x87ff
	v_cmp_lt_i32_e64 s[38:39], s0, v43
	s_and_saveexec_b64 s[42:43], vcc
	s_cbranch_execz .LBB0_325
	v_ashrrev_i32_e32 v63, 31, v43
	v_cmp_gt_i32_e32 vcc, s25, v43
	v_mov_b32_e32 v66, s87
	v_readlane_b32 s0, v254, 42
	v_cndmask_b32_e32 v65, 0, v63, vcc
	v_mov_b32_e32 v63, s31
	v_cndmask_b32_e32 v67, v63, v66, vcc
	v_mov_b32_e32 v63, s30
	v_mov_b32_e32 v66, s86
	v_cndmask_b32_e32 v64, v128, v43, vcc
	v_cndmask_b32_e32 v66, v63, v66, vcc
	v_min_i32_e32 v63, 0x8000, v43
	v_lshlrev_b64 v[64:65], 12, v[64:65]
	v_ashrrev_i32_e32 v63, 12, v63
	v_lshl_add_u64 v[64:65], v[66:67], 0, v[64:65]
	v_mul_hi_i32_i24_e32 v67, 0x9000, v63
	v_mul_i32_i24_e32 v66, 0x9000, v63
	v_readlane_b32 s1, v254, 43
	v_mov_b32_e32 v113, v129
	v_mov_b32_e32 v115, v129
	v_lshl_add_u64 v[66:67], s[0:1], 0, v[66:67]
	s_mov_b64 s[0:1], 0x1000
	v_lshl_add_u64 v[88:89], v[66:67], 0, s[0:1]
	v_mov_b32_e32 v117, v129
	v_mov_b32_e32 v119, v129
	v_lshl_add_u64 v[90:91], v[64:65], 0, v[112:113]
	v_lshl_add_u64 v[64:65], v[88:89], 0, v[112:113]
	v_lshl_add_u64 v[100:101], v[66:67], 0, v[112:113]
	v_lshl_add_u64 v[96:97], v[88:89], 0, v[114:115]
	v_lshl_add_u64 v[92:93], v[88:89], 0, v[116:117]
	v_lshl_add_u64 v[88:89], v[88:89], 0, v[118:119]
	global_load_dwordx4 v[68:71], v[64:65], off
	global_load_dwordx4 v[72:75], v[100:101], off
	global_load_dwordx4 v[64:67], v[90:91], off
	global_load_dwordx4 v[76:79], v[90:91], off offset:1024
	global_load_dwordx4 v[80:83], v[100:101], off offset:1024
	global_load_dwordx4 v[84:87], v[100:101], off offset:2048
	global_load_dwordx4 v[104:107], v[90:91], off offset:2048
	global_load_dwordx4 v[108:111], v[90:91], off offset:3072
	global_load_dwordx4 v[92:95], v[92:93], off
	global_load_dwordx4 v[88:91], v[88:89], off
	global_load_dwordx4 v[96:99], v[96:97], off
	global_load_dwordx4 v[100:103], v[100:101], off offset:3072
	v_cmp_lt_i32_e32 vcc, s19, v43
	s_and_saveexec_b64 s[44:45], vcc
	s_cbranch_execz .LBB0_324
	v_lshlrev_b64 v[150:151], 12, v[128:129]
	v_lshl_add_u64 v[154:155], v[122:123], 0, v[150:151]
	global_load_dwordx4 v[150:153], v[154:155], off
	v_readlane_b32 s0, v254, 61
	v_readlane_b32 s1, v254, 62
	s_andn2_b64 vcc, exec, s[0:1]
	s_waitcnt vmcnt(0)
	v_pk_add_f32 v[66:67], v[66:67], v[152:153]
	v_pk_add_f32 v[64:65], v[64:65], v[150:151]
	global_load_dwordx4 v[150:153], v[154:155], off offset:1024
	s_waitcnt vmcnt(0)
	v_pk_add_f32 v[78:79], v[78:79], v[152:153]
	v_pk_add_f32 v[76:77], v[76:77], v[150:151]
	global_load_dwordx4 v[150:153], v[154:155], off offset:2048
	s_waitcnt vmcnt(0)
	v_pk_add_f32 v[106:107], v[106:107], v[152:153]
	v_pk_add_f32 v[104:105], v[104:105], v[150:151]
	global_load_dwordx4 v[150:153], v[154:155], off offset:3072
	s_waitcnt vmcnt(0)
	v_pk_add_f32 v[110:111], v[110:111], v[152:153]
	v_pk_add_f32 v[108:109], v[108:109], v[150:151]
	s_cbranch_vccnz .LBB0_324
	v_lshlrev_b64 v[150:151], 10, v[128:129]
	v_lshlrev_b64 v[150:151], 2, v[150:151]
	v_lshl_add_u64 v[180:181], v[126:127], 0, v[150:151]
	v_lshl_add_u64 v[166:167], v[124:125], 0, v[150:151]
	global_load_dwordx4 v[150:153], v[180:181], off
	global_load_dwordx4 v[154:157], v[166:167], off
	global_load_dwordx4 v[158:161], v[166:167], off offset:1024
	global_load_dwordx4 v[162:165], v[180:181], off offset:1024
	global_load_dwordx4 v[184:187], v[180:181], off offset:2048
	global_load_dwordx4 v[188:191], v[166:167], off offset:2048
	global_load_dwordx4 v[192:195], v[166:167], off offset:3072
	global_load_dwordx4 v[196:199], v[180:181], off offset:3072
	s_waitcnt vmcnt(6)
	v_pk_add_f32 v[152:153], v[156:157], v[152:153]
	v_pk_add_f32 v[150:151], v[154:155], v[150:151]
	s_waitcnt vmcnt(4)
	v_pk_add_f32 v[154:155], v[160:161], v[164:165]
	v_pk_add_f32 v[156:157], v[158:159], v[162:163]
	s_waitcnt vmcnt(2)
	v_pk_add_f32 v[158:159], v[190:191], v[186:187]
	v_pk_add_f32 v[160:161], v[188:189], v[184:185]
	s_waitcnt vmcnt(0)
	v_pk_add_f32 v[162:163], v[194:195], v[198:199]
	v_pk_add_f32 v[164:165], v[192:193], v[196:197]
	v_pk_add_f32 v[66:67], v[66:67], v[152:153]
	v_pk_add_f32 v[64:65], v[64:65], v[150:151]
	v_pk_add_f32 v[78:79], v[78:79], v[154:155]
	v_pk_add_f32 v[76:77], v[76:77], v[156:157]
	v_pk_add_f32 v[106:107], v[106:107], v[158:159]
	v_pk_add_f32 v[104:105], v[104:105], v[160:161]
	v_pk_add_f32 v[110:111], v[110:111], v[162:163]
	v_pk_add_f32 v[108:109], v[108:109], v[164:165]

; #define GAS __attribute__((address_space(1)))
; __device__ __forceinline__ unsigned f2bf(float f) { unsigned u = __float_as_uint(f); return (u + 0x7fffu + ((u >> 16) & 1u)) >> 16; }
; __device__ __forceinline__ void dft_nyquist(const Params& P) {
;     ...
;     for (int wi = blockIdx.x * 8 + (tid >> 6); wi < NB * 256; wi += gridDim.x * 8) { const int b = wi >> 8, ch = wi & 255; const GAS bf16_t* fp = FT + ((size_t)b * 256 + ch) * 4096; float a = 0.f;
;         u32x4 qv[8];
; #pragma unroll
;         for (int j = 0; j < 8; ++j) qv[j] = *(const GAS u32x4*)(fp + (size_t)(j * 64 + lane) * 8);
;         __builtin_amdgcn_sched_barrier(0);
; #pragma unroll
;         for (int j = 0; j < 8; ++j) {
; #pragma unroll
;             for (int e = 0; e < 4; ++e) a += __uint_as_float(qv[j][e] << 16) - __uint_as_float(qv[j][e] & 0xffff0000u); }
;         a = wave_sum(a);
;         if (lane == 0) { GAS bf16_t* yr = Y + (size_t)(b * 4096 + 2048) * YW; yr[768 + ch] = (bf16_t)f2bf(a * (1.0f / 512.0f)); yr[1024 + ch] = (bf16_t)0; } }
.LBB0_543:
	v_ashrrev_i32_e32 v2, 8, v4
	s_waitcnt lgkmcnt(0)
	v_ashrrev_i32_e32 v3, 31, v2
	v_readlane_b32 s0, v251, 61
	v_lshlrev_b64 v[12:13], 21, v[2:3]
	v_readlane_b32 s1, v251, 62
	v_lshlrev_b32_sdwa v128, v175, v4 dst_sel:DWORD dst_unused:UNUSED_PAD src0_sel:DWORD src1_sel:BYTE_0
	v_mov_b32_e32 v1, v129
	v_lshl_add_u64 v[12:13], s[0:1], 0, v[12:13]
	v_lshl_add_u64 v[12:13], v[12:13], 0, v[128:129]
	v_lshl_add_u64 v[28:29], v[12:13], 0, v[0:1]
	s_movk_i32 s0, 0x1000
	v_add_co_u32_e64 v40, s[38:39], s0, v28
	global_load_dwordx4 v[12:15], v[28:29], off
	global_load_dwordx4 v[16:19], v[28:29], off offset:1024
	global_load_dwordx4 v[20:23], v[28:29], off offset:2048
	global_load_dwordx4 v[24:27], v[28:29], off offset:3072
	v_addc_co_u32_e64 v41, s[38:39], 0, v29, s[38:39]
	global_load_dwordx4 v[28:31], v[40:41], off
	global_load_dwordx4 v[32:35], v[40:41], off offset:1024
	global_load_dwordx4 v[36:39], v[40:41], off offset:2048
	global_load_dwordx4 v[40:43], v[40:41], off offset:3072
	s_waitcnt vmcnt(7)
	v_lshlrev_b32_e32 v1, 16, v12
	v_and_b32_e32 v3, 0xffff0000, v12
	v_sub_f32_e32 v1, v1, v3
	v_lshlrev_b32_e32 v3, 16, v13
	v_and_b32_e32 v11, 0xffff0000, v13
	v_add_f32_e32 v1, 0, v1
	v_sub_f32_e32 v3, v3, v11
	v_add_f32_e32 v1, v3, v1
	v_lshlrev_b32_e32 v3, 16, v14
	v_and_b32_e32 v11, 0xffff0000, v14
	v_sub_f32_e32 v3, v3, v11
	v_add_f32_e32 v1, v3, v1
	v_lshlrev_b32_e32 v3, 16, v15
	v_and_b32_e32 v11, 0xffff0000, v15
	v_sub_f32_e32 v3, v3, v11
	v_add_f32_e32 v1, v3, v1
	s_waitcnt vmcnt(6)
	v_lshlrev_b32_e32 v3, 16, v16
	v_and_b32_e32 v11, 0xffff0000, v16
	v_sub_f32_e32 v3, v3, v11
	v_add_f32_e32 v1, v3, v1
	v_lshlrev_b32_e32 v3, 16, v17
	v_and_b32_e32 v11, 0xffff0000, v17
	v_sub_f32_e32 v3, v3, v11
	v_add_f32_e32 v1, v3, v1
	v_lshlrev_b32_e32 v3, 16, v18
	v_and_b32_e32 v11, 0xffff0000, v18
	v_sub_f32_e32 v3, v3, v11
	v_add_f32_e32 v1, v3, v1
	v_lshlrev_b32_e32 v3, 16, v19
	v_and_b32_e32 v11, 0xffff0000, v19
	v_sub_f32_e32 v3, v3, v11
	v_add_f32_e32 v1, v3, v1
	s_waitcnt vmcnt(5)
	v_lshlrev_b32_e32 v3, 16, v20
	v_and_b32_e32 v11, 0xffff0000, v20
	v_sub_f32_e32 v3, v3, v11
	v_add_f32_e32 v1, v3, v1
	v_lshlrev_b32_e32 v3, 16, v21
	v_and_b32_e32 v11, 0xffff0000, v21
	v_sub_f32_e32 v3, v3, v11
	v_add_f32_e32 v1, v3, v1
	v_lshlrev_b32_e32 v3, 16, v22
	v_and_b32_e32 v11, 0xffff0000, v22
	v_sub_f32_e32 v3, v3, v11
	v_add_f32_e32 v1, v3, v1
	v_lshlrev_b32_e32 v3, 16, v23
	v_and_b32_e32 v11, 0xffff0000, v23
	v_sub_f32_e32 v3, v3, v11
	v_add_f32_e32 v1, v3, v1
	s_waitcnt vmcnt(4)
	v_lshlrev_b32_e32 v3, 16, v24
	v_and_b32_e32 v11, 0xffff0000, v24
	v_sub_f32_e32 v3, v3, v11
	v_add_f32_e32 v1, v3, v1
	v_lshlrev_b32_e32 v3, 16, v25
	v_and_b32_e32 v11, 0xffff0000, v25
	v_sub_f32_e32 v3, v3, v11
	v_add_f32_e32 v1, v3, v1
	v_lshlrev_b32_e32 v3, 16, v26
	v_and_b32_e32 v11, 0xffff0000, v26
	v_sub_f32_e32 v3, v3, v11
	v_add_f32_e32 v1, v3, v1
	v_lshlrev_b32_e32 v3, 16, v27
	v_and_b32_e32 v11, 0xffff0000, v27
	v_sub_f32_e32 v3, v3, v11
	v_add_f32_e32 v1, v3, v1
	s_waitcnt vmcnt(3)
	v_lshlrev_b32_e32 v3, 16, v28
	v_and_b32_e32 v11, 0xffff0000, v28
	v_sub_f32_e32 v3, v3, v11
	v_add_f32_e32 v1, v3, v1
	v_lshlrev_b32_e32 v3, 16, v29
	v_and_b32_e32 v11, 0xffff0000, v29
	v_sub_f32_e32 v3, v3, v11
	v_add_f32_e32 v1, v3, v1
	v_lshlrev_b32_e32 v3, 16, v30
	v_and_b32_e32 v11, 0xffff0000, v30
	v_sub_f32_e32 v3, v3, v11
	v_add_f32_e32 v1, v3, v1
	v_lshlrev_b32_e32 v3, 16, v31
	v_and_b32_e32 v11, 0xffff0000, v31
	v_sub_f32_e32 v3, v3, v11
	v_add_f32_e32 v1, v3, v1
	s_waitcnt vmcnt(2)
	v_lshlrev_b32_e32 v3, 16, v32
	v_and_b32_e32 v11, 0xffff0000, v32
	v_sub_f32_e32 v3, v3, v11
	v_add_f32_e32 v1, v3, v1
	v_lshlrev_b32_e32 v3, 16, v33
	v_and_b32_e32 v11, 0xffff0000, v33
	v_sub_f32_e32 v3, v3, v11
	v_add_f32_e32 v1, v3, v1
	v_lshlrev_b32_e32 v3, 16, v34
	v_and_b32_e32 v11, 0xffff0000, v34
	v_sub_f32_e32 v3, v3, v11
	v_add_f32_e32 v1, v3, v1
	v_lshlrev_b32_e32 v3, 16, v35
	v_and_b32_e32 v11, 0xffff0000, v35
	v_sub_f32_e32 v3, v3, v11
	v_add_f32_e32 v1, v3, v1
	s_waitcnt vmcnt(1)
	v_lshlrev_b32_e32 v3, 16, v36
	v_and_b32_e32 v11, 0xffff0000, v36
	v_sub_f32_e32 v3, v3, v11
	v_add_f32_e32 v1, v3, v1
	v_lshlrev_b32_e32 v3, 16, v37
	v_and_b32_e32 v11, 0xffff0000, v37
	v_sub_f32_e32 v3, v3, v11
	v_add_f32_e32 v1, v3, v1
	v_lshlrev_b32_e32 v3, 16, v38
	v_and_b32_e32 v11, 0xffff0000, v38
	v_sub_f32_e32 v3, v3, v11
	v_add_f32_e32 v1, v3, v1
	v_lshlrev_b32_e32 v3, 16, v39
	v_and_b32_e32 v11, 0xffff0000, v39
	v_sub_f32_e32 v3, v3, v11
	v_add_f32_e32 v1, v3, v1
	s_waitcnt vmcnt(0)
	v_lshlrev_b32_e32 v3, 16, v40
	v_and_b32_e32 v11, 0xffff0000, v40
	v_sub_f32_e32 v3, v3, v11
	v_add_f32_e32 v1, v3, v1
	v_lshlrev_b32_e32 v3, 16, v41
	v_and_b32_e32 v11, 0xffff0000, v41
	v_sub_f32_e32 v3, v3, v11
	v_add_f32_e32 v1, v3, v1
	v_lshlrev_b32_e32 v3, 16, v42
	v_and_b32_e32 v11, 0xffff0000, v42
	v_sub_f32_e32 v3, v3, v11
	v_add_f32_e32 v1, v3, v1
	v_lshlrev_b32_e32 v3, 16, v43
	v_and_b32_e32 v11, 0xffff0000, v43
	v_sub_f32_e32 v3, v3, v11
	v_add_f32_e32 v1, v3, v1
	ds_bpermute_b32 v3, v5, v1
	s_waitcnt lgkmcnt(0)
	v_add_f32_e32 v1, v1, v3
	ds_bpermute_b32 v3, v6, v1
	s_waitcnt lgkmcnt(0)
	v_add_f32_e32 v1, v1, v3
	ds_bpermute_b32 v3, v7, v1
	s_waitcnt lgkmcnt(0)
	v_add_f32_e32 v1, v1, v3
	ds_bpermute_b32 v3, v8, v1
	s_waitcnt lgkmcnt(0)
	v_add_f32_e32 v1, v1, v3
	ds_bpermute_b32 v3, v9, v1
	s_waitcnt lgkmcnt(0)
	v_add_f32_e32 v1, v1, v3
	ds_bpermute_b32 v3, v10, v1
	s_and_saveexec_b64 s[38:39], vcc
	s_cbranch_execz .LBB0_542
	v_readlane_b32 s0, v253, 20
	s_waitcnt lgkmcnt(0)
	v_add_f32_e32 v1, v1, v3
	v_readlane_b32 s1, v253, 21
	v_lshl_or_b32 v11, v2, 12, v176
	v_mul_f32_e32 v1, 0x3b000000, v1
	v_mov_b64_e32 v[2:3], s[0:1]
	v_mad_i64_i32 v[2:3], s[0:1], v11, s23, v[2:3]
	v_bfe_u32 v11, v1, 16, 1
	v_lshlrev_b32_sdwa v128, v170, v4 dst_sel:DWORD dst_unused:UNUSED_PAD src0_sel:DWORD src1_sel:BYTE_0
	v_add3_u32 v1, v1, v11, s19
	v_lshl_add_u64 v[2:3], v[2:3], 0, v[128:129]
	global_store_short_d16_hi v[2:3], v1, off offset:1536
	global_store_short v[2:3], v129, off offset:2048
	s_branch .LBB0_542

; #define LAS __attribute__((address_space(3)))
; #define GAS __attribute__((address_space(1)))
; __device__ __forceinline__ int lru_pass1(const Params& P, int l, LAS unsigned char* lds, unsigned* qw) {
;     ...
;         if (local >= 544) break;
;         const int wi = xq * 544 + local;
;         const int it = wi >> 3, h = wi & 7;
;         int b, j, q, Ls, r0seq;
;         if (it < 512) { b = it >> 6; j = it & 63; q = 4 + j; Ls = 4096; r0seq = b * 4096; } else { const int t2 = it - 512; b = t2 >> 2; j = t2 & 3; q = j; Ls = 256; r0seq = TL + b * 256; }
;         const int n0 = j * 64, r0 = r0seq + n0;
;         {
;             u32x4 tq[9];
; #pragma unroll
;             for (int jq = 0; jq < 9; ++jq) { const int qi = lane + 64 * jq, row = min(qi >> 3, 66), ch8 = qi & 7; const int n = n0 - 2 + row, nn = min(max(n, 0), Ls - 1);
;                 tq[jq] = *(const GAS u32x4*)(Z + (size_t)(r0seq + nn) * ZW + h * 64 + ch8 * 8); }
;             __builtin_amdgcn_sched_barrier(0);
; #pragma unroll
;             for (int jq = 0; jq < 9; ++jq) { const int qi = lane + 64 * jq, row = qi >> 3, ch8 = qi & 7; if (row < 67) *(LAS u32x4*)(xaS + row * 64 + ch8 * 8) = tq[jq]; }
.LBB0_549:
	v_readlane_b32 s0, v253, 33
	s_nop 1
	v_add_u32_e32 v0, s0, v32
	v_ashrrev_i32_e32 v1, 3, v0
	s_movk_i32 s0, 0x1ff
	v_cmp_lt_i32_e32 vcc, s0, v1
	s_and_saveexec_b64 s[0:1], vcc
	s_xor_b64 s[8:9], exec, s[0:1]
	v_add_u32_e32 v1, 0xfffffe00, v1
	v_lshrrev_b32_e32 v34, 2, v1
	v_bfe_u32 v35, v0, 3, 2
	v_lshl_add_u32 v36, v34, 8, v177
	s_or_saveexec_b64 s[8:9], s[8:9]
	v_mov_b32_e32 v5, 0x100
	v_mov_b32_e32 v1, v35
	s_xor_b64 exec, exec, s[8:9]
	v_ashrrev_i32_e32 v34, 9, v0
	v_bfe_u32 v1, v0, 3, 6
	v_add_u32_e32 v35, 4, v1
	v_lshlrev_b32_e32 v36, 12, v34
	v_mov_b32_e32 v5, 0x1000
	s_or_b64 exec, exec, s[8:9]
	v_lshlrev_b32_e32 v37, 6, v1
	v_add_u32_e32 v6, -2, v37
	v_lshlrev_b32_e32 v0, 6, v32
	v_add_u32_e32 v2, v6, v188
	v_add_u32_e32 v4, -1, v5
	v_and_b32_e32 v33, 0x1c0, v0
	v_max_i32_e32 v2, 0, v2
	v_add_u32_e32 v7, v6, v189
	v_lshlrev_b32_e32 v128, 1, v33
	v_min_u32_e32 v2, v2, v4
	v_min_u32_e32 v7, v7, v4
	v_lshl_add_u64 v[0:1], v[96:97], 0, v[128:129]
	v_add_u32_e32 v2, v2, v36
	v_add_u32_e32 v7, v7, v36
	v_mad_i64_i32 v[2:3], s[0:1], v2, s23, v[0:1]
	v_mad_i64_i32 v[12:13], s[0:1], v7, s23, v[0:1]
	global_load_dwordx4 v[8:11], v[2:3], off
	global_load_dwordx4 v[12:15], v[12:13], off
	v_add_u32_e32 v2, v6, v190
	v_add_u32_e32 v7, v6, v191
	v_min_u32_e32 v2, v2, v4
	v_min_u32_e32 v7, v7, v4
	v_add_u32_e32 v2, v2, v36
	v_add_u32_e32 v7, v7, v36
	v_mad_i64_i32 v[2:3], s[0:1], v2, s23, v[0:1]
	v_mad_i64_i32 v[20:21], s[0:1], v7, s23, v[0:1]
	global_load_dwordx4 v[16:19], v[2:3], off
	global_load_dwordx4 v[20:23], v[20:21], off
	v_add_u32_e32 v2, v6, v192
	v_add_u32_e32 v7, v6, v193
	v_min_u32_e32 v2, v2, v4
	v_min_u32_e32 v7, v7, v4
	v_add_u32_e32 v2, v2, v36
	v_add_u32_e32 v7, v7, v36
	v_mad_i64_i32 v[2:3], s[0:1], v2, s23, v[0:1]
	v_mad_i64_i32 v[28:29], s[0:1], v7, s23, v[0:1]
	global_load_dwordx4 v[24:27], v[2:3], off
	global_load_dwordx4 v[28:31], v[28:29], off
	v_add_u32_e32 v2, v6, v194
	v_add_u32_e32 v7, v6, v195
	v_min_u32_e32 v2, v2, v4
	v_min_u32_e32 v7, v7, v4
	v_add_u32_e32 v2, v2, v36
	v_add_u32_e32 v7, v7, v36
	v_mad_i64_i32 v[2:3], s[0:1], v2, s23, v[0:1]
	v_mad_i64_i32 v[42:43], s[0:1], v7, s23, v[0:1]
	global_load_dwordx4 v[38:41], v[2:3], off
	global_load_dwordx4 v[42:45], v[42:43], off
	v_add_u32_e32 v2, v6, v196
	v_min_u32_e32 v2, v2, v4
	v_add_u32_e32 v2, v2, v36
	v_mad_i64_i32 v[0:1], s[0:1], v2, s23, v[0:1]
	global_load_dwordx4 v[0:3], v[0:1], off
	s_waitcnt vmcnt(8)
	ds_write_b128 v197, v[8:11]
	s_waitcnt vmcnt(7)
	ds_write_b128 v198, v[12:15]
	s_waitcnt vmcnt(6)
	ds_write_b128 v199, v[16:19]
	s_waitcnt vmcnt(5)
	ds_write_b128 v200, v[20:23]
	s_waitcnt vmcnt(4)
	ds_write_b128 v201, v[24:27]
	s_waitcnt vmcnt(3)
	ds_write_b128 v202, v[28:31]
	s_waitcnt vmcnt(2)
	ds_write_b128 v203, v[38:41]
	s_waitcnt vmcnt(1)
	ds_write_b128 v204, v[42:45]
	s_and_saveexec_b64 s[8:9], s[42:43]
	s_cbranch_execz .LBB0_555
	s_waitcnt vmcnt(0)
	ds_write_b128 v205, v[0:3]

; #define GAS __attribute__((address_space(1)))
; __device__ __forceinline__ int lru_pass1(const Params& P, int l, LAS unsigned char* lds, unsigned* qw) {
;     ...
;         for (int jt = 0; jt < 4; ++jt) { const int cl = 16 * jt + fr, c = h * 64 + cl;
;             f32x4 acc[4][4];
; #pragma unroll
;             for (int mt = 0; mt < 4; ++mt)
; #pragma unroll
;                 for (int dt = 0; dt < 4; ++dt) acc[mt][dt] = (f32x4){0.f, 0.f, 0.f, 0.f};
;             bf16x8 Bfr[4][2];
; #pragma unroll
;             for (int dt = 0; dt < 4; ++dt)
; #pragma unroll
;                 for (int kk = 0; kk < 2; ++kk) Bfr[dt][kk] = *(const GAS bf16x8*)(WGT + ((size_t)((dt * 8 + h) * 64 + cl)) * 64 + kk * 32 + 8 * fq);
;             __builtin_amdgcn_sched_barrier(0);
; #pragma unroll
;             for (int dt = 0; dt < 4; ++dt)
; #pragma unroll
;                 for (int kk = 0; kk < 2; ++kk) {
; #pragma unroll
;                     for (int mt = 0; mt < 4; ++mt) acc[mt][dt] = __builtin_amdgcn_mfma_f32_16x16x32_bf16(Af[mt][kk], Bfr[dt][kk], acc[mt][dt], 0, 0, 0); }
;             u32x2 abw[16];
; #pragma unroll
;             for (int d = 0; d < 2; ++d) {
;                 const float bgr = P.lru_bg[((l * 2 + d) * 2 + 0) * 512 + c], bgi = P.lru_bg[((l * 2 + d) * 2 + 1) * 512 + c];
;                 const float sp8 = SP8[(l * 2 + d) * 512 + c];
; #pragma unroll
;                 for (int mt = 0; mt < 4; ++mt)
; #pragma unroll
;                     for (int ip = 0; ip < 2; ++ip) { const int p = 16 * fq + 4 * mt + 2 * ip;
;                         const f32x2 xcv = (f32x2){bf2f(xcS[p * 72 + cl]), bf2f(xcS[(p + 1) * 72 + cl])};
;                         const f32x2 tr = ((f32x2){acc[mt][2 * d][2 * ip], acc[mt][2 * d][2 * ip + 1]} + bgr) * (-1.4426950408889634f);
;                         const f32x2 ti = ((f32x2){acc[mt][2 * d + 1][2 * ip], acc[mt][2 * d + 1][2 * ip + 1]} + bgi) * (-1.4426950408889634f);
;                         const f32x2 dr = (f32x2){__builtin_amdgcn_exp2f(tr.x), __builtin_amdgcn_exp2f(tr.y)} + 1.0f, di = (f32x2){__builtin_amdgcn_exp2f(ti.x), __builtin_amdgcn_exp2f(ti.y)} + 1.0f;
;                         const f32x2 r = (f32x2){__builtin_amdgcn_rcpf(dr.x), __builtin_amdgcn_rcpf(dr.y)}, ig = (f32x2){__builtin_amdgcn_rcpf(di.x), __builtin_amdgcn_rcpf(di.y)};
;                         const f32x2 la = r * (-sp8), x2 = la + la;
.LBB0_557:
	v_lshl_add_u64 v[224:225], v[154:155], 0, s[50:51]
	v_lshl_add_u64 v[226:227], v[150:151], 0, s[50:51]
	v_lshl_add_u64 v[228:229], s[92:93], 0, v[152:153]
	v_lshl_add_u64 v[230:231], s[92:93], 0, v[146:147]
	global_load_dword v218, v[224:225], off offset:-2048
	global_load_dword v219, v[224:225], off
	global_load_dword v220, v[228:229], off
	global_load_dword v221, v[226:227], off offset:-2048
	global_load_dword v222, v[226:227], off
	global_load_dword v223, v[230:231], off
	v_lshl_add_u64 v[52:53], s[92:93], 0, v[148:149]
	v_add_co_u32_e32 v36, vcc, 0x4e00000, v52
	s_nop 1
	v_addc_co_u32_e32 v37, vcc, 0, v53, vcc
	v_add_co_u32_e32 v44, vcc, 0x4e10000, v52
	global_load_dwordx4 v[32:35], v[36:37], off
	global_load_dwordx4 v[36:39], v[36:37], off offset:64
	v_addc_co_u32_e32 v45, vcc, 0, v53, vcc
	v_add_co_u32_e32 v54, vcc, 0x4e20000, v52
	global_load_dwordx4 v[40:43], v[44:45], off
	global_load_dwordx4 v[44:47], v[44:45], off offset:64
	v_addc_co_u32_e32 v55, vcc, 0, v53, vcc
	v_add_co_u32_e32 v52, vcc, 0x4e30000, v52
	global_load_dwordx4 v[48:51], v[54:55], off
	global_load_dwordx4 v[56:59], v[54:55], off offset:64
	v_addc_co_u32_e32 v53, vcc, 0, v53, vcc
	global_load_dwordx4 v[158:161], v[52:53], off
	global_load_dwordx4 v[162:165], v[52:53], off offset:64
	s_waitcnt vmcnt(7) lgkmcnt(7)
	v_mfma_f32_16x16x32_bf16 v[52:55], v[0:3], v[32:35], 0
	s_waitcnt lgkmcnt(5)
	v_mfma_f32_16x16x32_bf16 v[60:63], v[8:11], v[32:35], 0
	s_waitcnt lgkmcnt(3)
	v_mfma_f32_16x16x32_bf16 v[64:67], v[16:19], v[32:35], 0
	s_waitcnt lgkmcnt(1)
	v_mfma_f32_16x16x32_bf16 v[32:35], v[24:27], v[32:35], 0
	s_waitcnt vmcnt(6)
	v_mfma_f32_16x16x32_bf16 v[92:95], v[4:7], v[36:39], v[52:55]
	v_mfma_f32_16x16x32_bf16 v[84:87], v[12:15], v[36:39], v[60:63]
	v_mfma_f32_16x16x32_bf16 v[76:79], v[20:23], v[36:39], v[64:67]
	s_waitcnt lgkmcnt(0)
	v_mfma_f32_16x16x32_bf16 v[68:71], v[28:31], v[36:39], v[32:35]
	s_waitcnt vmcnt(5)
	v_mfma_f32_16x16x32_bf16 v[32:35], v[0:3], v[40:43], 0
	v_mfma_f32_16x16x32_bf16 v[36:39], v[8:11], v[40:43], 0
	v_mfma_f32_16x16x32_bf16 v[52:55], v[16:19], v[40:43], 0
	v_mfma_f32_16x16x32_bf16 v[40:43], v[24:27], v[40:43], 0
	s_waitcnt vmcnt(4)
	v_mfma_f32_16x16x32_bf16 v[88:91], v[4:7], v[44:47], v[32:35]
	v_mfma_f32_16x16x32_bf16 v[64:67], v[28:31], v[44:47], v[40:43]
	s_waitcnt vmcnt(3)
	v_mfma_f32_16x16x32_bf16 v[32:35], v[0:3], v[48:51], 0
	v_mfma_f32_16x16x32_bf16 v[40:43], v[16:19], v[48:51], 0
	v_mfma_f32_16x16x32_bf16 v[80:83], v[12:15], v[44:47], v[36:39]
	v_mfma_f32_16x16x32_bf16 v[72:75], v[20:23], v[44:47], v[52:55]
	v_mfma_f32_16x16x32_bf16 v[36:39], v[8:11], v[48:51], 0
	v_mfma_f32_16x16x32_bf16 v[48:51], v[24:27], v[48:51], 0
	s_waitcnt vmcnt(2)
	v_mfma_f32_16x16x32_bf16 v[60:63], v[4:7], v[56:59], v[32:35]
	v_mfma_f32_16x16x32_bf16 v[44:47], v[20:23], v[56:59], v[40:43]
	s_waitcnt vmcnt(1)
	v_mfma_f32_16x16x32_bf16 v[32:35], v[0:3], v[158:161], 0
	v_mfma_f32_16x16x32_bf16 v[40:43], v[8:11], v[158:161], 0
	v_mfma_f32_16x16x32_bf16 v[214:217], v[16:19], v[158:161], 0
	v_mfma_f32_16x16x32_bf16 v[158:161], v[24:27], v[158:161], 0
	v_mfma_f32_16x16x32_bf16 v[52:55], v[12:15], v[56:59], v[36:39]
	v_mfma_f32_16x16x32_bf16 v[36:39], v[28:31], v[56:59], v[48:51]
	s_waitcnt vmcnt(0)
	v_mfma_f32_16x16x32_bf16 v[56:59], v[4:7], v[162:165], v[32:35]
	v_mfma_f32_16x16x32_bf16 v[32:35], v[28:31], v[162:165], v[158:161]
	s_nop 2
	v_lshl_add_u64 v[158:159], v[154:155], 0, s[50:51]
	v_mov_b32_e32 v160, v218
	s_nop 0
	v_mov_b32_e32 v158, v219
	v_mfma_f32_16x16x32_bf16 v[48:51], v[12:15], v[162:165], v[40:43]
	s_waitcnt vmcnt(1)
	v_pk_add_f32 v[92:93], v[92:93], v[160:161] op_sel_hi:[1,0]
	v_mfma_f32_16x16x32_bf16 v[40:43], v[20:23], v[162:165], v[214:217]
	v_lshl_add_u64 v[162:163], s[92:93], 0, v[152:153]
	v_mov_b32_e32 v128, v220
	v_pk_mul_f32 v[92:93], v[92:93], s[18:19] op_sel_hi:[1,0]
	ds_read_u16 v159, v213
	ds_read_u16 v166, v213 offset:144
	v_exp_f32_e32 v92, v92
	v_exp_f32_e32 v93, v93
	s_nop 0
	v_pk_add_f32 v[92:93], v[92:93], 1.0 op_sel_hi:[1,0]
	s_nop 0
	v_rcp_f32_e32 v92, v92
	v_rcp_f32_e32 v93, v93
	s_waitcnt vmcnt(0)
	v_pk_mul_f32 v[92:93], v[128:129], v[92:93] op_sel_hi:[0,1] neg_lo:[1,0] neg_hi:[1,0]
	v_pk_add_f32 v[162:163], v[92:93], v[92:93]
	s_nop 0
	v_pk_fma_f32 v[164:165], v[162:163], s[20:21], v[136:137] op_sel_hi:[1,0,0]
	v_cmp_gt_f32_e64 s[46:47], s33, v162
	v_pk_fma_f32 v[164:165], v[162:163], v[164:165], s[22:23] op_sel_hi:[1,1,0]
	v_cmp_gt_f32_e64 s[44:45], s33, v163
	v_pk_fma_f32 v[164:165], v[162:163], v[164:165], 0.5 op_sel_hi:[1,1,0]
	s_or_b64 vcc, s[46:47], s[44:45]
	v_pk_fma_f32 v[164:165], v[162:163], v[164:165], 1.0 op_sel_hi:[1,1,0]
	s_nop 0
	v_pk_mul_f32 v[164:165], v[162:163], v[164:165] neg_lo:[0,1] neg_hi:[0,1]
	s_cbranch_vccnz .LBB0_577

; #define GAS __attribute__((address_space(1)))
; __device__ __forceinline__ int queue_pull(unsigned* q, int lane) { unsigned nx = 0; if (lane == 0) nx = __hip_atomic_fetch_add(q, 1u, __ATOMIC_RELAXED, __HIP_MEMORY_SCOPE_AGENT); return 256 + (int)__builtin_amdgcn_readfirstlane(nx); }
; __device__ __forceinline__ void gmlp_items(const Params& P, int l, int local, unsigned* q) {
;     ...
;     for (; local < 680; local = queue_pull(q, lane)) { const int it = xq * 136 + (local - 544); const int ch = it >> 2, g = it & 3; const GAS bf16_t* VTb; int ldv;
;         if (ch < 256) { const int b = ch >> 5, n0 = (ch & 31) * 128; VTb = (const GAS bf16_t*)(P.ws + OFF_VT) + ((size_t)b * 256 + g * 64) * 4096 + n0; ldv = 4096; }
;         else { const int cc = ch - 256, b = cc >> 1, n0 = (cc & 1) * 128; VTb = (const GAS bf16_t*)(P.ws + OFF_VTC) + ((size_t)b * 256 + g * 64) * 256 + n0; ldv = 256; }
;         bf16x8 Afv[4][4];
; #pragma unroll
;         for (int kk = 0; kk < 4; ++kk)
; #pragma unroll
;             for (int mt = 0; mt < 4; ++mt) Afv[kk][mt] = *(const GAS bf16x8*)(VTb + (size_t)(mt * 16 + fr) * ldv + kk * 32 + 8 * fq);
; #pragma unroll 1
;         for (int half = 0; half < 2; ++half) {
;             bf16x8 Bfv[4][4]; u32x2 uua[4][4]; float bsv[4];
; #pragma unroll
;             for (int q = 0; q < 4; ++q) { const int p = 16 * (4 * half + q) + fr; const size_t row = (size_t)ch * 128 + p; bsv[q] = P.gmlp_bs[(l * 4 + g) * 128 + p];
; #pragma unroll
;                 for (int kk = 0; kk < 4; ++kk) Bfv[q][kk] = *(const GAS bf16x8*)(GWS + ((size_t)(g * 128 + p)) * 128 + kk * 32 + 8 * fq);
; #pragma unroll
;                 for (int mt = 0; mt < 4; ++mt) uua[q][mt] = *(const GAS u32x2*)(Z + row * ZW + 1024 + g * 64 + mt * 16 + 4 * fq); }
.LBB0_633:
	v_add_u32_e32 v5, s4, v32
	v_ashrrev_i32_e32 v64, 2, v5
	v_and_b32_e32 v66, 3, v32
	s_movk_i32 s0, 0xff
	v_cmp_lt_i32_e32 vcc, s0, v64
	v_lshlrev_b32_e32 v4, 8, v64
	v_lshlrev_b32_e32 v144, 14, v66
	s_and_saveexec_b64 s[0:1], vcc
	s_xor_b64 s[40:41], exec, s[0:1]
	v_add_u32_e32 v0, 0xffffff00, v64
	v_lshrrev_b32_e32 v128, 1, v0
	v_lshlrev_b64 v[0:1], 17, v[128:129]
	v_lshl_add_u64 v[0:1], s[10:11], 0, v[0:1]
	v_lshlrev_b32_e32 v128, 15, v66
	v_lshl_add_u64 v[0:1], v[0:1], 0, v[128:129]
	v_and_b32_e32 v128, 0x100, v4
	v_lshlrev_b32_e32 v144, 14, v66
	v_lshl_add_u64 v[0:1], v[0:1], 0, v[128:129]
	s_or_saveexec_b64 s[40:41], s[40:41]
	s_waitcnt lgkmcnt(0)
	v_mov_b64_e32 v[2:3], 0x100
	s_xor_b64 exec, exec, s[40:41]
	v_ashrrev_i32_e32 v0, 7, v5
	v_ashrrev_i32_e32 v1, 31, v0
	v_lshlrev_b64 v[0:1], 21, v[0:1]
	v_lshl_add_u64 v[0:1], s[12:13], 0, v[0:1]
	v_lshlrev_b32_e32 v128, 19, v66
	v_lshl_add_u64 v[0:1], v[0:1], 0, v[128:129]
	v_and_b32_e32 v128, 0x1f00, v4
	v_lshl_add_u64 v[0:1], v[0:1], 0, v[128:129]
	v_mov_b64_e32 v[2:3], 0x1000
	s_or_b64 exec, exec, s[40:41]
	v_mov_b32_e32 v103, v129
	v_mul_u32_u24_e32 v3, v2, v140
	v_lshl_add_u64 v[0:1], v[0:1], 0, v[102:103]
	v_lshlrev_b32_e32 v128, 1, v3
	v_mul_u32_u24_e32 v3, v2, v141
	v_lshl_add_u64 v[36:37], v[0:1], 0, v[128:129]
	v_lshlrev_b32_e32 v128, 1, v3
	v_mul_u32_u24_e32 v3, v2, v142
	v_lshl_add_u64 v[44:45], v[0:1], 0, v[128:129]
	v_lshlrev_b32_e32 v128, 1, v3
	v_mul_u32_u24_e32 v2, v2, v143
	v_lshl_add_u64 v[52:53], v[0:1], 0, v[128:129]
	v_lshlrev_b32_e32 v128, 1, v2
	v_lshl_add_u64 v[60:61], v[0:1], 0, v[128:129]
	global_load_dwordx4 v[0:3], v[36:37], off
	global_load_dwordx4 v[4:7], v[36:37], off offset:64
	global_load_dwordx4 v[8:11], v[44:45], off
	global_load_dwordx4 v[12:15], v[44:45], off offset:64
	global_load_dwordx4 v[16:19], v[52:53], off
	global_load_dwordx4 v[20:23], v[52:53], off offset:64
	global_load_dwordx4 v[24:27], v[60:61], off
	global_load_dwordx4 v[28:31], v[60:61], off offset:64
	global_load_dwordx4 v[32:35], v[36:37], off offset:128
	global_load_dwordx4 v[36:39], v[36:37], off offset:192
	global_load_dwordx4 v[40:43], v[44:45], off offset:128
	global_load_dwordx4 v[44:47], v[44:45], off offset:192
	global_load_dwordx4 v[48:51], v[52:53], off offset:128
	global_load_dwordx4 v[52:55], v[52:53], off offset:192
	global_load_dwordx4 v[56:59], v[60:61], off offset:128
	global_load_dwordx4 v[60:63], v[60:61], off offset:192
	v_ashrrev_i32_e32 v65, 31, v64
	v_lshlrev_b32_e32 v128, 7, v66
	v_readlane_b32 s0, v254, 52
	v_lshlrev_b64 v[104:105], 7, v[64:65]
	v_lshl_add_u64 v[106:107], v[98:99], 0, v[128:129]
	v_or_b32_e32 v103, s0, v128
	v_lshl_add_u64 v[108:109], v[100:101], 0, v[128:129]
	s_mov_b32 s0, 0
	s_mov_b64 s[40:41], -1
.LBB0_638:
	v_or_b32_e32 v68, s0, v140
	v_or_b32_e32 v128, v68, v103
	v_lshl_add_u64 v[64:65], v[128:129], 2, s[82:83]
	v_lshl_or_b32 v128, v68, 7, v144
	global_load_dword v145, v[64:65], off
	v_lshl_add_u64 v[64:65], v[128:129], 1, v[96:97]
	v_or_b32_e32 v200, v104, v68
	global_load_dwordx4 v[146:149], v[64:65], off
	global_load_dwordx4 v[150:153], v[64:65], off offset:64
	global_load_dwordx4 v[154:157], v[64:65], off offset:128
	global_load_dwordx4 v[158:161], v[64:65], off offset:192
	v_mad_u64_u32 v[64:65], s[0:1], v200, s23, v[106:107]
	v_mad_i32_i24 v65, v105, s23, v65
	v_or_b32_e32 v69, 16, v68
	v_add_u32_e32 v128, v68, v103
	global_load_dwordx2 v[166:167], v[64:65], off offset:2048
	global_load_dwordx2 v[180:181], v[64:65], off offset:2080
	global_load_dwordx2 v[182:183], v[64:65], off offset:2112
	global_load_dwordx2 v[204:205], v[64:65], off offset:2144
	v_lshl_add_u64 v[64:65], v[128:129], 2, s[82:83]
	v_lshl_or_b32 v128, v69, 7, v144
	v_lshl_add_u64 v[66:67], v[128:129], 1, v[96:97]
	v_or_b32_e32 v212, v104, v69
	global_load_dwordx4 v[162:165], v[66:67], off
	global_load_dwordx4 v[184:187], v[66:67], off offset:64
	global_load_dwordx4 v[188:191], v[66:67], off offset:128
	global_load_dwordx4 v[192:195], v[66:67], off offset:192
	v_mad_u64_u32 v[66:67], s[0:1], v212, s23, v[106:107]
	v_or_b32_e32 v69, 32, v68
	v_mad_i32_i24 v67, v105, s23, v67
	v_lshl_or_b32 v128, v69, 7, v144
	global_load_dwordx2 v[206:207], v[66:67], off offset:2048
	global_load_dwordx2 v[208:209], v[66:67], off offset:2080
	global_load_dwordx2 v[138:139], v[66:67], off offset:2112
	global_load_dwordx2 v[126:127], v[66:67], off offset:2144
	v_lshl_add_u64 v[66:67], v[128:129], 1, v[96:97]
	v_or_b32_e32 v213, v104, v69
	global_load_dwordx4 v[92:95], v[66:67], off
	global_load_dwordx4 v[88:91], v[66:67], off offset:64
	global_load_dwordx4 v[84:87], v[66:67], off offset:128
	global_load_dwordx4 v[80:83], v[66:67], off offset:192
	v_mad_u64_u32 v[66:67], s[0:1], v213, s23, v[106:107]
	v_or_b32_e32 v110, 48, v68
	v_mad_i32_i24 v67, v105, s23, v67
	v_lshl_or_b32 v128, v110, 7, v144
	global_load_dwordx2 v[124:125], v[66:67], off offset:2048
	global_load_dwordx2 v[122:123], v[66:67], off offset:2080
	global_load_dwordx2 v[120:121], v[66:67], off offset:2112
	global_load_dwordx2 v[118:119], v[66:67], off offset:2144
	global_load_dword v214, v[64:65], off offset:64
	global_load_dword v215, v[64:65], off offset:128
	global_load_dword v216, v[64:65], off offset:192
	v_lshl_add_u64 v[64:65], v[128:129], 1, v[96:97]
	v_or_b32_e32 v128, v104, v110
	v_mad_u64_u32 v[110:111], s[0:1], v128, s23, v[106:107]
	v_mad_i32_i24 v111, v105, s23, v111
	global_load_dwordx4 v[76:79], v[64:65], off
	global_load_dwordx4 v[72:75], v[64:65], off offset:64
	global_load_dwordx4 v[68:71], v[64:65], off offset:128
	global_load_dwordx4 v[64:67], v[64:65], off offset:192
	global_load_dwordx2 v[116:117], v[110:111], off offset:2048
	global_load_dwordx2 v[114:115], v[110:111], off offset:2080
	global_load_dwordx2 v[112:113], v[110:111], off offset:2112
	global_load_dwordx2 v[110:111], v[110:111], off offset:2144
	s_waitcnt vmcnt(34)
; #define GAS __attribute__((address_space(1)))
; __device__ __forceinline__ unsigned cvt_pk_bf16(float lo, float hi) { unsigned r; asm volatile("v_cvt_pk_bf16_f32 %0, %1, %2" : "=v"(r) : "v"(lo), "v"(hi)); return r; }
; __device__ __forceinline__ void gmlp_items(const Params& P, int l, int local, unsigned* q) {
;     ...
;             for (int q = 0; q < 4; ++q) { const int p = 16 * (4 * half + q) + fr; const size_t row = (size_t)ch * 128 + p;
;                 f32x4 acc[4];
; #pragma unroll
;                 for (int mt = 0; mt < 4; ++mt) acc[mt] = (f32x4){0.f, 0.f, 0.f, 0.f};
; #pragma unroll
;                 for (int kk = 0; kk < 4; ++kk)
; #pragma unroll
;                     for (int mt = 0; mt < 4; ++mt) acc[mt] = __builtin_amdgcn_mfma_f32_16x16x32_bf16(Afv[kk][mt], Bfv[q][kk], acc[mt], 0, 0, 0);
; #pragma unroll
;                 for (int mt = 0; mt < 4; ++mt) { const int d0 = mt * 16 + 4 * fq; const u32x2 uu = uua[q][mt];
;                     const float u0 = __uint_as_float(uu.x << 16), u1 = __uint_as_float(uu.x & 0xffff0000u), u2 = __uint_as_float(uu.y << 16), u3 = __uint_as_float(uu.y & 0xffff0000u);
;                     u32x2 o; o.x = cvt_pk_bf16(u0 * (acc[mt][0] + bsv[q]), u1 * (acc[mt][1] + bsv[q])); o.y = cvt_pk_bf16(u2 * (acc[mt][2] + bsv[q]), u3 * (acc[mt][3] + bsv[q]));
;                     *(GAS u32x2*)(Y + row * YW + 512 + g * 64 + d0) = o; } }
	v_mfma_f32_16x16x32_bf16 v[196:199], v[0:3], v[146:149], 0
	s_waitcnt vmcnt(30)
	v_lshlrev_b32_e32 v201, 16, v166
	v_and_b32_e32 v166, 0xffff0000, v166
	v_lshlrev_b32_e32 v202, 16, v167
	v_mfma_f32_16x16x32_bf16 v[196:199], v[4:7], v[150:153], v[196:199]
	v_and_b32_e32 v167, 0xffff0000, v167
	v_mad_u64_u32 v[210:211], s[0:1], v200, s23, v[108:109]
	v_mfma_f32_16x16x32_bf16 v[196:199], v[32:35], v[154:157], v[196:199]
	v_mad_i32_i24 v211, v105, s23, v211
	s_andn2_b64 vcc, exec, s[40:41]
	s_mov_b64 s[40:41], 0
	v_mfma_f32_16x16x32_bf16 v[196:199], v[36:39], v[158:161], v[196:199]
	s_nop 7
	v_add_f32_e32 v196, v145, v196
	v_add_f32_e32 v197, v145, v197
	v_add_f32_e32 v198, v145, v198
	v_add_f32_e32 v199, v145, v199
	v_mul_f32_e32 v196, v196, v201
	v_mul_f32_e32 v166, v197, v166
	v_mul_f32_e32 v201, v198, v202
	v_mul_f32_e32 v167, v199, v167
	v_cvt_pk_bf16_f32 v166, v196, v166
	v_mfma_f32_16x16x32_bf16 v[196:199], v[8:11], v[146:149], 0
	v_cvt_pk_bf16_f32 v167, v201, v167
	global_store_dwordx2 v[210:211], v[166:167], off offset:1024
	s_waitcnt vmcnt(30)
	v_lshlrev_b32_e32 v166, 16, v180
	v_mfma_f32_16x16x32_bf16 v[196:199], v[12:15], v[150:153], v[196:199]
	v_and_b32_e32 v167, 0xffff0000, v180
	v_lshlrev_b32_e32 v180, 16, v181
	v_and_b32_e32 v181, 0xffff0000, v181
	v_mfma_f32_16x16x32_bf16 v[196:199], v[40:43], v[154:157], v[196:199]
	v_mfma_f32_16x16x32_bf16 v[196:199], v[44:47], v[158:161], v[196:199]
	v_mfma_f32_16x16x32_bf16 v[200:203], v[16:19], v[146:149], 0
	v_mfma_f32_16x16x32_bf16 v[200:203], v[20:23], v[150:153], v[200:203]
	s_nop 5
	v_add_f32_e32 v196, v145, v196
	v_mul_f32_e32 v166, v196, v166
	v_add_f32_e32 v196, v145, v197
	v_mul_f32_e32 v167, v196, v167
	v_cvt_pk_bf16_f32 v166, v166, v167
	v_add_f32_e32 v167, v145, v198
	v_mfma_f32_16x16x32_bf16 v[146:149], v[24:27], v[146:149], 0
	v_mul_f32_e32 v167, v167, v180
	v_add_f32_e32 v180, v145, v199
	v_mul_f32_e32 v180, v180, v181
	v_mfma_f32_16x16x32_bf16 v[196:199], v[48:51], v[154:157], v[200:203]
	v_cvt_pk_bf16_f32 v167, v167, v180
	global_store_dwordx2 v[210:211], v[166:167], off offset:1056
	s_waitcnt vmcnt(30)
	v_lshlrev_b32_e32 v166, 16, v182
	v_mfma_f32_16x16x32_bf16 v[146:149], v[28:31], v[150:153], v[146:149]
	v_and_b32_e32 v167, 0xffff0000, v182
	v_lshlrev_b32_e32 v180, 16, v183
	v_and_b32_e32 v181, 0xffff0000, v183
	v_mfma_f32_16x16x32_bf16 v[196:199], v[52:55], v[158:161], v[196:199]
	v_mfma_f32_16x16x32_bf16 v[146:149], v[56:59], v[154:157], v[146:149]
	v_mfma_f32_16x16x32_bf16 v[146:149], v[60:63], v[158:161], v[146:149]
	s_nop 5
	v_add_f32_e32 v182, v145, v196
	v_add_f32_e32 v151, v145, v198
	v_mul_f32_e32 v166, v182, v166
	v_add_f32_e32 v182, v145, v197
	v_mul_f32_e32 v151, v151, v180
	v_add_f32_e32 v152, v145, v199
	v_mul_f32_e32 v167, v182, v167
	v_cvt_pk_bf16_f32 v150, v166, v167
	v_mul_f32_e32 v152, v152, v181
	v_cvt_pk_bf16_f32 v151, v151, v152
	global_store_dwordx2 v[210:211], v[150:151], off offset:1088
	s_waitcnt vmcnt(29)
	v_mfma_f32_16x16x32_bf16 v[150:153], v[0:3], v[162:165], 0
	v_lshlrev_b32_e32 v158, 16, v204
	v_add_f32_e32 v146, v145, v146
	v_and_b32_e32 v159, 0xffff0000, v204
	s_waitcnt vmcnt(28)
	v_mfma_f32_16x16x32_bf16 v[150:153], v[4:7], v[184:187], v[150:153]
	v_mul_f32_e32 v146, v146, v158
	v_add_f32_e32 v147, v145, v147
	v_lshlrev_b32_e32 v167, 16, v205
	v_mul_f32_e32 v147, v147, v159
	v_cvt_pk_bf16_f32 v166, v146, v147
	v_add_f32_e32 v146, v145, v148
	v_and_b32_e32 v180, 0xffff0000, v205
	v_mul_f32_e32 v146, v146, v167
	v_add_f32_e32 v145, v145, v149
	v_mul_f32_e32 v145, v145, v180
	v_cvt_pk_bf16_f32 v167, v146, v145
	s_waitcnt vmcnt(27)
	v_mfma_f32_16x16x32_bf16 v[146:149], v[32:35], v[188:191], v[150:153]
	s_waitcnt vmcnt(25)
	v_lshlrev_b32_e32 v145, 16, v206
	global_store_dwordx2 v[210:211], v[166:167], off offset:1120
	v_and_b32_e32 v166, 0xffff0000, v206
	v_mfma_f32_16x16x32_bf16 v[146:149], v[36:39], v[192:195], v[146:149]
	v_and_b32_e32 v180, 0xffff0000, v207
	v_lshlrev_b32_e32 v167, 16, v207
	v_mfma_f32_16x16x32_bf16 v[154:157], v[8:11], v[162:165], 0
	v_mfma_f32_16x16x32_bf16 v[150:153], v[24:27], v[162:165], 0
	s_waitcnt vmcnt(14)
	s_nop 2
	v_add_f32_e32 v146, v214, v146
	v_mul_f32_e32 v145, v146, v145
	v_add_f32_e32 v146, v214, v147
	v_mfma_f32_16x16x32_bf16 v[154:157], v[12:15], v[184:187], v[154:157]
	v_mul_f32_e32 v146, v146, v166
	v_mfma_f32_16x16x32_bf16 v[158:161], v[16:19], v[162:165], 0
	v_cvt_pk_bf16_f32 v162, v145, v146
	v_add_f32_e32 v146, v214, v149
	v_add_f32_e32 v145, v214, v148
	v_mul_f32_e32 v146, v146, v180
	v_mul_f32_e32 v145, v145, v167
	v_cvt_pk_bf16_f32 v163, v145, v146
	v_mfma_f32_16x16x32_bf16 v[146:149], v[28:31], v[184:187], v[150:153]
	v_mad_u64_u32 v[166:167], s[0:1], v212, s23, v[108:109]
	v_mad_i32_i24 v167, v105, s23, v167
	v_mfma_f32_16x16x32_bf16 v[150:153], v[40:43], v[188:191], v[154:157]
	v_lshlrev_b32_e32 v145, 16, v208
	global_store_dwordx2 v[166:167], v[162:163], off offset:1024
	v_and_b32_e32 v162, 0xffff0000, v208
	v_mfma_f32_16x16x32_bf16 v[158:161], v[20:23], v[184:187], v[158:161]
	v_and_b32_e32 v164, 0xffff0000, v209
	v_lshlrev_b32_e32 v163, 16, v209
	v_lshlrev_b32_e32 v180, 16, v139
	v_mfma_f32_16x16x32_bf16 v[150:153], v[44:47], v[192:195], v[150:153]
	v_and_b32_e32 v139, 0xffff0000, v139
	v_mfma_f32_16x16x32_bf16 v[154:157], v[48:51], v[188:191], v[158:161]
	v_mfma_f32_16x16x32_bf16 v[154:157], v[52:55], v[192:195], v[154:157]
	s_nop 4
	v_add_f32_e32 v150, v214, v150
	v_mul_f32_e32 v145, v150, v145
	v_add_f32_e32 v150, v214, v151
	v_mul_f32_e32 v150, v150, v162
	v_mfma_f32_16x16x32_bf16 v[146:149], v[56:59], v[188:191], v[146:149]
	v_add_f32_e32 v151, v214, v153
; #define GAS __attribute__((address_space(1)))
; __device__ __forceinline__ unsigned cvt_pk_bf16(float lo, float hi) { unsigned r; asm volatile("v_cvt_pk_bf16_f32 %0, %1, %2" : "=v"(r) : "v"(lo), "v"(hi)); return r; }
; __device__ __forceinline__ void gmlp_items(const Params& P, int l, int local, unsigned* q) {
;     ...
;             for (int q = 0; q < 4; ++q) { const int p = 16 * (4 * half + q) + fr; const size_t row = (size_t)ch * 128 + p;
;                 f32x4 acc[4];
; #pragma unroll
;                 for (int mt = 0; mt < 4; ++mt) acc[mt] = (f32x4){0.f, 0.f, 0.f, 0.f};
; #pragma unroll
;                 for (int kk = 0; kk < 4; ++kk)
; #pragma unroll
;                     for (int mt = 0; mt < 4; ++mt) acc[mt] = __builtin_amdgcn_mfma_f32_16x16x32_bf16(Afv[kk][mt], Bfv[q][kk], acc[mt], 0, 0, 0);
; #pragma unroll
;                 for (int mt = 0; mt < 4; ++mt) { const int d0 = mt * 16 + 4 * fq; const u32x2 uu = uua[q][mt];
;                     const float u0 = __uint_as_float(uu.x << 16), u1 = __uint_as_float(uu.x & 0xffff0000u), u2 = __uint_as_float(uu.y << 16), u3 = __uint_as_float(uu.y & 0xffff0000u);
;                     u32x2 o; o.x = cvt_pk_bf16(u0 * (acc[mt][0] + bsv[q]), u1 * (acc[mt][1] + bsv[q])); o.y = cvt_pk_bf16(u2 * (acc[mt][2] + bsv[q]), u3 * (acc[mt][3] + bsv[q]));
;                     *(GAS u32x2*)(Y + row * YW + 512 + g * 64 + d0) = o; } }
	v_cvt_pk_bf16_f32 v150, v145, v150
	v_add_f32_e32 v145, v214, v152
	v_mul_f32_e32 v151, v151, v164
	v_mul_f32_e32 v145, v145, v163
	v_cvt_pk_bf16_f32 v151, v145, v151
	global_store_dwordx2 v[166:167], v[150:151], off offset:1056
	v_lshlrev_b32_e32 v145, 16, v138
	v_mfma_f32_16x16x32_bf16 v[150:153], v[0:3], v[92:95], 0
	v_add_f32_e32 v154, v214, v154
	v_and_b32_e32 v138, 0xffff0000, v138
	v_mul_f32_e32 v145, v154, v145
	v_mfma_f32_16x16x32_bf16 v[146:149], v[60:63], v[192:195], v[146:149]
	v_add_f32_e32 v154, v214, v155
	v_mul_f32_e32 v138, v154, v138
	v_cvt_pk_bf16_f32 v138, v145, v138
	v_mfma_f32_16x16x32_bf16 v[158:161], v[8:11], v[92:95], 0
	v_add_f32_e32 v145, v214, v156
	v_add_f32_e32 v154, v214, v157
	v_mul_f32_e32 v145, v145, v180
	v_mfma_f32_16x16x32_bf16 v[162:165], v[16:19], v[92:95], 0
	v_mul_f32_e32 v139, v154, v139
	v_cvt_pk_bf16_f32 v139, v145, v139
	global_store_dwordx2 v[166:167], v[138:139], off offset:1088
	v_mfma_f32_16x16x32_bf16 v[92:95], v[24:27], v[92:95], 0
	v_lshlrev_b32_e32 v138, 16, v126
	v_add_f32_e32 v145, v214, v146
	v_and_b32_e32 v126, 0xffff0000, v126
	v_mfma_f32_16x16x32_bf16 v[150:153], v[4:7], v[88:91], v[150:153]
	v_mul_f32_e32 v138, v145, v138
	v_add_f32_e32 v145, v214, v147
	v_lshlrev_b32_e32 v139, 16, v127
	v_mfma_f32_16x16x32_bf16 v[154:157], v[12:15], v[88:91], v[158:161]
	v_mul_f32_e32 v126, v145, v126
	v_cvt_pk_bf16_f32 v126, v138, v126
	v_and_b32_e32 v127, 0xffff0000, v127
	v_mfma_f32_16x16x32_bf16 v[158:161], v[20:23], v[88:91], v[162:165]
	v_lshlrev_b32_e32 v145, 16, v125
	v_mfma_f32_16x16x32_bf16 v[88:91], v[28:31], v[88:91], v[92:95]
	s_nop 2
	v_add_f32_e32 v92, v214, v148
	v_mul_f32_e32 v138, v92, v139
	v_mfma_f32_16x16x32_bf16 v[92:95], v[32:35], v[84:87], v[150:153]
	v_add_f32_e32 v139, v214, v149
	v_mul_f32_e32 v127, v139, v127
	v_cvt_pk_bf16_f32 v127, v138, v127
	v_mfma_f32_16x16x32_bf16 v[92:95], v[36:39], v[80:83], v[92:95]
	global_store_dwordx2 v[166:167], v[126:127], off offset:1120
	v_lshlrev_b32_e32 v138, 16, v124
	v_and_b32_e32 v139, 0xffff0000, v124
	v_mfma_f32_16x16x32_bf16 v[146:149], v[40:43], v[84:87], v[154:157]
	v_and_b32_e32 v150, 0xffff0000, v125
	s_waitcnt vmcnt(17)
	s_nop 1
	v_add_f32_e32 v92, v215, v92
	v_add_f32_e32 v93, v215, v93
	v_mfma_f32_16x16x32_bf16 v[124:127], v[48:51], v[84:87], v[158:161]
	v_mul_f32_e32 v92, v92, v138
	v_mul_f32_e32 v93, v93, v139
	v_cvt_pk_bf16_f32 v138, v92, v93
	v_mfma_f32_16x16x32_bf16 v[84:87], v[56:59], v[84:87], v[88:91]
	v_add_f32_e32 v93, v215, v95
	v_mul_f32_e32 v93, v93, v150
	v_and_b32_e32 v150, 0xffff0000, v123
	v_add_f32_e32 v88, v215, v94
	v_mul_f32_e32 v92, v88, v145
	v_mfma_f32_16x16x32_bf16 v[88:91], v[44:47], v[80:83], v[146:149]
	v_cvt_pk_bf16_f32 v139, v92, v93
	v_lshlrev_b32_e32 v145, 16, v123
	v_mfma_f32_16x16x32_bf16 v[92:95], v[52:55], v[80:83], v[124:127]
	s_nop 2
	v_mad_u64_u32 v[126:127], s[0:1], v213, s23, v[108:109]
	v_mfma_f32_16x16x32_bf16 v[80:83], v[60:63], v[80:83], v[84:87]
	v_mad_i32_i24 v127, v105, s23, v127
	global_store_dwordx2 v[126:127], v[138:139], off offset:1024
	v_lshlrev_b32_e32 v138, 16, v122
	s_waitcnt vmcnt(16)
	v_mfma_f32_16x16x32_bf16 v[84:87], v[0:3], v[76:79], 0
	v_and_b32_e32 v139, 0xffff0000, v122
	v_add_f32_e32 v88, v215, v88
	v_add_f32_e32 v89, v215, v89
	v_mfma_f32_16x16x32_bf16 v[122:125], v[8:11], v[76:79], 0
	v_mul_f32_e32 v88, v88, v138
	v_mul_f32_e32 v89, v89, v139
	v_cvt_pk_bf16_f32 v88, v88, v89
	v_mfma_f32_16x16x32_bf16 v[146:149], v[16:19], v[76:79], 0
	v_add_f32_e32 v89, v215, v90
	v_mul_f32_e32 v89, v89, v145
	v_add_f32_e32 v90, v215, v91
	v_mfma_f32_16x16x32_bf16 v[76:79], v[24:27], v[76:79], 0
	v_mul_f32_e32 v90, v90, v150
	v_cvt_pk_bf16_f32 v89, v89, v90
	v_lshlrev_b32_e32 v138, 16, v120
	s_waitcnt vmcnt(15)
	v_mfma_f32_16x16x32_bf16 v[84:87], v[4:7], v[72:75], v[84:87]
	v_and_b32_e32 v139, 0xffff0000, v120
	v_add_f32_e32 v92, v215, v92
	v_add_f32_e32 v93, v215, v93
	global_store_dwordx2 v[126:127], v[88:89], off offset:1056
	v_mfma_f32_16x16x32_bf16 v[88:91], v[12:15], v[72:75], v[122:125]
	v_mul_f32_e32 v92, v92, v138
	v_mul_f32_e32 v93, v93, v139
	v_cvt_pk_bf16_f32 v92, v92, v93
	v_add_f32_e32 v80, v215, v80
	v_lshlrev_b32_e32 v124, 16, v121
	v_and_b32_e32 v125, 0xffff0000, v121
	v_mfma_f32_16x16x32_bf16 v[120:123], v[20:23], v[72:75], v[146:149]
	v_mfma_f32_16x16x32_bf16 v[72:75], v[28:31], v[72:75], v[76:79]
	s_nop 2
	v_add_f32_e32 v76, v215, v94
	v_mul_f32_e32 v93, v76, v124
	s_waitcnt vmcnt(15)
; #define GAS __attribute__((address_space(1)))
; __device__ __forceinline__ unsigned cvt_pk_bf16(float lo, float hi) { unsigned r; asm volatile("v_cvt_pk_bf16_f32 %0, %1, %2" : "=v"(r) : "v"(lo), "v"(hi)); return r; }
; __device__ __forceinline__ void gmlp_items(const Params& P, int l, int local, unsigned* q) {
;     ...
;             for (int q = 0; q < 4; ++q) { const int p = 16 * (4 * half + q) + fr; const size_t row = (size_t)ch * 128 + p;
;                 f32x4 acc[4];
; #pragma unroll
;                 for (int mt = 0; mt < 4; ++mt) acc[mt] = (f32x4){0.f, 0.f, 0.f, 0.f};
; #pragma unroll
;                 for (int kk = 0; kk < 4; ++kk)
; #pragma unroll
;                     for (int mt = 0; mt < 4; ++mt) acc[mt] = __builtin_amdgcn_mfma_f32_16x16x32_bf16(Afv[kk][mt], Bfv[q][kk], acc[mt], 0, 0, 0);
; #pragma unroll
;                 for (int mt = 0; mt < 4; ++mt) { const int d0 = mt * 16 + 4 * fq; const u32x2 uu = uua[q][mt];
;                     const float u0 = __uint_as_float(uu.x << 16), u1 = __uint_as_float(uu.x & 0xffff0000u), u2 = __uint_as_float(uu.y << 16), u3 = __uint_as_float(uu.y & 0xffff0000u);
;                     u32x2 o; o.x = cvt_pk_bf16(u0 * (acc[mt][0] + bsv[q]), u1 * (acc[mt][1] + bsv[q])); o.y = cvt_pk_bf16(u2 * (acc[mt][2] + bsv[q]), u3 * (acc[mt][3] + bsv[q]));
;                     *(GAS u32x2*)(Y + row * YW + 512 + g * 64 + d0) = o; } }
	v_mfma_f32_16x16x32_bf16 v[76:79], v[32:35], v[68:71], v[84:87]
	v_lshlrev_b32_e32 v94, 16, v119
	s_nop 1
	v_add_f32_e32 v84, v215, v95
	v_mul_f32_e32 v84, v84, v125
	v_cvt_pk_bf16_f32 v93, v93, v84
	v_mfma_f32_16x16x32_bf16 v[84:87], v[40:43], v[68:71], v[88:91]
	global_store_dwordx2 v[126:127], v[92:93], off offset:1088
	v_and_b32_e32 v93, 0xffff0000, v118
	v_lshlrev_b32_e32 v92, 16, v118
	v_mfma_f32_16x16x32_bf16 v[88:91], v[48:51], v[68:71], v[120:123]
	v_and_b32_e32 v95, 0xffff0000, v119
	v_mul_f32_e32 v80, v80, v92
	v_mfma_f32_16x16x32_bf16 v[68:71], v[56:59], v[68:71], v[72:75]
	s_nop 2
	v_add_f32_e32 v72, v215, v81
	v_mul_f32_e32 v81, v72, v93
	s_waitcnt vmcnt(15)
	v_mfma_f32_16x16x32_bf16 v[72:75], v[36:39], v[64:67], v[76:79]
	v_cvt_pk_bf16_f32 v92, v80, v81
	v_add_f32_e32 v81, v215, v83
	v_mul_f32_e32 v81, v81, v95
	s_nop 0
	v_add_f32_e32 v76, v215, v82
	v_mul_f32_e32 v80, v76, v94
	v_mfma_f32_16x16x32_bf16 v[76:79], v[44:47], v[64:67], v[84:87]
	v_cvt_pk_bf16_f32 v93, v80, v81
	global_store_dwordx2 v[126:127], v[92:93], off offset:1120
	v_mfma_f32_16x16x32_bf16 v[80:83], v[52:55], v[64:67], v[88:91]
	s_waitcnt vmcnt(15)
	v_lshlrev_b32_e32 v84, 16, v116
	v_and_b32_e32 v85, 0xffff0000, v116
	v_mfma_f32_16x16x32_bf16 v[64:67], v[60:63], v[64:67], v[68:71]
	s_nop 2
	v_add_f32_e32 v68, v216, v72
	v_add_f32_e32 v71, v216, v73
	v_mul_f32_e32 v68, v68, v84
	v_mul_f32_e32 v71, v71, v85
	v_lshlrev_b32_e32 v69, 16, v117
	v_cvt_pk_bf16_f32 v68, v68, v71
	v_add_f32_e32 v71, v216, v74
	v_and_b32_e32 v70, 0xffff0000, v117
	v_mul_f32_e32 v69, v71, v69
	v_add_f32_e32 v71, v216, v75
	v_mul_f32_e32 v70, v71, v70
	v_cvt_pk_bf16_f32 v69, v69, v70
	v_mad_u64_u32 v[70:71], s[0:1], v128, s23, v[108:109]
	v_mad_i32_i24 v71, v105, s23, v71
	global_store_dwordx2 v[70:71], v[68:69], off offset:1024
	s_waitcnt vmcnt(15)
	v_lshlrev_b32_e32 v68, 16, v114
	v_add_f32_e32 v74, v216, v76
	v_and_b32_e32 v69, 0xffff0000, v114
	v_mul_f32_e32 v68, v74, v68
	v_add_f32_e32 v74, v216, v77
	v_mul_f32_e32 v69, v74, v69
	v_lshlrev_b32_e32 v72, 16, v115
	v_cvt_pk_bf16_f32 v68, v68, v69
	v_add_f32_e32 v69, v216, v78
	v_and_b32_e32 v73, 0xffff0000, v115
	v_mul_f32_e32 v69, v69, v72
	v_add_f32_e32 v72, v216, v79
	v_mul_f32_e32 v72, v72, v73
	v_cvt_pk_bf16_f32 v69, v69, v72
	global_store_dwordx2 v[70:71], v[68:69], off offset:1056
	s_waitcnt vmcnt(15)
	v_lshlrev_b32_e32 v68, 16, v112
	v_add_f32_e32 v74, v216, v80
	v_and_b32_e32 v69, 0xffff0000, v112
	v_mul_f32_e32 v68, v74, v68
	v_add_f32_e32 v74, v216, v81
	v_mul_f32_e32 v69, v74, v69
	v_lshlrev_b32_e32 v72, 16, v113
	v_cvt_pk_bf16_f32 v68, v68, v69
	v_add_f32_e32 v69, v216, v82
	v_and_b32_e32 v73, 0xffff0000, v113
	v_mul_f32_e32 v69, v69, v72
	v_add_f32_e32 v72, v216, v83
	v_mul_f32_e32 v72, v72, v73
	v_cvt_pk_bf16_f32 v69, v69, v72
	global_store_dwordx2 v[70:71], v[68:69], off offset:1088
	s_waitcnt vmcnt(15)
	v_lshlrev_b32_e32 v68, 16, v110
	v_and_b32_e32 v69, 0xffff0000, v110
	v_add_f32_e32 v64, v216, v64
	v_add_f32_e32 v65, v216, v65
	v_mul_f32_e32 v64, v64, v68
	v_mul_f32_e32 v65, v65, v69
	v_lshlrev_b32_e32 v72, 16, v111
	v_cvt_pk_bf16_f32 v64, v64, v65
	v_add_f32_e32 v65, v216, v66
	v_and_b32_e32 v73, 0xffff0000, v111
	v_mul_f32_e32 v65, v65, v72
	v_add_f32_e32 v66, v216, v67
	s_mov_b32 s0, 64
	v_mul_f32_e32 v66, v66, v73
	v_cvt_pk_bf16_f32 v65, v65, v66
	global_store_dwordx2 v[70:71], v[64:65], off offset:1120
	s_cbranch_vccz .LBB0_638
	v_mov_b32_e32 v0, 0
	s_and_saveexec_b64 s[40:41], s[38:39]
	s_cbranch_execz .LBB0_632
	s_mov_b64 s[44:45], exec
	v_mbcnt_lo_u32_b32 v0, s44, 0
	v_mbcnt_hi_u32_b32 v0, s45, v0
	v_cmp_eq_u32_e32 vcc, 0, v0
	s_and_saveexec_b64 s[42:43], vcc
	s_cbranch_execz .LBB0_631
	s_bcnt1_i32_b64 s0, s[44:45]
	v_mov_b32_e32 v1, s0
	v_readlane_b32 s0, v254, 50
	v_readlane_b32 s1, v254, 51
	s_nop 4
	global_atomic_add v1, v129, v1, s[0:1] sc0
	s_branch .LBB0_631

; #define GAS __attribute__((address_space(1)))
; __device__ __forceinline__ void lru_scan(const Params& P, int l) {
;     ...
;         const GAS u32x2* abp = (const GAS u32x2*)(AB + ((size_t)r0 * 512 + c) * 2);
;         u32x2 w[64];
; #pragma unroll
;         for (int p = 0; p < 64; ++p) w[p] = abp[(size_t)p * 512];
;         float hf[64]; { float hh = hin[0];
; #pragma unroll
;             for (int p = 0; p < 64; ++p) { const float om = __uint_as_float(w[p].x << 16), bb = __uint_as_float(w[p].x & 0xffff0000u); hh = (hh - om * hh) + bb; hf[p] = hh; } }
.LBB0_702:
	v_readlane_b32 s1, v255, 36
	s_lshl_b32 s0, s19, 6
	s_add_i32 s38, s0, s1
	s_ashr_i32 s39, s38, 31
	s_lshl_b64 s[0:1], s[38:39], 12
	v_lshl_add_u64 v[138:139], v[2:3], 0, s[0:1]
	v_add_co_u32_e32 v10, vcc, 0x1000, v138
	s_mov_b32 s2, 0x9000
	s_nop 0
	v_addc_co_u32_e32 v11, vcc, 0, v139, vcc
	v_add_co_u32_e32 v12, vcc, 0x2000, v138
	s_mov_b32 s0, 0x21000
	s_nop 0
	v_addc_co_u32_e32 v13, vcc, 0, v139, vcc
	v_add_co_u32_e32 v14, vcc, 0x3000, v138
	s_add_i32 s72, s38, 63
	s_nop 0
	v_addc_co_u32_e32 v15, vcc, 0, v139, vcc
	global_load_dwordx2 v[8:9], v[138:139], off
	global_load_dwordx2 v[10:11], v[10:11], off
	global_load_dwordx2 v[12:13], v[12:13], off
	global_load_dwordx2 v[14:15], v[14:15], off
	v_add_co_u32_e32 v16, vcc, 0x4000, v138
	s_add_i32 s76, s38, 62
	s_nop 0
	v_addc_co_u32_e32 v17, vcc, 0, v139, vcc
	v_add_co_u32_e32 v18, vcc, 0x5000, v138
	s_add_i32 s75, s38, 61
	s_nop 0
	v_addc_co_u32_e32 v19, vcc, 0, v139, vcc
	v_add_co_u32_e32 v20, vcc, 0x6000, v138
	s_add_i32 s73, s38, 59
	s_nop 0
	v_addc_co_u32_e32 v21, vcc, 0, v139, vcc
	v_add_co_u32_e32 v22, vcc, 0x7000, v138
	s_add_i32 s74, s38, 60
	s_nop 0
	v_addc_co_u32_e32 v23, vcc, 0, v139, vcc
	global_load_dwordx2 v[16:17], v[16:17], off
	global_load_dwordx2 v[18:19], v[18:19], off
	global_load_dwordx2 v[20:21], v[20:21], off
	global_load_dwordx2 v[22:23], v[22:23], off
	v_add_co_u32_e32 v26, vcc, s2, v138
	v_mad_i64_i32 v[214:215], s[28:29], s73, v178, v[6:7]
	s_nop 0
	v_addc_co_u32_e32 v27, vcc, 0, v139, vcc
	v_add_co_u32_e32 v30, vcc, s4, v138
	s_add_i32 s70, s38, 57
	s_nop 0
	v_addc_co_u32_e32 v31, vcc, 0, v139, vcc
	global_load_dwordx2 v[24:25], v[26:27], off offset:-4096
	global_load_dwordx2 v[26:27], v[26:27], off
	global_load_dwordx2 v[28:29], v[30:31], off offset:-4096
	global_load_dwordx2 v[30:31], v[30:31], off
	s_waitcnt vmcnt(0)
	v_add_co_u32_e32 v34, vcc, s5, v138
	s_add_i32 s71, s38, 58
	s_nop 0
	v_addc_co_u32_e32 v35, vcc, 0, v139, vcc
	v_add_co_u32_e32 v38, vcc, s8, v138
	v_mad_i64_i32 v[212:213], s[28:29], s70, v178, v[6:7]
	s_nop 0
	v_addc_co_u32_e32 v39, vcc, 0, v139, vcc
	global_load_dwordx2 v[32:33], v[34:35], off offset:-4096
	global_load_dwordx2 v[34:35], v[34:35], off
	global_load_dwordx2 v[36:37], v[38:39], off offset:-4096
	global_load_dwordx2 v[38:39], v[38:39], off
	v_add_co_u32_e32 v42, vcc, s9, v138
	s_add_i32 s68, s38, 55
	s_nop 0
	v_addc_co_u32_e32 v43, vcc, 0, v139, vcc
	v_add_co_u32_e32 v46, vcc, s10, v138
	s_add_i32 s69, s38, 56
	s_nop 0
	v_addc_co_u32_e32 v47, vcc, 0, v139, vcc
	global_load_dwordx2 v[40:41], v[42:43], off offset:-4096
	global_load_dwordx2 v[42:43], v[42:43], off
	global_load_dwordx2 v[44:45], v[46:47], off offset:-4096
	global_load_dwordx2 v[46:47], v[46:47], off
	v_add_co_u32_e32 v50, vcc, s11, v138
	s_add_i32 s3, s38, 19
	s_nop 0
	v_addc_co_u32_e32 v51, vcc, 0, v139, vcc
	v_add_co_u32_e32 v54, vcc, s12, v138
	v_mad_i64_i32 v[210:211], s[28:29], s68, v178, v[6:7]
	s_nop 0
	v_addc_co_u32_e32 v55, vcc, 0, v139, vcc
	global_load_dwordx2 v[48:49], v[50:51], off offset:-4096
	global_load_dwordx2 v[50:51], v[50:51], off
	global_load_dwordx2 v[52:53], v[54:55], off offset:-4096
	global_load_dwordx2 v[54:55], v[54:55], off
	v_add_co_u32_e32 v58, vcc, s13, v138
	s_add_i32 s66, s38, 53
	s_nop 0
	v_addc_co_u32_e32 v59, vcc, 0, v139, vcc
	v_add_co_u32_e32 v62, vcc, s14, v138
	s_add_i32 s67, s38, 54
	s_nop 0
	v_addc_co_u32_e32 v63, vcc, 0, v139, vcc
	global_load_dwordx2 v[56:57], v[58:59], off offset:-4096
	global_load_dwordx2 v[58:59], v[58:59], off
	global_load_dwordx2 v[60:61], v[62:63], off offset:-4096
	global_load_dwordx2 v[62:63], v[62:63], off
	v_add_co_u32_e32 v66, vcc, s15, v138
	v_lshlrev_b32_e32 v146, 16, v8
	s_nop 0
	v_addc_co_u32_e32 v67, vcc, 0, v139, vcc
	v_add_co_u32_e32 v70, vcc, s16, v138
	v_and_b32_e32 v8, 0xffff0000, v8
	s_nop 0
	v_addc_co_u32_e32 v71, vcc, 0, v139, vcc
	global_load_dwordx2 v[64:65], v[66:67], off offset:-4096
	global_load_dwordx2 v[66:67], v[66:67], off
	global_load_dwordx2 v[68:69], v[70:71], off offset:-4096
	global_load_dwordx2 v[70:71], v[70:71], off
	v_add_co_u32_e32 v74, vcc, s0, v138
	s_mov_b32 s0, 0x23000
	s_nop 0
	v_addc_co_u32_e32 v75, vcc, 0, v139, vcc
	v_add_co_u32_e32 v78, vcc, s0, v138
	s_mov_b32 s0, 0x25000
	s_nop 0
	v_addc_co_u32_e32 v79, vcc, 0, v139, vcc
	global_load_dwordx2 v[72:73], v[74:75], off offset:-4096
	global_load_dwordx2 v[74:75], v[74:75], off
	global_load_dwordx2 v[76:77], v[78:79], off offset:-4096
	global_load_dwordx2 v[78:79], v[78:79], off
	v_add_co_u32_e32 v82, vcc, s0, v138
	s_mov_b32 s0, 0x27000
	s_nop 0
	v_addc_co_u32_e32 v83, vcc, 0, v139, vcc
	v_add_co_u32_e32 v86, vcc, s0, v138
	s_mov_b32 s0, 0x29000
	s_nop 0
	v_addc_co_u32_e32 v87, vcc, 0, v139, vcc
	global_load_dwordx2 v[80:81], v[82:83], off offset:-4096
	global_load_dwordx2 v[82:83], v[82:83], off
	global_load_dwordx2 v[84:85], v[86:87], off offset:-4096
	global_load_dwordx2 v[86:87], v[86:87], off
	v_add_co_u32_e32 v90, vcc, s0, v138
	s_mov_b32 s0, 0x2b000
	s_nop 0
	v_addc_co_u32_e32 v91, vcc, 0, v139, vcc
	v_add_co_u32_e32 v94, vcc, s0, v138
	v_fma_f32 v128, -v128, v146, v128
	s_nop 0
	v_addc_co_u32_e32 v95, vcc, 0, v139, vcc
	v_add_f32_e32 v8, v128, v8
	v_lshlrev_b32_e32 v128, 16, v10
	global_load_dwordx2 v[88:89], v[90:91], off offset:-4096
	global_load_dwordx2 v[90:91], v[90:91], off
	global_load_dwordx2 v[92:93], v[94:95], off offset:-4096
	global_load_dwordx2 v[94:95], v[94:95], off
	v_and_b32_e32 v10, 0xffff0000, v10
	v_fma_f32 v128, -v8, v128, v8
	v_add_f32_e32 v10, v128, v10
	v_lshlrev_b32_e32 v128, 16, v12
	v_and_b32_e32 v12, 0xffff0000, v12
	v_fma_f32 v128, -v10, v128, v10
; #define GAS __attribute__((address_space(1)))
; __device__ __forceinline__ void lru_scan(const Params& P, int l) {
;     ...
;         const GAS u32x2* abp = (const GAS u32x2*)(AB + ((size_t)r0 * 512 + c) * 2);
;         u32x2 w[64];
; #pragma unroll
;         for (int p = 0; p < 64; ++p) w[p] = abp[(size_t)p * 512];
;         float hf[64]; { float hh = hin[0];
; #pragma unroll
;             for (int p = 0; p < 64; ++p) { const float om = __uint_as_float(w[p].x << 16), bb = __uint_as_float(w[p].x & 0xffff0000u); hh = (hh - om * hh) + bb; hf[p] = hh; } }
	s_mov_b32 s0, 0x2d000
	v_add_f32_e32 v12, v128, v12
	v_lshlrev_b32_e32 v128, 16, v14
	v_add_co_u32_e32 v98, vcc, s0, v138
	v_and_b32_e32 v14, 0xffff0000, v14
	v_fma_f32 v128, -v12, v128, v12
	v_addc_co_u32_e32 v99, vcc, 0, v139, vcc
	s_mov_b32 s0, 0x2f000
	v_add_f32_e32 v14, v128, v14
	v_lshlrev_b32_e32 v128, 16, v16
	v_add_co_u32_e32 v102, vcc, s0, v138
	v_and_b32_e32 v16, 0xffff0000, v16
	v_fma_f32 v128, -v14, v128, v14
	v_addc_co_u32_e32 v103, vcc, 0, v139, vcc
	v_add_f32_e32 v16, v128, v16
	v_lshlrev_b32_e32 v128, 16, v18
	global_load_dwordx2 v[96:97], v[98:99], off offset:-4096
	global_load_dwordx2 v[98:99], v[98:99], off
	global_load_dwordx2 v[100:101], v[102:103], off offset:-4096
	global_load_dwordx2 v[102:103], v[102:103], off
	v_and_b32_e32 v18, 0xffff0000, v18
	v_fma_f32 v128, -v16, v128, v16
	v_add_f32_e32 v18, v128, v18
	v_lshlrev_b32_e32 v128, 16, v20
	v_and_b32_e32 v20, 0xffff0000, v20
	v_fma_f32 v128, -v18, v128, v18
	s_mov_b32 s0, 0x31000
	v_add_f32_e32 v20, v128, v20
	v_lshlrev_b32_e32 v128, 16, v22
	v_add_co_u32_e32 v106, vcc, s0, v138
	v_and_b32_e32 v22, 0xffff0000, v22
	v_fma_f32 v128, -v20, v128, v20
	v_addc_co_u32_e32 v107, vcc, 0, v139, vcc
	s_mov_b32 s0, 0x33000
	v_add_f32_e32 v22, v128, v22
	v_lshlrev_b32_e32 v128, 16, v24
	v_add_co_u32_e32 v110, vcc, s0, v138
	v_and_b32_e32 v24, 0xffff0000, v24
	v_fma_f32 v128, -v22, v128, v22
	v_addc_co_u32_e32 v111, vcc, 0, v139, vcc
	v_add_f32_e32 v24, v128, v24
	v_lshlrev_b32_e32 v128, 16, v26
	global_load_dwordx2 v[104:105], v[106:107], off offset:-4096
	global_load_dwordx2 v[106:107], v[106:107], off
	global_load_dwordx2 v[108:109], v[110:111], off offset:-4096
	global_load_dwordx2 v[110:111], v[110:111], off
	v_and_b32_e32 v26, 0xffff0000, v26
	v_fma_f32 v128, -v24, v128, v24
	v_add_f32_e32 v26, v128, v26
	v_lshlrev_b32_e32 v128, 16, v28
	v_and_b32_e32 v28, 0xffff0000, v28
	v_fma_f32 v128, -v26, v128, v26
	s_mov_b32 s0, 0x35000
	v_add_f32_e32 v28, v128, v28
	v_lshlrev_b32_e32 v128, 16, v30
	v_add_co_u32_e32 v114, vcc, s0, v138
	v_and_b32_e32 v30, 0xffff0000, v30
	v_fma_f32 v128, -v28, v128, v28
	v_addc_co_u32_e32 v115, vcc, 0, v139, vcc
	s_mov_b32 s0, 0x37000
	v_add_f32_e32 v30, v128, v30
	s_waitcnt vmcnt(39)
	v_lshlrev_b32_e32 v128, 16, v32
	v_add_co_u32_e32 v118, vcc, s0, v138
	v_and_b32_e32 v32, 0xffff0000, v32
	v_fma_f32 v128, -v30, v128, v30
	v_addc_co_u32_e32 v119, vcc, 0, v139, vcc
	v_add_f32_e32 v32, v128, v32
	s_waitcnt vmcnt(38)
	v_lshlrev_b32_e32 v128, 16, v34
	global_load_dwordx2 v[112:113], v[114:115], off offset:-4096
	global_load_dwordx2 v[114:115], v[114:115], off
	global_load_dwordx2 v[116:117], v[118:119], off offset:-4096
	global_load_dwordx2 v[118:119], v[118:119], off
	v_and_b32_e32 v34, 0xffff0000, v34
	v_fma_f32 v128, -v32, v128, v32
	v_add_f32_e32 v34, v128, v34
	s_waitcnt vmcnt(41)
	v_lshlrev_b32_e32 v128, 16, v36
	v_and_b32_e32 v36, 0xffff0000, v36
	v_fma_f32 v128, -v34, v128, v34
	s_mov_b32 s0, 0x39000
	v_add_f32_e32 v36, v128, v36
	s_waitcnt vmcnt(40)
	v_lshlrev_b32_e32 v128, 16, v38
	v_add_co_u32_e32 v122, vcc, s0, v138
	v_and_b32_e32 v38, 0xffff0000, v38
	v_fma_f32 v128, -v36, v128, v36
	v_addc_co_u32_e32 v123, vcc, 0, v139, vcc
	s_mov_b32 s0, 0x3b000
	v_add_f32_e32 v38, v128, v38
	s_waitcnt vmcnt(39)
	v_lshlrev_b32_e32 v128, 16, v40
	v_add_co_u32_e32 v126, vcc, s0, v138
	v_and_b32_e32 v40, 0xffff0000, v40
	v_fma_f32 v128, -v38, v128, v38
	v_addc_co_u32_e32 v127, vcc, 0, v139, vcc
	v_add_f32_e32 v40, v128, v40
	s_waitcnt vmcnt(38)
	v_lshlrev_b32_e32 v128, 16, v42
	global_load_dwordx2 v[120:121], v[122:123], off offset:-4096
	global_load_dwordx2 v[122:123], v[122:123], off
	global_load_dwordx2 v[124:125], v[126:127], off offset:-4096
	global_load_dwordx2 v[126:127], v[126:127], off
	v_and_b32_e32 v42, 0xffff0000, v42
	v_fma_f32 v128, -v40, v128, v40
	v_add_f32_e32 v42, v128, v42
	s_waitcnt vmcnt(41)
	v_lshlrev_b32_e32 v128, 16, v44
	v_and_b32_e32 v44, 0xffff0000, v44
	v_fma_f32 v128, -v42, v128, v42
	s_mov_b32 s0, 0x3d000
	v_add_f32_e32 v44, v128, v44
	s_waitcnt vmcnt(40)
	v_lshlrev_b32_e32 v128, 16, v46
	v_add_co_u32_e32 v140, vcc, s0, v138
	v_and_b32_e32 v46, 0xffff0000, v46
	v_fma_f32 v128, -v44, v128, v44
	v_addc_co_u32_e32 v141, vcc, 0, v139, vcc
	s_mov_b32 s0, 0x3f000
	v_add_f32_e32 v46, v128, v46
	s_waitcnt vmcnt(39)
	v_lshlrev_b32_e32 v128, 16, v48
	v_add_co_u32_e32 v144, vcc, s0, v138
	v_and_b32_e32 v48, 0xffff0000, v48
	v_fma_f32 v128, -v46, v128, v46
	v_addc_co_u32_e32 v145, vcc, 0, v139, vcc
	v_add_f32_e32 v48, v128, v48
	s_waitcnt vmcnt(38)
	v_lshlrev_b32_e32 v128, 16, v50
	global_load_dwordx2 v[138:139], v[140:141], off offset:-4096
	global_load_dwordx2 v[140:141], v[140:141], off
	global_load_dwordx2 v[142:143], v[144:145], off offset:-4096
	global_load_dwordx2 v[144:145], v[144:145], off
	v_and_b32_e32 v50, 0xffff0000, v50
	v_fma_f32 v128, -v48, v128, v48
	v_add_f32_e32 v50, v128, v50
	s_waitcnt vmcnt(41)
	v_lshlrev_b32_e32 v128, 16, v52
	v_and_b32_e32 v52, 0xffff0000, v52
	v_fma_f32 v128, -v50, v128, v50
	v_add_f32_e32 v52, v128, v52
	s_waitcnt vmcnt(40)
	v_lshlrev_b32_e32 v128, 16, v54
	v_and_b32_e32 v54, 0xffff0000, v54
	v_fma_f32 v128, -v52, v128, v52
	v_add_f32_e32 v54, v128, v54
	s_waitcnt vmcnt(39)
	v_lshlrev_b32_e32 v128, 16, v56
	v_and_b32_e32 v56, 0xffff0000, v56
	v_fma_f32 v128, -v54, v128, v54
	v_add_f32_e32 v56, v128, v56
	s_waitcnt vmcnt(38)
	v_lshlrev_b32_e32 v128, 16, v58
	v_and_b32_e32 v58, 0xffff0000, v58
	v_fma_f32 v128, -v56, v128, v56
	v_add_f32_e32 v58, v128, v58
	s_waitcnt vmcnt(37)
	v_lshlrev_b32_e32 v128, 16, v60
	v_and_b32_e32 v60, 0xffff0000, v60
	v_fma_f32 v128, -v58, v128, v58
	v_add_f32_e32 v60, v128, v60
	s_waitcnt vmcnt(36)
; __device__ __forceinline__ void lru_scan(const Params& P, int l) {
;     ...
;         float hf[64]; { float hh = hin[0];
; #pragma unroll
;             for (int p = 0; p < 64; ++p) { const float om = __uint_as_float(w[p].x << 16), bb = __uint_as_float(w[p].x & 0xffff0000u); hh = (hh - om * hh) + bb; hf[p] = hh; } }
	v_lshlrev_b32_e32 v128, 16, v62
	v_and_b32_e32 v62, 0xffff0000, v62
	v_fma_f32 v128, -v60, v128, v60
	v_add_f32_e32 v62, v128, v62
	s_waitcnt vmcnt(35)
	v_lshlrev_b32_e32 v128, 16, v64
	v_and_b32_e32 v64, 0xffff0000, v64
	v_fma_f32 v128, -v62, v128, v62
	v_add_f32_e32 v64, v128, v64
	s_waitcnt vmcnt(34)
	v_lshlrev_b32_e32 v128, 16, v66
	v_and_b32_e32 v66, 0xffff0000, v66
	v_fma_f32 v128, -v64, v128, v64
	v_add_f32_e32 v66, v128, v66
	s_waitcnt vmcnt(33)
	v_lshlrev_b32_e32 v128, 16, v68
	v_and_b32_e32 v68, 0xffff0000, v68
	v_fma_f32 v128, -v66, v128, v66
	v_add_f32_e32 v68, v128, v68
	s_waitcnt vmcnt(32)
	v_lshlrev_b32_e32 v128, 16, v70
	v_and_b32_e32 v70, 0xffff0000, v70
	v_fma_f32 v128, -v68, v128, v68
	v_add_f32_e32 v70, v128, v70
	s_waitcnt vmcnt(31)
	v_lshlrev_b32_e32 v128, 16, v72
	v_and_b32_e32 v72, 0xffff0000, v72
	v_fma_f32 v128, -v70, v128, v70
	v_add_f32_e32 v72, v128, v72
	s_waitcnt vmcnt(30)
	v_lshlrev_b32_e32 v128, 16, v74
	v_and_b32_e32 v74, 0xffff0000, v74
	v_fma_f32 v128, -v72, v128, v72
	v_add_f32_e32 v74, v128, v74
	s_waitcnt vmcnt(29)
	v_lshlrev_b32_e32 v128, 16, v76
	v_and_b32_e32 v76, 0xffff0000, v76
	v_fma_f32 v128, -v74, v128, v74
	v_add_f32_e32 v76, v128, v76
	s_waitcnt vmcnt(28)
	v_lshlrev_b32_e32 v128, 16, v78
	v_and_b32_e32 v78, 0xffff0000, v78
	v_fma_f32 v128, -v76, v128, v76
	v_add_f32_e32 v78, v128, v78
	s_waitcnt vmcnt(27)
	v_lshlrev_b32_e32 v128, 16, v80
	v_and_b32_e32 v80, 0xffff0000, v80
	v_fma_f32 v128, -v78, v128, v78
	v_add_f32_e32 v80, v128, v80
	s_waitcnt vmcnt(26)
	v_lshlrev_b32_e32 v128, 16, v82
	v_and_b32_e32 v82, 0xffff0000, v82
	v_fma_f32 v128, -v80, v128, v80
	v_add_f32_e32 v82, v128, v82
	s_waitcnt vmcnt(25)
	v_lshlrev_b32_e32 v128, 16, v84
	v_and_b32_e32 v84, 0xffff0000, v84
	v_fma_f32 v128, -v82, v128, v82
	v_add_f32_e32 v84, v128, v84
	s_waitcnt vmcnt(24)
	v_lshlrev_b32_e32 v128, 16, v86
	v_and_b32_e32 v86, 0xffff0000, v86
	v_fma_f32 v128, -v84, v128, v84
	v_add_f32_e32 v86, v128, v86
	s_waitcnt vmcnt(23)
	v_lshlrev_b32_e32 v128, 16, v88
	v_and_b32_e32 v88, 0xffff0000, v88
	v_fma_f32 v128, -v86, v128, v86
	v_add_f32_e32 v88, v128, v88
	s_waitcnt vmcnt(22)
	v_lshlrev_b32_e32 v128, 16, v90
	v_and_b32_e32 v90, 0xffff0000, v90
	v_fma_f32 v128, -v88, v128, v88
	v_add_f32_e32 v90, v128, v90
	s_waitcnt vmcnt(21)
	v_lshlrev_b32_e32 v128, 16, v92
	v_and_b32_e32 v92, 0xffff0000, v92
	v_fma_f32 v128, -v90, v128, v90
	v_add_f32_e32 v92, v128, v92
	s_waitcnt vmcnt(20)
	v_lshlrev_b32_e32 v128, 16, v94
	v_and_b32_e32 v94, 0xffff0000, v94
	v_fma_f32 v128, -v92, v128, v92
	v_add_f32_e32 v94, v128, v94
	s_waitcnt vmcnt(19)
	v_lshlrev_b32_e32 v128, 16, v96
	v_and_b32_e32 v96, 0xffff0000, v96
	v_fma_f32 v128, -v94, v128, v94
	v_add_f32_e32 v96, v128, v96
	s_waitcnt vmcnt(18)
	v_lshlrev_b32_e32 v128, 16, v98
	v_and_b32_e32 v98, 0xffff0000, v98
	v_fma_f32 v128, -v96, v128, v96
	v_add_f32_e32 v98, v128, v98
	s_waitcnt vmcnt(17)
	v_lshlrev_b32_e32 v128, 16, v100
	v_and_b32_e32 v100, 0xffff0000, v100
	v_fma_f32 v128, -v98, v128, v98
	v_add_f32_e32 v100, v128, v100
	s_waitcnt vmcnt(16)
	v_lshlrev_b32_e32 v128, 16, v102
	v_and_b32_e32 v102, 0xffff0000, v102
	v_fma_f32 v128, -v100, v128, v100
	v_add_f32_e32 v102, v128, v102
	s_waitcnt vmcnt(15)
	v_lshlrev_b32_e32 v128, 16, v104
	v_and_b32_e32 v104, 0xffff0000, v104
	v_fma_f32 v128, -v102, v128, v102
	v_add_f32_e32 v104, v128, v104
	s_waitcnt vmcnt(14)
	v_lshlrev_b32_e32 v128, 16, v106
	v_and_b32_e32 v106, 0xffff0000, v106
	v_fma_f32 v128, -v104, v128, v104
	v_add_f32_e32 v128, v128, v106
	s_waitcnt vmcnt(13)
	v_lshlrev_b32_e32 v106, 16, v108
	v_and_b32_e32 v108, 0xffff0000, v108
	v_fma_f32 v106, -v128, v106, v128
	v_add_f32_e32 v155, v106, v108
	s_waitcnt vmcnt(12)
	v_lshlrev_b32_e32 v106, 16, v110
	v_and_b32_e32 v108, 0xffff0000, v110
	v_fma_f32 v106, -v155, v106, v155
	v_add_f32_e32 v156, v106, v108
	s_waitcnt vmcnt(11)
	v_lshlrev_b32_e32 v106, 16, v112
	v_and_b32_e32 v108, 0xffff0000, v112
	v_fma_f32 v106, -v156, v106, v156
	v_add_f32_e32 v157, v106, v108
	s_waitcnt vmcnt(10)
	v_lshlrev_b32_e32 v106, 16, v114
	v_and_b32_e32 v108, 0xffff0000, v114
	v_fma_f32 v106, -v157, v106, v157
	v_add_f32_e32 v158, v106, v108
	s_waitcnt vmcnt(9)
	v_lshlrev_b32_e32 v106, 16, v116
	v_and_b32_e32 v108, 0xffff0000, v116
	v_fma_f32 v106, -v158, v106, v158
	v_add_f32_e32 v159, v106, v108
	s_waitcnt vmcnt(8)
	v_lshlrev_b32_e32 v106, 16, v118
	v_and_b32_e32 v108, 0xffff0000, v118
	v_fma_f32 v106, -v159, v106, v159
	v_add_f32_e32 v160, v106, v108
	s_waitcnt vmcnt(7)
	v_lshlrev_b32_e32 v106, 16, v120
	v_and_b32_e32 v108, 0xffff0000, v120
	v_fma_f32 v106, -v160, v106, v160
	v_add_f32_e32 v161, v106, v108
	s_waitcnt vmcnt(6)
	v_lshlrev_b32_e32 v106, 16, v122
	v_and_b32_e32 v108, 0xffff0000, v122
	v_fma_f32 v106, -v161, v106, v161
	v_add_f32_e32 v162, v106, v108
	s_waitcnt vmcnt(5)
	v_lshlrev_b32_e32 v106, 16, v124
	v_and_b32_e32 v108, 0xffff0000, v124
	v_fma_f32 v106, -v162, v106, v162
	v_add_f32_e32 v163, v106, v108
	s_waitcnt vmcnt(4)
	v_lshlrev_b32_e32 v106, 16, v126
	v_and_b32_e32 v108, 0xffff0000, v126
	v_fma_f32 v106, -v163, v106, v163
	v_add_f32_e32 v167, v106, v108
	s_waitcnt vmcnt(3)
	v_lshlrev_b32_e32 v106, 16, v138
	v_and_b32_e32 v108, 0xffff0000, v138
	v_fma_f32 v106, -v167, v106, v167
	v_add_f32_e32 v186, v106, v108
	s_waitcnt vmcnt(2)
	v_lshlrev_b32_e32 v106, 16, v140
	v_and_b32_e32 v108, 0xffff0000, v140
	v_fma_f32 v106, -v186, v106, v186
	v_add_f32_e32 v190, v106, v108
	s_waitcnt vmcnt(1)
	v_lshlrev_b32_e32 v106, 16, v142
	v_and_b32_e32 v108, 0xffff0000, v142
	v_fma_f32 v106, -v190, v106, v190
	v_add_f32_e32 v216, v106, v108
	s_waitcnt vmcnt(0)
; __device__ __forceinline__ void lru_scan(const Params& P, int l) {
;     ...
;         float hf[64]; { float hh = hin[0];
; #pragma unroll
;             for (int p = 0; p < 64; ++p) { const float om = __uint_as_float(w[p].x << 16), bb = __uint_as_float(w[p].x & 0xffff0000u); hh = (hh - om * hh) + bb; hf[p] = hh; } }
;         unsigned short gar[64];
; #pragma unroll
;         for (int p = 0; p < 64; ++p) gar[p] = Z[(size_t)(r0 + p) * ZW + 512 + c];
	v_lshlrev_b32_e32 v106, 16, v144
	v_and_b32_e32 v108, 0xffff0000, v144
	v_fma_f32 v106, -v216, v106, v216
	v_mad_i64_i32 v[164:165], s[14:15], s72, v178, v[6:7]
	v_add_f32_e32 v106, v106, v108
	global_load_ushort v108, v[164:165], off offset:1024
	v_lshlrev_b32_e32 v110, 16, v145
	v_and_b32_e32 v112, 0xffff0000, v145
	v_mad_i64_i32 v[144:145], s[28:29], s76, v178, v[6:7]
	global_load_ushort v218, v[144:145], off offset:1024
	v_mad_i64_i32 v[144:145], s[28:29], s75, v178, v[6:7]
	global_load_ushort v220, v[144:145], off offset:1024
	v_mad_i64_i32 v[144:145], s[28:29], s74, v178, v[6:7]
	global_load_ushort v221, v[144:145], off offset:1024
	s_nop 0
	global_load_ushort v214, v[214:215], off offset:1024
	v_mad_i64_i32 v[144:145], s[28:29], s71, v178, v[6:7]
	global_load_ushort v215, v[144:145], off offset:1024
	s_nop 0
	global_load_ushort v212, v[212:213], off offset:1024
	v_mad_i64_i32 v[144:145], s[28:29], s69, v178, v[6:7]
	v_mad_i64_i32 v[146:147], s[4:5], s3, v178, v[6:7]
	global_load_ushort v213, v[144:145], off offset:1024
	s_nop 0
	global_load_ushort v210, v[210:211], off offset:1024
	s_add_i32 s5, s38, 21
	v_mad_i64_i32 v[148:149], s[8:9], s5, v178, v[6:7]
	s_add_i32 s9, s38, 23
	s_add_i32 s64, s38, 51
	s_add_i32 s65, s38, 52
	v_mad_i64_i32 v[208:209], s[28:29], s66, v178, v[6:7]
	v_mad_i64_i32 v[144:145], s[28:29], s67, v178, v[6:7]
	v_mad_i64_i32 v[150:151], s[10:11], s9, v178, v[6:7]
	s_add_i32 s62, s38, 49
	s_add_i32 s63, s38, 50
	v_mad_i64_i32 v[206:207], s[28:29], s64, v178, v[6:7]
	global_load_ushort v211, v[144:145], off offset:1024
	s_nop 0
	global_load_ushort v208, v[208:209], off offset:1024
	v_mad_i64_i32 v[144:145], s[28:29], s65, v178, v[6:7]
	s_add_i32 s11, s38, 25
	s_add_i32 s60, s38, 47
	s_add_i32 s61, s38, 48
	v_mad_i64_i32 v[204:205], s[28:29], s62, v178, v[6:7]
	global_load_ushort v209, v[144:145], off offset:1024
	s_nop 0
	global_load_ushort v206, v[206:207], off offset:1024
	v_mad_i64_i32 v[144:145], s[28:29], s63, v178, v[6:7]
	v_mad_i64_i32 v[152:153], s[12:13], s11, v178, v[6:7]
	s_add_i32 s58, s38, 45
	s_add_i32 s59, s38, 46
	v_mad_i64_i32 v[202:203], s[28:29], s60, v178, v[6:7]
	global_load_ushort v207, v[144:145], off offset:1024
	s_nop 0
	global_load_ushort v204, v[204:205], off offset:1024
	v_mad_i64_i32 v[144:145], s[28:29], s61, v178, v[6:7]
	s_add_i32 s13, s38, 27
	s_add_i32 s56, s38, 43
	s_add_i32 s57, s38, 44
	v_mad_i64_i32 v[200:201], s[28:29], s58, v178, v[6:7]
	global_load_ushort v205, v[144:145], off offset:1024
	s_nop 0
	global_load_ushort v202, v[202:203], off offset:1024
	v_mad_i64_i32 v[144:145], s[28:29], s59, v178, v[6:7]
	v_mad_i64_i32 v[164:165], s[14:15], s13, v178, v[6:7]
	s_add_i32 s54, s38, 41
	s_add_i32 s55, s38, 42
	v_mad_i64_i32 v[198:199], s[28:29], s56, v178, v[6:7]
	global_load_ushort v203, v[144:145], off offset:1024
	s_nop 0
	global_load_ushort v200, v[200:201], off offset:1024
	v_mad_i64_i32 v[144:145], s[28:29], s57, v178, v[6:7]
	s_add_i32 s15, s38, 29
	s_add_i32 s53, s38, 40
	v_mad_i64_i32 v[196:197], s[28:29], s54, v178, v[6:7]
	global_load_ushort v201, v[144:145], off offset:1024
	s_nop 0
	global_load_ushort v198, v[198:199], off offset:1024
	v_mad_i64_i32 v[144:145], s[28:29], s55, v178, v[6:7]
	v_mad_i64_i32 v[180:181], s[16:17], s15, v178, v[6:7]
	s_add_i32 s47, s38, 38
	s_add_i32 s50, s38, 39
	global_load_ushort v199, v[144:145], off offset:1024
	s_nop 0
	global_load_ushort v196, v[196:197], off offset:1024
	v_mad_i64_i32 v[144:145], s[28:29], s53, v178, v[6:7]
	s_add_i32 s17, s38, 31
	s_add_i32 s41, s38, 36
	s_add_i32 s44, s38, 37
	v_mad_i64_i32 v[194:195], s[28:29], s50, v178, v[6:7]
	global_load_ushort v197, v[144:145], off offset:1024
	global_load_ushort v222, v[194:195], off offset:1024
	v_mad_i64_i32 v[144:145], s[28:29], s47, v178, v[6:7]
	v_mad_i64_i32 v[182:183], s[26:27], s17, v178, v[6:7]
	s_add_i32 s31, s38, 34
	s_add_i32 s39, s38, 35
	v_mad_i64_i32 v[192:193], s[28:29], s44, v178, v[6:7]
	global_load_ushort v223, v[144:145], off offset:1024
	global_load_ushort v224, v[192:193], off offset:1024
	v_mad_i64_i32 v[144:145], s[28:29], s41, v178, v[6:7]
	s_add_i32 s21, s38, 32
	s_add_i32 s27, s38, 33
	v_mad_i64_i32 v[188:189], s[28:29], s39, v178, v[6:7]
	global_load_ushort v225, v[144:145], off offset:1024
	global_load_ushort v193, v[188:189], off offset:1024
	v_mad_i64_i32 v[144:145], s[28:29], s31, v178, v[6:7]
	s_add_i32 s16, s38, 30
	v_mad_i64_i32 v[184:185], s[28:29], s27, v178, v[6:7]
	global_load_ushort v192, v[144:145], off offset:1024
	global_load_ushort v189, v[184:185], off offset:1024
	v_mad_i64_i32 v[144:145], s[28:29], s21, v178, v[6:7]
	s_add_i32 s14, s38, 28
	global_load_ushort v191, v[144:145], off offset:1024
	global_load_ushort v188, v[182:183], off offset:1024
	v_mad_i64_i32 v[144:145], s[28:29], s16, v178, v[6:7]
	s_add_i32 s12, s38, 26
	global_load_ushort v187, v[144:145], off offset:1024
	global_load_ushort v185, v[180:181], off offset:1024
	v_mad_i64_i32 v[144:145], s[28:29], s14, v178, v[6:7]
	s_add_i32 s10, s38, 24
	global_load_ushort v184, v[144:145], off offset:1024
	global_load_ushort v166, v[164:165], off offset:1024
	v_mad_i64_i32 v[144:145], s[28:29], s12, v178, v[6:7]
	s_add_i32 s8, s38, 22
	v_fma_f32 v110, -v154, v110, v154
	global_load_ushort v165, v[144:145], off offset:1024
	global_load_ushort v154, v[152:153], off offset:1024
	v_mad_i64_i32 v[144:145], s[28:29], s10, v178, v[6:7]
	s_add_i32 s4, s38, 20
	global_load_ushort v164, v[144:145], off offset:1024
	global_load_ushort v153, v[150:151], off offset:1024
	v_mad_i64_i32 v[144:145], s[28:29], s8, v178, v[6:7]
	s_add_i32 s2, s38, 18
	global_load_ushort v152, v[144:145], off offset:1024
; __device__ __forceinline__ float bf2f(unsigned short b) { return __uint_as_float(((unsigned)b) << 16); }
; __device__ __forceinline__ unsigned cvt_pk_bf16(float lo, float hi) { unsigned r; asm volatile("v_cvt_pk_bf16_f32 %0, %1, %2" : "=v"(r) : "v"(lo), "v"(hi)); return r; }
; __device__ __forceinline__ void lru_scan(const Params& P, int l) {
;     ...
;         unsigned short gar[64];
; #pragma unroll
;         for (int p = 0; p < 64; ++p) gar[p] = Z[(size_t)(r0 + p) * ZW + 512 + c];
;         { float hh = hin[1];
; #pragma unroll
;             for (int p = 63; p >= 0; --p) { const float om = __uint_as_float(w[p].y << 16), bb = __uint_as_float(w[p].y & 0xffff0000u); hh = (hh - om * hh) + bb;
;                 const float yo = (hf[p] + hh) * bf2f(gar[p]); Y[(size_t)(r0 + p) * YW + c] = (bf16_t)cvt_pk_bf16(yo, yo); } }
	global_load_ushort v151, v[148:149], off offset:1024
	v_mad_i64_i32 v[144:145], s[28:29], s4, v178, v[6:7]
	s_add_i32 s1, s38, 17
	global_load_ushort v150, v[144:145], off offset:1024
	global_load_ushort v149, v[146:147], off offset:1024
	v_mad_i64_i32 v[144:145], s[28:29], s2, v178, v[6:7]
	s_add_i32 s0, s38, 16
	global_load_ushort v148, v[144:145], off offset:1024
	v_mad_i64_i32 v[144:145], s[28:29], s1, v178, v[6:7]
	global_load_ushort v146, v[144:145], off offset:1024
	v_mad_i64_i32 v[144:145], s[28:29], s0, v178, v[6:7]
	s_add_i32 s52, s38, 15
	s_add_i32 s51, s38, 14
	global_load_ushort v147, v[144:145], off offset:1024
	v_mad_i64_i32 v[144:145], s[28:29], s52, v178, v[6:7]
	v_mad_i64_i32 v[180:181], s[28:29], s51, v178, v[6:7]
	s_add_i32 s49, s38, 13
	global_load_ushort v145, v[144:145], off offset:1024
	s_add_i32 s48, s38, 12
	global_load_ushort v144, v[180:181], off offset:1024
	v_mad_i64_i32 v[180:181], s[28:29], s49, v178, v[6:7]
	global_load_ushort v142, v[180:181], off offset:1024
	v_mad_i64_i32 v[180:181], s[28:29], s48, v178, v[6:7]
	s_add_i32 s46, s38, 11
	global_load_ushort v140, v[180:181], off offset:1024
	v_mad_i64_i32 v[180:181], s[28:29], s46, v178, v[6:7]
	s_add_i32 s45, s38, 10
	global_load_ushort v138, v[180:181], off offset:1024
	v_mad_i64_i32 v[180:181], s[28:29], s45, v178, v[6:7]
	s_add_i32 s43, s38, 9
	global_load_ushort v126, v[180:181], off offset:1024
	v_mad_i64_i32 v[180:181], s[28:29], s43, v178, v[6:7]
	s_add_i32 s42, s38, 8
	global_load_ushort v124, v[180:181], off offset:1024
	v_mad_i64_i32 v[180:181], s[28:29], s42, v178, v[6:7]
	s_add_i32 s40, s38, 7
	global_load_ushort v122, v[180:181], off offset:1024
	v_mad_i64_i32 v[180:181], s[28:29], s40, v178, v[6:7]
	s_add_i32 s35, s38, 6
	global_load_ushort v120, v[180:181], off offset:1024
	v_mad_i64_i32 v[180:181], s[28:29], s35, v178, v[6:7]
	s_add_i32 s34, s38, 5
	global_load_ushort v118, v[180:181], off offset:1024
	v_mad_i64_i32 v[180:181], s[28:29], s34, v178, v[6:7]
	s_add_i32 s30, s38, 4
	global_load_ushort v116, v[180:181], off offset:1024
	v_mad_i64_i32 v[180:181], s[28:29], s30, v178, v[6:7]
	s_add_i32 s26, s38, 3
	global_load_ushort v114, v[180:181], off offset:1024
	v_mad_i64_i32 v[180:181], s[28:29], s26, v178, v[6:7]
	s_add_i32 s25, s38, 2
	v_add_f32_e32 v217, v110, v112
	global_load_ushort v112, v[180:181], off offset:1024
	v_mad_i64_i32 v[180:181], s[28:29], s25, v178, v[6:7]
	s_add_i32 s19, s38, 1
	v_add_f32_e32 v106, v217, v106
	s_waitcnt vmcnt(60)
	v_lshlrev_b32_e32 v108, 16, v108
	global_load_ushort v110, v[180:181], off offset:1024
	v_mad_i64_i32 v[180:181], s[28:29], s19, v178, v[6:7]
	v_mul_f32_e32 v219, v106, v108
	global_load_ushort v108, v[180:181], off offset:1024
	v_mad_i64_i32 v[180:181], s[28:29], s38, v178, v[6:7]
	global_load_ushort v106, v[180:181], off offset:1024
	v_mad_i64_i32 v[180:181], s[28:29], s72, v178, v[4:5]
	v_cvt_pk_bf16_f32 v182, v219, v219
	global_store_short v[180:181], v182, off
	v_lshlrev_b32_e32 v180, 16, v143
	v_and_b32_e32 v143, 0xffff0000, v143
	v_fma_f32 v180, -v217, v180, v217
	v_add_f32_e32 v143, v180, v143
	v_add_f32_e32 v180, v143, v216
	s_waitcnt vmcnt(62)
	v_lshlrev_b32_e32 v181, 16, v218
	v_mul_f32_e32 v180, v180, v181
	v_cvt_pk_bf16_f32 v182, v180, v180
	v_mad_i64_i32 v[180:181], s[28:29], s76, v178, v[4:5]
	global_store_short v[180:181], v182, off
	v_lshlrev_b32_e32 v180, 16, v141
	v_and_b32_e32 v141, 0xffff0000, v141
	v_fma_f32 v143, -v143, v180, v143
	v_add_f32_e32 v141, v143, v141
	v_add_f32_e32 v143, v141, v190
	v_lshlrev_b32_e32 v180, 16, v220
	v_mul_f32_e32 v143, v143, v180
	v_cvt_pk_bf16_f32 v143, v143, v143
	v_mad_i64_i32 v[180:181], s[28:29], s75, v178, v[4:5]
	global_store_short v[180:181], v143, off
	v_lshlrev_b32_e32 v143, 16, v139
	v_and_b32_e32 v139, 0xffff0000, v139
	v_fma_f32 v141, -v141, v143, v141
	v_add_f32_e32 v139, v141, v139
	v_add_f32_e32 v141, v139, v186
	s_waitcnt vmcnt(62)
	v_lshlrev_b32_e32 v143, 16, v221
	v_mul_f32_e32 v141, v141, v143
	v_cvt_pk_bf16_f32 v141, v141, v141
	v_mad_i64_i32 v[180:181], s[28:29], s74, v178, v[4:5]
	global_store_short v[180:181], v141, off
	v_lshlrev_b32_e32 v141, 16, v127
	v_and_b32_e32 v127, 0xffff0000, v127
	v_fma_f32 v139, -v139, v141, v139
	v_add_f32_e32 v127, v139, v127
	v_add_f32_e32 v139, v127, v167
	v_lshlrev_b32_e32 v141, 16, v214
	v_mul_f32_e32 v139, v139, v141
	v_cvt_pk_bf16_f32 v139, v139, v139
	v_mad_i64_i32 v[180:181], s[28:29], s73, v178, v[4:5]
	global_store_short v[180:181], v139, off
	v_lshlrev_b32_e32 v139, 16, v125
	v_and_b32_e32 v125, 0xffff0000, v125
	v_fma_f32 v127, -v127, v139, v127
	v_add_f32_e32 v125, v127, v125
	v_add_f32_e32 v127, v125, v163
	s_waitcnt vmcnt(62)
	v_lshlrev_b32_e32 v139, 16, v215
	v_mul_f32_e32 v127, v127, v139
	v_mad_i64_i32 v[180:181], s[28:29], s71, v178, v[4:5]
	v_cvt_pk_bf16_f32 v127, v127, v127
	global_store_short v[180:181], v127, off
	v_lshlrev_b32_e32 v127, 16, v123
	v_and_b32_e32 v123, 0xffff0000, v123
	v_fma_f32 v125, -v125, v127, v125
	v_add_f32_e32 v123, v125, v123
	v_add_f32_e32 v125, v123, v162
	v_lshlrev_b32_e32 v127, 16, v212
	v_mul_f32_e32 v125, v125, v127
	v_mad_i64_i32 v[182:183], s[28:29], s70, v178, v[4:5]
	v_cvt_pk_bf16_f32 v125, v125, v125
	global_store_short v[182:183], v125, off
	v_lshlrev_b32_e32 v125, 16, v121
	v_and_b32_e32 v121, 0xffff0000, v121
	v_fma_f32 v123, -v123, v125, v123
	v_add_f32_e32 v121, v123, v121
	v_add_f32_e32 v123, v121, v161
	s_waitcnt vmcnt(62)
; __device__ __forceinline__ float bf2f(unsigned short b) { return __uint_as_float(((unsigned)b) << 16); }
; __device__ __forceinline__ unsigned cvt_pk_bf16(float lo, float hi) { unsigned r; asm volatile("v_cvt_pk_bf16_f32 %0, %1, %2" : "=v"(r) : "v"(lo), "v"(hi)); return r; }
; __device__ __forceinline__ void lru_scan(const Params& P, int l) {
;     ...
;         { float hh = hin[1];
; #pragma unroll
;             for (int p = 63; p >= 0; --p) { const float om = __uint_as_float(w[p].y << 16), bb = __uint_as_float(w[p].y & 0xffff0000u); hh = (hh - om * hh) + bb;
;                 const float yo = (hf[p] + hh) * bf2f(gar[p]); Y[(size_t)(r0 + p) * YW + c] = (bf16_t)cvt_pk_bf16(yo, yo); } }
	v_lshlrev_b32_e32 v125, 16, v213
	v_mul_f32_e32 v123, v123, v125
	v_mad_i64_i32 v[180:181], s[28:29], s69, v178, v[4:5]
	v_cvt_pk_bf16_f32 v123, v123, v123
	global_store_short v[180:181], v123, off
	v_lshlrev_b32_e32 v123, 16, v119
	v_and_b32_e32 v119, 0xffff0000, v119
	v_fma_f32 v121, -v121, v123, v121
	v_add_f32_e32 v119, v121, v119
	v_add_f32_e32 v121, v119, v160
	v_lshlrev_b32_e32 v123, 16, v210
	v_mul_f32_e32 v121, v121, v123
	v_mad_i64_i32 v[194:195], s[28:29], s68, v178, v[4:5]
	v_cvt_pk_bf16_f32 v121, v121, v121
	global_store_short v[194:195], v121, off
	v_lshlrev_b32_e32 v121, 16, v117
	v_and_b32_e32 v117, 0xffff0000, v117
	v_fma_f32 v119, -v119, v121, v119
	v_add_f32_e32 v117, v119, v117
	v_add_f32_e32 v119, v117, v159
	s_waitcnt vmcnt(62)
	v_lshlrev_b32_e32 v121, 16, v211
	v_mul_f32_e32 v119, v119, v121
	v_cvt_pk_bf16_f32 v119, v119, v119
	v_mad_i64_i32 v[160:161], s[28:29], s67, v178, v[4:5]
	global_store_short v[160:161], v119, off
	v_lshlrev_b32_e32 v119, 16, v115
	v_and_b32_e32 v115, 0xffff0000, v115
	v_fma_f32 v117, -v117, v119, v117
	v_add_f32_e32 v115, v117, v115
	v_add_f32_e32 v117, v115, v158
	v_lshlrev_b32_e32 v119, 16, v208
	v_mul_f32_e32 v117, v117, v119
	v_cvt_pk_bf16_f32 v117, v117, v117
	v_mad_i64_i32 v[158:159], s[28:29], s66, v178, v[4:5]
	global_store_short v[158:159], v117, off
	v_lshlrev_b32_e32 v117, 16, v113
	v_and_b32_e32 v113, 0xffff0000, v113
	v_fma_f32 v115, -v115, v117, v115
	v_add_f32_e32 v113, v115, v113
	v_add_f32_e32 v115, v113, v157
	s_waitcnt vmcnt(62)
	v_lshlrev_b32_e32 v117, 16, v209
	v_mul_f32_e32 v115, v115, v117
	v_cvt_pk_bf16_f32 v115, v115, v115
	v_mad_i64_i32 v[158:159], s[28:29], s65, v178, v[4:5]
	global_store_short v[158:159], v115, off
	v_lshlrev_b32_e32 v115, 16, v111
	v_and_b32_e32 v111, 0xffff0000, v111
	v_fma_f32 v113, -v113, v115, v113
	v_add_f32_e32 v111, v113, v111
	v_add_f32_e32 v113, v111, v156
	v_lshlrev_b32_e32 v115, 16, v206
	v_mul_f32_e32 v113, v113, v115
	v_cvt_pk_bf16_f32 v113, v113, v113
	v_mad_i64_i32 v[156:157], s[28:29], s64, v178, v[4:5]
	global_store_short v[156:157], v113, off
	v_lshlrev_b32_e32 v113, 16, v109
	v_and_b32_e32 v109, 0xffff0000, v109
	v_fma_f32 v111, -v111, v113, v111
	v_add_f32_e32 v109, v111, v109
	v_add_f32_e32 v111, v109, v155
	s_waitcnt vmcnt(62)
	v_lshlrev_b32_e32 v113, 16, v207
	v_mul_f32_e32 v111, v111, v113
	v_cvt_pk_bf16_f32 v111, v111, v111
	v_mad_i64_i32 v[156:157], s[28:29], s63, v178, v[4:5]
	global_store_short v[156:157], v111, off
	v_lshlrev_b32_e32 v111, 16, v107
	v_and_b32_e32 v107, 0xffff0000, v107
	v_fma_f32 v109, -v109, v111, v109
	v_add_f32_e32 v107, v109, v107
	v_add_f32_e32 v109, v107, v128
	v_lshlrev_b32_e32 v111, 16, v204
	v_mul_f32_e32 v109, v109, v111
	v_cvt_pk_bf16_f32 v109, v109, v109
	v_mad_i64_i32 v[156:157], s[28:29], s62, v178, v[4:5]
	global_store_short v[156:157], v109, off
	v_lshlrev_b32_e32 v109, 16, v105
	v_and_b32_e32 v105, 0xffff0000, v105
	v_fma_f32 v107, -v107, v109, v107
	v_add_f32_e32 v107, v107, v105
	v_add_f32_e32 v104, v107, v104
	s_waitcnt vmcnt(62)
	v_lshlrev_b32_e32 v105, 16, v205
	v_mul_f32_e32 v104, v104, v105
	v_cvt_pk_bf16_f32 v109, v104, v104
	v_mad_i64_i32 v[104:105], s[28:29], s61, v178, v[4:5]
	global_store_short v[104:105], v109, off
	v_lshlrev_b32_e32 v104, 16, v103
	v_and_b32_e32 v103, 0xffff0000, v103
	v_fma_f32 v104, -v107, v104, v107
	v_add_f32_e32 v104, v104, v103
	v_add_f32_e32 v102, v104, v102
	v_lshlrev_b32_e32 v103, 16, v202
	v_mul_f32_e32 v102, v102, v103
	v_cvt_pk_bf16_f32 v105, v102, v102
	v_mad_i64_i32 v[102:103], s[28:29], s60, v178, v[4:5]
	global_store_short v[102:103], v105, off
	v_lshlrev_b32_e32 v102, 16, v101
	v_and_b32_e32 v101, 0xffff0000, v101
	v_fma_f32 v102, -v104, v102, v104
	v_add_f32_e32 v102, v102, v101
	v_add_f32_e32 v100, v102, v100
	s_waitcnt vmcnt(62)
	v_lshlrev_b32_e32 v101, 16, v203
	v_mul_f32_e32 v100, v100, v101
	v_cvt_pk_bf16_f32 v103, v100, v100
	v_mad_i64_i32 v[100:101], s[28:29], s59, v178, v[4:5]
	global_store_short v[100:101], v103, off
	v_lshlrev_b32_e32 v100, 16, v99
	v_and_b32_e32 v99, 0xffff0000, v99
	v_fma_f32 v100, -v102, v100, v102
	v_add_f32_e32 v100, v100, v99
	v_add_f32_e32 v98, v100, v98
	v_lshlrev_b32_e32 v99, 16, v200
	v_mul_f32_e32 v98, v98, v99
	v_cvt_pk_bf16_f32 v101, v98, v98
	v_mad_i64_i32 v[98:99], s[28:29], s58, v178, v[4:5]
	global_store_short v[98:99], v101, off
	v_lshlrev_b32_e32 v98, 16, v97
	v_and_b32_e32 v97, 0xffff0000, v97
	v_fma_f32 v98, -v100, v98, v100
	v_add_f32_e32 v98, v98, v97
	v_add_f32_e32 v96, v98, v96
	s_waitcnt vmcnt(62)
	v_lshlrev_b32_e32 v97, 16, v201
	v_mul_f32_e32 v96, v96, v97
	v_cvt_pk_bf16_f32 v99, v96, v96
	v_mad_i64_i32 v[96:97], s[28:29], s57, v178, v[4:5]
	global_store_short v[96:97], v99, off
	v_lshlrev_b32_e32 v96, 16, v95
	v_and_b32_e32 v95, 0xffff0000, v95
	v_fma_f32 v96, -v98, v96, v98
	v_add_f32_e32 v96, v96, v95
	v_add_f32_e32 v94, v96, v94
	v_lshlrev_b32_e32 v95, 16, v198
	v_mul_f32_e32 v94, v94, v95
	v_cvt_pk_bf16_f32 v97, v94, v94
	v_mad_i64_i32 v[94:95], s[28:29], s56, v178, v[4:5]
	global_store_short v[94:95], v97, off
	v_lshlrev_b32_e32 v94, 16, v93
	v_and_b32_e32 v93, 0xffff0000, v93
	v_fma_f32 v94, -v96, v94, v96
	v_add_f32_e32 v94, v94, v93
	v_add_f32_e32 v92, v92, v94
	s_waitcnt vmcnt(62)
	v_lshlrev_b32_e32 v93, 16, v199
	v_mul_f32_e32 v92, v92, v93
	v_cvt_pk_bf16_f32 v95, v92, v92
	v_mad_i64_i32 v[92:93], s[28:29], s55, v178, v[4:5]
	global_store_short v[92:93], v95, off
	v_lshlrev_b32_e32 v92, 16, v91
	v_and_b32_e32 v91, 0xffff0000, v91
	v_fma_f32 v92, -v94, v92, v94
	v_add_f32_e32 v92, v92, v91
	v_add_f32_e32 v90, v90, v92
	v_lshlrev_b32_e32 v91, 16, v196
	v_mul_f32_e32 v90, v90, v91
	v_cvt_pk_bf16_f32 v93, v90, v90
	v_mad_i64_i32 v[90:91], s[28:29], s54, v178, v[4:5]
	global_store_short v[90:91], v93, off
	v_lshlrev_b32_e32 v90, 16, v89
	v_and_b32_e32 v89, 0xffff0000, v89
	v_fma_f32 v90, -v92, v90, v92
	v_add_f32_e32 v90, v90, v89
	v_add_f32_e32 v88, v88, v90
	s_waitcnt vmcnt(62)
; __device__ __forceinline__ float bf2f(unsigned short b) { return __uint_as_float(((unsigned)b) << 16); }
; __device__ __forceinline__ unsigned cvt_pk_bf16(float lo, float hi) { unsigned r; asm volatile("v_cvt_pk_bf16_f32 %0, %1, %2" : "=v"(r) : "v"(lo), "v"(hi)); return r; }
; __device__ __forceinline__ void lru_scan(const Params& P, int l) {
;     ...
;         { float hh = hin[1];
; #pragma unroll
;             for (int p = 63; p >= 0; --p) { const float om = __uint_as_float(w[p].y << 16), bb = __uint_as_float(w[p].y & 0xffff0000u); hh = (hh - om * hh) + bb;
;                 const float yo = (hf[p] + hh) * bf2f(gar[p]); Y[(size_t)(r0 + p) * YW + c] = (bf16_t)cvt_pk_bf16(yo, yo); } }
	v_lshlrev_b32_e32 v89, 16, v197
	v_mul_f32_e32 v88, v88, v89
	v_cvt_pk_bf16_f32 v91, v88, v88
	v_mad_i64_i32 v[88:89], s[28:29], s53, v178, v[4:5]
	global_store_short v[88:89], v91, off
	v_lshlrev_b32_e32 v88, 16, v87
	v_and_b32_e32 v87, 0xffff0000, v87
	v_fma_f32 v88, -v90, v88, v90
	v_add_f32_e32 v88, v88, v87
	v_add_f32_e32 v86, v86, v88
	v_lshlrev_b32_e32 v87, 16, v222
	v_mul_f32_e32 v86, v86, v87
	v_cvt_pk_bf16_f32 v89, v86, v86
	v_mad_i64_i32 v[86:87], s[28:29], s50, v178, v[4:5]
	global_store_short v[86:87], v89, off
	v_lshlrev_b32_e32 v86, 16, v85
	v_and_b32_e32 v85, 0xffff0000, v85
	v_fma_f32 v86, -v88, v86, v88
	v_add_f32_e32 v86, v86, v85
	v_add_f32_e32 v84, v84, v86
	s_waitcnt vmcnt(62)
	v_lshlrev_b32_e32 v85, 16, v223
	v_mul_f32_e32 v84, v84, v85
	v_cvt_pk_bf16_f32 v87, v84, v84
	v_mad_i64_i32 v[84:85], s[28:29], s47, v178, v[4:5]
	global_store_short v[84:85], v87, off
	v_lshlrev_b32_e32 v84, 16, v83
	v_and_b32_e32 v83, 0xffff0000, v83
	v_fma_f32 v84, -v86, v84, v86
	v_add_f32_e32 v84, v84, v83
	v_add_f32_e32 v82, v82, v84
	v_lshlrev_b32_e32 v83, 16, v224
	v_mul_f32_e32 v82, v82, v83
	v_cvt_pk_bf16_f32 v85, v82, v82
	v_mad_i64_i32 v[82:83], s[28:29], s44, v178, v[4:5]
	global_store_short v[82:83], v85, off
	v_lshlrev_b32_e32 v82, 16, v81
	v_and_b32_e32 v81, 0xffff0000, v81
	v_fma_f32 v82, -v84, v82, v84
	v_add_f32_e32 v82, v82, v81
	v_add_f32_e32 v80, v80, v82
	s_waitcnt vmcnt(62)
	v_lshlrev_b32_e32 v81, 16, v225
	v_mul_f32_e32 v80, v80, v81
	v_cvt_pk_bf16_f32 v83, v80, v80
	v_mad_i64_i32 v[80:81], s[28:29], s41, v178, v[4:5]
	global_store_short v[80:81], v83, off
	v_lshlrev_b32_e32 v80, 16, v79
	v_and_b32_e32 v79, 0xffff0000, v79
	v_fma_f32 v80, -v82, v80, v82
	v_add_f32_e32 v80, v80, v79
	v_add_f32_e32 v78, v78, v80
	v_lshlrev_b32_e32 v79, 16, v193
	v_mul_f32_e32 v78, v78, v79
	v_cvt_pk_bf16_f32 v81, v78, v78
	v_mad_i64_i32 v[78:79], s[28:29], s39, v178, v[4:5]
	global_store_short v[78:79], v81, off
	v_lshlrev_b32_e32 v78, 16, v77
	v_and_b32_e32 v77, 0xffff0000, v77
	v_fma_f32 v78, -v80, v78, v80
	v_add_f32_e32 v78, v78, v77
	v_add_f32_e32 v76, v76, v78
	s_waitcnt vmcnt(62)
	v_lshlrev_b32_e32 v77, 16, v192
	v_mul_f32_e32 v76, v76, v77
	v_cvt_pk_bf16_f32 v79, v76, v76
	v_mad_i64_i32 v[76:77], s[28:29], s31, v178, v[4:5]
	global_store_short v[76:77], v79, off
	v_lshlrev_b32_e32 v76, 16, v75
	v_and_b32_e32 v75, 0xffff0000, v75
	v_fma_f32 v76, -v78, v76, v78
	v_add_f32_e32 v76, v76, v75
	v_add_f32_e32 v74, v74, v76
	v_lshlrev_b32_e32 v75, 16, v189
	v_mul_f32_e32 v74, v74, v75
	v_cvt_pk_bf16_f32 v77, v74, v74
	v_mad_i64_i32 v[74:75], s[28:29], s27, v178, v[4:5]
	global_store_short v[74:75], v77, off
	v_lshlrev_b32_e32 v74, 16, v73
	v_and_b32_e32 v73, 0xffff0000, v73
	v_fma_f32 v74, -v76, v74, v76
	v_add_f32_e32 v74, v74, v73
	v_add_f32_e32 v72, v72, v74
	s_waitcnt vmcnt(62)
	v_lshlrev_b32_e32 v73, 16, v191
	v_mul_f32_e32 v72, v72, v73
	v_cvt_pk_bf16_f32 v75, v72, v72
	v_mad_i64_i32 v[72:73], s[28:29], s21, v178, v[4:5]
	global_store_short v[72:73], v75, off
	v_lshlrev_b32_e32 v72, 16, v71
	v_and_b32_e32 v71, 0xffff0000, v71
	v_fma_f32 v72, -v74, v72, v74
	v_add_f32_e32 v72, v72, v71
	v_add_f32_e32 v70, v70, v72
	v_lshlrev_b32_e32 v71, 16, v188
	v_mul_f32_e32 v70, v70, v71
	v_cvt_pk_bf16_f32 v73, v70, v70
	v_mad_i64_i32 v[70:71], s[28:29], s17, v178, v[4:5]
	global_store_short v[70:71], v73, off
	v_lshlrev_b32_e32 v70, 16, v69
	v_and_b32_e32 v69, 0xffff0000, v69
	v_fma_f32 v70, -v72, v70, v72
	v_add_f32_e32 v70, v70, v69
	v_add_f32_e32 v68, v68, v70
	s_waitcnt vmcnt(62)
	v_lshlrev_b32_e32 v69, 16, v187
	v_mul_f32_e32 v68, v68, v69
	v_cvt_pk_bf16_f32 v71, v68, v68
	v_mad_i64_i32 v[68:69], s[16:17], s16, v178, v[4:5]
	global_store_short v[68:69], v71, off
	v_lshlrev_b32_e32 v68, 16, v67
	v_and_b32_e32 v67, 0xffff0000, v67
	v_fma_f32 v68, -v70, v68, v70
	v_add_f32_e32 v68, v68, v67
	v_add_f32_e32 v66, v66, v68
	v_lshlrev_b32_e32 v67, 16, v185
	v_mul_f32_e32 v66, v66, v67
	v_cvt_pk_bf16_f32 v69, v66, v66
	v_mad_i64_i32 v[66:67], s[16:17], s15, v178, v[4:5]
	global_store_short v[66:67], v69, off
	v_lshlrev_b32_e32 v66, 16, v65
	v_and_b32_e32 v65, 0xffff0000, v65
	v_fma_f32 v66, -v68, v66, v68
	v_add_f32_e32 v66, v66, v65
	v_add_f32_e32 v64, v64, v66
	s_waitcnt vmcnt(62)
	v_lshlrev_b32_e32 v65, 16, v184
	v_mul_f32_e32 v64, v64, v65
	v_cvt_pk_bf16_f32 v67, v64, v64
	v_mad_i64_i32 v[64:65], s[14:15], s14, v178, v[4:5]
	global_store_short v[64:65], v67, off
	v_lshlrev_b32_e32 v64, 16, v63
	v_and_b32_e32 v63, 0xffff0000, v63
	v_fma_f32 v64, -v66, v64, v66
	v_add_f32_e32 v64, v64, v63
	v_add_f32_e32 v62, v62, v64
	v_lshlrev_b32_e32 v63, 16, v166
	v_mul_f32_e32 v62, v62, v63
	v_cvt_pk_bf16_f32 v65, v62, v62
	v_mad_i64_i32 v[62:63], s[14:15], s13, v178, v[4:5]
	global_store_short v[62:63], v65, off
	v_lshlrev_b32_e32 v62, 16, v61
	v_and_b32_e32 v61, 0xffff0000, v61
	v_fma_f32 v62, -v64, v62, v64
	v_add_f32_e32 v62, v62, v61
	v_add_f32_e32 v60, v60, v62
	s_waitcnt vmcnt(62)
	v_lshlrev_b32_e32 v61, 16, v165
	v_mul_f32_e32 v60, v60, v61
	v_cvt_pk_bf16_f32 v63, v60, v60
	v_mad_i64_i32 v[60:61], s[12:13], s12, v178, v[4:5]
	global_store_short v[60:61], v63, off
	v_lshlrev_b32_e32 v60, 16, v59
	v_and_b32_e32 v59, 0xffff0000, v59
	v_fma_f32 v60, -v62, v60, v62
	v_add_f32_e32 v60, v60, v59
	v_add_f32_e32 v58, v58, v60
	v_lshlrev_b32_e32 v59, 16, v154
	v_mul_f32_e32 v58, v58, v59
	v_cvt_pk_bf16_f32 v61, v58, v58
	v_mad_i64_i32 v[58:59], s[12:13], s11, v178, v[4:5]
	global_store_short v[58:59], v61, off
	v_lshlrev_b32_e32 v58, 16, v57
	v_and_b32_e32 v57, 0xffff0000, v57
	v_fma_f32 v58, -v60, v58, v60
	v_add_f32_e32 v58, v58, v57
	v_add_f32_e32 v56, v56, v58
	s_waitcnt vmcnt(62)
; __device__ __forceinline__ float bf2f(unsigned short b) { return __uint_as_float(((unsigned)b) << 16); }
; __device__ __forceinline__ unsigned cvt_pk_bf16(float lo, float hi) { unsigned r; asm volatile("v_cvt_pk_bf16_f32 %0, %1, %2" : "=v"(r) : "v"(lo), "v"(hi)); return r; }
; __device__ __forceinline__ void lru_scan(const Params& P, int l) {
;     ...
;         { float hh = hin[1];
; #pragma unroll
;             for (int p = 63; p >= 0; --p) { const float om = __uint_as_float(w[p].y << 16), bb = __uint_as_float(w[p].y & 0xffff0000u); hh = (hh - om * hh) + bb;
;                 const float yo = (hf[p] + hh) * bf2f(gar[p]); Y[(size_t)(r0 + p) * YW + c] = (bf16_t)cvt_pk_bf16(yo, yo); } }
	v_lshlrev_b32_e32 v57, 16, v164
	v_mul_f32_e32 v56, v56, v57
	v_cvt_pk_bf16_f32 v59, v56, v56
	v_mad_i64_i32 v[56:57], s[10:11], s10, v178, v[4:5]
	global_store_short v[56:57], v59, off
	v_lshlrev_b32_e32 v56, 16, v55
	v_and_b32_e32 v55, 0xffff0000, v55
	v_fma_f32 v56, -v58, v56, v58
	v_add_f32_e32 v56, v56, v55
	v_add_f32_e32 v54, v54, v56
	v_lshlrev_b32_e32 v55, 16, v153
	v_mul_f32_e32 v54, v54, v55
	v_cvt_pk_bf16_f32 v57, v54, v54
	v_mad_i64_i32 v[54:55], s[10:11], s9, v178, v[4:5]
	global_store_short v[54:55], v57, off
	v_lshlrev_b32_e32 v54, 16, v53
	v_and_b32_e32 v53, 0xffff0000, v53
	v_fma_f32 v54, -v56, v54, v56
	v_add_f32_e32 v54, v54, v53
	v_add_f32_e32 v52, v52, v54
	s_waitcnt vmcnt(62)
	v_lshlrev_b32_e32 v53, 16, v152
	v_mul_f32_e32 v52, v52, v53
	v_cvt_pk_bf16_f32 v55, v52, v52
	v_mad_i64_i32 v[52:53], s[8:9], s8, v178, v[4:5]
	global_store_short v[52:53], v55, off
	v_lshlrev_b32_e32 v52, 16, v51
	v_and_b32_e32 v51, 0xffff0000, v51
	v_fma_f32 v52, -v54, v52, v54
	v_add_f32_e32 v52, v52, v51
	v_add_f32_e32 v50, v50, v52
	v_lshlrev_b32_e32 v51, 16, v151
	v_mul_f32_e32 v50, v50, v51
	v_cvt_pk_bf16_f32 v53, v50, v50
	v_mad_i64_i32 v[50:51], s[8:9], s5, v178, v[4:5]
	global_store_short v[50:51], v53, off
	v_lshlrev_b32_e32 v50, 16, v49
	v_and_b32_e32 v49, 0xffff0000, v49
	v_fma_f32 v50, -v52, v50, v52
	v_add_f32_e32 v50, v50, v49
	v_add_f32_e32 v48, v48, v50
	s_waitcnt vmcnt(62)
	v_lshlrev_b32_e32 v49, 16, v150
	v_mul_f32_e32 v48, v48, v49
	v_cvt_pk_bf16_f32 v51, v48, v48
	v_mad_i64_i32 v[48:49], s[4:5], s4, v178, v[4:5]
	global_store_short v[48:49], v51, off
	v_lshlrev_b32_e32 v48, 16, v47
	v_and_b32_e32 v47, 0xffff0000, v47
	v_fma_f32 v48, -v50, v48, v50
	v_add_f32_e32 v48, v48, v47
	v_add_f32_e32 v46, v46, v48
	v_lshlrev_b32_e32 v47, 16, v149
	v_mul_f32_e32 v46, v46, v47
	v_cvt_pk_bf16_f32 v49, v46, v46
	v_mad_i64_i32 v[46:47], s[4:5], s3, v178, v[4:5]
	global_store_short v[46:47], v49, off
	v_lshlrev_b32_e32 v46, 16, v45
	v_and_b32_e32 v45, 0xffff0000, v45
	v_fma_f32 v46, -v48, v46, v48
	v_add_f32_e32 v46, v46, v45
	v_add_f32_e32 v44, v44, v46
	s_waitcnt vmcnt(62)
	v_lshlrev_b32_e32 v45, 16, v148
	v_mul_f32_e32 v44, v44, v45
	v_cvt_pk_bf16_f32 v47, v44, v44
	v_mad_i64_i32 v[44:45], s[2:3], s2, v178, v[4:5]
	global_store_short v[44:45], v47, off
	v_lshlrev_b32_e32 v44, 16, v43
	v_and_b32_e32 v43, 0xffff0000, v43
	v_fma_f32 v44, -v46, v44, v46
	v_add_f32_e32 v44, v44, v43
	v_add_f32_e32 v42, v42, v44
	v_lshlrev_b32_e32 v43, 16, v146
	v_mul_f32_e32 v42, v42, v43
	v_cvt_pk_bf16_f32 v45, v42, v42
	v_mad_i64_i32 v[42:43], s[2:3], s1, v178, v[4:5]
	global_store_short v[42:43], v45, off
	v_lshlrev_b32_e32 v42, 16, v41
	v_and_b32_e32 v41, 0xffff0000, v41
	v_fma_f32 v42, -v44, v42, v44
	v_add_f32_e32 v42, v42, v41
	v_add_f32_e32 v40, v40, v42
	s_waitcnt vmcnt(62)
	v_lshlrev_b32_e32 v41, 16, v147
	v_mul_f32_e32 v40, v40, v41
	v_cvt_pk_bf16_f32 v43, v40, v40
	v_mad_i64_i32 v[40:41], s[0:1], s0, v178, v[4:5]
	global_store_short v[40:41], v43, off
	v_lshlrev_b32_e32 v40, 16, v39
	v_and_b32_e32 v39, 0xffff0000, v39
	v_fma_f32 v40, -v42, v40, v42
	v_add_f32_e32 v40, v40, v39
	v_add_f32_e32 v38, v38, v40
	v_lshlrev_b32_e32 v39, 16, v145
	v_mul_f32_e32 v38, v38, v39
	v_cvt_pk_bf16_f32 v41, v38, v38
	v_mad_i64_i32 v[38:39], s[0:1], s52, v178, v[4:5]
	global_store_short v[38:39], v41, off
	v_lshlrev_b32_e32 v38, 16, v37
	v_and_b32_e32 v37, 0xffff0000, v37
	v_fma_f32 v38, -v40, v38, v40
	v_add_f32_e32 v38, v38, v37
	v_add_f32_e32 v36, v36, v38
	s_waitcnt vmcnt(62)
	v_lshlrev_b32_e32 v37, 16, v144
	v_mul_f32_e32 v36, v36, v37
	v_cvt_pk_bf16_f32 v39, v36, v36
	v_mad_i64_i32 v[36:37], s[0:1], s51, v178, v[4:5]
	global_store_short v[36:37], v39, off
	v_lshlrev_b32_e32 v36, 16, v35
	v_and_b32_e32 v35, 0xffff0000, v35
	v_fma_f32 v36, -v38, v36, v38
	v_add_f32_e32 v36, v36, v35
	v_add_f32_e32 v34, v34, v36
	v_lshlrev_b32_e32 v35, 16, v142
	v_mul_f32_e32 v34, v34, v35
	v_cvt_pk_bf16_f32 v37, v34, v34
	v_mad_i64_i32 v[34:35], s[0:1], s49, v178, v[4:5]
	global_store_short v[34:35], v37, off
	v_lshlrev_b32_e32 v34, 16, v33
	v_and_b32_e32 v33, 0xffff0000, v33
	v_fma_f32 v34, -v36, v34, v36
	v_add_f32_e32 v34, v34, v33
	v_add_f32_e32 v32, v32, v34
	s_waitcnt vmcnt(62)
	v_lshlrev_b32_e32 v33, 16, v140
	v_mul_f32_e32 v32, v32, v33
	v_cvt_pk_bf16_f32 v35, v32, v32
	v_mad_i64_i32 v[32:33], s[0:1], s48, v178, v[4:5]
	global_store_short v[32:33], v35, off
	v_lshlrev_b32_e32 v32, 16, v31
	v_and_b32_e32 v31, 0xffff0000, v31
	v_fma_f32 v32, -v34, v32, v34
	v_add_f32_e32 v32, v32, v31
	v_add_f32_e32 v30, v30, v32
	v_lshlrev_b32_e32 v31, 16, v138
	v_mul_f32_e32 v30, v30, v31
	v_cvt_pk_bf16_f32 v33, v30, v30
	v_mad_i64_i32 v[30:31], s[0:1], s46, v178, v[4:5]
	global_store_short v[30:31], v33, off
	v_lshlrev_b32_e32 v30, 16, v29
	v_and_b32_e32 v29, 0xffff0000, v29
	v_fma_f32 v30, -v32, v30, v32
	v_add_f32_e32 v30, v30, v29
	v_add_f32_e32 v28, v28, v30
	s_waitcnt vmcnt(62)
; __device__ __forceinline__ float bf2f(unsigned short b) { return __uint_as_float(((unsigned)b) << 16); }
; __device__ __forceinline__ unsigned cvt_pk_bf16(float lo, float hi) { unsigned r; asm volatile("v_cvt_pk_bf16_f32 %0, %1, %2" : "=v"(r) : "v"(lo), "v"(hi)); return r; }
; __device__ __forceinline__ void lru_scan(const Params& P, int l) {
;     ...
;     for (int it = blockIdx.x; it < nitems; it += gridDim.x) {
;     ...
;         { float hh = hin[1];
; #pragma unroll
;             for (int p = 63; p >= 0; --p) { const float om = __uint_as_float(w[p].y << 16), bb = __uint_as_float(w[p].y & 0xffff0000u); hh = (hh - om * hh) + bb;
;                 const float yo = (hf[p] + hh) * bf2f(gar[p]); Y[(size_t)(r0 + p) * YW + c] = (bf16_t)cvt_pk_bf16(yo, yo); } }
	v_lshlrev_b32_e32 v29, 16, v126
	v_mul_f32_e32 v28, v28, v29
	v_cvt_pk_bf16_f32 v31, v28, v28
	v_mad_i64_i32 v[28:29], s[0:1], s45, v178, v[4:5]
	global_store_short v[28:29], v31, off
	v_lshlrev_b32_e32 v28, 16, v27
	v_and_b32_e32 v27, 0xffff0000, v27
	v_fma_f32 v28, -v30, v28, v30
	v_add_f32_e32 v28, v28, v27
	v_add_f32_e32 v26, v26, v28
	v_lshlrev_b32_e32 v27, 16, v124
	v_mul_f32_e32 v26, v26, v27
	v_cvt_pk_bf16_f32 v29, v26, v26
	v_mad_i64_i32 v[26:27], s[0:1], s43, v178, v[4:5]
	global_store_short v[26:27], v29, off
	v_lshlrev_b32_e32 v26, 16, v25
	v_and_b32_e32 v25, 0xffff0000, v25
	v_fma_f32 v26, -v28, v26, v28
	v_add_f32_e32 v26, v26, v25
	v_add_f32_e32 v24, v24, v26
	s_waitcnt vmcnt(62)
	v_lshlrev_b32_e32 v25, 16, v122
	v_mul_f32_e32 v24, v24, v25
	v_cvt_pk_bf16_f32 v27, v24, v24
	v_mad_i64_i32 v[24:25], s[0:1], s42, v178, v[4:5]
	global_store_short v[24:25], v27, off
	v_lshlrev_b32_e32 v24, 16, v23
	v_and_b32_e32 v23, 0xffff0000, v23
	v_fma_f32 v24, -v26, v24, v26
	v_add_f32_e32 v24, v24, v23
	v_add_f32_e32 v22, v22, v24
	v_lshlrev_b32_e32 v23, 16, v120
	v_mul_f32_e32 v22, v22, v23
	v_cvt_pk_bf16_f32 v25, v22, v22
	v_mad_i64_i32 v[22:23], s[0:1], s40, v178, v[4:5]
	global_store_short v[22:23], v25, off
	v_lshlrev_b32_e32 v22, 16, v21
	v_and_b32_e32 v21, 0xffff0000, v21
	v_fma_f32 v22, -v24, v22, v24
	v_add_f32_e32 v22, v22, v21
	v_add_f32_e32 v20, v20, v22
	s_waitcnt vmcnt(62)
	v_lshlrev_b32_e32 v21, 16, v118
	v_mul_f32_e32 v20, v20, v21
	v_cvt_pk_bf16_f32 v23, v20, v20
	v_mad_i64_i32 v[20:21], s[0:1], s35, v178, v[4:5]
	global_store_short v[20:21], v23, off
	v_lshlrev_b32_e32 v20, 16, v19
	v_and_b32_e32 v19, 0xffff0000, v19
	v_fma_f32 v20, -v22, v20, v22
	v_add_f32_e32 v20, v20, v19
	v_add_f32_e32 v18, v18, v20
	v_lshlrev_b32_e32 v19, 16, v116
	v_mul_f32_e32 v18, v18, v19
	v_cvt_pk_bf16_f32 v21, v18, v18
	v_mad_i64_i32 v[18:19], s[0:1], s34, v178, v[4:5]
	global_store_short v[18:19], v21, off
	v_lshlrev_b32_e32 v18, 16, v17
	v_and_b32_e32 v17, 0xffff0000, v17
	v_fma_f32 v18, -v20, v18, v20
	v_add_f32_e32 v18, v18, v17
	v_add_f32_e32 v16, v16, v18
	s_waitcnt vmcnt(62)
	v_lshlrev_b32_e32 v17, 16, v114
	v_mul_f32_e32 v16, v16, v17
	v_cvt_pk_bf16_f32 v19, v16, v16
	v_mad_i64_i32 v[16:17], s[0:1], s30, v178, v[4:5]
	global_store_short v[16:17], v19, off
	v_lshlrev_b32_e32 v16, 16, v15
	v_and_b32_e32 v15, 0xffff0000, v15
	v_fma_f32 v16, -v18, v16, v18
	v_add_f32_e32 v16, v16, v15
	v_add_f32_e32 v14, v14, v16
	v_lshlrev_b32_e32 v15, 16, v112
	v_mul_f32_e32 v14, v14, v15
	v_cvt_pk_bf16_f32 v17, v14, v14
	v_mad_i64_i32 v[14:15], s[0:1], s26, v178, v[4:5]
	global_store_short v[14:15], v17, off
	v_lshlrev_b32_e32 v14, 16, v13
	v_and_b32_e32 v13, 0xffff0000, v13
	v_fma_f32 v14, -v16, v14, v16
	v_add_f32_e32 v14, v14, v13
	v_add_f32_e32 v12, v12, v14
	s_waitcnt vmcnt(62)
	v_lshlrev_b32_e32 v13, 16, v110
	v_mul_f32_e32 v12, v12, v13
	v_cvt_pk_bf16_f32 v15, v12, v12
	v_mad_i64_i32 v[12:13], s[0:1], s25, v178, v[4:5]
	global_store_short v[12:13], v15, off
	v_lshlrev_b32_e32 v12, 16, v11
	v_and_b32_e32 v11, 0xffff0000, v11
	v_fma_f32 v12, -v14, v12, v14
	v_add_f32_e32 v12, v12, v11
	v_add_f32_e32 v10, v10, v12
	v_lshlrev_b32_e32 v11, 16, v108
	v_mul_f32_e32 v10, v10, v11
	v_cvt_pk_bf16_f32 v13, v10, v10
	v_mad_i64_i32 v[10:11], s[0:1], s19, v178, v[4:5]
	global_store_short v[10:11], v13, off
	v_lshlrev_b32_e32 v10, 16, v9
	v_and_b32_e32 v9, 0xffff0000, v9
	v_fma_f32 v10, -v12, v10, v12
	v_add_f32_e32 v9, v10, v9
	v_add_f32_e32 v8, v8, v9
	s_waitcnt vmcnt(62)
	v_lshlrev_b32_e32 v9, 16, v106
	v_mul_f32_e32 v8, v8, v9
	v_readlane_b32 s64, v254, 2
	v_readlane_b32 s90, v254, 30
	v_cvt_pk_bf16_f32 v10, v8, v8
	v_mad_i64_i32 v[8:9], s[0:1], s38, v178, v[4:5]
	v_readlane_b32 s17, v255, 37
	v_readlane_b32 s74, v254, 12
	v_readlane_b32 s75, v254, 13
	v_readlane_b32 s88, v254, 24
	v_readlane_b32 s92, v254, 26
	s_add_i32 s17, s17, s90
	v_readlane_b32 s0, v254, 58
	v_readlane_b32 s65, v254, 3
	v_readlane_b32 s30, v254, 34
	v_readlane_b32 s28, v254, 18
	v_readlane_b32 s34, v254, 20
	v_readlane_b32 s60, v254, 22
	v_readlane_b32 s74, v255, 34
	v_readlane_b32 s26, v255, 32
	v_readlane_b32 s89, v254, 25
	v_readlane_b32 s93, v254, 27
	v_readlane_b32 s94, v254, 28
	v_readlane_b32 s95, v254, 29
	v_readlane_b32 s96, v254, 32
	s_cmp_ge_i32 s17, s0
	v_readlane_b32 s76, v254, 14
	v_readlane_b32 s77, v254, 15
	v_readlane_b32 s31, v254, 35
	v_readlane_b32 s29, v254, 19
	v_readlane_b32 s35, v254, 21
	v_readlane_b32 s61, v254, 23
	s_mov_b32 s25, 0x8000
	s_movk_i32 s19, 0x7fff
	v_readlane_b32 s75, v255, 35
	s_mov_b64 s[64:65], 0x800
	v_readlane_b32 s27, v255, 33
	v_readlane_b32 s91, v254, 31
	v_readlane_b32 s97, v254, 33
	global_store_short v[8:9], v10, off
	v_readlane_b32 s66, v254, 4
	v_readlane_b32 s67, v254, 5
	v_readlane_b32 s68, v254, 6
	v_readlane_b32 s69, v254, 7
	v_readlane_b32 s70, v254, 8
	v_readlane_b32 s71, v254, 9
	v_readlane_b32 s72, v254, 10
	v_readlane_b32 s73, v254, 11
	v_readlane_b32 s78, v254, 16
	v_readlane_b32 s79, v254, 17
	s_cbranch_scc1 .LBB0_716

; #define GAS __attribute__((address_space(1)))
; __device__ __forceinline__ void lru_scan(const Params& P, int l) {
;     ...
;         for (int d = 0; d < 2; ++d) { const int rank = d == 0 ? q : (q < 4 ? 3 - q : 71 - q); float hh = 0.f;
; #pragma unroll 1
;             for (int r8 = 0; r8 < rank; r8 += 34) { float aa[34], bv[34];
; #pragma unroll
;                 for (int k = 0; k < 34; ++k) { const int rho = r8 + k; const bool ok = rho < rank; const int rr = ok ? rho : 0; const int qq = d == 0 ? rr : (rr < 4 ? 3 - rr : 71 - rr);
;                     const GAS float* ap = AGG + ((size_t)((b * NQ + qq) * 2 + d) * 2) * 512 + c; const float a0 = ap[0], b0 = ap[512]; aa[k] = ok ? a0 : 1.f; bv[k] = ok ? b0 : 0.f; }
; #pragma unroll
;                 for (int k = 0; k < 34; ++k) hh = aa[k] * hh + bv[k]; }
;             hin[d] = hh; }
.LBB0_709:
	s_ashr_i32 s9, s8, 31
	s_add_i32 s4, s1, 1
	s_lshl_b64 s[2:3], s[8:9], 12
	s_cmp_lt_u32 s4, s0
	s_cselect_b64 s[44:45], -1, 0
	v_lshl_add_u64 v[8:9], v[0:1], 0, s[2:3]
	s_and_b64 s[2:3], s[44:45], exec
	s_cselect_b32 s2, s4, 0
	s_add_i32 s2, s2, s96
	s_lshl_b32 s2, s2, 1
	s_ashr_i32 s3, s2, 31
	s_add_i32 s4, s1, 2
	s_lshl_b64 s[2:3], s[2:3], 12
	global_load_dword v14, v[8:9], off
	global_load_dword v16, v[8:9], off offset:2048
	v_lshl_add_u64 v[8:9], v[0:1], 0, s[2:3]
	s_cmp_lt_u32 s4, s0
	global_load_dword v15, v[8:9], off
	global_load_dword v17, v[8:9], off offset:2048
	s_cselect_b64 s[46:47], -1, 0
	s_and_b64 s[2:3], s[46:47], exec
	s_cselect_b32 s2, s4, 0
	s_add_i32 s2, s2, s96
	s_lshl_b32 s2, s2, 1
	s_ashr_i32 s3, s2, 31
	s_add_i32 s4, s1, 3
	s_lshl_b64 s[2:3], s[2:3], 12
	v_lshl_add_u64 v[8:9], v[0:1], 0, s[2:3]
	s_cmp_lt_u32 s4, s0
	global_load_dword v18, v[8:9], off
	global_load_dword v19, v[8:9], off offset:2048
	s_cselect_b64 s[48:49], -1, 0
	s_and_b64 s[2:3], s[48:49], exec
	s_cselect_b32 s2, s4, 0
	s_add_i32 s2, s2, s96
	s_lshl_b32 s2, s2, 1
	s_ashr_i32 s3, s2, 31
	s_add_i32 s4, s1, 4
	s_lshl_b64 s[2:3], s[2:3], 12
	v_lshl_add_u64 v[8:9], v[0:1], 0, s[2:3]
	s_cmp_lt_u32 s4, s0
	global_load_dword v20, v[8:9], off
	global_load_dword v21, v[8:9], off offset:2048
	s_cselect_b64 s[50:51], -1, 0
	s_and_b64 s[2:3], s[50:51], exec
	s_cselect_b32 s2, s4, 0
	s_add_i32 s2, s2, s96
	s_lshl_b32 s2, s2, 1
	s_ashr_i32 s3, s2, 31
	s_add_i32 s4, s1, 5
	s_lshl_b64 s[2:3], s[2:3], 12
	v_lshl_add_u64 v[8:9], v[0:1], 0, s[2:3]
	s_cmp_lt_u32 s4, s0
	global_load_dword v22, v[8:9], off
	global_load_dword v23, v[8:9], off offset:2048
	s_cselect_b64 s[52:53], -1, 0
	s_and_b64 s[2:3], s[52:53], exec
	s_cselect_b32 s2, s4, 0
	s_add_i32 s2, s2, s96
	s_lshl_b32 s2, s2, 1
	s_ashr_i32 s3, s2, 31
	s_add_i32 s4, s1, 6
	s_lshl_b64 s[2:3], s[2:3], 12
	v_lshl_add_u64 v[8:9], v[0:1], 0, s[2:3]
	s_cmp_lt_u32 s4, s0
	global_load_dword v24, v[8:9], off
	global_load_dword v25, v[8:9], off offset:2048
	s_cselect_b64 s[54:55], -1, 0
	s_and_b64 s[2:3], s[54:55], exec
	s_cselect_b32 s2, s4, 0
	s_add_i32 s2, s2, s96
	s_lshl_b32 s2, s2, 1
	s_ashr_i32 s3, s2, 31
	s_add_i32 s4, s1, 7
	s_lshl_b64 s[2:3], s[2:3], 12
	v_lshl_add_u64 v[8:9], v[0:1], 0, s[2:3]
	s_cmp_lt_u32 s4, s0
	global_load_dword v26, v[8:9], off
	global_load_dword v27, v[8:9], off offset:2048
	s_cselect_b64 s[56:57], -1, 0
	s_and_b64 s[2:3], s[56:57], exec
	s_cselect_b32 s2, s4, 0
	s_add_i32 s2, s2, s96
	s_lshl_b32 s2, s2, 1
	s_ashr_i32 s3, s2, 31
	s_add_i32 s4, s1, 8
	s_lshl_b64 s[2:3], s[2:3], 12
	v_lshl_add_u64 v[8:9], v[0:1], 0, s[2:3]
	s_cmp_lt_u32 s4, s0
	global_load_dword v28, v[8:9], off
	global_load_dword v29, v[8:9], off offset:2048
	s_cselect_b64 vcc, -1, 0
	s_and_b64 s[2:3], vcc, exec
	s_cselect_b32 s2, s4, 0
	s_add_i32 s2, s2, s96
	s_lshl_b32 s2, s2, 1
	s_ashr_i32 s3, s2, 31
	s_add_i32 s4, s1, 9
	s_lshl_b64 s[2:3], s[2:3], 12
	s_cmp_lt_u32 s4, s0
	s_cselect_b64 s[38:39], -1, 0
	v_lshl_add_u64 v[8:9], v[0:1], 0, s[2:3]
	s_and_b64 s[2:3], s[38:39], exec
	s_cselect_b32 s2, s4, 0
	s_add_i32 s2, s2, s96
	s_lshl_b32 s2, s2, 1
	s_ashr_i32 s3, s2, 31
	s_add_i32 s4, s1, 10
	s_lshl_b64 s[2:3], s[2:3], 12
	s_cmp_lt_u32 s4, s0
	s_cselect_b64 s[40:41], -1, 0
	v_lshl_add_u64 v[10:11], v[0:1], 0, s[2:3]
	s_and_b64 s[2:3], s[40:41], exec
	s_cselect_b32 s3, s4, 0
	s_add_i32 s3, s3, s96
	s_lshl_b32 s4, s3, 1
	s_ashr_i32 s5, s4, 31
	s_add_i32 s2, s1, 11
	s_lshl_b64 s[4:5], s[4:5], 12
	s_cmp_lt_u32 s2, s0
	s_cselect_b64 s[42:43], -1, 0
	v_lshl_add_u64 v[30:31], v[0:1], 0, s[4:5]
	s_and_b64 s[4:5], s[42:43], exec
	s_cselect_b32 s2, s2, 0
	s_add_i32 s2, s2, s96
	s_lshl_b32 s2, s2, 1
	s_ashr_i32 s3, s2, 31
	s_add_i32 s4, s1, 12
	s_lshl_b64 s[2:3], s[2:3], 12
	s_cmp_lt_u32 s4, s0
	s_waitcnt vmcnt(0)
	v_cndmask_b32_e64 v32, 1.0, v15, s[44:45]
	v_cndmask_b32_e64 v33, 0, v17, s[44:45]
	s_cselect_b64 s[44:45], -1, 0
	global_load_dword v13, v[8:9], off
	global_load_dword v8, v[8:9], off offset:2048
	global_load_dword v9, v[10:11], off
	global_load_dword v10, v[10:11], off offset:2048
	global_load_dword v11, v[30:31], off
	global_load_dword v12, v[30:31], off offset:2048
	v_lshl_add_u64 v[30:31], v[0:1], 0, s[2:3]
	s_and_b64 s[2:3], s[44:45], exec
	s_cselect_b32 s2, s4, 0
	s_add_i32 s2, s2, s96
	s_lshl_b32 s2, s2, 1
	s_ashr_i32 s3, s2, 31
	s_add_i32 s4, s1, 13
	s_lshl_b64 s[2:3], s[2:3], 12
	v_fmac_f32_e32 v16, v128, v14
	s_cmp_lt_u32 s4, s0
	v_fmac_f32_e32 v33, v16, v32
	v_cndmask_b32_e64 v18, 1.0, v18, s[46:47]
	v_cndmask_b32_e64 v32, 0, v19, s[46:47]
	s_cselect_b64 s[46:47], -1, 0
	global_load_dword v14, v[30:31], off
	global_load_dword v15, v[30:31], off offset:2048
	v_lshl_add_u64 v[30:31], v[0:1], 0, s[2:3]
	s_and_b64 s[2:3], s[46:47], exec
	s_cselect_b32 s2, s4, 0
	s_add_i32 s2, s2, s96
	s_lshl_b32 s2, s2, 1
	s_ashr_i32 s3, s2, 31
	s_add_i32 s4, s1, 14
	s_lshl_b64 s[2:3], s[2:3], 12
	s_cmp_lt_u32 s4, s0
	v_fmac_f32_e32 v32, v33, v18
	v_cndmask_b32_e64 v20, 1.0, v20, s[48:49]
	v_cndmask_b32_e64 v33, 0, v21, s[48:49]
	s_cselect_b64 s[48:49], -1, 0
	global_load_dword v16, v[30:31], off
	global_load_dword v17, v[30:31], off offset:2048
	v_lshl_add_u64 v[30:31], v[0:1], 0, s[2:3]
	s_and_b64 s[2:3], s[48:49], exec
	s_cselect_b32 s2, s4, 0
	s_add_i32 s2, s2, s96
	s_lshl_b32 s2, s2, 1
	s_ashr_i32 s3, s2, 31
	s_add_i32 s4, s1, 15
	s_lshl_b64 s[2:3], s[2:3], 12
	s_cmp_lt_u32 s4, s0
	v_fmac_f32_e32 v33, v32, v20
	v_cndmask_b32_e64 v22, 1.0, v22, s[50:51]
	v_cndmask_b32_e64 v32, 0, v23, s[50:51]
	s_cselect_b64 s[50:51], -1, 0
	global_load_dword v18, v[30:31], off
	global_load_dword v19, v[30:31], off offset:2048
; #define GAS __attribute__((address_space(1)))
; __device__ __forceinline__ void lru_scan(const Params& P, int l) {
;     ...
;         for (int d = 0; d < 2; ++d) { const int rank = d == 0 ? q : (q < 4 ? 3 - q : 71 - q); float hh = 0.f;
; #pragma unroll 1
;             for (int r8 = 0; r8 < rank; r8 += 34) { float aa[34], bv[34];
; #pragma unroll
;                 for (int k = 0; k < 34; ++k) { const int rho = r8 + k; const bool ok = rho < rank; const int rr = ok ? rho : 0; const int qq = d == 0 ? rr : (rr < 4 ? 3 - rr : 71 - rr);
;                     const GAS float* ap = AGG + ((size_t)((b * NQ + qq) * 2 + d) * 2) * 512 + c; const float a0 = ap[0], b0 = ap[512]; aa[k] = ok ? a0 : 1.f; bv[k] = ok ? b0 : 0.f; }
; #pragma unroll
;                 for (int k = 0; k < 34; ++k) hh = aa[k] * hh + bv[k]; }
;             hin[d] = hh; }
	v_lshl_add_u64 v[30:31], v[0:1], 0, s[2:3]
	s_and_b64 s[2:3], s[50:51], exec
	s_cselect_b32 s2, s4, 0
	s_add_i32 s2, s2, s96
	s_lshl_b32 s2, s2, 1
	s_ashr_i32 s3, s2, 31
	s_add_i32 s4, s1, 16
	s_lshl_b64 s[2:3], s[2:3], 12
	s_cmp_lt_u32 s4, s0
	v_fmac_f32_e32 v32, v33, v22
	v_cndmask_b32_e64 v24, 1.0, v24, s[52:53]
	v_cndmask_b32_e64 v33, 0, v25, s[52:53]
	s_cselect_b64 s[52:53], -1, 0
	global_load_dword v20, v[30:31], off
	global_load_dword v21, v[30:31], off offset:2048
	v_lshl_add_u64 v[30:31], v[0:1], 0, s[2:3]
	s_and_b64 s[2:3], s[52:53], exec
	s_cselect_b32 s2, s4, 0
	s_add_i32 s2, s2, s96
	s_lshl_b32 s2, s2, 1
	s_ashr_i32 s3, s2, 31
	s_add_i32 s4, s1, 17
	s_lshl_b64 s[2:3], s[2:3], 12
	s_cmp_lt_u32 s4, s0
	v_fmac_f32_e32 v33, v32, v24
	v_cndmask_b32_e64 v26, 1.0, v26, s[54:55]
	v_cndmask_b32_e64 v32, 0, v27, s[54:55]
	s_cselect_b64 s[54:55], -1, 0
	global_load_dword v22, v[30:31], off
	global_load_dword v23, v[30:31], off offset:2048
	v_lshl_add_u64 v[30:31], v[0:1], 0, s[2:3]
	s_and_b64 s[2:3], s[54:55], exec
	s_cselect_b32 s2, s4, 0
	s_add_i32 s2, s2, s96
	s_lshl_b32 s2, s2, 1
	s_ashr_i32 s3, s2, 31
	s_add_i32 s4, s1, 18
	s_lshl_b64 s[2:3], s[2:3], 12
	s_cmp_lt_u32 s4, s0
	v_cndmask_b32_e64 v28, 1.0, v28, s[56:57]
	v_cndmask_b32_e64 v36, 0, v29, s[56:57]
	s_cselect_b64 s[56:57], -1, 0
	global_load_dword v24, v[30:31], off
	global_load_dword v25, v[30:31], off offset:2048
	v_lshl_add_u64 v[30:31], v[0:1], 0, s[2:3]
	s_and_b64 s[2:3], s[56:57], exec
	s_cselect_b32 s2, s4, 0
	s_add_i32 s2, s2, s96
	s_lshl_b32 s2, s2, 1
	s_ashr_i32 s3, s2, 31
	s_add_i32 s4, s1, 19
	s_lshl_b64 s[2:3], s[2:3], 12
	s_cmp_lt_u32 s4, s0
	s_cselect_b64 s[58:59], -1, 0
	v_fmac_f32_e32 v32, v33, v26
	global_load_dword v26, v[30:31], off
	global_load_dword v27, v[30:31], off offset:2048
	v_lshl_add_u64 v[30:31], v[0:1], 0, s[2:3]
	s_and_b64 s[2:3], s[58:59], exec
	s_cselect_b32 s2, s4, 0
	s_add_i32 s2, s2, s96
	s_lshl_b32 s2, s2, 1
	s_ashr_i32 s3, s2, 31
	s_add_i32 s4, s1, 20
	s_lshl_b64 s[2:3], s[2:3], 12
	s_cmp_lt_u32 s4, s0
	s_cselect_b64 s[62:63], -1, 0
	v_fmac_f32_e32 v36, v32, v28
	v_lshl_add_u64 v[32:33], v[0:1], 0, s[2:3]
	s_and_b64 s[2:3], s[62:63], exec
	s_cselect_b32 s2, s4, 0
	s_add_i32 s2, s2, s96
	s_lshl_b32 s2, s2, 1
	s_ashr_i32 s3, s2, 31
	s_add_i32 s4, s1, 21
	s_lshl_b64 s[2:3], s[2:3], 12
	s_cmp_lt_u32 s4, s0
	s_cselect_b64 s[64:65], -1, 0
	global_load_dword v28, v[30:31], off
	global_load_dword v29, v[30:31], off offset:2048
	global_load_dword v30, v[32:33], off
	global_load_dword v31, v[32:33], off offset:2048
	v_lshl_add_u64 v[32:33], v[0:1], 0, s[2:3]
	s_and_b64 s[2:3], s[64:65], exec
	s_cselect_b32 s2, s4, 0
	s_add_i32 s2, s2, s96
	s_lshl_b32 s2, s2, 1
	s_ashr_i32 s3, s2, 31
	s_add_i32 s4, s1, 22
	s_lshl_b64 s[2:3], s[2:3], 12
	s_cmp_lt_u32 s4, s0
	s_cselect_b64 s[68:69], -1, 0
	global_load_dword v34, v[32:33], off
	global_load_dword v35, v[32:33], off offset:2048
	v_lshl_add_u64 v[32:33], v[0:1], 0, s[2:3]
	s_and_b64 s[2:3], s[68:69], exec
	s_cselect_b32 s2, s4, 0
	s_add_i32 s2, s2, s96
	s_lshl_b32 s2, s2, 1
	s_ashr_i32 s3, s2, 31
	s_add_i32 s4, s1, 23
	s_lshl_b64 s[2:3], s[2:3], 12
	s_cmp_lt_u32 s4, s0
	s_cselect_b64 s[60:61], -1, 0
	global_load_dword v37, v[32:33], off
	global_load_dword v38, v[32:33], off offset:2048
	v_lshl_add_u64 v[32:33], v[0:1], 0, s[2:3]
	s_and_b64 s[2:3], s[60:61], exec
	s_cselect_b32 s2, s4, 0
	s_add_i32 s2, s2, s96
	s_lshl_b32 s2, s2, 1
	s_ashr_i32 s3, s2, 31
	s_add_i32 s4, s1, 24
	s_lshl_b64 s[2:3], s[2:3], 12
	s_cmp_lt_u32 s4, s0
	s_cselect_b64 s[66:67], -1, 0
	v_lshl_add_u64 v[44:45], v[0:1], 0, s[2:3]
	s_and_b64 s[2:3], s[66:67], exec
	s_cselect_b32 s2, s4, 0
	s_add_i32 s2, s2, s96
	s_lshl_b32 s2, s2, 1
	s_ashr_i32 s3, s2, 31
	s_add_i32 s4, s1, 25
	s_lshl_b64 s[2:3], s[2:3], 12
	s_cmp_lt_u32 s4, s0
	s_cselect_b64 s[70:71], -1, 0
	global_load_dword v41, v[32:33], off
	global_load_dword v42, v[32:33], off offset:2048
	global_load_dword v32, v[44:45], off
	global_load_dword v33, v[44:45], off offset:2048
	v_lshl_add_u64 v[44:45], v[0:1], 0, s[2:3]
	s_and_b64 s[2:3], s[70:71], exec
	s_cselect_b32 s2, s4, 0
	s_add_i32 s2, s2, s96
	s_lshl_b32 s2, s2, 1
	s_ashr_i32 s3, s2, 31
	s_add_i32 s4, s1, 26
	s_lshl_b64 s[2:3], s[2:3], 12
	s_cmp_lt_u32 s4, s0
	s_cselect_b64 s[72:73], -1, 0
	global_load_dword v39, v[44:45], off
	global_load_dword v40, v[44:45], off offset:2048
	v_lshl_add_u64 v[44:45], v[0:1], 0, s[2:3]
	s_and_b64 s[2:3], s[72:73], exec
	s_cselect_b32 s2, s4, 0
	s_add_i32 s2, s2, s96
	s_lshl_b32 s2, s2, 1
	s_ashr_i32 s3, s2, 31
	s_add_i32 s4, s1, 27
	s_lshl_b64 s[2:3], s[2:3], 12
	s_cmp_lt_u32 s4, s0
	s_cselect_b64 s[74:75], -1, 0
	v_lshl_add_u64 v[46:47], v[0:1], 0, s[2:3]
	s_and_b64 s[2:3], s[74:75], exec
	s_cselect_b32 s2, s4, 0
	s_add_i32 s2, s2, s96
	s_lshl_b32 s2, s2, 1
	s_ashr_i32 s3, s2, 31
	s_add_i32 s4, s1, 28
	s_lshl_b64 s[2:3], s[2:3], 12
	s_cmp_lt_u32 s4, s0
	s_cselect_b64 s[76:77], -1, 0
	v_lshl_add_u64 v[48:49], v[0:1], 0, s[2:3]
	s_and_b64 s[2:3], s[76:77], exec
	s_cselect_b32 s2, s4, 0
	s_add_i32 s2, s2, s96
	s_lshl_b32 s2, s2, 1
	s_ashr_i32 s3, s2, 31
	s_add_i32 s4, s1, 29
	s_lshl_b64 s[2:3], s[2:3], 12
	s_cmp_lt_u32 s4, s0
	s_cselect_b64 s[78:79], -1, 0
	v_lshl_add_u64 v[50:51], v[0:1], 0, s[2:3]
	s_and_b64 s[2:3], s[78:79], exec
	s_cselect_b32 s2, s4, 0
	s_add_i32 s2, s2, s96
	s_lshl_b32 s2, s2, 1
	s_ashr_i32 s3, s2, 31
	s_add_i32 s4, s1, 30
	s_lshl_b64 s[2:3], s[2:3], 12
	s_cmp_lt_u32 s4, s0
	s_cselect_b64 s[80:81], -1, 0
	v_lshl_add_u64 v[52:53], v[0:1], 0, s[2:3]
	s_and_b64 s[2:3], s[80:81], exec
	s_cselect_b32 s2, s4, 0
	s_add_i32 s2, s2, s96
	s_lshl_b32 s2, s2, 1
	s_ashr_i32 s3, s2, 31
; #define GAS __attribute__((address_space(1)))
; __device__ __forceinline__ void lru_scan(const Params& P, int l) {
;     ...
;         for (int d = 0; d < 2; ++d) { const int rank = d == 0 ? q : (q < 4 ? 3 - q : 71 - q); float hh = 0.f;
; #pragma unroll 1
;             for (int r8 = 0; r8 < rank; r8 += 34) { float aa[34], bv[34];
; #pragma unroll
;                 for (int k = 0; k < 34; ++k) { const int rho = r8 + k; const bool ok = rho < rank; const int rr = ok ? rho : 0; const int qq = d == 0 ? rr : (rr < 4 ? 3 - rr : 71 - rr);
;                     const GAS float* ap = AGG + ((size_t)((b * NQ + qq) * 2 + d) * 2) * 512 + c; const float a0 = ap[0], b0 = ap[512]; aa[k] = ok ? a0 : 1.f; bv[k] = ok ? b0 : 0.f; }
; #pragma unroll
;                 for (int k = 0; k < 34; ++k) hh = aa[k] * hh + bv[k]; }
;             hin[d] = hh; }
	s_add_i32 s4, s1, 31
	s_lshl_b64 s[2:3], s[2:3], 12
	s_cmp_lt_u32 s4, s0
	s_cselect_b64 s[82:83], -1, 0
	v_lshl_add_u64 v[54:55], v[0:1], 0, s[2:3]
	s_and_b64 s[2:3], s[82:83], exec
	s_cselect_b32 s2, s4, 0
	s_add_i32 s2, s2, s96
	s_lshl_b32 s2, s2, 1
	s_ashr_i32 s3, s2, 31
	s_add_i32 s4, s1, 32
	s_lshl_b64 s[2:3], s[2:3], 12
	s_cmp_lt_u32 s4, s0
	s_cselect_b64 s[84:85], -1, 0
	global_load_dword v43, v[44:45], off
	global_load_dword v44, v[44:45], off offset:2048
	global_load_dword v45, v[46:47], off
	global_load_dword v46, v[46:47], off offset:2048
	global_load_dword v47, v[48:49], off
	global_load_dword v48, v[48:49], off offset:2048
	global_load_dword v49, v[50:51], off
	global_load_dword v50, v[50:51], off offset:2048
	global_load_dword v51, v[52:53], off
	global_load_dword v52, v[52:53], off offset:2048
	global_load_dword v53, v[54:55], off
	global_load_dword v56, v[54:55], off offset:2048
	v_lshl_add_u64 v[54:55], v[0:1], 0, s[2:3]
	s_and_b64 s[2:3], s[84:85], exec
	s_cselect_b32 s2, s4, 0
	s_add_i32 s2, s2, s96
	s_lshl_b32 s2, s2, 1
	s_ashr_i32 s3, s2, 31
	s_add_i32 s4, s1, 33
	s_lshl_b64 s[2:3], s[2:3], 12
	s_cmp_lt_u32 s4, s0
	s_cselect_b64 s[86:87], -1, 0
	global_load_dword v57, v[54:55], off
	global_load_dword v58, v[54:55], off offset:2048
	v_lshl_add_u64 v[54:55], v[0:1], 0, s[2:3]
	s_and_b64 s[2:3], s[86:87], exec
	s_cselect_b32 s2, s4, 0
	s_add_i32 s2, s2, s96
	s_lshl_b32 s2, s2, 1
	s_ashr_i32 s3, s2, 31
	s_lshl_b64 s[2:3], s[2:3], 12
	global_load_dword v59, v[54:55], off
	global_load_dword v60, v[54:55], off offset:2048
	v_lshl_add_u64 v[54:55], v[0:1], 0, s[2:3]
	global_load_dword v61, v[54:55], off
	global_load_dword v54, v[54:55], off offset:2048
	s_waitcnt vmcnt(51)
	v_cndmask_b32_e32 v13, 1.0, v13, vcc
	s_waitcnt vmcnt(50)
	v_cndmask_b32_e32 v8, 0, v8, vcc
	v_fmac_f32_e32 v8, v36, v13
	s_waitcnt vmcnt(49)
	v_cndmask_b32_e64 v9, 1.0, v9, s[38:39]
	s_waitcnt vmcnt(48)
	v_cndmask_b32_e64 v10, 0, v10, s[38:39]
	v_fmac_f32_e32 v10, v8, v9
	s_waitcnt vmcnt(47)
	v_cndmask_b32_e64 v8, 1.0, v11, s[40:41]
	s_waitcnt vmcnt(46)
	v_cndmask_b32_e64 v9, 0, v12, s[40:41]
	v_fmac_f32_e32 v9, v10, v8
	s_waitcnt vmcnt(45)
	v_cndmask_b32_e64 v8, 1.0, v14, s[42:43]
	s_waitcnt vmcnt(44)
	v_cndmask_b32_e64 v10, 0, v15, s[42:43]
	v_fmac_f32_e32 v10, v9, v8
	s_waitcnt vmcnt(43)
	v_cndmask_b32_e64 v8, 1.0, v16, s[44:45]
	s_waitcnt vmcnt(42)
	v_cndmask_b32_e64 v9, 0, v17, s[44:45]
	v_fmac_f32_e32 v9, v10, v8
	s_waitcnt vmcnt(41)
	v_cndmask_b32_e64 v8, 1.0, v18, s[46:47]
	s_waitcnt vmcnt(40)
	v_cndmask_b32_e64 v10, 0, v19, s[46:47]
	v_fmac_f32_e32 v10, v9, v8
	s_waitcnt vmcnt(39)
	v_cndmask_b32_e64 v8, 1.0, v20, s[48:49]
	s_waitcnt vmcnt(38)
	v_cndmask_b32_e64 v9, 0, v21, s[48:49]
	v_fmac_f32_e32 v9, v10, v8
	s_waitcnt vmcnt(37)
	v_cndmask_b32_e64 v8, 1.0, v22, s[50:51]
	s_waitcnt vmcnt(36)
	v_cndmask_b32_e64 v10, 0, v23, s[50:51]
	v_fmac_f32_e32 v10, v9, v8
	s_waitcnt vmcnt(35)
	v_cndmask_b32_e64 v8, 1.0, v24, s[52:53]
	s_waitcnt vmcnt(34)
	v_cndmask_b32_e64 v9, 0, v25, s[52:53]
	v_fmac_f32_e32 v9, v10, v8
	s_waitcnt vmcnt(33)
	v_cndmask_b32_e64 v8, 1.0, v26, s[54:55]
	s_waitcnt vmcnt(32)
	v_cndmask_b32_e64 v10, 0, v27, s[54:55]
	v_fmac_f32_e32 v10, v9, v8
	s_waitcnt vmcnt(31)
	v_cndmask_b32_e64 v8, 1.0, v28, s[56:57]
	s_waitcnt vmcnt(30)
	v_cndmask_b32_e64 v9, 0, v29, s[56:57]
	v_fmac_f32_e32 v9, v10, v8
	s_waitcnt vmcnt(29)
	v_cndmask_b32_e64 v8, 1.0, v30, s[58:59]
	s_waitcnt vmcnt(28)
	v_cndmask_b32_e64 v10, 0, v31, s[58:59]
	v_fmac_f32_e32 v10, v9, v8
	s_waitcnt vmcnt(27)
	v_cndmask_b32_e64 v8, 1.0, v34, s[62:63]
	s_waitcnt vmcnt(26)
	v_cndmask_b32_e64 v9, 0, v35, s[62:63]
	v_fmac_f32_e32 v9, v10, v8
	s_waitcnt vmcnt(25)
	v_cndmask_b32_e64 v8, 1.0, v37, s[64:65]
	s_waitcnt vmcnt(24)
	v_cndmask_b32_e64 v10, 0, v38, s[64:65]
	v_fmac_f32_e32 v10, v9, v8
	s_waitcnt vmcnt(23)
	v_cndmask_b32_e64 v8, 1.0, v41, s[68:69]
	s_waitcnt vmcnt(22)
	v_cndmask_b32_e64 v9, 0, v42, s[68:69]
	v_fmac_f32_e32 v9, v10, v8
	s_waitcnt vmcnt(21)
	v_cndmask_b32_e64 v8, 1.0, v32, s[60:61]
	s_waitcnt vmcnt(20)
	v_cndmask_b32_e64 v10, 0, v33, s[60:61]
	v_fmac_f32_e32 v10, v9, v8
	s_waitcnt vmcnt(19)
	v_cndmask_b32_e64 v8, 1.0, v39, s[66:67]
	s_waitcnt vmcnt(18)
	v_cndmask_b32_e64 v9, 0, v40, s[66:67]
	v_fmac_f32_e32 v9, v10, v8
	s_add_i32 s1, s1, 34
	s_waitcnt vmcnt(17)
	v_cndmask_b32_e64 v8, 1.0, v43, s[70:71]
	s_waitcnt vmcnt(16)
	v_cndmask_b32_e64 v10, 0, v44, s[70:71]
	v_fmac_f32_e32 v10, v9, v8
	s_waitcnt vmcnt(15)
	v_cndmask_b32_e64 v8, 1.0, v45, s[72:73]
	s_waitcnt vmcnt(14)
	v_cndmask_b32_e64 v9, 0, v46, s[72:73]
	v_fmac_f32_e32 v9, v10, v8
	s_waitcnt vmcnt(13)
	v_cndmask_b32_e64 v8, 1.0, v47, s[74:75]
	s_waitcnt vmcnt(12)
	v_cndmask_b32_e64 v10, 0, v48, s[74:75]
	v_fmac_f32_e32 v10, v9, v8
	s_waitcnt vmcnt(11)
	v_cndmask_b32_e64 v8, 1.0, v49, s[76:77]
	s_waitcnt vmcnt(10)
	v_cndmask_b32_e64 v9, 0, v50, s[76:77]
	v_fmac_f32_e32 v9, v10, v8
	s_waitcnt vmcnt(9)
	v_cndmask_b32_e64 v8, 1.0, v51, s[78:79]
	s_waitcnt vmcnt(8)
	v_cndmask_b32_e64 v10, 0, v52, s[78:79]
	v_fmac_f32_e32 v10, v9, v8
	s_waitcnt vmcnt(7)
	v_cndmask_b32_e64 v8, 1.0, v53, s[80:81]
	s_waitcnt vmcnt(6)
	v_cndmask_b32_e64 v9, 0, v56, s[80:81]
	v_fmac_f32_e32 v9, v10, v8
	s_waitcnt vmcnt(5)
	v_cndmask_b32_e64 v8, 1.0, v57, s[82:83]
	s_waitcnt vmcnt(4)
	v_cndmask_b32_e64 v10, 0, v58, s[82:83]
	v_fmac_f32_e32 v10, v9, v8
	s_addk_i32 s8, 0x44
	s_cmp_ge_u32 s1, s0
	s_waitcnt vmcnt(3)
	v_cndmask_b32_e64 v8, 1.0, v59, s[84:85]
	s_waitcnt vmcnt(2)
	v_cndmask_b32_e64 v9, 0, v60, s[84:85]
	v_fmac_f32_e32 v9, v10, v8
	s_waitcnt vmcnt(1)
	v_cndmask_b32_e64 v8, 1.0, v61, s[86:87]
	s_waitcnt vmcnt(0)
	v_cndmask_b32_e64 v128, 0, v54, s[86:87]
	v_fmac_f32_e32 v128, v9, v8
	s_cbranch_scc0 .LBB0_709
	v_readlane_b32 s80, v253, 58
	v_readlane_b32 s81, v253, 59
	v_readlane_b32 s82, v253, 60
	v_readlane_b32 s83, v253, 61
	v_readlane_b32 s84, v253, 62
	v_readlane_b32 s85, v253, 63
	v_readlane_b32 s86, v254, 0
	v_readlane_b32 s87, v254, 1
	s_mov_b32 s4, 0xb000
	s_mov_b32 s5, 0xd000
	s_mov_b32 s8, 0xf000
	s_mov_b32 s9, 0x11000
	s_mov_b32 s10, 0x13000
	s_mov_b32 s11, 0x15000
	s_mov_b32 s12, 0x17000
	s_mov_b32 s13, 0x19000
	s_mov_b32 s14, 0x1b000
	s_mov_b32 s15, 0x1d000
	s_mov_b32 s16, 0x1f000
	s_branch .LBB0_712

; #define GAS __attribute__((address_space(1)))
; __device__ __forceinline__ void lru_scan(const Params& P, int l) {
;     ...
;         for (int d = 0; d < 2; ++d) { const int rank = d == 0 ? q : (q < 4 ? 3 - q : 71 - q); float hh = 0.f;
; #pragma unroll 1
;             for (int r8 = 0; r8 < rank; r8 += 34) { float aa[34], bv[34];
; #pragma unroll
;                 for (int k = 0; k < 34; ++k) { const int rho = r8 + k; const bool ok = rho < rank; const int rr = ok ? rho : 0; const int qq = d == 0 ? rr : (rr < 4 ? 3 - rr : 71 - rr);
;                     const GAS float* ap = AGG + ((size_t)((b * NQ + qq) * 2 + d) * 2) * 512 + c; const float a0 = ap[0], b0 = ap[512]; aa[k] = ok ? a0 : 1.f; bv[k] = ok ? b0 : 0.f; }
; #pragma unroll
;                 for (int k = 0; k < 34; ++k) hh = aa[k] * hh + bv[k]; }
;             hin[d] = hh; }
.LBB0_714:
	s_cmp_gt_u32 s13, 3
	s_cselect_b32 s15, 0x47, 3
	s_add_i32 s15, s96, s15
	s_add_i32 s15, s15, s14
	s_lshl_b32 s15, s15, 1
	s_add_i32 s38, s15, 0xffffffb5
	s_ashr_i32 s39, s38, 31
	s_add_i32 s28, s13, 1
	s_lshl_b64 s[38:39], s[38:39], 12
	s_cmp_lt_i32 s28, s3
	s_cselect_b64 s[42:43], -1, 0
	v_lshl_add_u64 v[8:9], v[0:1], 0, s[38:39]
	s_and_b64 s[38:39], s[42:43], exec
	s_cselect_b32 s15, s28, 0
	s_cmp_gt_u32 s15, 3
	s_cselect_b32 s28, 0x47, 3
	s_sub_i32 s15, s96, s15
	s_add_i32 s15, s15, s28
	s_lshl_b32 s15, s15, 1
	s_or_b32 s38, s15, 1
	s_ashr_i32 s39, s38, 31
	s_add_i32 s29, s13, 2
	s_lshl_b64 s[38:39], s[38:39], 12
	s_cmp_lt_i32 s29, s3
	global_load_dword v10, v[8:9], off
	global_load_dword v12, v[8:9], off offset:2048
	v_lshl_add_u64 v[8:9], v[0:1], 0, s[38:39]
	s_cselect_b64 s[44:45], -1, 0
	global_load_dword v13, v[8:9], off
	global_load_dword v14, v[8:9], off offset:2048
	s_and_b64 s[38:39], s[44:45], exec
	s_cselect_b32 s15, s29, 0
	s_cmp_gt_u32 s15, 3
	s_cselect_b32 s28, 0x47, 3
	s_sub_i32 s15, s96, s15
	s_add_i32 s15, s15, s28
	s_lshl_b32 s15, s15, 1
	s_or_b32 s38, s15, 1
	s_ashr_i32 s39, s38, 31
	s_add_i32 s29, s13, 3
	s_lshl_b64 s[38:39], s[38:39], 12
	s_cmp_lt_i32 s29, s3
	v_lshl_add_u64 v[8:9], v[0:1], 0, s[38:39]
	s_cselect_b64 s[46:47], -1, 0
	global_load_dword v15, v[8:9], off
	global_load_dword v16, v[8:9], off offset:2048
	s_and_b64 s[38:39], s[46:47], exec
	s_cselect_b32 s15, s29, 0
	s_cmp_gt_u32 s15, 3
	s_cselect_b32 s28, 0x47, 3
	s_sub_i32 s15, s96, s15
	s_add_i32 s15, s15, s28
	s_lshl_b32 s15, s15, 1
	s_or_b32 s38, s15, 1
	s_ashr_i32 s39, s38, 31
	s_add_i32 s29, s14, 29
	s_lshl_b64 s[38:39], s[38:39], 12
	s_cmp_lt_i32 s13, s8
	v_lshl_add_u64 v[8:9], v[0:1], 0, s[38:39]
	s_cselect_b64 s[48:49], -1, 0
	global_load_dword v17, v[8:9], off
	global_load_dword v18, v[8:9], off offset:2048
	s_and_b64 s[38:39], s[48:49], exec
	s_cselect_b32 s15, s29, 3
	s_add_i32 s15, s15, s96
	s_lshl_b32 s15, s15, 1
	s_or_b32 s38, s15, 1
	s_ashr_i32 s39, s38, 31
	s_add_i32 s28, s14, 28
	s_lshl_b64 s[38:39], s[38:39], 12
	s_cmp_lt_i32 s13, s9
	v_lshl_add_u64 v[8:9], v[0:1], 0, s[38:39]
	s_cselect_b64 s[50:51], -1, 0
	global_load_dword v19, v[8:9], off
	global_load_dword v20, v[8:9], off offset:2048
	s_and_b64 s[38:39], s[50:51], exec
	s_cselect_b32 s15, s28, 3
	s_add_i32 s15, s15, s96
	s_lshl_b32 s15, s15, 1
	s_or_b32 s38, s15, 1
	s_ashr_i32 s39, s38, 31
	s_add_i32 s28, s14, 27
	s_lshl_b64 s[38:39], s[38:39], 12
	s_cmp_lt_i32 s13, s2
	v_lshl_add_u64 v[8:9], v[0:1], 0, s[38:39]
	s_cselect_b64 s[52:53], -1, 0
	global_load_dword v21, v[8:9], off
	global_load_dword v22, v[8:9], off offset:2048
	s_and_b64 s[38:39], s[52:53], exec
	s_cselect_b32 s15, s28, 3
	s_add_i32 s15, s15, s96
	s_lshl_b32 s15, s15, 1
	s_or_b32 s38, s15, 1
	s_ashr_i32 s39, s38, 31
	s_add_i32 s28, s14, 26
	s_lshl_b64 s[38:39], s[38:39], 12
	s_cmp_lt_i32 s13, s0
	v_lshl_add_u64 v[8:9], v[0:1], 0, s[38:39]
	s_cselect_b64 s[54:55], -1, 0
	global_load_dword v23, v[8:9], off
	global_load_dword v24, v[8:9], off offset:2048
	s_and_b64 s[38:39], s[54:55], exec
	s_cselect_b32 s15, s28, 3
	s_add_i32 s15, s15, s96
	s_lshl_b32 s15, s15, 1
	s_or_b32 s38, s15, 1
	s_ashr_i32 s39, s38, 31
	s_add_i32 s28, s14, 25
	s_lshl_b64 s[38:39], s[38:39], 12
	s_cmp_lt_i32 s13, s16
	v_lshl_add_u64 v[8:9], v[0:1], 0, s[38:39]
	s_cselect_b64 vcc, -1, 0
	global_load_dword v25, v[8:9], off
	global_load_dword v26, v[8:9], off offset:2048
	s_and_b64 s[38:39], vcc, exec
	s_cselect_b32 s15, s28, 3
	s_add_i32 s15, s15, s96
	s_lshl_b32 s15, s15, 1
	s_or_b32 s38, s15, 1
	s_ashr_i32 s39, s38, 31
	s_add_i32 s28, s14, 24
	s_lshl_b64 s[38:39], s[38:39], 12
	s_cmp_lt_i32 s13, s1
	v_lshl_add_u64 v[28:29], v[0:1], 0, s[38:39]
	s_cselect_b64 s[38:39], -1, 0
	s_and_b64 s[40:41], s[38:39], exec
	s_cselect_b32 s15, s28, 3
	s_add_i32 s15, s15, s96
	s_lshl_b32 s15, s15, 1
	s_or_b32 s40, s15, 1
	s_ashr_i32 s41, s40, 31
	s_add_i32 s56, s14, 23
	s_lshl_b64 s[40:41], s[40:41], 12
	s_cmp_lt_i32 s13, s21
	global_load_dword v9, v[28:29], off
	global_load_dword v8, v[28:29], off offset:2048
	v_lshl_add_u64 v[28:29], v[0:1], 0, s[40:41]
	s_cselect_b64 s[40:41], -1, 0
	s_and_b64 s[58:59], s[40:41], exec
	s_cselect_b32 s15, s56, 3
	s_add_i32 s15, s15, s96
	s_lshl_b32 s15, s15, 1
	s_waitcnt vmcnt(0)
; #define GAS __attribute__((address_space(1)))
; __device__ __forceinline__ void lru_scan(const Params& P, int l) {
;     ...
;         for (int d = 0; d < 2; ++d) { const int rank = d == 0 ? q : (q < 4 ? 3 - q : 71 - q); float hh = 0.f;
; #pragma unroll 1
;             for (int r8 = 0; r8 < rank; r8 += 34) { float aa[34], bv[34];
; #pragma unroll
;                 for (int k = 0; k < 34; ++k) { const int rho = r8 + k; const bool ok = rho < rank; const int rr = ok ? rho : 0; const int qq = d == 0 ? rr : (rr < 4 ? 3 - rr : 71 - rr);
;                     const GAS float* ap = AGG + ((size_t)((b * NQ + qq) * 2 + d) * 2) * 512 + c; const float a0 = ap[0], b0 = ap[512]; aa[k] = ok ? a0 : 1.f; bv[k] = ok ? b0 : 0.f; }
; #pragma unroll
;                 for (int k = 0; k < 34; ++k) hh = aa[k] * hh + bv[k]; }
;             hin[d] = hh; }
	v_cndmask_b32_e64 v13, 1.0, v13, s[42:43]
	v_cndmask_b32_e64 v14, 0, v14, s[42:43]
	s_or_b32 s42, s15, 1
	s_ashr_i32 s43, s42, 31
	s_add_i32 s28, s14, 22
	s_lshl_b64 s[42:43], s[42:43], 12
	s_cmp_lt_i32 s13, s19
	v_fmac_f32_e32 v12, v154, v10
	global_load_dword v10, v[28:29], off
	global_load_dword v11, v[28:29], off offset:2048
	v_lshl_add_u64 v[28:29], v[0:1], 0, s[42:43]
	s_cselect_b64 s[42:43], -1, 0
	s_and_b64 s[56:57], s[42:43], exec
	s_cselect_b32 s15, s28, 3
	s_add_i32 s15, s15, s96
	s_lshl_b32 s15, s15, 1
	s_or_b32 s56, s15, 1
	s_ashr_i32 s57, s56, 31
	s_add_i32 s28, s14, 21
	v_cndmask_b32_e64 v15, 1.0, v15, s[44:45]
	v_cndmask_b32_e64 v27, 0, v16, s[44:45]
	s_lshl_b64 s[44:45], s[56:57], 12
	s_cmp_lt_i32 s13, s97
	v_fmac_f32_e32 v14, v12, v13
	global_load_dword v12, v[28:29], off
	global_load_dword v13, v[28:29], off offset:2048
	v_lshl_add_u64 v[28:29], v[0:1], 0, s[44:45]
	s_cselect_b64 s[44:45], -1, 0
	s_and_b64 s[56:57], s[44:45], exec
	s_cselect_b32 s15, s28, 3
	s_add_i32 s15, s15, s96
	s_lshl_b32 s15, s15, 1
	s_or_b32 s56, s15, 1
	s_ashr_i32 s57, s56, 31
	s_add_i32 s28, s14, 20
	s_lshl_b64 s[56:57], s[56:57], 12
	s_cmp_lt_i32 s13, s17
	v_cndmask_b32_e64 v30, 1.0, v17, s[46:47]
	v_cndmask_b32_e64 v31, 0, v18, s[46:47]
	s_cselect_b64 s[46:47], -1, 0
	v_fmac_f32_e32 v27, v14, v15
	global_load_dword v14, v[28:29], off
	global_load_dword v15, v[28:29], off offset:2048
	v_lshl_add_u64 v[28:29], v[0:1], 0, s[56:57]
	s_and_b64 s[56:57], s[46:47], exec
	s_cselect_b32 s15, s28, 3
	s_add_i32 s15, s15, s96
	s_lshl_b32 s15, s15, 1
	s_or_b32 s56, s15, 1
	s_ashr_i32 s57, s56, 31
	s_add_i32 s28, s14, 19
	s_lshl_b64 s[56:57], s[56:57], 12
	s_cmp_lt_i32 s13, s34
	v_fmac_f32_e32 v31, v27, v30
	v_cndmask_b32_e64 v27, 1.0, v19, s[48:49]
	v_cndmask_b32_e64 v30, 0, v20, s[48:49]
	s_cselect_b64 s[48:49], -1, 0
	global_load_dword v16, v[28:29], off
	global_load_dword v17, v[28:29], off offset:2048
	v_lshl_add_u64 v[28:29], v[0:1], 0, s[56:57]
	s_and_b64 s[56:57], s[48:49], exec
	s_cselect_b32 s15, s28, 3
	s_add_i32 s15, s15, s96
	s_lshl_b32 s15, s15, 1
	s_or_b32 s56, s15, 1
	s_ashr_i32 s57, s56, 31
	s_add_i32 s28, s14, 18
	s_lshl_b64 s[56:57], s[56:57], 12
	s_cmp_lt_i32 s13, s25
	v_fmac_f32_e32 v30, v31, v27
	v_cndmask_b32_e64 v27, 1.0, v21, s[50:51]
	v_cndmask_b32_e64 v31, 0, v22, s[50:51]
	s_cselect_b64 s[50:51], -1, 0
	global_load_dword v18, v[28:29], off
	global_load_dword v19, v[28:29], off offset:2048
	v_lshl_add_u64 v[28:29], v[0:1], 0, s[56:57]
	s_and_b64 s[56:57], s[50:51], exec
	s_cselect_b32 s15, s28, 3
	s_add_i32 s15, s15, s96
	s_lshl_b32 s15, s15, 1
	s_or_b32 s56, s15, 1
	s_ashr_i32 s57, s56, 31
	s_add_i32 s28, s14, 17
	s_lshl_b64 s[56:57], s[56:57], 12
	s_cmp_lt_i32 s13, s4
	v_fmac_f32_e32 v31, v30, v27
	v_cndmask_b32_e64 v27, 1.0, v23, s[52:53]
	v_cndmask_b32_e64 v32, 0, v24, s[52:53]
	s_cselect_b64 s[52:53], -1, 0
	global_load_dword v20, v[28:29], off
	global_load_dword v21, v[28:29], off offset:2048
	v_lshl_add_u64 v[28:29], v[0:1], 0, s[56:57]
	s_and_b64 s[56:57], s[52:53], exec
	s_cselect_b32 s15, s28, 3
	s_add_i32 s15, s15, s96
	s_lshl_b32 s15, s15, 1
	s_or_b32 s56, s15, 1
	s_ashr_i32 s57, s56, 31
	s_add_i32 s28, s14, 16
	s_lshl_b64 s[56:57], s[56:57], 12
	s_cmp_lt_i32 s13, s5
	global_load_dword v22, v[28:29], off
	global_load_dword v23, v[28:29], off offset:2048
	v_cndmask_b32_e64 v28, 1.0, v25, s[54:55]
	v_cndmask_b32_e64 v30, 0, v26, s[54:55]
	s_cselect_b64 s[54:55], -1, 0
	v_fmac_f32_e32 v32, v31, v27
	v_lshl_add_u64 v[26:27], v[0:1], 0, s[56:57]
	s_and_b64 s[56:57], s[54:55], exec
	s_cselect_b32 s15, s28, 3
	s_add_i32 s15, s15, s96
	s_lshl_b32 s15, s15, 1
	s_or_b32 s56, s15, 1
	s_ashr_i32 s57, s56, 31
	s_add_i32 s28, s14, 15
	s_lshl_b64 s[56:57], s[56:57], 12
	s_cmp_lt_i32 s13, s30
	v_fmac_f32_e32 v30, v32, v28
	v_lshl_add_u64 v[28:29], v[0:1], 0, s[56:57]
	s_cselect_b64 s[56:57], -1, 0
	s_and_b64 s[58:59], s[56:57], exec
	s_cselect_b32 s15, s28, 3
	s_add_i32 s15, s15, s96
	s_lshl_b32 s15, s15, 1
	s_or_b32 s58, s15, 1
	s_ashr_i32 s59, s58, 31
	s_add_i32 s28, s14, 14
	s_lshl_b64 s[58:59], s[58:59], 12
	s_cmp_lt_i32 s13, s31
	v_lshl_add_u64 v[32:33], v[0:1], 0, s[58:59]
	s_cselect_b64 s[58:59], -1, 0
	s_and_b64 s[60:61], s[58:59], exec
	s_cselect_b32 s15, s28, 3
	s_add_i32 s15, s15, s96
	s_lshl_b32 s15, s15, 1
	s_or_b32 s60, s15, 1
	s_ashr_i32 s61, s60, 31
	s_add_i32 s28, s14, 13
	s_lshl_b64 s[60:61], s[60:61], 12
	s_cmp_lt_i32 s13, s10
	global_load_dword v24, v[26:27], off
	global_load_dword v25, v[26:27], off offset:2048
	global_load_dword v26, v[28:29], off
	global_load_dword v27, v[28:29], off offset:2048
	global_load_dword v28, v[32:33], off
	global_load_dword v29, v[32:33], off offset:2048
	v_lshl_add_u64 v[32:33], v[0:1], 0, s[60:61]
	s_cselect_b64 s[60:61], -1, 0
	s_and_b64 s[62:63], s[60:61], exec
	s_cselect_b32 s15, s28, 3
	s_add_i32 s15, s15, s96
	s_lshl_b32 s15, s15, 1
	s_or_b32 s62, s15, 1
	s_ashr_i32 s63, s62, 31
	s_add_i32 s28, s14, 12
	s_lshl_b64 s[62:63], s[62:63], 12
	s_cmp_lt_i32 s13, s11
	v_lshl_add_u64 v[34:35], v[0:1], 0, s[62:63]
	s_cselect_b64 s[62:63], -1, 0
	s_and_b64 s[64:65], s[62:63], exec
	s_cselect_b32 s15, s28, 3
	s_add_i32 s15, s15, s96
	s_lshl_b32 s15, s15, 1
	s_or_b32 s64, s15, 1
	s_ashr_i32 s65, s64, 31
	s_add_i32 s28, s14, 11
	s_lshl_b64 s[64:65], s[64:65], 12
	s_cmp_lt_i32 s13, s35
	s_cselect_b64 s[66:67], -1, 0
	v_lshl_add_u64 v[36:37], v[0:1], 0, s[64:65]
	s_and_b64 s[64:65], s[66:67], exec
	s_cselect_b32 s15, s28, 3
	s_add_i32 s15, s15, s96
	s_lshl_b32 s15, s15, 1
	s_or_b32 s64, s15, 1
	s_ashr_i32 s65, s64, 31
	s_add_i32 s28, s14, 10
	s_lshl_b64 s[64:65], s[64:65], 12
; #define GAS __attribute__((address_space(1)))
; __device__ __forceinline__ void lru_scan(const Params& P, int l) {
;     ...
;         for (int d = 0; d < 2; ++d) { const int rank = d == 0 ? q : (q < 4 ? 3 - q : 71 - q); float hh = 0.f;
; #pragma unroll 1
;             for (int r8 = 0; r8 < rank; r8 += 34) { float aa[34], bv[34];
; #pragma unroll
;                 for (int k = 0; k < 34; ++k) { const int rho = r8 + k; const bool ok = rho < rank; const int rr = ok ? rho : 0; const int qq = d == 0 ? rr : (rr < 4 ? 3 - rr : 71 - rr);
;                     const GAS float* ap = AGG + ((size_t)((b * NQ + qq) * 2 + d) * 2) * 512 + c; const float a0 = ap[0], b0 = ap[512]; aa[k] = ok ? a0 : 1.f; bv[k] = ok ? b0 : 0.f; }
; #pragma unroll
;                 for (int k = 0; k < 34; ++k) hh = aa[k] * hh + bv[k]; }
;             hin[d] = hh; }
	s_cmp_lt_i32 s13, s26
	s_cselect_b64 s[70:71], -1, 0
	v_lshl_add_u64 v[40:41], v[0:1], 0, s[64:65]
	s_and_b64 s[64:65], s[70:71], exec
	s_cselect_b32 s15, s28, 3
	s_add_i32 s15, s15, s96
	s_lshl_b32 s15, s15, 1
	s_or_b32 s64, s15, 1
	s_ashr_i32 s65, s64, 31
	s_add_i32 s28, s14, 9
	s_lshl_b64 s[64:65], s[64:65], 12
	s_cmp_lt_i32 s13, s88
	v_lshl_add_u64 v[44:45], v[0:1], 0, s[64:65]
	s_cselect_b64 s[64:65], -1, 0
	s_and_b64 s[68:69], s[64:65], exec
	s_cselect_b32 s15, s28, 3
	s_add_i32 s15, s15, s96
	s_lshl_b32 s15, s15, 1
	s_or_b32 s68, s15, 1
	s_ashr_i32 s69, s68, 31
	s_add_i32 s28, s14, 8
	s_lshl_b64 s[68:69], s[68:69], 12
	s_cmp_lt_i32 s13, s89
	v_lshl_add_u64 v[46:47], v[0:1], 0, s[68:69]
	s_cselect_b64 s[68:69], -1, 0
	s_and_b64 s[72:73], s[68:69], exec
	s_cselect_b32 s15, s28, 3
	s_add_i32 s15, s15, s96
	s_lshl_b32 s15, s15, 1
	s_or_b32 s72, s15, 1
	s_ashr_i32 s73, s72, 31
	s_add_i32 s28, s14, 7
	s_lshl_b64 s[72:73], s[72:73], 12
	s_cmp_lt_i32 s13, s90
	global_load_dword v31, v[32:33], off
	global_load_dword v32, v[32:33], off offset:2048
	global_load_dword v33, v[34:35], off
	global_load_dword v34, v[34:35], off offset:2048
	global_load_dword v35, v[36:37], off
	global_load_dword v36, v[36:37], off offset:2048
	global_load_dword v39, v[40:41], off
	global_load_dword v40, v[40:41], off offset:2048
	global_load_dword v43, v[44:45], off
	global_load_dword v44, v[44:45], off offset:2048
	global_load_dword v37, v[46:47], off
	global_load_dword v38, v[46:47], off offset:2048
	v_lshl_add_u64 v[46:47], v[0:1], 0, s[72:73]
	s_cselect_b64 s[72:73], -1, 0
	s_and_b64 s[74:75], s[72:73], exec
	s_cselect_b32 s15, s28, 3
	s_add_i32 s15, s15, s96
	s_lshl_b32 s15, s15, 1
	s_or_b32 s74, s15, 1
	s_ashr_i32 s75, s74, 31
	s_add_i32 s28, s14, 6
	s_lshl_b64 s[74:75], s[74:75], 12
	s_cmp_lt_i32 s13, s91
	global_load_dword v41, v[46:47], off
	global_load_dword v42, v[46:47], off offset:2048
	v_lshl_add_u64 v[46:47], v[0:1], 0, s[74:75]
	s_cselect_b64 s[74:75], -1, 0
	s_and_b64 s[76:77], s[74:75], exec
	s_cselect_b32 s15, s28, 3
	s_add_i32 s15, s15, s96
	s_lshl_b32 s15, s15, 1
	s_or_b32 s76, s15, 1
	s_ashr_i32 s77, s76, 31
	s_add_i32 s28, s14, 5
	s_lshl_b64 s[76:77], s[76:77], 12
	s_cmp_lt_i32 s13, s92
	v_lshl_add_u64 v[48:49], v[0:1], 0, s[76:77]
	s_cselect_b64 s[76:77], -1, 0
	s_and_b64 s[78:79], s[76:77], exec
	s_cselect_b32 s15, s28, 3
	s_add_i32 s15, s15, s96
	s_lshl_b32 s15, s15, 1
	s_or_b32 s78, s15, 1
	s_ashr_i32 s79, s78, 31
	s_add_i32 s28, s14, 4
	s_lshl_b64 s[78:79], s[78:79], 12
	s_cmp_lt_i32 s13, s93
	v_lshl_add_u64 v[50:51], v[0:1], 0, s[78:79]
	s_cselect_b64 s[78:79], -1, 0
	s_and_b64 s[80:81], s[78:79], exec
	s_cselect_b32 s15, s28, 3
	s_add_i32 s15, s15, s96
	s_lshl_b32 s15, s15, 1
	s_or_b32 s80, s15, 1
	s_ashr_i32 s81, s80, 31
	s_add_i32 s28, s14, 3
	s_lshl_b64 s[80:81], s[80:81], 12
	s_cmp_lt_i32 s13, s94
	v_lshl_add_u64 v[52:53], v[0:1], 0, s[80:81]
	s_cselect_b64 s[80:81], -1, 0
	s_and_b64 s[82:83], s[80:81], exec
	s_cselect_b32 s15, s28, 3
	s_add_i32 s15, s15, s96
	s_lshl_b32 s15, s15, 1
	s_or_b32 s82, s15, 1
	s_ashr_i32 s83, s82, 31
	s_add_i32 s28, s14, 2
	s_lshl_b64 s[82:83], s[82:83], 12
	s_cmp_lt_i32 s13, s95
	v_lshl_add_u64 v[54:55], v[0:1], 0, s[82:83]
	s_cselect_b64 s[82:83], -1, 0
	s_and_b64 s[84:85], s[82:83], exec
	s_cselect_b32 s15, s28, 3
	s_add_i32 s15, s15, s96
	s_lshl_b32 s15, s15, 1
	s_or_b32 s84, s15, 1
	s_ashr_i32 s85, s84, 31
	s_add_i32 s28, s14, 1
	s_lshl_b64 s[84:85], s[84:85], 12
	s_cmp_lt_i32 s13, s27
	v_lshl_add_u64 v[56:57], v[0:1], 0, s[84:85]
	s_cselect_b64 s[84:85], -1, 0
	s_and_b64 s[86:87], s[84:85], exec
	s_cselect_b32 s15, s28, 3
	s_add_i32 s15, s15, s96
	s_lshl_b32 s15, s15, 1
	s_or_b32 s86, s15, 1
	s_ashr_i32 s87, s86, 31
	s_lshl_b64 s[86:87], s[86:87], 12
	s_cmp_lt_i32 s13, s12
	v_lshl_add_u64 v[58:59], v[0:1], 0, s[86:87]
	s_cselect_b64 s[86:87], -1, 0
	s_and_b64 s[28:29], s[86:87], exec
	global_load_dword v45, v[46:47], off
	global_load_dword v46, v[46:47], off offset:2048
	s_cselect_b32 s15, s14, 3
	global_load_dword v47, v[48:49], off
	global_load_dword v48, v[48:49], off offset:2048
	s_add_i32 s15, s15, s96
	global_load_dword v49, v[50:51], off
	global_load_dword v50, v[50:51], off offset:2048
	s_lshl_b32 s15, s15, 1
	global_load_dword v51, v[52:53], off
	global_load_dword v52, v[52:53], off offset:2048
	s_or_b32 s28, s15, 1
	global_load_dword v53, v[54:55], off
	global_load_dword v54, v[54:55], off offset:2048
	s_ashr_i32 s29, s28, 31
	global_load_dword v55, v[56:57], off
	global_load_dword v56, v[56:57], off offset:2048
	s_lshl_b64 s[28:29], s[28:29], 12
	global_load_dword v57, v[58:59], off
	global_load_dword v58, v[58:59], off offset:2048
	v_lshl_add_u64 v[60:61], v[0:1], 0, s[28:29]
	global_load_dword v59, v[60:61], off
	global_load_dword v60, v[60:61], off offset:2048
	v_cndmask_b32_e32 v9, 1.0, v9, vcc
	v_cndmask_b32_e32 v8, 0, v8, vcc
	v_fmac_f32_e32 v8, v30, v9
	s_waitcnt vmcnt(49)
; #define GAS __attribute__((address_space(1)))
; __device__ __forceinline__ void lru_scan(const Params& P, int l) {
;     ...
;         for (int d = 0; d < 2; ++d) { const int rank = d == 0 ? q : (q < 4 ? 3 - q : 71 - q); float hh = 0.f;
; #pragma unroll 1
;             for (int r8 = 0; r8 < rank; r8 += 34) { float aa[34], bv[34];
; #pragma unroll
;                 for (int k = 0; k < 34; ++k) { const int rho = r8 + k; const bool ok = rho < rank; const int rr = ok ? rho : 0; const int qq = d == 0 ? rr : (rr < 4 ? 3 - rr : 71 - rr);
;                     const GAS float* ap = AGG + ((size_t)((b * NQ + qq) * 2 + d) * 2) * 512 + c; const float a0 = ap[0], b0 = ap[512]; aa[k] = ok ? a0 : 1.f; bv[k] = ok ? b0 : 0.f; }
; #pragma unroll
;                 for (int k = 0; k < 34; ++k) hh = aa[k] * hh + bv[k]; }
;             hin[d] = hh; }
	v_cndmask_b32_e64 v9, 1.0, v10, s[38:39]
	s_waitcnt vmcnt(48)
	v_cndmask_b32_e64 v10, 0, v11, s[38:39]
	v_fmac_f32_e32 v10, v8, v9
	s_waitcnt vmcnt(47)
	v_cndmask_b32_e64 v8, 1.0, v12, s[40:41]
	s_waitcnt vmcnt(46)
	v_cndmask_b32_e64 v9, 0, v13, s[40:41]
	v_fmac_f32_e32 v9, v10, v8
	s_waitcnt vmcnt(45)
	v_cndmask_b32_e64 v8, 1.0, v14, s[42:43]
	s_waitcnt vmcnt(44)
	v_cndmask_b32_e64 v10, 0, v15, s[42:43]
	v_fmac_f32_e32 v10, v9, v8
	s_waitcnt vmcnt(43)
	v_cndmask_b32_e64 v8, 1.0, v16, s[44:45]
	s_waitcnt vmcnt(42)
	v_cndmask_b32_e64 v9, 0, v17, s[44:45]
	v_fmac_f32_e32 v9, v10, v8
	s_waitcnt vmcnt(41)
	v_cndmask_b32_e64 v8, 1.0, v18, s[46:47]
	s_waitcnt vmcnt(40)
	v_cndmask_b32_e64 v10, 0, v19, s[46:47]
	v_fmac_f32_e32 v10, v9, v8
	s_waitcnt vmcnt(39)
	v_cndmask_b32_e64 v8, 1.0, v20, s[48:49]
	s_waitcnt vmcnt(38)
	v_cndmask_b32_e64 v9, 0, v21, s[48:49]
	v_fmac_f32_e32 v9, v10, v8
	s_waitcnt vmcnt(37)
	v_cndmask_b32_e64 v8, 1.0, v22, s[50:51]
	s_waitcnt vmcnt(36)
	v_cndmask_b32_e64 v10, 0, v23, s[50:51]
	v_fmac_f32_e32 v10, v9, v8
	s_waitcnt vmcnt(35)
	v_cndmask_b32_e64 v8, 1.0, v24, s[52:53]
	s_waitcnt vmcnt(34)
	v_cndmask_b32_e64 v9, 0, v25, s[52:53]
	v_fmac_f32_e32 v9, v10, v8
	s_waitcnt vmcnt(33)
	v_cndmask_b32_e64 v8, 1.0, v26, s[54:55]
	s_waitcnt vmcnt(32)
	v_cndmask_b32_e64 v10, 0, v27, s[54:55]
	v_fmac_f32_e32 v10, v9, v8
	s_waitcnt vmcnt(31)
	v_cndmask_b32_e64 v8, 1.0, v28, s[56:57]
	s_waitcnt vmcnt(30)
	v_cndmask_b32_e64 v9, 0, v29, s[56:57]
	v_fmac_f32_e32 v9, v10, v8
	s_waitcnt vmcnt(29)
	v_cndmask_b32_e64 v8, 1.0, v31, s[58:59]
	s_waitcnt vmcnt(28)
	v_cndmask_b32_e64 v10, 0, v32, s[58:59]
	v_fmac_f32_e32 v10, v9, v8
	s_waitcnt vmcnt(27)
	v_cndmask_b32_e64 v8, 1.0, v33, s[60:61]
	s_waitcnt vmcnt(26)
	v_cndmask_b32_e64 v9, 0, v34, s[60:61]
	v_fmac_f32_e32 v9, v10, v8
	s_waitcnt vmcnt(25)
	v_cndmask_b32_e64 v8, 1.0, v35, s[62:63]
	s_waitcnt vmcnt(24)
	v_cndmask_b32_e64 v10, 0, v36, s[62:63]
	v_fmac_f32_e32 v10, v9, v8
	s_waitcnt vmcnt(23)
	v_cndmask_b32_e64 v8, 1.0, v39, s[66:67]
	s_waitcnt vmcnt(22)
	v_cndmask_b32_e64 v9, 0, v40, s[66:67]
	v_fmac_f32_e32 v9, v10, v8
	s_waitcnt vmcnt(21)
	v_cndmask_b32_e64 v8, 1.0, v43, s[70:71]
	s_waitcnt vmcnt(20)
	v_cndmask_b32_e64 v10, 0, v44, s[70:71]
	v_fmac_f32_e32 v10, v9, v8
	s_waitcnt vmcnt(19)
	v_cndmask_b32_e64 v8, 1.0, v37, s[64:65]
	s_waitcnt vmcnt(18)
	v_cndmask_b32_e64 v9, 0, v38, s[64:65]
	v_fmac_f32_e32 v9, v10, v8
	s_waitcnt vmcnt(17)
	v_cndmask_b32_e64 v8, 1.0, v41, s[68:69]
	s_waitcnt vmcnt(16)
	v_cndmask_b32_e64 v10, 0, v42, s[68:69]
	v_fmac_f32_e32 v10, v9, v8
	s_sub_i32 s14, s14, 34
	s_add_i32 s13, s13, 34
	s_cmp_lt_i32 s13, s3
	s_waitcnt vmcnt(15)
	v_cndmask_b32_e64 v8, 1.0, v45, s[72:73]
	s_waitcnt vmcnt(14)
	v_cndmask_b32_e64 v9, 0, v46, s[72:73]
	v_fmac_f32_e32 v9, v10, v8
	s_waitcnt vmcnt(13)
	v_cndmask_b32_e64 v8, 1.0, v47, s[74:75]
	s_waitcnt vmcnt(12)
	v_cndmask_b32_e64 v10, 0, v48, s[74:75]
	v_fmac_f32_e32 v10, v9, v8
	s_waitcnt vmcnt(11)
	v_cndmask_b32_e64 v8, 1.0, v49, s[76:77]
	s_waitcnt vmcnt(10)
	v_cndmask_b32_e64 v9, 0, v50, s[76:77]
	v_fmac_f32_e32 v9, v10, v8
	s_waitcnt vmcnt(9)
	v_cndmask_b32_e64 v8, 1.0, v51, s[78:79]
	s_waitcnt vmcnt(8)
	v_cndmask_b32_e64 v10, 0, v52, s[78:79]
	v_fmac_f32_e32 v10, v9, v8
	s_waitcnt vmcnt(7)
	v_cndmask_b32_e64 v8, 1.0, v53, s[80:81]
	s_waitcnt vmcnt(6)
	v_cndmask_b32_e64 v9, 0, v54, s[80:81]
	v_fmac_f32_e32 v9, v10, v8
	s_waitcnt vmcnt(5)
	v_cndmask_b32_e64 v8, 1.0, v55, s[82:83]
	s_waitcnt vmcnt(4)
	v_cndmask_b32_e64 v10, 0, v56, s[82:83]
	v_fmac_f32_e32 v10, v9, v8
	s_waitcnt vmcnt(3)
	v_cndmask_b32_e64 v8, 1.0, v57, s[84:85]
	s_waitcnt vmcnt(2)
	v_cndmask_b32_e64 v9, 0, v58, s[84:85]
	v_fmac_f32_e32 v9, v10, v8
	s_waitcnt vmcnt(1)
	v_cndmask_b32_e64 v8, 1.0, v59, s[86:87]
	s_waitcnt vmcnt(0)
	v_cndmask_b32_e64 v154, 0, v60, s[86:87]
	v_fmac_f32_e32 v154, v9, v8
	s_cbranch_scc1 .LBB0_714
	v_readlane_b32 s80, v253, 58
	v_readlane_b32 s81, v253, 59
	v_readlane_b32 s82, v253, 60
	v_readlane_b32 s83, v253, 61
	v_readlane_b32 s84, v253, 62
	v_readlane_b32 s85, v253, 63
	v_readlane_b32 s86, v254, 0
	v_readlane_b32 s87, v254, 1
	s_mov_b32 s4, 0xb000
	s_mov_b32 s5, 0xd000
	s_mov_b32 s8, 0xf000
	s_mov_b32 s9, 0x11000
	s_mov_b32 s10, 0x13000
	s_mov_b32 s11, 0x15000
	s_mov_b32 s12, 0x17000
	s_mov_b32 s13, 0x19000
	s_mov_b32 s14, 0x1b000
	s_mov_b32 s15, 0x1d000
	s_mov_b32 s16, 0x1f000
	v_readlane_b32 s19, v255, 39
	s_branch .LBB0_702

; __device__ __forceinline__ void phase_norm(const Params& P, int l, int sub, int addpart) {
;     ...
;     if (rbeg < rend) NR_LOAD(rbeg, v, sc, sh);
.LBB0_883:
	s_andn2_b64 vcc, exec, s[8:9]
	s_cbranch_vccnz .LBB0_951
	s_waitcnt vmcnt(0)
	v_mov_b32_e32 v66, v168
	v_readlane_b32 s0, v250, 18
	v_ashrrev_i32_e32 v67, 6, v66
	s_nop 0
	v_add_u32_e32 v64, s0, v67
	s_mov_b32 s0, 0x8800
	v_cmp_gt_i32_e32 vcc, s0, v64
	s_and_saveexec_b64 s[8:9], vcc
	s_cbranch_execz .LBB0_897
	v_add_u32_e32 v128, 0xffff8000, v64
	v_ashrrev_i32_e32 v65, 31, v64
	v_cmp_gt_i32_e32 vcc, s25, v64
	v_mov_b32_e32 v18, s31
	v_mov_b32_e32 v19, s87
	v_lshlrev_b32_e32 v0, 2, v66
	v_cndmask_b32_e32 v17, 0, v65, vcc
	v_cndmask_b32_e32 v16, v128, v64, vcc
	v_cndmask_b32_e32 v19, v18, v19, vcc
	v_mov_b32_e32 v18, s30
	v_mov_b32_e32 v20, s86
	v_and_b32_e32 v48, 0xfc, v0
	v_readlane_b32 s0, v255, 8
	v_cndmask_b32_e32 v18, v18, v20, vcc
	v_lshlrev_b64 v[16:17], 12, v[16:17]
	v_lshlrev_b32_e32 v112, 2, v48
	v_readlane_b32 s1, v255, 9
	v_lshl_add_u64 v[16:17], v[18:19], 0, v[16:17]
	v_min_i32_e32 v18, 0x8000, v64
	s_waitcnt lgkmcnt(0)
	s_nop 1
	global_load_dwordx4 v[0:3], v112, s[0:1]
	global_load_dwordx4 v[4:7], v112, s[0:1] offset:1024
	global_load_dwordx4 v[8:11], v112, s[0:1] offset:2048
	global_load_dwordx4 v[12:15], v112, s[0:1] offset:3072
	v_ashrrev_i32_e32 v18, 12, v18
	v_readlane_b32 s0, v255, 12
	v_mul_hi_i32_i24_e32 v19, 0x9000, v18
	v_mul_i32_i24_e32 v18, 0x9000, v18
	v_readlane_b32 s1, v255, 13
	v_mov_b32_e32 v113, v129
	v_mov_b32_e32 v115, v129
	v_lshl_add_u64 v[18:19], s[0:1], 0, v[18:19]
	s_mov_b64 s[0:1], 0x6000
	v_lshl_add_u64 v[20:21], v[18:19], 0, s[0:1]
	s_mov_b64 s[0:1], 0x7000
	v_lshl_add_u64 v[18:19], v[18:19], 0, s[0:1]
	v_lshl_add_u64 v[22:23], v[18:19], 0, v[112:113]
	v_lshl_add_u64 v[24:25], v[20:21], 0, v[112:113]
	global_load_dwordx4 v[40:43], v[22:23], off
	global_load_dwordx4 v[44:47], v[24:25], off
	v_or_b32_e32 v22, 0x100, v48
	v_lshlrev_b32_e32 v114, 2, v22
	v_lshl_add_u64 v[16:17], v[16:17], 0, v[112:113]
	v_lshl_add_u64 v[22:23], v[18:19], 0, v[114:115]
	global_load_dwordx4 v[60:63], v[16:17], off
	global_load_dwordx4 v[56:59], v[16:17], off offset:1024
	v_lshl_add_u64 v[24:25], v[20:21], 0, v[114:115]
	global_load_dwordx4 v[32:35], v[22:23], off
	global_load_dwordx4 v[36:39], v[24:25], off
	v_or_b32_e32 v22, 0x200, v48
	v_lshlrev_b32_e32 v116, 2, v22
	v_mov_b32_e32 v117, v129
	v_lshl_add_u64 v[22:23], v[18:19], 0, v[116:117]
	v_lshl_add_u64 v[28:29], v[20:21], 0, v[116:117]
	global_load_dwordx4 v[24:27], v[22:23], off
	global_load_dwordx4 v[28:31], v[28:29], off
	v_or_b32_e32 v22, 0x300, v48
	v_lshlrev_b32_e32 v118, 2, v22
	v_mov_b32_e32 v119, v129
	global_load_dwordx4 v[52:55], v[16:17], off offset:2048
	global_load_dwordx4 v[48:51], v[16:17], off offset:3072
	v_lshl_add_u64 v[16:17], v[18:19], 0, v[118:119]
	v_lshl_add_u64 v[20:21], v[20:21], 0, v[118:119]
	global_load_dwordx4 v[16:19], v[16:17], off
	global_load_dwordx4 v[20:23], v[20:21], off
	v_cmp_lt_i32_e32 vcc, s19, v64
	s_and_b64 s[0:1], s[26:27], vcc
	s_and_saveexec_b64 s[38:39], s[0:1]
	s_cbranch_execz .LBB0_887
	v_readlane_b32 s0, v250, 21
	v_lshlrev_b64 v[84:85], 12, v[128:129]
	v_readlane_b32 s1, v250, 22
	s_nop 1
	v_lshl_add_u64 v[68:69], s[0:1], 0, v[84:85]
	v_readlane_b32 s0, v251, 61
	v_readlane_b32 s1, v251, 62
	v_lshl_add_u64 v[80:81], v[68:69], 0, v[112:113]
	global_load_dwordx4 v[68:71], v[80:81], off
	global_load_dwordx4 v[72:75], v[80:81], off offset:1024
	global_load_dwordx4 v[76:79], v[80:81], off offset:2048
	global_load_dwordx4 v[80:83], v[80:81], off offset:3072
	v_lshl_add_u64 v[86:87], s[0:1], 0, v[84:85]
	v_readlane_b32 s0, v250, 23
	v_readlane_b32 s1, v250, 24
	v_lshl_add_u64 v[108:109], v[86:87], 0, v[112:113]
	s_waitcnt vmcnt(3)
	v_pk_add_f32 v[62:63], v[62:63], v[70:71]
	v_lshl_add_u64 v[84:85], s[0:1], 0, v[84:85]
	v_lshl_add_u64 v[120:121], v[84:85], 0, v[112:113]
	global_load_dwordx4 v[84:87], v[120:121], off
	global_load_dwordx4 v[88:91], v[108:109], off
	global_load_dwordx4 v[92:95], v[108:109], off offset:1024
	global_load_dwordx4 v[96:99], v[120:121], off offset:1024
	global_load_dwordx4 v[100:103], v[120:121], off offset:2048
	global_load_dwordx4 v[104:107], v[108:109], off offset:2048
	global_load_dwordx4 v[108:111], v[108:109], off offset:3072
	global_load_dwordx4 v[120:123], v[120:121], off offset:3072
	v_pk_add_f32 v[60:61], v[60:61], v[68:69]
	s_waitcnt vmcnt(10)
	v_pk_add_f32 v[58:59], v[58:59], v[74:75]
	v_pk_add_f32 v[56:57], v[56:57], v[72:73]
	s_waitcnt vmcnt(9)
	v_pk_add_f32 v[54:55], v[54:55], v[78:79]
	v_pk_add_f32 v[52:53], v[52:53], v[76:77]
	s_waitcnt vmcnt(8)
	v_pk_add_f32 v[50:51], v[50:51], v[82:83]
	v_pk_add_f32 v[48:49], v[48:49], v[80:81]
	s_waitcnt vmcnt(6)
	v_pk_add_f32 v[68:69], v[90:91], v[86:87]
	v_pk_add_f32 v[70:71], v[88:89], v[84:85]
	s_waitcnt vmcnt(4)
	v_pk_add_f32 v[72:73], v[94:95], v[98:99]
	v_pk_add_f32 v[74:75], v[92:93], v[96:97]
	s_waitcnt vmcnt(2)
	v_pk_add_f32 v[76:77], v[106:107], v[102:103]
	v_pk_add_f32 v[78:79], v[104:105], v[100:101]
	s_waitcnt vmcnt(0)
	v_pk_add_f32 v[80:81], v[110:111], v[122:123]
	v_pk_add_f32 v[82:83], v[108:109], v[120:121]
	v_pk_add_f32 v[62:63], v[62:63], v[68:69]
	v_pk_add_f32 v[60:61], v[60:61], v[70:71]
	v_pk_add_f32 v[58:59], v[58:59], v[72:73]
	v_pk_add_f32 v[56:57], v[56:57], v[74:75]
	v_pk_add_f32 v[54:55], v[54:55], v[76:77]
	v_pk_add_f32 v[52:53], v[52:53], v[78:79]
	v_pk_add_f32 v[50:51], v[50:51], v[80:81]
	v_pk_add_f32 v[48:49], v[48:49], v[82:83]

; __device__ __forceinline__ void phase_norm(const Params& P, int l, int sub, int addpart) {
;     ...
;     for (int r = rbeg; r < rend; r += rstride) { const int rn = r + rstride; f32x4 vn[4], scn[4], shn[4];
;         if (rn < rend) NR_LOAD(rn, vn, scn, shn);
.LBB0_889:
	v_add_u32_e32 v128, s96, v142
	v_add_u32_e32 v51, 0x8000, v128
	s_mov_b32 s0, 0x8800
	v_cmp_gt_i32_e64 s[38:39], s0, v51
	s_mov_b32 s0, 0x87ff
	v_cmp_lt_i32_e32 vcc, s0, v51
	s_and_saveexec_b64 s[42:43], s[38:39]
	s_cbranch_execz .LBB0_893
	v_ashrrev_i32_e32 v63, 31, v51
	v_cmp_gt_i32_e64 s[38:39], s25, v51
	v_mov_b32_e32 v66, s87
	v_readlane_b32 s0, v255, 14
	v_cndmask_b32_e64 v65, 0, v63, s[38:39]
	v_mov_b32_e32 v63, s31
	v_cndmask_b32_e64 v67, v63, v66, s[38:39]
	v_mov_b32_e32 v63, s30
	v_mov_b32_e32 v66, s86
	v_cndmask_b32_e64 v64, v128, v51, s[38:39]
	v_cndmask_b32_e64 v66, v63, v66, s[38:39]
	v_min_i32_e32 v63, 0x8000, v51
	v_lshlrev_b64 v[64:65], 12, v[64:65]
	v_ashrrev_i32_e32 v63, 12, v63
	v_lshl_add_u64 v[64:65], v[66:67], 0, v[64:65]
	v_mul_hi_i32_i24_e32 v67, 0x9000, v63
	v_mul_i32_i24_e32 v66, 0x9000, v63
	v_readlane_b32 s1, v255, 15
	v_mov_b32_e32 v113, v129
	v_mov_b32_e32 v115, v129
	v_lshl_add_u64 v[66:67], s[0:1], 0, v[66:67]
	s_mov_b64 s[0:1], 0x1000
	v_lshl_add_u64 v[80:81], v[66:67], 0, s[0:1]
	v_mov_b32_e32 v117, v129
	v_mov_b32_e32 v119, v129
	v_lshl_add_u64 v[82:83], v[64:65], 0, v[112:113]
	v_lshl_add_u64 v[64:65], v[80:81], 0, v[112:113]
	v_lshl_add_u64 v[92:93], v[66:67], 0, v[112:113]
	v_lshl_add_u64 v[88:89], v[80:81], 0, v[114:115]
	v_lshl_add_u64 v[84:85], v[80:81], 0, v[116:117]
	v_lshl_add_u64 v[80:81], v[80:81], 0, v[118:119]
	global_load_dwordx4 v[64:67], v[64:65], off
	global_load_dwordx4 v[68:71], v[92:93], off
	global_load_dwordx4 v[96:99], v[82:83], off
	global_load_dwordx4 v[100:103], v[82:83], off offset:1024
	global_load_dwordx4 v[72:75], v[92:93], off offset:1024
	global_load_dwordx4 v[76:79], v[92:93], off offset:2048
	global_load_dwordx4 v[104:107], v[82:83], off offset:2048
	global_load_dwordx4 v[108:111], v[82:83], off offset:3072
	global_load_dwordx4 v[84:87], v[84:85], off
	global_load_dwordx4 v[80:83], v[80:81], off
	global_load_dwordx4 v[88:91], v[88:89], off
	global_load_dwordx4 v[92:95], v[92:93], off offset:3072
	v_cmp_lt_i32_e64 s[38:39], s19, v51
	s_and_b64 s[0:1], s[26:27], s[38:39]
	s_and_saveexec_b64 s[38:39], s[0:1]
	s_cbranch_execz .LBB0_892
	v_lshlrev_b64 v[162:163], 12, v[128:129]
	v_lshl_add_u64 v[164:165], v[122:123], 0, v[162:163]
	v_lshl_add_u64 v[208:209], v[126:127], 0, v[162:163]
	global_load_dwordx4 v[150:153], v[164:165], off
	global_load_dwordx4 v[154:157], v[164:165], off offset:1024
	v_lshl_add_u64 v[166:167], v[124:125], 0, v[162:163]
	global_load_dwordx4 v[158:161], v[164:165], off offset:2048
	global_load_dwordx4 v[162:165], v[164:165], off offset:3072
	global_load_dwordx4 v[180:183], v[208:209], off
	global_load_dwordx4 v[184:187], v[166:167], off
	global_load_dwordx4 v[188:191], v[166:167], off offset:1024
	global_load_dwordx4 v[192:195], v[208:209], off offset:1024
	global_load_dwordx4 v[196:199], v[208:209], off offset:2048
	global_load_dwordx4 v[200:203], v[166:167], off offset:2048
	global_load_dwordx4 v[204:207], v[166:167], off offset:3072
	global_load_dwordx4 v[208:211], v[208:209], off offset:3072
	s_waitcnt vmcnt(8)
	v_pk_add_f32 v[110:111], v[110:111], v[164:165]
	v_pk_add_f32 v[108:109], v[108:109], v[162:163]
	v_pk_add_f32 v[98:99], v[98:99], v[152:153]
	v_pk_add_f32 v[96:97], v[96:97], v[150:151]
	v_pk_add_f32 v[102:103], v[102:103], v[156:157]
	v_pk_add_f32 v[100:101], v[100:101], v[154:155]
	v_pk_add_f32 v[106:107], v[106:107], v[160:161]
	v_pk_add_f32 v[104:105], v[104:105], v[158:159]
	s_waitcnt vmcnt(6)
	v_pk_add_f32 v[150:151], v[186:187], v[182:183]
	v_pk_add_f32 v[152:153], v[184:185], v[180:181]
	s_waitcnt vmcnt(4)
	v_pk_add_f32 v[154:155], v[190:191], v[194:195]
	v_pk_add_f32 v[156:157], v[188:189], v[192:193]
	s_waitcnt vmcnt(2)
	v_pk_add_f32 v[158:159], v[202:203], v[198:199]
	v_pk_add_f32 v[160:161], v[200:201], v[196:197]
	s_waitcnt vmcnt(0)
	v_pk_add_f32 v[162:163], v[206:207], v[210:211]
	v_pk_add_f32 v[164:165], v[204:205], v[208:209]
	v_pk_add_f32 v[98:99], v[98:99], v[150:151]
	v_pk_add_f32 v[96:97], v[96:97], v[152:153]
	v_pk_add_f32 v[102:103], v[102:103], v[154:155]
	v_pk_add_f32 v[100:101], v[100:101], v[156:157]
	v_pk_add_f32 v[106:107], v[106:107], v[158:159]
	v_pk_add_f32 v[104:105], v[104:105], v[160:161]
	v_pk_add_f32 v[110:111], v[110:111], v[162:163]
	v_pk_add_f32 v[108:109], v[108:109], v[164:165]

; #define LAS __attribute__((address_space(3)))
; __device__ __forceinline__ void transpose_item(const float* W, int ldw, int k0, int n0, bf16_t* WT, int ldt, int drow0, int dk0, LAS float* scr, int lane) {
;     float tv[32];
; #pragma unroll
;     for (int i = 0; i < 32; ++i) { const int kk = 2 * i + (lane >> 5); tv[i] = W[(size_t)(k0 + kk) * ldw + n0 + (lane & 31)]; }
; __device__ __forceinline__ void prep_weights(const Params& P, LAS unsigned char* lds, int lay, int bid, int G, int sel) {
;     ...
;           if (sel & 32) { const int mat = lay, kb = r / 32, nb = r % 32;
;               transpose_item(P.w_out + (size_t)mat * 1024 * 1024, 1024, kb * 64, nb * 32, (bf16_t*)(ws + OFF_WOUT + mat * SZ_WOUT1), 1280, nb * 32, kb * 64, scr, lane); } } }
.LBB0_1098:
	s_movk_i32 s0, 0x15ff
	v_cmp_lt_i32_e32 vcc, s0, v3
	s_and_saveexec_b64 s[0:1], vcc
	s_xor_b64 s[42:43], exec, s[0:1]
	s_cbranch_execz .LBB0_1108
	s_movk_i32 s0, 0x20ff
	v_cmp_lt_u32_e32 vcc, s0, v3
	s_and_saveexec_b64 s[0:1], vcc
	s_xor_b64 s[8:9], exec, s[0:1]
	s_cbranch_execz .LBB0_1105
	s_movk_i32 s0, 0x247f
	v_cmp_lt_u32_e32 vcc, s0, v3
	s_and_saveexec_b64 s[0:1], vcc
	s_xor_b64 s[46:47], exec, s[0:1]
	s_cbranch_execz .LBB0_1102
	v_and_b32_e32 v12, 0x7fffffc0, v25
	v_add_u32_e32 v12, 0xffffb700, v12
	v_and_b32_e32 v27, 0x3e0, v26
	v_or_b32_e32 v16, v12, v18
	v_lshlrev_b32_e32 v128, 2, v27
	v_mov_b32_e32 v17, v129
	v_lshl_add_u64 v[14:15], v[8:9], 0, v[128:129]
	v_lshlrev_b64 v[28:29], 12, v[16:17]
	v_lshl_add_u64 v[28:29], v[14:15], 0, v[28:29]
	v_or_b32_e32 v128, 2, v16
	global_load_dword v13, v[28:29], off
	v_lshlrev_b64 v[28:29], 12, v[128:129]
	v_lshl_add_u64 v[28:29], v[14:15], 0, v[28:29]
	v_or_b32_e32 v128, 4, v16
	global_load_dword v30, v[28:29], off
	v_lshlrev_b64 v[28:29], 12, v[128:129]
	v_lshl_add_u64 v[28:29], v[14:15], 0, v[28:29]
	v_or_b32_e32 v128, 6, v16
	global_load_dword v31, v[28:29], off
	v_lshlrev_b64 v[28:29], 12, v[128:129]
	v_lshl_add_u64 v[28:29], v[14:15], 0, v[28:29]
	v_or_b32_e32 v128, 8, v16
	global_load_dword v32, v[28:29], off
	v_lshlrev_b64 v[28:29], 12, v[128:129]
	v_lshl_add_u64 v[28:29], v[14:15], 0, v[28:29]
	v_or_b32_e32 v128, 10, v16
	global_load_dword v33, v[28:29], off
	v_lshlrev_b64 v[28:29], 12, v[128:129]
	v_lshl_add_u64 v[28:29], v[14:15], 0, v[28:29]
	v_or_b32_e32 v128, 12, v16
	global_load_dword v34, v[28:29], off
	v_lshlrev_b64 v[28:29], 12, v[128:129]
	v_lshl_add_u64 v[28:29], v[14:15], 0, v[28:29]
	v_or_b32_e32 v128, 14, v16
	global_load_dword v35, v[28:29], off
	v_lshlrev_b64 v[28:29], 12, v[128:129]
	v_lshl_add_u64 v[28:29], v[14:15], 0, v[28:29]
	v_or_b32_e32 v128, 16, v16
	global_load_dword v36, v[28:29], off
	v_lshlrev_b64 v[28:29], 12, v[128:129]
	v_lshl_add_u64 v[28:29], v[14:15], 0, v[28:29]
	v_or_b32_e32 v128, 18, v16
	global_load_dword v37, v[28:29], off
	v_lshlrev_b64 v[28:29], 12, v[128:129]
	v_lshl_add_u64 v[28:29], v[14:15], 0, v[28:29]
	v_or_b32_e32 v128, 20, v16
	global_load_dword v38, v[28:29], off
	v_lshlrev_b64 v[28:29], 12, v[128:129]
	v_lshl_add_u64 v[28:29], v[14:15], 0, v[28:29]
	v_or_b32_e32 v128, 22, v16
	global_load_dword v39, v[28:29], off
	v_lshlrev_b64 v[28:29], 12, v[128:129]
	v_lshl_add_u64 v[28:29], v[14:15], 0, v[28:29]
	v_or_b32_e32 v128, 24, v16
	global_load_dword v40, v[28:29], off
	v_lshlrev_b64 v[28:29], 12, v[128:129]
	v_lshl_add_u64 v[28:29], v[14:15], 0, v[28:29]
	v_or_b32_e32 v128, 26, v16
	global_load_dword v41, v[28:29], off
	v_lshlrev_b64 v[28:29], 12, v[128:129]
	v_lshl_add_u64 v[28:29], v[14:15], 0, v[28:29]
	v_or_b32_e32 v128, 28, v16
	global_load_dword v42, v[28:29], off
	v_lshlrev_b64 v[28:29], 12, v[128:129]
	v_lshl_add_u64 v[28:29], v[14:15], 0, v[28:29]
	v_or_b32_e32 v128, 30, v16
	global_load_dword v43, v[28:29], off
	v_lshlrev_b64 v[28:29], 12, v[128:129]
	v_lshl_add_u64 v[28:29], v[14:15], 0, v[28:29]
	v_or_b32_e32 v128, 32, v16
	global_load_dword v44, v[28:29], off
	v_lshlrev_b64 v[28:29], 12, v[128:129]
	v_lshl_add_u64 v[28:29], v[14:15], 0, v[28:29]
	v_or_b32_e32 v128, 34, v16
	global_load_dword v45, v[28:29], off
	v_lshlrev_b64 v[28:29], 12, v[128:129]
	v_lshl_add_u64 v[28:29], v[14:15], 0, v[28:29]
	v_or_b32_e32 v128, 36, v16
	global_load_dword v46, v[28:29], off
	v_lshlrev_b64 v[28:29], 12, v[128:129]
	v_lshl_add_u64 v[28:29], v[14:15], 0, v[28:29]
	v_or_b32_e32 v128, 38, v16
	global_load_dword v47, v[28:29], off
	v_lshlrev_b64 v[28:29], 12, v[128:129]
	v_lshl_add_u64 v[28:29], v[14:15], 0, v[28:29]
	v_or_b32_e32 v128, 40, v16
	global_load_dword v48, v[28:29], off
	v_lshlrev_b64 v[28:29], 12, v[128:129]
	v_lshl_add_u64 v[28:29], v[14:15], 0, v[28:29]
	v_or_b32_e32 v128, 42, v16
	global_load_dword v49, v[28:29], off
	v_lshlrev_b64 v[28:29], 12, v[128:129]
	v_lshl_add_u64 v[28:29], v[14:15], 0, v[28:29]
	v_or_b32_e32 v128, 44, v16
	global_load_dword v50, v[28:29], off
	v_lshlrev_b64 v[28:29], 12, v[128:129]
	v_lshl_add_u64 v[28:29], v[14:15], 0, v[28:29]
	v_or_b32_e32 v128, 46, v16
	global_load_dword v51, v[28:29], off
	v_lshlrev_b64 v[28:29], 12, v[128:129]
	v_lshl_add_u64 v[28:29], v[14:15], 0, v[28:29]
	v_or_b32_e32 v128, 48, v16
	global_load_dword v52, v[28:29], off
	v_lshlrev_b64 v[28:29], 12, v[128:129]
	v_lshl_add_u64 v[28:29], v[14:15], 0, v[28:29]
	v_or_b32_e32 v128, 50, v16
	global_load_dword v53, v[28:29], off
	v_lshlrev_b64 v[28:29], 12, v[128:129]
	v_lshl_add_u64 v[28:29], v[14:15], 0, v[28:29]
	v_or_b32_e32 v128, 52, v16
	global_load_dword v54, v[28:29], off
	v_lshlrev_b64 v[28:29], 12, v[128:129]
	v_lshl_add_u64 v[28:29], v[14:15], 0, v[28:29]
	v_or_b32_e32 v128, 54, v16
	global_load_dword v55, v[28:29], off
	v_lshlrev_b64 v[28:29], 12, v[128:129]
	v_lshl_add_u64 v[28:29], v[14:15], 0, v[28:29]
	v_or_b32_e32 v128, 56, v16
	global_load_dword v56, v[28:29], off
	v_lshlrev_b64 v[28:29], 12, v[128:129]
	v_lshl_add_u64 v[28:29], v[14:15], 0, v[28:29]
	v_or_b32_e32 v128, 58, v16
	global_load_dword v57, v[28:29], off
	v_lshlrev_b64 v[28:29], 12, v[128:129]
	v_lshl_add_u64 v[28:29], v[14:15], 0, v[28:29]
	v_or_b32_e32 v128, 60, v16
	global_load_dword v58, v[28:29], off
	v_lshlrev_b64 v[28:29], 12, v[128:129]
	v_or_b32_e32 v128, 62, v16
	v_lshlrev_b64 v[16:17], 12, v[128:129]
	v_lshl_add_u64 v[28:29], v[14:15], 0, v[28:29]
	v_lshl_add_u64 v[14:15], v[14:15], 0, v[16:17]
	global_load_dword v28, v[28:29], off
	global_load_dword v14, v[14:15], off
	s_waitcnt vmcnt(30)
; #define LAS __attribute__((address_space(3)))
; #define GAS __attribute__((address_space(1)))
; __device__ __forceinline__ unsigned cvt_pk_bf16(float lo, float hi) { unsigned r; asm volatile("v_cvt_pk_bf16_f32 %0, %1, %2" : "=v"(r) : "v"(lo), "v"(hi)); return r; }
; __device__ __forceinline__ void transpose_item(const float* W, int ldw, int k0, int n0, bf16_t* WT, int ldt, int drow0, int dk0, LAS float* scr, int lane) {
;     ...
;     for (int i = 0; i < 32; ++i) { const int kk = 2 * i + (lane >> 5); scr[kk * 33 + (lane & 31)] = tv[i]; }
;     asm volatile("s_waitcnt lgkmcnt(0)" ::: "memory");
;     const int c = lane & 7;
; #pragma unroll
;     for (int j = 0; j < 4; ++j) { const int n = (lane >> 3) + 8 * j; const LAS float* s = scr + (8 * c) * 33 + n;
;         u32x4 o; o.x = cvt_pk_bf16(s[0 * 33], s[1 * 33]); o.y = cvt_pk_bf16(s[2 * 33], s[3 * 33]); o.z = cvt_pk_bf16(s[4 * 33], s[5 * 33]); o.w = cvt_pk_bf16(s[6 * 33], s[7 * 33]);
;         *(GAS u32x4*)((GAS bf16_t*)WT + (size_t)(drow0 + n) * ldt + dk0 + 8 * c) = o; }
	ds_write2_b32 v19, v13, v30 offset1:66
	s_waitcnt vmcnt(28)
	ds_write2_b32 v19, v31, v32 offset0:132 offset1:198
	v_add_u32_e32 v13, 0x400, v19
	s_waitcnt vmcnt(26)
	ds_write2_b32 v13, v33, v34 offset0:8 offset1:74
	s_waitcnt vmcnt(24)
	ds_write2_b32 v13, v35, v36 offset0:140 offset1:206
	v_add_u32_e32 v13, 0x800, v19
	s_waitcnt vmcnt(22)
	ds_write2_b32 v13, v37, v38 offset0:16 offset1:82
	s_waitcnt vmcnt(20)
	ds_write2_b32 v13, v39, v40 offset0:148 offset1:214
	v_add_u32_e32 v13, 0xc00, v19
	s_waitcnt vmcnt(18)
	ds_write2_b32 v13, v41, v42 offset0:24 offset1:90
	s_waitcnt vmcnt(16)
	ds_write2_b32 v13, v43, v44 offset0:156 offset1:222
	v_add_u32_e32 v13, 0x1000, v19
	s_waitcnt vmcnt(14)
	ds_write2_b32 v13, v45, v46 offset0:32 offset1:98
	s_waitcnt vmcnt(12)
	ds_write2_b32 v13, v47, v48 offset0:164 offset1:230
	v_add_u32_e32 v13, 0x1400, v19
	s_waitcnt vmcnt(10)
	ds_write2_b32 v13, v49, v50 offset0:40 offset1:106
	s_waitcnt vmcnt(8)
	ds_write2_b32 v13, v51, v52 offset0:172 offset1:238
	v_add_u32_e32 v13, 0x1800, v19
	s_waitcnt vmcnt(6)
	ds_write2_b32 v13, v53, v54 offset0:48 offset1:114
	s_waitcnt vmcnt(4)
	ds_write2_b32 v13, v55, v56 offset0:180 offset1:246
	v_add_u32_e32 v13, 0x1c00, v19
	s_waitcnt vmcnt(2)
	ds_write2_b32 v13, v57, v58 offset0:56 offset1:122
	s_waitcnt vmcnt(0)
	ds_write2_b32 v13, v28, v14 offset0:188 offset1:254
	s_waitcnt lgkmcnt(0)
	v_mov_b32_e32 v13, v129
	v_lshl_add_u64 v[16:17], v[12:13], 1, v[4:5]
	ds_read2_b32 v[12:13], v21 offset1:33
	s_waitcnt lgkmcnt(0)
	v_cvt_pk_bf16_f32 v12, v12, v13
	ds_read2_b32 v[14:15], v21 offset0:66 offset1:99
	s_waitcnt lgkmcnt(0)
	v_cvt_pk_bf16_f32 v13, v14, v15
	ds_read2_b32 v[14:15], v21 offset0:132 offset1:165
	s_waitcnt lgkmcnt(0)
	v_cvt_pk_bf16_f32 v14, v14, v15
	ds_read2_b32 v[28:29], v21 offset0:198 offset1:231
	s_waitcnt lgkmcnt(0)
	v_cvt_pk_bf16_f32 v15, v28, v29
	v_or_b32_e32 v28, v27, v20
	v_mul_u32_u24_e32 v28, 0x500, v28
	v_lshlrev_b32_e32 v128, 1, v28
	v_lshl_add_u64 v[28:29], v[16:17], 0, v[128:129]
	global_store_dwordx4 v[28:29], v[12:15], off
	ds_read2_b32 v[12:13], v21 offset0:8 offset1:41
	s_waitcnt lgkmcnt(0)
	v_cvt_pk_bf16_f32 v12, v12, v13
	ds_read2_b32 v[14:15], v21 offset0:74 offset1:107
	s_waitcnt lgkmcnt(0)
	v_cvt_pk_bf16_f32 v13, v14, v15
	ds_read2_b32 v[14:15], v21 offset0:140 offset1:173
	s_waitcnt lgkmcnt(0)
	v_cvt_pk_bf16_f32 v14, v14, v15
	ds_read2_b32 v[28:29], v21 offset0:206 offset1:239
	s_waitcnt lgkmcnt(0)
	v_cvt_pk_bf16_f32 v15, v28, v29
	v_or_b32_e32 v28, v27, v22
	v_mul_u32_u24_e32 v28, 0x500, v28
	v_lshlrev_b32_e32 v128, 1, v28
	v_lshl_add_u64 v[28:29], v[16:17], 0, v[128:129]
	global_store_dwordx4 v[28:29], v[12:15], off
	ds_read2_b32 v[12:13], v21 offset0:16 offset1:49
	s_waitcnt lgkmcnt(0)
	v_cvt_pk_bf16_f32 v12, v12, v13
	ds_read2_b32 v[14:15], v21 offset0:82 offset1:115
	s_waitcnt lgkmcnt(0)
	v_cvt_pk_bf16_f32 v13, v14, v15
	ds_read2_b32 v[14:15], v21 offset0:148 offset1:181
	s_waitcnt lgkmcnt(0)
	v_cvt_pk_bf16_f32 v14, v14, v15
	ds_read2_b32 v[28:29], v21 offset0:214 offset1:247
	s_waitcnt lgkmcnt(0)
	v_cvt_pk_bf16_f32 v15, v28, v29
	v_or_b32_e32 v28, v27, v23
	v_mul_u32_u24_e32 v28, 0x500, v28
	v_lshlrev_b32_e32 v128, 1, v28
	v_lshl_add_u64 v[28:29], v[16:17], 0, v[128:129]
	v_or_b32_e32 v27, v27, v24
	global_store_dwordx4 v[28:29], v[12:15], off
	ds_read2_b32 v[12:13], v21 offset0:24 offset1:57
	v_mul_u32_u24_e32 v27, 0x500, v27
	s_waitcnt lgkmcnt(0)
	v_cvt_pk_bf16_f32 v12, v12, v13
	ds_read2_b32 v[14:15], v21 offset0:90 offset1:123
	v_lshlrev_b32_e32 v128, 1, v27
	s_waitcnt lgkmcnt(0)
	v_cvt_pk_bf16_f32 v13, v14, v15
	ds_read2_b32 v[14:15], v21 offset0:156 offset1:189
	v_lshl_add_u64 v[16:17], v[16:17], 0, v[128:129]
	s_waitcnt lgkmcnt(0)
	v_cvt_pk_bf16_f32 v14, v14, v15
	ds_read2_b32 v[28:29], v21 offset0:222 offset1:255
	s_waitcnt lgkmcnt(0)
	v_cvt_pk_bf16_f32 v15, v28, v29
	global_store_dwordx4 v[16:17], v[12:15], off
	s_waitcnt lgkmcnt(0)

; __device__ __forceinline__ void prep_weights(const Params& P, LAS unsigned char* lds, int lay, int bid, int G, int sel) {
;     ...
;     { const int gt = bid * 512 + tid, NGT = G * 512; const int l = lay;
;       for (int idx = gt; idx < ((sel & 32) ? 256 * 1024 : 0); idx += NGT) { const int n = idx & 1023, gj = (idx >> 10) & 255, g = gj >> 6, j = gj & 63;
;           const float* wp = P.w_out + (size_t)l * 1024 * 1024 + (size_t)(768 + g * 64) * 1024 + n; float cs = 0.f, sn = 0.f;
; #pragma unroll 1
;           for (int m0 = 0; m0 < 64; m0 += 32) { float wv[32];
; #pragma unroll
;               for (int m = 0; m < 32; ++m) wv[m] = wp[(size_t)(m0 + m) * 1024];
; #pragma unroll
;               for (int m = 0; m < 32; ++m) { const int t = ((m0 + m) * j) & 63; cs += tab64[t] * wv[m]; sn += tab64[(t + 48) & 63] * wv[m]; } }
.LBB0_1117:
	s_lshl_b32 s74, s3, 10
	v_lshl_add_u64 v[24:25], s[74:75], 2, v[2:3]
	v_add_co_u32_e32 v12, vcc, 0x1000, v24
	global_load_dword v50, v[24:25], off
	s_nop 0
	v_addc_co_u32_e32 v13, vcc, 0, v25, vcc
	global_load_dword v52, v[12:13], off
	v_add_co_u32_e32 v12, vcc, 0x2000, v24
	s_add_i32 s0, 0, 0x24000
	s_nop 0
	v_addc_co_u32_e32 v13, vcc, 0, v25, vcc
	global_load_dword v54, v[12:13], off
	v_add_co_u32_e32 v12, vcc, 0x3000, v24
	s_nop 1
	v_addc_co_u32_e32 v13, vcc, 0, v25, vcc
	global_load_dword v56, v[12:13], off
	v_add_co_u32_e32 v12, vcc, 0x4000, v24
	s_nop 1
	v_addc_co_u32_e32 v13, vcc, 0, v25, vcc
	global_load_dword v58, v[12:13], off
	v_add_co_u32_e32 v12, vcc, 0x5000, v24
	s_nop 1
	v_addc_co_u32_e32 v13, vcc, 0, v25, vcc
	global_load_dword v60, v[12:13], off
	v_add_co_u32_e32 v12, vcc, 0x6000, v24
	s_nop 1
	v_addc_co_u32_e32 v13, vcc, 0, v25, vcc
	global_load_dword v62, v[12:13], off
	v_add_co_u32_e32 v12, vcc, 0x7000, v24
	s_nop 1
	v_addc_co_u32_e32 v13, vcc, 0, v25, vcc
	global_load_dword v64, v[12:13], off
	v_add_co_u32_e32 v12, vcc, s21, v24
	s_nop 1
	v_addc_co_u32_e32 v13, vcc, 0, v25, vcc
	global_load_dword v66, v[12:13], off offset:-4096
	global_load_dword v68, v[12:13], off
	v_add_co_u32_e32 v12, vcc, s14, v24
	s_nop 1
	v_addc_co_u32_e32 v13, vcc, 0, v25, vcc
	global_load_dword v28, v[12:13], off offset:-4096
	global_load_dword v30, v[12:13], off
	v_add_co_u32_e32 v12, vcc, s15, v24
	s_nop 1
	v_addc_co_u32_e32 v13, vcc, 0, v25, vcc
	global_load_dword v32, v[12:13], off offset:-4096
	global_load_dword v34, v[12:13], off
	v_add_co_u32_e32 v12, vcc, s26, v24
	s_nop 1
	v_addc_co_u32_e32 v13, vcc, 0, v25, vcc
	global_load_dword v36, v[12:13], off offset:-4096
	global_load_dword v38, v[12:13], off
	v_add_co_u32_e32 v12, vcc, s27, v24
	s_nop 1
	v_addc_co_u32_e32 v13, vcc, 0, v25, vcc
	global_load_dword v40, v[12:13], off offset:-4096
	global_load_dword v42, v[12:13], off
	v_add_co_u32_e32 v12, vcc, s63, v24
	s_nop 1
	v_addc_co_u32_e32 v13, vcc, 0, v25, vcc
	global_load_dword v44, v[12:13], off offset:-4096
	global_load_dword v46, v[12:13], off
	v_add_co_u32_e32 v12, vcc, s64, v24
	s_nop 1
	v_addc_co_u32_e32 v13, vcc, 0, v25, vcc
	global_load_dword v48, v[12:13], off offset:-4096
	global_load_dword v6, v[12:13], off
	v_add_co_u32_e32 v12, vcc, s65, v24
	s_nop 1
	v_addc_co_u32_e32 v13, vcc, 0, v25, vcc
	v_add_co_u32_e32 v14, vcc, s66, v24
	global_load_dword v8, v[12:13], off offset:-4096
	global_load_dword v10, v[12:13], off
	v_addc_co_u32_e32 v15, vcc, 0, v25, vcc
	v_add_co_u32_e32 v18, vcc, s67, v24
	v_mul_u32_u24_e32 v13, s3, v11
	s_nop 0
	v_addc_co_u32_e32 v19, vcc, 0, v25, vcc
	v_add_co_u32_e32 v22, vcc, s68, v24
	v_and_b32_e32 v13, 32, v13
	s_nop 0
	v_addc_co_u32_e32 v23, vcc, 0, v25, vcc
	v_add_co_u32_e32 v26, vcc, s69, v24
	v_lshl_add_u32 v13, v13, 2, s0
	s_nop 0
	v_addc_co_u32_e32 v27, vcc, 0, v25, vcc
	global_load_dword v12, v[14:15], off offset:-4096
	global_load_dword v14, v[14:15], off
	global_load_dword v16, v[18:19], off offset:-4096
	global_load_dword v18, v[18:19], off
	global_load_dword v20, v[22:23], off offset:-4096
	global_load_dword v22, v[22:23], off
	global_load_dword v24, v[26:27], off offset:-4096
	global_load_dword v26, v[26:27], off
	ds_read_b32 v70, v13
	v_mad_u32_u24 v13, s3, v11, 48
	v_and_b32_e32 v13, 48, v13
	v_lshl_add_u32 v13, v13, 2, s0
	ds_read_b32 v71, v13
	v_mad_u32_u24 v13, s3, v11, v11
	v_and_b32_e32 v15, 63, v13
	v_lshl_add_u32 v15, v15, 2, s0
	ds_read_b32 v72, v15
	v_add_u32_e32 v15, 48, v13
	v_and_b32_e32 v15, 63, v15
	v_lshl_add_u32 v15, v15, 2, s0
	v_add_u32_e32 v13, v13, v11
	ds_read_b32 v73, v15
	v_and_b32_e32 v15, 62, v13
	v_lshl_add_u32 v15, v15, 2, s0
	ds_read_b32 v74, v15
	v_add_u32_e32 v15, 48, v13
	v_and_b32_e32 v15, 62, v15
	v_lshl_add_u32 v15, v15, 2, s0
	v_add_u32_e32 v13, v13, v11
	ds_read_b32 v75, v15
	v_and_b32_e32 v15, 63, v13
	v_lshl_add_u32 v15, v15, 2, s0
	ds_read_b32 v76, v15
	v_add_u32_e32 v15, 48, v13
	v_and_b32_e32 v15, 63, v15
	v_lshl_add_u32 v15, v15, 2, s0
	v_add_u32_e32 v13, v13, v11
	ds_read_b32 v77, v15
	v_and_b32_e32 v15, 60, v13
	v_lshl_add_u32 v15, v15, 2, s0
	ds_read_b32 v78, v15
	v_add_u32_e32 v15, 48, v13
	v_and_b32_e32 v15, 60, v15
	v_lshl_add_u32 v15, v15, 2, s0
	v_add_u32_e32 v13, v13, v11
	ds_read_b32 v79, v15
	v_and_b32_e32 v15, 63, v13
	v_lshl_add_u32 v15, v15, 2, s0
	ds_read_b32 v80, v15
	v_add_u32_e32 v15, 48, v13
	v_and_b32_e32 v15, 63, v15
	v_lshl_add_u32 v15, v15, 2, s0
	v_add_u32_e32 v13, v13, v11
	ds_read_b32 v81, v15
	v_and_b32_e32 v15, 62, v13
	v_lshl_add_u32 v15, v15, 2, s0
	ds_read_b32 v82, v15
	v_add_u32_e32 v15, 48, v13
	v_and_b32_e32 v15, 62, v15
	v_lshl_add_u32 v15, v15, 2, s0
	v_add_u32_e32 v13, v13, v11
	ds_read_b32 v83, v15
	v_and_b32_e32 v15, 63, v13
	v_lshl_add_u32 v15, v15, 2, s0
	ds_read_b32 v84, v15
	v_add_u32_e32 v15, 48, v13
	v_and_b32_e32 v15, 63, v15
	v_lshl_add_u32 v15, v15, 2, s0
	v_add_u32_e32 v13, v13, v11
	ds_read_b32 v85, v15
	v_and_b32_e32 v15, 56, v13
	v_lshl_add_u32 v15, v15, 2, s0
	ds_read_b32 v86, v15
	v_add_u32_e32 v15, 48, v13
	v_and_b32_e32 v15, 56, v15
	v_lshl_add_u32 v15, v15, 2, s0
	v_add_u32_e32 v13, v13, v11
	ds_read_b32 v87, v15
	v_and_b32_e32 v15, 63, v13
	v_lshl_add_u32 v15, v15, 2, s0
	ds_read_b32 v88, v15
	v_add_u32_e32 v15, 48, v13
	v_and_b32_e32 v15, 63, v15
	v_lshl_add_u32 v15, v15, 2, s0
	v_add_u32_e32 v13, v13, v11
	ds_read_b32 v89, v15
	v_and_b32_e32 v15, 62, v13
	v_lshl_add_u32 v15, v15, 2, s0
	s_waitcnt vmcnt(31) lgkmcnt(14)
; __device__ __forceinline__ void prep_weights(const Params& P, LAS unsigned char* lds, int lay, int bid, int G, int sel) {
;     ...
; #pragma unroll
;               for (int m = 0; m < 32; ++m) { const int t = ((m0 + m) * j) & 63; cs += tab64[t] * wv[m]; sn += tab64[(t + 48) & 63] * wv[m]; } }
	v_pk_fma_f32 v[4:5], v[50:51], v[70:71], v[4:5] op_sel_hi:[0,1,1]
	ds_read_b32 v50, v15
	v_add_u32_e32 v15, 48, v13
	v_and_b32_e32 v15, 62, v15
	v_lshl_add_u32 v15, v15, 2, s0
	v_add_u32_e32 v13, v13, v11
	ds_read_b32 v51, v15
	v_and_b32_e32 v15, 63, v13
	v_lshl_add_u32 v15, v15, 2, s0
	s_waitcnt vmcnt(30)
	v_pk_fma_f32 v[4:5], v[52:53], v[72:73], v[4:5] op_sel_hi:[0,1,1]
	ds_read_b32 v52, v15
	v_add_u32_e32 v15, 48, v13
	v_and_b32_e32 v15, 63, v15
	v_lshl_add_u32 v15, v15, 2, s0
	v_add_u32_e32 v13, v13, v11
	ds_read_b32 v53, v15
	v_and_b32_e32 v15, 60, v13
	v_lshl_add_u32 v15, v15, 2, s0
	s_waitcnt vmcnt(29)
	v_pk_fma_f32 v[4:5], v[54:55], v[74:75], v[4:5] op_sel_hi:[0,1,1]
	ds_read_b32 v54, v15
	v_add_u32_e32 v15, 48, v13
	v_and_b32_e32 v15, 60, v15
	v_lshl_add_u32 v15, v15, 2, s0
	v_add_u32_e32 v13, v13, v11
	ds_read_b32 v55, v15
	v_and_b32_e32 v15, 63, v13
	v_lshl_add_u32 v15, v15, 2, s0
	s_waitcnt vmcnt(28) lgkmcnt(14)
	v_pk_fma_f32 v[4:5], v[56:57], v[76:77], v[4:5] op_sel_hi:[0,1,1]
	ds_read_b32 v56, v15
	v_add_u32_e32 v15, 48, v13
	v_and_b32_e32 v15, 63, v15
	v_lshl_add_u32 v15, v15, 2, s0
	v_add_u32_e32 v13, v13, v11
	ds_read_b32 v57, v15
	v_and_b32_e32 v15, 62, v13
	v_lshl_add_u32 v15, v15, 2, s0
	s_waitcnt vmcnt(27)
	v_pk_fma_f32 v[4:5], v[58:59], v[78:79], v[4:5] op_sel_hi:[0,1,1]
	ds_read_b32 v58, v15
	v_add_u32_e32 v15, 48, v13
	v_and_b32_e32 v15, 62, v15
	v_lshl_add_u32 v15, v15, 2, s0
	v_add_u32_e32 v13, v13, v11
	ds_read_b32 v59, v15
	v_and_b32_e32 v15, 63, v13
	v_lshl_add_u32 v15, v15, 2, s0
	s_waitcnt vmcnt(26)
	v_pk_fma_f32 v[4:5], v[60:61], v[80:81], v[4:5] op_sel_hi:[0,1,1]
	ds_read_b32 v60, v15
	v_add_u32_e32 v15, 48, v13
	v_and_b32_e32 v15, 63, v15
	v_lshl_add_u32 v15, v15, 2, s0
	v_add_u32_e32 v13, v13, v11
	ds_read_b32 v61, v15
	v_and_b32_e32 v15, 48, v13
	v_lshl_add_u32 v15, v15, 2, s0
	s_waitcnt vmcnt(25) lgkmcnt(14)
	v_pk_fma_f32 v[4:5], v[62:63], v[82:83], v[4:5] op_sel_hi:[0,1,1]
	ds_read_b32 v62, v15
	v_add_u32_e32 v15, 48, v13
	v_and_b32_e32 v15, 48, v15
	v_lshl_add_u32 v15, v15, 2, s0
	v_add_u32_e32 v13, v13, v11
	ds_read_b32 v63, v15
	v_and_b32_e32 v15, 63, v13
	v_lshl_add_u32 v15, v15, 2, s0
	s_waitcnt vmcnt(24)
	v_pk_fma_f32 v[4:5], v[64:65], v[84:85], v[4:5] op_sel_hi:[0,1,1]
	ds_read_b32 v64, v15
	v_add_u32_e32 v15, 48, v13
	v_and_b32_e32 v15, 63, v15
	v_lshl_add_u32 v15, v15, 2, s0
	v_add_u32_e32 v13, v13, v11
	ds_read_b32 v65, v15
	v_and_b32_e32 v15, 62, v13
	v_lshl_add_u32 v15, v15, 2, s0
	s_waitcnt vmcnt(23)
	v_pk_fma_f32 v[4:5], v[66:67], v[86:87], v[4:5] op_sel_hi:[0,1,1]
	ds_read_b32 v66, v15
	v_add_u32_e32 v15, 48, v13
	v_and_b32_e32 v15, 62, v15
	v_lshl_add_u32 v15, v15, 2, s0
	v_add_u32_e32 v13, v13, v11
	ds_read_b32 v67, v15
	v_and_b32_e32 v15, 63, v13
	v_lshl_add_u32 v15, v15, 2, s0
	s_waitcnt vmcnt(22) lgkmcnt(14)
	v_pk_fma_f32 v[4:5], v[68:69], v[88:89], v[4:5] op_sel_hi:[0,1,1]
	ds_read_b32 v68, v15
	v_add_u32_e32 v15, 48, v13
	v_and_b32_e32 v15, 63, v15
	v_lshl_add_u32 v15, v15, 2, s0
	v_add_u32_e32 v13, v13, v11
	ds_read_b32 v69, v15
	v_and_b32_e32 v15, 60, v13
	v_lshl_add_u32 v15, v15, 2, s0
	ds_read_b32 v70, v15
	v_add_u32_e32 v15, 48, v13
	v_and_b32_e32 v15, 60, v15
	v_lshl_add_u32 v15, v15, 2, s0
	v_add_u32_e32 v13, v13, v11
	ds_read_b32 v71, v15
	v_and_b32_e32 v15, 63, v13
	v_lshl_add_u32 v15, v15, 2, s0
	s_waitcnt vmcnt(21)
	v_pk_fma_f32 v[4:5], v[28:29], v[50:51], v[4:5] op_sel_hi:[0,1,1]
	ds_read_b32 v28, v15
	v_add_u32_e32 v15, 48, v13
	v_and_b32_e32 v15, 63, v15
	v_lshl_add_u32 v15, v15, 2, s0
	v_add_u32_e32 v13, v13, v11
	ds_read_b32 v29, v15
	v_and_b32_e32 v15, 62, v13
	v_lshl_add_u32 v15, v15, 2, s0
	s_waitcnt vmcnt(20)
	v_pk_fma_f32 v[4:5], v[30:31], v[52:53], v[4:5] op_sel_hi:[0,1,1]
	ds_read_b32 v30, v15
	v_add_u32_e32 v15, 48, v13
	v_and_b32_e32 v15, 62, v15
	v_lshl_add_u32 v15, v15, 2, s0
	v_add_u32_e32 v13, v13, v11
	ds_read_b32 v31, v15
	v_and_b32_e32 v15, 63, v13
	v_lshl_add_u32 v15, v15, 2, s0
	s_waitcnt vmcnt(19) lgkmcnt(14)
	v_pk_fma_f32 v[4:5], v[32:33], v[54:55], v[4:5] op_sel_hi:[0,1,1]
	ds_read_b32 v32, v15
	v_add_u32_e32 v15, 48, v13
	v_and_b32_e32 v15, 63, v15
	v_lshl_add_u32 v15, v15, 2, s0
	v_add_u32_e32 v13, v13, v11
	ds_read_b32 v33, v15
	v_and_b32_e32 v15, 56, v13
	v_lshl_add_u32 v15, v15, 2, s0
	s_waitcnt vmcnt(18)
; __device__ __forceinline__ unsigned f2bf(float f) { unsigned u = __float_as_uint(f); return (u + 0x7fffu + ((u >> 16) & 1u)) >> 16; }
; __device__ __forceinline__ void prep_weights(const Params& P, LAS unsigned char* lds, int lay, int bid, int G, int sel) {
;     ...
;           for (int m0 = 0; m0 < 64; m0 += 32) { float wv[32];
; #pragma unroll
;               for (int m = 0; m < 32; ++m) wv[m] = wp[(size_t)(m0 + m) * 1024];
; #pragma unroll
;               for (int m = 0; m < 32; ++m) { const int t = ((m0 + m) * j) & 63; cs += tab64[t] * wv[m]; sn += tab64[(t + 48) & 63] * wv[m]; } }
;           bf16_t* o = (bf16_t*)(ws + OFF_WOUT + l * SZ_WOUT1) + (size_t)n * 1280; o[768 + gj] = (bf16_t)f2bf(cs); o[1024 + gj] = (bf16_t)f2bf(-sn); }
	v_pk_fma_f32 v[4:5], v[34:35], v[56:57], v[4:5] op_sel_hi:[0,1,1]
	ds_read_b32 v34, v15
	v_add_u32_e32 v15, 48, v13
	v_and_b32_e32 v15, 56, v15
	v_lshl_add_u32 v15, v15, 2, s0
	v_add_u32_e32 v13, v13, v11
	ds_read_b32 v35, v15
	v_and_b32_e32 v15, 63, v13
	v_lshl_add_u32 v15, v15, 2, s0
	s_waitcnt vmcnt(17)
	v_pk_fma_f32 v[4:5], v[36:37], v[58:59], v[4:5] op_sel_hi:[0,1,1]
	ds_read_b32 v36, v15
	v_add_u32_e32 v15, 48, v13
	v_and_b32_e32 v15, 63, v15
	v_lshl_add_u32 v15, v15, 2, s0
	v_add_u32_e32 v13, v13, v11
	ds_read_b32 v37, v15
	v_and_b32_e32 v15, 62, v13
	v_lshl_add_u32 v15, v15, 2, s0
	s_waitcnt vmcnt(16)
	v_pk_fma_f32 v[4:5], v[38:39], v[60:61], v[4:5] op_sel_hi:[0,1,1]
	ds_read_b32 v38, v15
	v_add_u32_e32 v15, 48, v13
	v_and_b32_e32 v15, 62, v15
	v_lshl_add_u32 v15, v15, 2, s0
	v_add_u32_e32 v13, v13, v11
	ds_read_b32 v39, v15
	v_and_b32_e32 v15, 63, v13
	v_lshl_add_u32 v15, v15, 2, s0
	s_waitcnt vmcnt(15) lgkmcnt(14)
	v_pk_fma_f32 v[4:5], v[40:41], v[62:63], v[4:5] op_sel_hi:[0,1,1]
	ds_read_b32 v40, v15
	v_add_u32_e32 v15, 48, v13
	v_and_b32_e32 v15, 63, v15
	v_lshl_add_u32 v15, v15, 2, s0
	v_add_u32_e32 v13, v13, v11
	ds_read_b32 v41, v15
	v_and_b32_e32 v15, 60, v13
	v_lshl_add_u32 v15, v15, 2, s0
	s_waitcnt vmcnt(14)
	v_pk_fma_f32 v[4:5], v[42:43], v[64:65], v[4:5] op_sel_hi:[0,1,1]
	ds_read_b32 v42, v15
	v_add_u32_e32 v15, 48, v13
	v_and_b32_e32 v15, 60, v15
	v_lshl_add_u32 v15, v15, 2, s0
	v_add_u32_e32 v13, v13, v11
	ds_read_b32 v43, v15
	v_and_b32_e32 v15, 63, v13
	v_lshl_add_u32 v15, v15, 2, s0
	s_waitcnt vmcnt(13)
	v_pk_fma_f32 v[4:5], v[44:45], v[66:67], v[4:5] op_sel_hi:[0,1,1]
	ds_read_b32 v44, v15
	v_add_u32_e32 v15, 48, v13
	v_and_b32_e32 v15, 63, v15
	v_lshl_add_u32 v15, v15, 2, s0
	v_add_u32_e32 v13, v13, v11
	ds_read_b32 v45, v15
	v_and_b32_e32 v15, 62, v13
	v_lshl_add_u32 v15, v15, 2, s0
	s_waitcnt vmcnt(12)
	v_pk_fma_f32 v[4:5], v[46:47], v[68:69], v[4:5] op_sel_hi:[0,1,1]
	ds_read_b32 v46, v15
	v_add_u32_e32 v15, 48, v13
	v_and_b32_e32 v15, 62, v15
	s_waitcnt vmcnt(11) lgkmcnt(14)
	v_pk_fma_f32 v[4:5], v[48:49], v[70:71], v[4:5] op_sel_hi:[0,1,1]
	v_lshl_add_u32 v15, v15, 2, s0
	v_add_u32_e32 v13, v13, v11
	ds_read_b32 v47, v15
	v_and_b32_e32 v15, 63, v13
	v_add_u32_e32 v13, 48, v13
	s_waitcnt vmcnt(10)
	v_pk_fma_f32 v[4:5], v[6:7], v[28:29], v[4:5] op_sel_hi:[0,1,1]
	v_and_b32_e32 v13, 63, v13
	s_waitcnt vmcnt(9)
	v_pk_fma_f32 v[4:5], v[8:9], v[30:31], v[4:5] op_sel_hi:[0,1,1]
	v_lshl_add_u32 v13, v13, 2, s0
	s_waitcnt vmcnt(8) lgkmcnt(14)
	v_pk_fma_f32 v[4:5], v[10:11], v[32:33], v[4:5] op_sel_hi:[0,1,1]
	v_lshl_add_u32 v15, v15, 2, s0
	s_waitcnt vmcnt(7) lgkmcnt(12)
	v_pk_fma_f32 v[4:5], v[12:13], v[34:35], v[4:5] op_sel_hi:[0,1,1]
	s_waitcnt vmcnt(6) lgkmcnt(10)
	v_pk_fma_f32 v[4:5], v[14:15], v[36:37], v[4:5] op_sel_hi:[0,1,1]
	ds_read_b32 v48, v15
	ds_read_b32 v49, v13
	s_waitcnt vmcnt(5) lgkmcnt(10)
	v_pk_fma_f32 v[4:5], v[16:17], v[38:39], v[4:5] op_sel_hi:[0,1,1]
	s_waitcnt vmcnt(4) lgkmcnt(8)
	v_pk_fma_f32 v[4:5], v[18:19], v[40:41], v[4:5] op_sel_hi:[0,1,1]
	s_waitcnt vmcnt(3) lgkmcnt(6)
	v_pk_fma_f32 v[4:5], v[20:21], v[42:43], v[4:5] op_sel_hi:[0,1,1]
	s_waitcnt vmcnt(2) lgkmcnt(4)
	v_pk_fma_f32 v[4:5], v[22:23], v[44:45], v[4:5] op_sel_hi:[0,1,1]
	s_waitcnt vmcnt(1) lgkmcnt(2)
	v_pk_fma_f32 v[4:5], v[24:25], v[46:47], v[4:5] op_sel_hi:[0,1,1]
	s_waitcnt vmcnt(0) lgkmcnt(0)
	v_pk_fma_f32 v[4:5], v[26:27], v[48:49], v[4:5] op_sel_hi:[0,1,1]
	s_and_b64 vcc, exec, s[42:43]
	s_mov_b64 s[42:43], 0
	s_mov_b32 s3, 32
	s_cbranch_vccnz .LBB0_1117
	v_readlane_b32 s0, v252, 60
	v_readlane_b32 s1, v252, 61
	v_bfe_u32 v6, v4, 16, 1
	v_add3_u32 v4, v4, v6, s19
	v_mov_b64_e32 v[2:3], s[0:1]
	v_lshrrev_b32_e32 v6, 9, v7
	v_mad_u64_u32 v[2:3], s[0:1], v9, s23, v[2:3]
	v_and_b32_e32 v128, 0x1fe, v6
	v_lshl_add_u64 v[2:3], v[2:3], 0, v[128:129]
	global_store_short_d16_hi v[2:3], v4, off offset:1536
	v_xor_b32_e32 v4, 0x80000000, v5
	v_bfe_u32 v5, v4, 16, 1
	v_add3_u32 v4, v4, v5, s19
	s_mov_b32 s0, 0x27fff
	global_store_short_d16_hi v[2:3], v4, off offset:2048
	v_add_u32_e32 v2, 0x18000, v7
	v_cmp_lt_i32_e32 vcc, s0, v7
	s_or_b64 s[40:41], vcc, s[40:41]
	v_mov_b32_e32 v7, v2
	s_andn2_b64 exec, exec, s[40:41]
	s_cbranch_execnz .LBB0_1116

; __device__ __forceinline__ unsigned f2bf(float f) { unsigned u = __float_as_uint(f); return (u + 0x7fffu + ((u >> 16) & 1u)) >> 16; }
; __device__ __forceinline__ void prep_weights(const Params& P, LAS unsigned char* lds, int lay, int bid, int G, int sel) {
;     ...
;       for (int i0 = gt; i0 < ((sel & 64) ? 131072 : 0); i0 += NGT) { const int idx = l * 131072 + i0; const int i = idx & 63, j = (idx >> 6) & 63, hi = idx >> 12;
;           ((bf16_t*)(ws + OFF_WGT))[idx] = (bf16_t)f2bf(P.lru_wg[(size_t)hi * 4096 + i * 64 + j]); }
.LBB0_1122:
	v_add_u32_e32 v8, 0x20000, v2
	v_add_u32_e32 v10, 0x20000, v3
	v_ashrrev_i32_e32 v14, 12, v8
	v_lshlrev_b32_e32 v13, 6, v2
	v_ashrrev_i32_e32 v12, 12, v10
	v_ashrrev_i32_e32 v15, 31, v14
	v_lshlrev_b32_e32 v11, 6, v3
	v_and_b32_e32 v16, 0xfc0, v13
	v_ashrrev_i32_e32 v13, 31, v12
	v_lshlrev_b64 v[14:15], 14, v[14:15]
	v_lshrrev_b32_e32 v9, 6, v2
	v_and_b32_e32 v11, 0xfc0, v11
	v_lshlrev_b32_e32 v128, 2, v16
	v_lshlrev_b64 v[12:13], 14, v[12:13]
	v_lshl_add_u64 v[14:15], s[58:59], 0, v[14:15]
	v_lshrrev_b32_e32 v1, 6, v3
	v_and_b32_e32 v9, 63, v9
	v_lshl_add_u64 v[12:13], s[58:59], 0, v[12:13]
	v_lshl_add_u64 v[14:15], v[14:15], 0, v[128:129]
	v_lshlrev_b32_e32 v128, 2, v11
	v_and_b32_e32 v1, 63, v1
	v_lshl_add_u64 v[12:13], v[12:13], 0, v[128:129]
	v_lshlrev_b32_e32 v128, 2, v9
	v_lshl_add_u64 v[14:15], v[14:15], 0, v[128:129]
	v_lshlrev_b32_e32 v128, 2, v1
	v_lshl_add_u64 v[12:13], v[12:13], 0, v[128:129]
	global_load_dword v1, v[14:15], off
	global_load_dword v12, v[12:13], off
	v_add_u32_e32 v7, -2, v7
	v_ashrrev_i32_e32 v9, 31, v8
	v_cmp_eq_u32_e32 vcc, 0, v7
	v_add_u32_e32 v3, 0x30000, v3
	v_add_u32_e32 v2, 0x30000, v2
	v_ashrrev_i32_e32 v11, 31, v10
	v_lshl_add_u64 v[8:9], v[8:9], 1, s[12:13]
	s_or_b64 s[40:41], vcc, s[40:41]
	v_lshl_add_u64 v[10:11], v[10:11], 1, s[12:13]
	s_waitcnt vmcnt(1)
	v_and_b32_sdwa v13, v1, v170 dst_sel:DWORD dst_unused:UNUSED_PAD src0_sel:WORD_1 src1_sel:DWORD
	s_waitcnt vmcnt(0)
	v_and_b32_sdwa v14, v12, v170 dst_sel:DWORD dst_unused:UNUSED_PAD src0_sel:WORD_1 src1_sel:DWORD
	v_add3_u32 v1, v1, v13, s19
	v_add3_u32 v12, v12, v14, s19
	global_store_short_d16_hi v[8:9], v1, off
	global_store_short_d16_hi v[10:11], v12, off
	s_andn2_b64 exec, exec, s[40:41]
	s_cbranch_execnz .LBB0_1122
	s_or_b64 exec, exec, s[40:41]
	s_mov_b32 s0, 0x18000
	v_cmp_ne_u32_e32 vcc, v4, v5
	v_mad_u32_u24 v2, v5, s0, v0
	s_orn2_b64 s[40:41], vcc, exec

; #define LAS __attribute__((address_space(3)))
; __device__ __forceinline__ void transpose_item(const float* W, int ldw, int k0, int n0, bf16_t* WT, int ldt, int drow0, int dk0, LAS float* scr, int lane) {
;     float tv[32];
; #pragma unroll
;     for (int i = 0; i < 32; ++i) { const int kk = 2 * i + (lane >> 5); tv[i] = W[(size_t)(k0 + kk) * ldw + n0 + (lane & 31)]; }
; __device__ __forceinline__ void prep_weights(const Params& P, LAS unsigned char* lds, int lay, int bid, int G, int sel) {
;     ...
;           if (sel & 32) { const int mat = lay, kb = r / 32, nb = r % 32;
;               transpose_item(P.w_out + (size_t)mat * 1024 * 1024, 1024, kb * 64, nb * 32, (bf16_t*)(ws + OFF_WOUT + mat * SZ_WOUT1), 1280, nb * 32, kb * 64, scr, lane); } } }
.LBB0_1157:
	s_movk_i32 s0, 0x15ff
	v_cmp_lt_i32_e32 vcc, s0, v20
	s_and_saveexec_b64 s[0:1], vcc
	s_xor_b64 s[42:43], exec, s[0:1]
	s_cbranch_execz .LBB0_1169
	s_movk_i32 s0, 0x20ff
	v_cmp_lt_u32_e32 vcc, s0, v20
	s_and_saveexec_b64 s[0:1], vcc
	s_xor_b64 s[8:9], exec, s[0:1]
	s_cbranch_execz .LBB0_1164
	s_movk_i32 s0, 0x247f
	v_cmp_lt_u32_e32 vcc, s0, v20
	s_and_saveexec_b64 s[0:1], vcc
	s_xor_b64 s[46:47], exec, s[0:1]
	s_cbranch_execz .LBB0_1161
	v_and_b32_e32 v13, 0x7fffffc0, v29
	v_add_u32_e32 v14, 0xffffb700, v13
	v_and_b32_e32 v13, 0x3e0, v30
	v_or_b32_e32 v18, v14, v22
	v_lshlrev_b32_e32 v16, 2, v13
	v_mov_b32_e32 v17, v129
	v_mov_b32_e32 v19, v129
	v_lshl_add_u64 v[16:17], v[4:5], 0, v[16:17]
	v_lshlrev_b64 v[32:33], 12, v[18:19]
	v_lshl_add_u64 v[32:33], v[16:17], 0, v[32:33]
	global_load_dword v15, v[32:33], off
	v_or_b32_e32 v32, 2, v18
	v_mov_b32_e32 v33, v129
	v_lshlrev_b64 v[32:33], 12, v[32:33]
	v_lshl_add_u64 v[32:33], v[16:17], 0, v[32:33]
	global_load_dword v31, v[32:33], off
	v_or_b32_e32 v32, 4, v18
	v_mov_b32_e32 v33, v129
	v_lshlrev_b64 v[32:33], 12, v[32:33]
	v_lshl_add_u64 v[32:33], v[16:17], 0, v[32:33]
	global_load_dword v34, v[32:33], off
	v_or_b32_e32 v32, 6, v18
	v_mov_b32_e32 v33, v129
	v_lshlrev_b64 v[32:33], 12, v[32:33]
	v_lshl_add_u64 v[32:33], v[16:17], 0, v[32:33]
	global_load_dword v35, v[32:33], off
	v_or_b32_e32 v32, 8, v18
	v_mov_b32_e32 v33, v129
	v_lshlrev_b64 v[32:33], 12, v[32:33]
	v_lshl_add_u64 v[32:33], v[16:17], 0, v[32:33]
	global_load_dword v36, v[32:33], off
	v_or_b32_e32 v32, 10, v18
	v_mov_b32_e32 v33, v129
	v_lshlrev_b64 v[32:33], 12, v[32:33]
	v_lshl_add_u64 v[32:33], v[16:17], 0, v[32:33]
	global_load_dword v37, v[32:33], off
	v_or_b32_e32 v32, 12, v18
	v_mov_b32_e32 v33, v129
	v_lshlrev_b64 v[32:33], 12, v[32:33]
	v_lshl_add_u64 v[32:33], v[16:17], 0, v[32:33]
	global_load_dword v38, v[32:33], off
	v_or_b32_e32 v32, 14, v18
	v_mov_b32_e32 v33, v129
	v_lshlrev_b64 v[32:33], 12, v[32:33]
	v_lshl_add_u64 v[32:33], v[16:17], 0, v[32:33]
	global_load_dword v39, v[32:33], off
	v_or_b32_e32 v32, 16, v18
	v_mov_b32_e32 v33, v129
	v_lshlrev_b64 v[32:33], 12, v[32:33]
	v_lshl_add_u64 v[32:33], v[16:17], 0, v[32:33]
	global_load_dword v40, v[32:33], off
	v_or_b32_e32 v32, 18, v18
	v_mov_b32_e32 v33, v129
	v_lshlrev_b64 v[32:33], 12, v[32:33]
	v_lshl_add_u64 v[32:33], v[16:17], 0, v[32:33]
	global_load_dword v41, v[32:33], off
	v_or_b32_e32 v32, 20, v18
	v_mov_b32_e32 v33, v129
	v_lshlrev_b64 v[32:33], 12, v[32:33]
	v_lshl_add_u64 v[32:33], v[16:17], 0, v[32:33]
	global_load_dword v42, v[32:33], off
	v_or_b32_e32 v32, 22, v18
	v_mov_b32_e32 v33, v129
	v_lshlrev_b64 v[32:33], 12, v[32:33]
	v_lshl_add_u64 v[32:33], v[16:17], 0, v[32:33]
	global_load_dword v43, v[32:33], off
	v_or_b32_e32 v32, 24, v18
	v_mov_b32_e32 v33, v129
	v_lshlrev_b64 v[32:33], 12, v[32:33]
	v_lshl_add_u64 v[32:33], v[16:17], 0, v[32:33]
	global_load_dword v44, v[32:33], off
	v_or_b32_e32 v32, 26, v18
	v_mov_b32_e32 v33, v129
	v_lshlrev_b64 v[32:33], 12, v[32:33]
	v_lshl_add_u64 v[32:33], v[16:17], 0, v[32:33]
	global_load_dword v45, v[32:33], off
	v_or_b32_e32 v32, 28, v18
	v_mov_b32_e32 v33, v129
	v_lshlrev_b64 v[32:33], 12, v[32:33]
	v_lshl_add_u64 v[32:33], v[16:17], 0, v[32:33]
	global_load_dword v46, v[32:33], off
	v_or_b32_e32 v32, 30, v18
	v_mov_b32_e32 v33, v129
	v_lshlrev_b64 v[32:33], 12, v[32:33]
	v_lshl_add_u64 v[32:33], v[16:17], 0, v[32:33]
	global_load_dword v47, v[32:33], off
	v_or_b32_e32 v32, 32, v18
	v_mov_b32_e32 v33, v129
	v_lshlrev_b64 v[32:33], 12, v[32:33]
	v_lshl_add_u64 v[32:33], v[16:17], 0, v[32:33]
	global_load_dword v48, v[32:33], off
	v_or_b32_e32 v32, 34, v18
	v_mov_b32_e32 v33, v129
	v_lshlrev_b64 v[32:33], 12, v[32:33]
	v_lshl_add_u64 v[32:33], v[16:17], 0, v[32:33]
	global_load_dword v49, v[32:33], off
	v_or_b32_e32 v32, 36, v18
	v_mov_b32_e32 v33, v129
	v_lshlrev_b64 v[32:33], 12, v[32:33]
	v_lshl_add_u64 v[32:33], v[16:17], 0, v[32:33]
	global_load_dword v50, v[32:33], off
	v_or_b32_e32 v32, 38, v18
	v_mov_b32_e32 v33, v129
	v_lshlrev_b64 v[32:33], 12, v[32:33]
	v_lshl_add_u64 v[32:33], v[16:17], 0, v[32:33]
	global_load_dword v51, v[32:33], off
	v_or_b32_e32 v32, 40, v18
	v_mov_b32_e32 v33, v129
	v_lshlrev_b64 v[32:33], 12, v[32:33]
	v_lshl_add_u64 v[32:33], v[16:17], 0, v[32:33]
	global_load_dword v52, v[32:33], off
	v_or_b32_e32 v32, 42, v18
	v_mov_b32_e32 v33, v129
	v_lshlrev_b64 v[32:33], 12, v[32:33]
	v_lshl_add_u64 v[32:33], v[16:17], 0, v[32:33]
	global_load_dword v53, v[32:33], off
	v_or_b32_e32 v32, 44, v18
	v_mov_b32_e32 v33, v129
	v_lshlrev_b64 v[32:33], 12, v[32:33]
	v_lshl_add_u64 v[32:33], v[16:17], 0, v[32:33]
	global_load_dword v54, v[32:33], off
	v_or_b32_e32 v32, 46, v18
	v_mov_b32_e32 v33, v129
	v_lshlrev_b64 v[32:33], 12, v[32:33]
	v_lshl_add_u64 v[32:33], v[16:17], 0, v[32:33]
	global_load_dword v55, v[32:33], off
	v_or_b32_e32 v32, 48, v18
	v_mov_b32_e32 v33, v129
	v_lshlrev_b64 v[32:33], 12, v[32:33]
	v_lshl_add_u64 v[32:33], v[16:17], 0, v[32:33]
	global_load_dword v56, v[32:33], off
	v_or_b32_e32 v32, 50, v18
	v_mov_b32_e32 v33, v129
	v_lshlrev_b64 v[32:33], 12, v[32:33]
	v_lshl_add_u64 v[32:33], v[16:17], 0, v[32:33]
	global_load_dword v57, v[32:33], off
	v_or_b32_e32 v32, 52, v18
	v_mov_b32_e32 v33, v129
	v_lshlrev_b64 v[32:33], 12, v[32:33]
	v_lshl_add_u64 v[32:33], v[16:17], 0, v[32:33]
	global_load_dword v58, v[32:33], off
	v_or_b32_e32 v32, 54, v18
	v_mov_b32_e32 v33, v129
	v_lshlrev_b64 v[32:33], 12, v[32:33]
	v_lshl_add_u64 v[32:33], v[16:17], 0, v[32:33]
	global_load_dword v59, v[32:33], off
	v_or_b32_e32 v32, 56, v18
	v_mov_b32_e32 v33, v129
	v_lshlrev_b64 v[32:33], 12, v[32:33]
	v_lshl_add_u64 v[32:33], v[16:17], 0, v[32:33]
	global_load_dword v60, v[32:33], off
	v_or_b32_e32 v32, 58, v18
	v_mov_b32_e32 v33, v129
	v_lshlrev_b64 v[32:33], 12, v[32:33]
	v_lshl_add_u64 v[32:33], v[16:17], 0, v[32:33]
	global_load_dword v61, v[32:33], off
	v_or_b32_e32 v32, 60, v18
	v_mov_b32_e32 v33, v129
	v_or_b32_e32 v18, 62, v18
	v_lshlrev_b64 v[32:33], 12, v[32:33]
	v_lshlrev_b64 v[18:19], 12, v[18:19]
	v_lshl_add_u64 v[32:33], v[16:17], 0, v[32:33]
	v_lshl_add_u64 v[16:17], v[16:17], 0, v[18:19]
	global_load_dword v32, v[32:33], off
	global_load_dword v16, v[16:17], off
	s_waitcnt vmcnt(30)
; #define LAS __attribute__((address_space(3)))
; #define GAS __attribute__((address_space(1)))
; __device__ __forceinline__ unsigned cvt_pk_bf16(float lo, float hi) { unsigned r; asm volatile("v_cvt_pk_bf16_f32 %0, %1, %2" : "=v"(r) : "v"(lo), "v"(hi)); return r; }
; __device__ __forceinline__ void transpose_item(const float* W, int ldw, int k0, int n0, bf16_t* WT, int ldt, int drow0, int dk0, LAS float* scr, int lane) {
;     ...
;     for (int i = 0; i < 32; ++i) { const int kk = 2 * i + (lane >> 5); scr[kk * 33 + (lane & 31)] = tv[i]; }
;     asm volatile("s_waitcnt lgkmcnt(0)" ::: "memory");
;     const int c = lane & 7;
; #pragma unroll
;     for (int j = 0; j < 4; ++j) { const int n = (lane >> 3) + 8 * j; const LAS float* s = scr + (8 * c) * 33 + n;
;         u32x4 o; o.x = cvt_pk_bf16(s[0 * 33], s[1 * 33]); o.y = cvt_pk_bf16(s[2 * 33], s[3 * 33]); o.z = cvt_pk_bf16(s[4 * 33], s[5 * 33]); o.w = cvt_pk_bf16(s[6 * 33], s[7 * 33]);
;         *(GAS u32x4*)((GAS bf16_t*)WT + (size_t)(drow0 + n) * ldt + dk0 + 8 * c) = o; }
; __device__ __forceinline__ void prep_weights(const Params& P, LAS unsigned char* lds, int lay, int bid, int G, int sel) {
;     ...
;           if (sel & 32) { const int mat = lay, kb = r / 32, nb = r % 32;
;               transpose_item(P.w_out + (size_t)mat * 1024 * 1024, 1024, kb * 64, nb * 32, (bf16_t*)(ws + OFF_WOUT + mat * SZ_WOUT1), 1280, nb * 32, kb * 64, scr, lane); } } }
	ds_write2_b32 v23, v15, v31 offset1:66
	s_waitcnt vmcnt(28)
	ds_write2_b32 v23, v34, v35 offset0:132 offset1:198
	v_add_u32_e32 v15, 0x400, v23
	s_waitcnt vmcnt(26)
	ds_write2_b32 v15, v36, v37 offset0:8 offset1:74
	s_waitcnt vmcnt(24)
	ds_write2_b32 v15, v38, v39 offset0:140 offset1:206
	v_add_u32_e32 v15, 0x800, v23
	s_waitcnt vmcnt(22)
	ds_write2_b32 v15, v40, v41 offset0:16 offset1:82
	s_waitcnt vmcnt(20)
	ds_write2_b32 v15, v42, v43 offset0:148 offset1:214
	v_add_u32_e32 v15, 0xc00, v23
	s_waitcnt vmcnt(18)
	ds_write2_b32 v15, v44, v45 offset0:24 offset1:90
	s_waitcnt vmcnt(16)
	ds_write2_b32 v15, v46, v47 offset0:156 offset1:222
	v_add_u32_e32 v15, 0x1000, v23
	s_waitcnt vmcnt(14)
	ds_write2_b32 v15, v48, v49 offset0:32 offset1:98
	s_waitcnt vmcnt(12)
	ds_write2_b32 v15, v50, v51 offset0:164 offset1:230
	v_add_u32_e32 v15, 0x1400, v23
	s_waitcnt vmcnt(10)
	ds_write2_b32 v15, v52, v53 offset0:40 offset1:106
	s_waitcnt vmcnt(8)
	ds_write2_b32 v15, v54, v55 offset0:172 offset1:238
	v_add_u32_e32 v15, 0x1800, v23
	s_waitcnt vmcnt(6)
	ds_write2_b32 v15, v56, v57 offset0:48 offset1:114
	s_waitcnt vmcnt(4)
	ds_write2_b32 v15, v58, v59 offset0:180 offset1:246
	v_add_u32_e32 v15, 0x1c00, v23
	s_waitcnt vmcnt(2)
	ds_write2_b32 v15, v60, v61 offset0:56 offset1:122
	s_waitcnt vmcnt(0)
	ds_write2_b32 v15, v32, v16 offset0:188 offset1:254
	s_waitcnt lgkmcnt(0)
	v_mov_b32_e32 v15, v129
	v_lshl_add_u64 v[18:19], v[14:15], 1, v[0:1]
	ds_read2_b32 v[14:15], v25 offset1:33
	s_waitcnt lgkmcnt(0)
	v_cvt_pk_bf16_f32 v14, v14, v15
	ds_read2_b32 v[16:17], v25 offset0:66 offset1:99
	s_waitcnt lgkmcnt(0)
	v_cvt_pk_bf16_f32 v15, v16, v17
	ds_read2_b32 v[16:17], v25 offset0:132 offset1:165
	v_or_b32_e32 v31, v13, v24
	s_waitcnt lgkmcnt(0)
	v_cvt_pk_bf16_f32 v16, v16, v17
	ds_read2_b32 v[32:33], v25 offset0:198 offset1:231
	v_mul_u32_u24_e32 v31, 0x500, v31
	s_waitcnt lgkmcnt(0)
	v_cvt_pk_bf16_f32 v17, v32, v33
	v_lshlrev_b32_e32 v32, 1, v31
	v_mov_b32_e32 v33, v129
	v_lshl_add_u64 v[32:33], v[18:19], 0, v[32:33]
	global_store_dwordx4 v[32:33], v[14:17], off
	ds_read2_b32 v[14:15], v25 offset0:8 offset1:41
	v_or_b32_e32 v31, v13, v26
	s_waitcnt lgkmcnt(0)
	v_cvt_pk_bf16_f32 v14, v14, v15
	ds_read2_b32 v[16:17], v25 offset0:74 offset1:107
	s_waitcnt lgkmcnt(0)
	v_cvt_pk_bf16_f32 v15, v16, v17
	ds_read2_b32 v[16:17], v25 offset0:140 offset1:173
	s_waitcnt lgkmcnt(0)
	v_cvt_pk_bf16_f32 v16, v16, v17
	ds_read2_b32 v[32:33], v25 offset0:206 offset1:239
	v_mul_u32_u24_e32 v31, 0x500, v31
	s_waitcnt lgkmcnt(0)
	v_cvt_pk_bf16_f32 v17, v32, v33
	v_lshlrev_b32_e32 v32, 1, v31
	v_mov_b32_e32 v33, v129
	v_lshl_add_u64 v[32:33], v[18:19], 0, v[32:33]
	global_store_dwordx4 v[32:33], v[14:17], off
	ds_read2_b32 v[14:15], v25 offset0:16 offset1:49
	v_or_b32_e32 v31, v13, v27
	s_waitcnt lgkmcnt(0)
	v_cvt_pk_bf16_f32 v14, v14, v15
	ds_read2_b32 v[16:17], v25 offset0:82 offset1:115
	s_waitcnt lgkmcnt(0)
	v_cvt_pk_bf16_f32 v15, v16, v17
	ds_read2_b32 v[16:17], v25 offset0:148 offset1:181
	s_waitcnt lgkmcnt(0)
	v_cvt_pk_bf16_f32 v16, v16, v17
	ds_read2_b32 v[32:33], v25 offset0:214 offset1:247
	v_mul_u32_u24_e32 v31, 0x500, v31
	s_waitcnt lgkmcnt(0)
	v_cvt_pk_bf16_f32 v17, v32, v33
	v_lshlrev_b32_e32 v32, 1, v31
	v_mov_b32_e32 v33, v129
	v_lshl_add_u64 v[32:33], v[18:19], 0, v[32:33]
	global_store_dwordx4 v[32:33], v[14:17], off
	ds_read2_b32 v[14:15], v25 offset0:24 offset1:57
	v_or_b32_e32 v13, v13, v28
	s_waitcnt lgkmcnt(0)
	v_cvt_pk_bf16_f32 v14, v14, v15
	ds_read2_b32 v[16:17], v25 offset0:90 offset1:123
	s_waitcnt lgkmcnt(0)
	v_cvt_pk_bf16_f32 v15, v16, v17
	ds_read2_b32 v[16:17], v25 offset0:156 offset1:189
	s_waitcnt lgkmcnt(0)
	v_cvt_pk_bf16_f32 v16, v16, v17
	ds_read2_b32 v[32:33], v25 offset0:222 offset1:255
	v_mul_u32_u24_e32 v13, 0x500, v13
	s_waitcnt lgkmcnt(0)
	v_cvt_pk_bf16_f32 v17, v32, v33
	v_lshlrev_b32_e32 v32, 1, v13
	v_mov_b32_e32 v33, v129
	v_lshl_add_u64 v[18:19], v[18:19], 0, v[32:33]
	global_store_dwordx4 v[18:19], v[14:17], off
	s_waitcnt lgkmcnt(0)

; __device__ __forceinline__ void prep_weights(const Params& P, LAS unsigned char* lds, int lay, int bid, int G, int sel) {
;     ...
;       for (int idx = gt; idx < ((sel & 32) ? 256 * 1024 : 0); idx += NGT) { const int n = idx & 1023, gj = (idx >> 10) & 255, g = gj >> 6, j = gj & 63;
;           const float* wp = P.w_out + (size_t)l * 1024 * 1024 + (size_t)(768 + g * 64) * 1024 + n; float cs = 0.f, sn = 0.f;
; #pragma unroll 1
;           for (int m0 = 0; m0 < 64; m0 += 32) { float wv[32];
; #pragma unroll
;               for (int m = 0; m < 32; ++m) wv[m] = wp[(size_t)(m0 + m) * 1024];
; #pragma unroll
;               for (int m = 0; m < 32; ++m) { const int t = ((m0 + m) * j) & 63; cs += tab64[t] * wv[m]; sn += tab64[(t + 48) & 63] * wv[m]; } }
.LBB0_1178:
	s_lshl_b32 s74, s3, 10
	v_lshl_add_u64 v[24:25], s[74:75], 2, v[2:3]
	v_add_co_u32_e32 v10, vcc, 0x1000, v24
	global_load_dword v50, v[24:25], off
	s_nop 0
	v_addc_co_u32_e32 v11, vcc, 0, v25, vcc
	global_load_dword v52, v[10:11], off
	v_add_co_u32_e32 v10, vcc, 0x2000, v24
	s_add_i32 s0, 0, 0x24000
	s_nop 0
	v_addc_co_u32_e32 v11, vcc, 0, v25, vcc
	global_load_dword v54, v[10:11], off
	v_add_co_u32_e32 v10, vcc, 0x3000, v24
	s_nop 1
	v_addc_co_u32_e32 v11, vcc, 0, v25, vcc
	global_load_dword v56, v[10:11], off
	v_add_co_u32_e32 v10, vcc, 0x4000, v24
	s_nop 1
	v_addc_co_u32_e32 v11, vcc, 0, v25, vcc
	global_load_dword v58, v[10:11], off
	v_add_co_u32_e32 v10, vcc, 0x5000, v24
	s_nop 1
	v_addc_co_u32_e32 v11, vcc, 0, v25, vcc
	global_load_dword v60, v[10:11], off
	v_add_co_u32_e32 v10, vcc, 0x6000, v24
	s_nop 1
	v_addc_co_u32_e32 v11, vcc, 0, v25, vcc
	global_load_dword v62, v[10:11], off
	v_add_co_u32_e32 v10, vcc, 0x7000, v24
	s_nop 1
	v_addc_co_u32_e32 v11, vcc, 0, v25, vcc
	global_load_dword v64, v[10:11], off
	v_add_co_u32_e32 v10, vcc, s21, v24
	s_nop 1
	v_addc_co_u32_e32 v11, vcc, 0, v25, vcc
	global_load_dword v66, v[10:11], off offset:-4096
	global_load_dword v68, v[10:11], off
	v_add_co_u32_e32 v10, vcc, s14, v24
	s_nop 1
	v_addc_co_u32_e32 v11, vcc, 0, v25, vcc
	global_load_dword v28, v[10:11], off offset:-4096
	global_load_dword v30, v[10:11], off
	v_add_co_u32_e32 v10, vcc, s15, v24
	s_nop 1
	v_addc_co_u32_e32 v11, vcc, 0, v25, vcc
	global_load_dword v32, v[10:11], off offset:-4096
	global_load_dword v34, v[10:11], off
	v_add_co_u32_e32 v10, vcc, s26, v24
	s_nop 1
	v_addc_co_u32_e32 v11, vcc, 0, v25, vcc
	global_load_dword v36, v[10:11], off offset:-4096
	global_load_dword v38, v[10:11], off
	v_add_co_u32_e32 v10, vcc, s27, v24
	s_nop 1
	v_addc_co_u32_e32 v11, vcc, 0, v25, vcc
	global_load_dword v40, v[10:11], off offset:-4096
	global_load_dword v42, v[10:11], off
	v_add_co_u32_e32 v10, vcc, s63, v24
	s_nop 1
	v_addc_co_u32_e32 v11, vcc, 0, v25, vcc
	global_load_dword v44, v[10:11], off offset:-4096
	global_load_dword v46, v[10:11], off
	v_add_co_u32_e32 v10, vcc, s64, v24
	s_nop 1
	v_addc_co_u32_e32 v11, vcc, 0, v25, vcc
	global_load_dword v48, v[10:11], off offset:-4096
	global_load_dword v6, v[10:11], off
	v_add_co_u32_e32 v10, vcc, s65, v24
	s_nop 1
	v_addc_co_u32_e32 v11, vcc, 0, v25, vcc
	v_add_co_u32_e32 v14, vcc, s66, v24
	global_load_dword v8, v[10:11], off offset:-4096
	global_load_dword v10, v[10:11], off
	v_addc_co_u32_e32 v15, vcc, 0, v25, vcc
	v_add_co_u32_e32 v18, vcc, s67, v24
	v_mul_u32_u24_e32 v11, s3, v9
	s_nop 0
	v_addc_co_u32_e32 v19, vcc, 0, v25, vcc
	v_add_co_u32_e32 v22, vcc, s68, v24
	v_and_b32_e32 v11, 32, v11
	s_nop 0
	v_addc_co_u32_e32 v23, vcc, 0, v25, vcc
	v_add_co_u32_e32 v26, vcc, s69, v24
	v_lshl_add_u32 v11, v11, 2, s0
	s_nop 0
	v_addc_co_u32_e32 v27, vcc, 0, v25, vcc
	global_load_dword v12, v[14:15], off offset:-4096
	global_load_dword v14, v[14:15], off
	global_load_dword v16, v[18:19], off offset:-4096
	global_load_dword v18, v[18:19], off
	global_load_dword v20, v[22:23], off offset:-4096
	global_load_dword v22, v[22:23], off
	global_load_dword v24, v[26:27], off offset:-4096
	global_load_dword v26, v[26:27], off
	ds_read_b32 v70, v11
	v_mad_u32_u24 v11, s3, v9, 48
	v_and_b32_e32 v11, 48, v11
	v_lshl_add_u32 v11, v11, 2, s0
	ds_read_b32 v71, v11
	v_mad_u32_u24 v11, s3, v9, v9
	v_and_b32_e32 v13, 63, v11
	v_lshl_add_u32 v13, v13, 2, s0
	ds_read_b32 v72, v13
	v_add_u32_e32 v13, 48, v11
	v_and_b32_e32 v13, 63, v13
	v_lshl_add_u32 v13, v13, 2, s0
	v_add_u32_e32 v11, v11, v9
	ds_read_b32 v73, v13
	v_and_b32_e32 v13, 62, v11
	v_lshl_add_u32 v13, v13, 2, s0
	ds_read_b32 v74, v13
	v_add_u32_e32 v13, 48, v11
	v_and_b32_e32 v13, 62, v13
	v_lshl_add_u32 v13, v13, 2, s0
	v_add_u32_e32 v11, v11, v9
	ds_read_b32 v75, v13
	v_and_b32_e32 v13, 63, v11
	v_lshl_add_u32 v13, v13, 2, s0
	ds_read_b32 v76, v13
	v_add_u32_e32 v13, 48, v11
	v_and_b32_e32 v13, 63, v13
	v_lshl_add_u32 v13, v13, 2, s0
	v_add_u32_e32 v11, v11, v9
	ds_read_b32 v77, v13
	v_and_b32_e32 v13, 60, v11
	v_lshl_add_u32 v13, v13, 2, s0
	ds_read_b32 v78, v13
	v_add_u32_e32 v13, 48, v11
	v_and_b32_e32 v13, 60, v13
	v_lshl_add_u32 v13, v13, 2, s0
	v_add_u32_e32 v11, v11, v9
	ds_read_b32 v79, v13
	v_and_b32_e32 v13, 63, v11
	v_lshl_add_u32 v13, v13, 2, s0
	ds_read_b32 v80, v13
	v_add_u32_e32 v13, 48, v11
	v_and_b32_e32 v13, 63, v13
	v_lshl_add_u32 v13, v13, 2, s0
	v_add_u32_e32 v11, v11, v9
	ds_read_b32 v81, v13
	v_and_b32_e32 v13, 62, v11
	v_lshl_add_u32 v13, v13, 2, s0
	ds_read_b32 v82, v13
	v_add_u32_e32 v13, 48, v11
	v_and_b32_e32 v13, 62, v13
	v_lshl_add_u32 v13, v13, 2, s0
	v_add_u32_e32 v11, v11, v9
	ds_read_b32 v83, v13
	v_and_b32_e32 v13, 63, v11
	v_lshl_add_u32 v13, v13, 2, s0
	ds_read_b32 v84, v13
	v_add_u32_e32 v13, 48, v11
	v_and_b32_e32 v13, 63, v13
	v_lshl_add_u32 v13, v13, 2, s0
	v_add_u32_e32 v11, v11, v9
	ds_read_b32 v85, v13
	v_and_b32_e32 v13, 56, v11
	v_lshl_add_u32 v13, v13, 2, s0
	ds_read_b32 v86, v13
	v_add_u32_e32 v13, 48, v11
	v_and_b32_e32 v13, 56, v13
	v_lshl_add_u32 v13, v13, 2, s0
	v_add_u32_e32 v11, v11, v9
	ds_read_b32 v87, v13
	v_and_b32_e32 v13, 63, v11
	v_lshl_add_u32 v13, v13, 2, s0
	ds_read_b32 v88, v13
	v_add_u32_e32 v13, 48, v11
	v_and_b32_e32 v13, 63, v13
	v_lshl_add_u32 v13, v13, 2, s0
	v_add_u32_e32 v11, v11, v9
	ds_read_b32 v89, v13
	v_and_b32_e32 v13, 62, v11
	v_lshl_add_u32 v13, v13, 2, s0
	s_waitcnt vmcnt(31) lgkmcnt(14)
	v_pk_fma_f32 v[4:5], v[50:51], v[70:71], v[4:5] op_sel_hi:[0,1,1]
	ds_read_b32 v50, v13
	v_add_u32_e32 v13, 48, v11
	v_and_b32_e32 v13, 62, v13
	v_lshl_add_u32 v13, v13, 2, s0
	v_add_u32_e32 v11, v11, v9
	ds_read_b32 v51, v13
	v_and_b32_e32 v13, 63, v11
	v_lshl_add_u32 v13, v13, 2, s0
	s_waitcnt vmcnt(30)
; __device__ __forceinline__ void prep_weights(const Params& P, LAS unsigned char* lds, int lay, int bid, int G, int sel) {
;     ...
;           for (int m0 = 0; m0 < 64; m0 += 32) { float wv[32];
; #pragma unroll
;               for (int m = 0; m < 32; ++m) wv[m] = wp[(size_t)(m0 + m) * 1024];
; #pragma unroll
;               for (int m = 0; m < 32; ++m) { const int t = ((m0 + m) * j) & 63; cs += tab64[t] * wv[m]; sn += tab64[(t + 48) & 63] * wv[m]; } }
	v_pk_fma_f32 v[4:5], v[52:53], v[72:73], v[4:5] op_sel_hi:[0,1,1]
	ds_read_b32 v52, v13
	v_add_u32_e32 v13, 48, v11
	v_and_b32_e32 v13, 63, v13
	v_lshl_add_u32 v13, v13, 2, s0
	v_add_u32_e32 v11, v11, v9
	ds_read_b32 v53, v13
	v_and_b32_e32 v13, 60, v11
	v_lshl_add_u32 v13, v13, 2, s0
	s_waitcnt vmcnt(29)
	v_pk_fma_f32 v[4:5], v[54:55], v[74:75], v[4:5] op_sel_hi:[0,1,1]
	ds_read_b32 v54, v13
	v_add_u32_e32 v13, 48, v11
	v_and_b32_e32 v13, 60, v13
	v_lshl_add_u32 v13, v13, 2, s0
	v_add_u32_e32 v11, v11, v9
	ds_read_b32 v55, v13
	v_and_b32_e32 v13, 63, v11
	v_lshl_add_u32 v13, v13, 2, s0
	s_waitcnt vmcnt(28) lgkmcnt(14)
	v_pk_fma_f32 v[4:5], v[56:57], v[76:77], v[4:5] op_sel_hi:[0,1,1]
	ds_read_b32 v56, v13
	v_add_u32_e32 v13, 48, v11
	v_and_b32_e32 v13, 63, v13
	v_lshl_add_u32 v13, v13, 2, s0
	v_add_u32_e32 v11, v11, v9
	ds_read_b32 v57, v13
	v_and_b32_e32 v13, 62, v11
	v_lshl_add_u32 v13, v13, 2, s0
	s_waitcnt vmcnt(27)
	v_pk_fma_f32 v[4:5], v[58:59], v[78:79], v[4:5] op_sel_hi:[0,1,1]
	ds_read_b32 v58, v13
	v_add_u32_e32 v13, 48, v11
	v_and_b32_e32 v13, 62, v13
	v_lshl_add_u32 v13, v13, 2, s0
	v_add_u32_e32 v11, v11, v9
	ds_read_b32 v59, v13
	v_and_b32_e32 v13, 63, v11
	v_lshl_add_u32 v13, v13, 2, s0
	s_waitcnt vmcnt(26)
	v_pk_fma_f32 v[4:5], v[60:61], v[80:81], v[4:5] op_sel_hi:[0,1,1]
	ds_read_b32 v60, v13
	v_add_u32_e32 v13, 48, v11
	v_and_b32_e32 v13, 63, v13
	v_lshl_add_u32 v13, v13, 2, s0
	v_add_u32_e32 v11, v11, v9
	ds_read_b32 v61, v13
	v_and_b32_e32 v13, 48, v11
	v_lshl_add_u32 v13, v13, 2, s0
	s_waitcnt vmcnt(25) lgkmcnt(14)
	v_pk_fma_f32 v[4:5], v[62:63], v[82:83], v[4:5] op_sel_hi:[0,1,1]
	ds_read_b32 v62, v13
	v_add_u32_e32 v13, 48, v11
	v_and_b32_e32 v13, 48, v13
	v_lshl_add_u32 v13, v13, 2, s0
	v_add_u32_e32 v11, v11, v9
	ds_read_b32 v63, v13
	v_and_b32_e32 v13, 63, v11
	v_lshl_add_u32 v13, v13, 2, s0
	s_waitcnt vmcnt(24)
	v_pk_fma_f32 v[4:5], v[64:65], v[84:85], v[4:5] op_sel_hi:[0,1,1]
	ds_read_b32 v64, v13
	v_add_u32_e32 v13, 48, v11
	v_and_b32_e32 v13, 63, v13
	v_lshl_add_u32 v13, v13, 2, s0
	v_add_u32_e32 v11, v11, v9
	ds_read_b32 v65, v13
	v_and_b32_e32 v13, 62, v11
	v_lshl_add_u32 v13, v13, 2, s0
	s_waitcnt vmcnt(23)
	v_pk_fma_f32 v[4:5], v[66:67], v[86:87], v[4:5] op_sel_hi:[0,1,1]
	ds_read_b32 v66, v13
	v_add_u32_e32 v13, 48, v11
	v_and_b32_e32 v13, 62, v13
	v_lshl_add_u32 v13, v13, 2, s0
	v_add_u32_e32 v11, v11, v9
	ds_read_b32 v67, v13
	v_and_b32_e32 v13, 63, v11
	v_lshl_add_u32 v13, v13, 2, s0
	s_waitcnt vmcnt(22) lgkmcnt(14)
	v_pk_fma_f32 v[4:5], v[68:69], v[88:89], v[4:5] op_sel_hi:[0,1,1]
	ds_read_b32 v68, v13
	v_add_u32_e32 v13, 48, v11
	v_and_b32_e32 v13, 63, v13
	v_lshl_add_u32 v13, v13, 2, s0
	v_add_u32_e32 v11, v11, v9
	ds_read_b32 v69, v13
	v_and_b32_e32 v13, 60, v11
	v_lshl_add_u32 v13, v13, 2, s0
	ds_read_b32 v70, v13
	v_add_u32_e32 v13, 48, v11
	v_and_b32_e32 v13, 60, v13
	v_lshl_add_u32 v13, v13, 2, s0
	v_add_u32_e32 v11, v11, v9
	ds_read_b32 v71, v13
	v_and_b32_e32 v13, 63, v11
	v_lshl_add_u32 v13, v13, 2, s0
	s_waitcnt vmcnt(21)
	v_pk_fma_f32 v[4:5], v[28:29], v[50:51], v[4:5] op_sel_hi:[0,1,1]
	ds_read_b32 v28, v13
	v_add_u32_e32 v13, 48, v11
	v_and_b32_e32 v13, 63, v13
	v_lshl_add_u32 v13, v13, 2, s0
	v_add_u32_e32 v11, v11, v9
	ds_read_b32 v29, v13
	v_and_b32_e32 v13, 62, v11
	v_lshl_add_u32 v13, v13, 2, s0
	s_waitcnt vmcnt(20)
	v_pk_fma_f32 v[4:5], v[30:31], v[52:53], v[4:5] op_sel_hi:[0,1,1]
	ds_read_b32 v30, v13
	v_add_u32_e32 v13, 48, v11
	v_and_b32_e32 v13, 62, v13
	v_lshl_add_u32 v13, v13, 2, s0
	v_add_u32_e32 v11, v11, v9
	ds_read_b32 v31, v13
	v_and_b32_e32 v13, 63, v11
	v_lshl_add_u32 v13, v13, 2, s0
	s_waitcnt vmcnt(19) lgkmcnt(14)
	v_pk_fma_f32 v[4:5], v[32:33], v[54:55], v[4:5] op_sel_hi:[0,1,1]
	ds_read_b32 v32, v13
	v_add_u32_e32 v13, 48, v11
	v_and_b32_e32 v13, 63, v13
	v_lshl_add_u32 v13, v13, 2, s0
	v_add_u32_e32 v11, v11, v9
	ds_read_b32 v33, v13
	v_and_b32_e32 v13, 56, v11
	v_lshl_add_u32 v13, v13, 2, s0
	s_waitcnt vmcnt(18)
; __device__ __forceinline__ unsigned f2bf(float f) { unsigned u = __float_as_uint(f); return (u + 0x7fffu + ((u >> 16) & 1u)) >> 16; }
; __device__ __forceinline__ void prep_weights(const Params& P, LAS unsigned char* lds, int lay, int bid, int G, int sel) {
;     ...
;       for (int idx = gt; idx < ((sel & 32) ? 256 * 1024 : 0); idx += NGT) { const int n = idx & 1023, gj = (idx >> 10) & 255, g = gj >> 6, j = gj & 63;
;           const float* wp = P.w_out + (size_t)l * 1024 * 1024 + (size_t)(768 + g * 64) * 1024 + n; float cs = 0.f, sn = 0.f;
; #pragma unroll 1
;           for (int m0 = 0; m0 < 64; m0 += 32) { float wv[32];
; #pragma unroll
;               for (int m = 0; m < 32; ++m) wv[m] = wp[(size_t)(m0 + m) * 1024];
; #pragma unroll
;               for (int m = 0; m < 32; ++m) { const int t = ((m0 + m) * j) & 63; cs += tab64[t] * wv[m]; sn += tab64[(t + 48) & 63] * wv[m]; } }
;           bf16_t* o = (bf16_t*)(ws + OFF_WOUT + l * SZ_WOUT1) + (size_t)n * 1280; o[768 + gj] = (bf16_t)f2bf(cs); o[1024 + gj] = (bf16_t)f2bf(-sn); }
	v_pk_fma_f32 v[4:5], v[34:35], v[56:57], v[4:5] op_sel_hi:[0,1,1]
	ds_read_b32 v34, v13
	v_add_u32_e32 v13, 48, v11
	v_and_b32_e32 v13, 56, v13
	v_lshl_add_u32 v13, v13, 2, s0
	v_add_u32_e32 v11, v11, v9
	ds_read_b32 v35, v13
	v_and_b32_e32 v13, 63, v11
	v_lshl_add_u32 v13, v13, 2, s0
	s_waitcnt vmcnt(17)
	v_pk_fma_f32 v[4:5], v[36:37], v[58:59], v[4:5] op_sel_hi:[0,1,1]
	ds_read_b32 v36, v13
	v_add_u32_e32 v13, 48, v11
	v_and_b32_e32 v13, 63, v13
	v_lshl_add_u32 v13, v13, 2, s0
	v_add_u32_e32 v11, v11, v9
	ds_read_b32 v37, v13
	v_and_b32_e32 v13, 62, v11
	v_lshl_add_u32 v13, v13, 2, s0
	s_waitcnt vmcnt(16)
	v_pk_fma_f32 v[4:5], v[38:39], v[60:61], v[4:5] op_sel_hi:[0,1,1]
	ds_read_b32 v38, v13
	v_add_u32_e32 v13, 48, v11
	v_and_b32_e32 v13, 62, v13
	v_lshl_add_u32 v13, v13, 2, s0
	v_add_u32_e32 v11, v11, v9
	ds_read_b32 v39, v13
	v_and_b32_e32 v13, 63, v11
	v_lshl_add_u32 v13, v13, 2, s0
	s_waitcnt vmcnt(15) lgkmcnt(14)
	v_pk_fma_f32 v[4:5], v[40:41], v[62:63], v[4:5] op_sel_hi:[0,1,1]
	ds_read_b32 v40, v13
	v_add_u32_e32 v13, 48, v11
	v_and_b32_e32 v13, 63, v13
	v_lshl_add_u32 v13, v13, 2, s0
	v_add_u32_e32 v11, v11, v9
	ds_read_b32 v41, v13
	v_and_b32_e32 v13, 60, v11
	v_lshl_add_u32 v13, v13, 2, s0
	s_waitcnt vmcnt(14)
	v_pk_fma_f32 v[4:5], v[42:43], v[64:65], v[4:5] op_sel_hi:[0,1,1]
	ds_read_b32 v42, v13
	v_add_u32_e32 v13, 48, v11
	v_and_b32_e32 v13, 60, v13
	v_lshl_add_u32 v13, v13, 2, s0
	v_add_u32_e32 v11, v11, v9
	ds_read_b32 v43, v13
	v_and_b32_e32 v13, 63, v11
	v_lshl_add_u32 v13, v13, 2, s0
	s_waitcnt vmcnt(13)
	v_pk_fma_f32 v[4:5], v[44:45], v[66:67], v[4:5] op_sel_hi:[0,1,1]
	ds_read_b32 v44, v13
	v_add_u32_e32 v13, 48, v11
	v_and_b32_e32 v13, 63, v13
	v_lshl_add_u32 v13, v13, 2, s0
	v_add_u32_e32 v11, v11, v9
	ds_read_b32 v45, v13
	v_and_b32_e32 v13, 62, v11
	v_lshl_add_u32 v13, v13, 2, s0
	s_waitcnt vmcnt(12)
	v_pk_fma_f32 v[4:5], v[46:47], v[68:69], v[4:5] op_sel_hi:[0,1,1]
	ds_read_b32 v46, v13
	v_add_u32_e32 v13, 48, v11
	v_and_b32_e32 v13, 62, v13
	v_lshl_add_u32 v13, v13, 2, s0
	v_add_u32_e32 v11, v11, v9
	s_waitcnt vmcnt(11) lgkmcnt(14)
	v_pk_fma_f32 v[4:5], v[48:49], v[70:71], v[4:5] op_sel_hi:[0,1,1]
	ds_read_b32 v47, v13
	v_and_b32_e32 v13, 63, v11
	v_add_u32_e32 v11, 48, v11
	v_and_b32_e32 v11, 63, v11
	s_waitcnt vmcnt(10)
	v_pk_fma_f32 v[4:5], v[6:7], v[28:29], v[4:5] op_sel_hi:[0,1,1]
	v_lshl_add_u32 v11, v11, 2, s0
	s_waitcnt vmcnt(9)
	v_pk_fma_f32 v[4:5], v[8:9], v[30:31], v[4:5] op_sel_hi:[0,1,1]
	v_lshl_add_u32 v13, v13, 2, s0
	s_waitcnt vmcnt(8) lgkmcnt(14)
	v_pk_fma_f32 v[4:5], v[10:11], v[32:33], v[4:5] op_sel_hi:[0,1,1]
	s_waitcnt vmcnt(7) lgkmcnt(12)
	v_pk_fma_f32 v[4:5], v[12:13], v[34:35], v[4:5] op_sel_hi:[0,1,1]
	s_waitcnt vmcnt(6) lgkmcnt(10)
	v_pk_fma_f32 v[4:5], v[14:15], v[36:37], v[4:5] op_sel_hi:[0,1,1]
	ds_read_b32 v48, v13
	ds_read_b32 v49, v11
	s_waitcnt vmcnt(5) lgkmcnt(10)
	v_pk_fma_f32 v[4:5], v[16:17], v[38:39], v[4:5] op_sel_hi:[0,1,1]
	s_waitcnt vmcnt(4) lgkmcnt(8)
	v_pk_fma_f32 v[4:5], v[18:19], v[40:41], v[4:5] op_sel_hi:[0,1,1]
	s_waitcnt vmcnt(3) lgkmcnt(6)
	v_pk_fma_f32 v[4:5], v[20:21], v[42:43], v[4:5] op_sel_hi:[0,1,1]
	s_waitcnt vmcnt(2) lgkmcnt(4)
	v_pk_fma_f32 v[4:5], v[22:23], v[44:45], v[4:5] op_sel_hi:[0,1,1]
	s_waitcnt vmcnt(1) lgkmcnt(2)
	v_pk_fma_f32 v[4:5], v[24:25], v[46:47], v[4:5] op_sel_hi:[0,1,1]
	s_waitcnt vmcnt(0) lgkmcnt(0)
	v_pk_fma_f32 v[4:5], v[26:27], v[48:49], v[4:5] op_sel_hi:[0,1,1]
	s_and_b64 vcc, exec, s[42:43]
	s_mov_b64 s[42:43], 0
	s_mov_b32 s3, 32
	s_cbranch_vccnz .LBB0_1178
	v_readlane_b32 s0, v252, 40
	v_readlane_b32 s1, v252, 41
	v_bfe_u32 v6, v4, 16, 1
	v_add3_u32 v4, v4, v6, s19
	v_mov_b64_e32 v[2:3], s[0:1]
	v_lshrrev_b32_e32 v6, 9, v1
	v_mad_u64_u32 v[2:3], s[0:1], v7, s23, v[2:3]
	v_and_b32_e32 v128, 0x1fe, v6
	v_lshl_add_u64 v[2:3], v[2:3], 0, v[128:129]
	global_store_short_d16_hi v[2:3], v4, off offset:1536
	v_xor_b32_e32 v4, 0x80000000, v5
	v_bfe_u32 v5, v4, 16, 1
	v_add3_u32 v4, v4, v5, s19
	s_mov_b32 s0, 0x27fff
	global_store_short_d16_hi v[2:3], v4, off offset:2048
	v_add_u32_e32 v2, 0x18000, v1
	v_cmp_lt_i32_e32 vcc, s0, v1
	s_or_b64 s[40:41], vcc, s[40:41]
	v_mov_b32_e32 v1, v2
	s_andn2_b64 exec, exec, s[40:41]
	s_cbranch_execnz .LBB0_1177

; __device__ __forceinline__ void phase_final(const Params& P) {
;     int tid = threadIdx.x; asm volatile("" : "+v"(tid)); const int lane = tid & 63, wave = tid >> 6, gw = blockIdx.x * 8 + wave, NGW = gridDim.x * 8;
;     f32x4 gg[4], v[4];
; #pragma unroll
;     for (int j = 0; j < 4; ++j) gg[j] = *(const f32x4*)(P.final_g + 4 * lane + 256 * j);
;     if (gw < TL) {
; #pragma unroll
;         for (int j = 0; j < 4; ++j) v[j] = *(const f32x4*)(P.out + (size_t)gw * 1024 + 4 * lane + 256 * j); }
;     for (int r = gw; r < TL; r += NGW) { float* hr = P.out + (size_t)r * 1024; const int rn = r + NGW; f32x4 vn[4];
.LBB0_1255:
	v_readlane_b32 s2, v253, 47
	s_cmp_ge_i32 s2, s94
	s_cselect_b64 s[0:1], -1, 0
	s_cmp_lt_i32 s2, s95
	s_cselect_b64 s[2:3], -1, 0
	s_and_b64 s[8:9], s[0:1], s[2:3]
	v_readlane_b32 s0, v254, 38
	v_readlane_b32 s1, v254, 39
	s_and_b64 vcc, exec, s[0:1]
	s_cbranch_vccz .LBB0_1262
	s_mov_b64 s[26:27], 0
	s_and_b64 vcc, exec, s[8:9]
	s_mov_b64 s[40:41], 0
	s_cbranch_vccz .LBB0_1263
	s_waitcnt vmcnt(0)
	v_mov_b32_e32 v33, v168
	v_readlane_b32 s0, v250, 18
	v_ashrrev_i32_e32 v32, 6, v33
	s_nop 0
	v_add_u32_e32 v48, s0, v32
	v_cmp_gt_i32_e32 vcc, s25, v48
	s_and_saveexec_b64 s[40:41], vcc
	s_cbranch_execz .LBB0_1278
	v_ashrrev_i32_e32 v49, 31, v48
	v_lshlrev_b32_e32 v0, 4, v33
	v_lshlrev_b64 v[16:17], 12, v[48:49]
	v_and_b32_e32 v128, 0x3f0, v0
	v_lshl_add_u64 v[50:51], s[86:87], 0, v[16:17]
	v_lshl_add_u64 v[16:17], v[50:51], 0, v[128:129]
	s_waitcnt lgkmcnt(0)
	global_load_dwordx4 v[0:3], v128, s[84:85]
	global_load_dwordx4 v[4:7], v128, s[84:85] offset:1024
	global_load_dwordx4 v[8:11], v128, s[84:85] offset:2048
	global_load_dwordx4 v[12:15], v128, s[84:85] offset:3072
	global_load_dwordx4 v[28:31], v[16:17], off
	global_load_dwordx4 v[24:27], v[16:17], off offset:1024
	global_load_dwordx4 v[20:23], v[16:17], off offset:2048
	global_load_dwordx4 v[16:19], v[16:17], off offset:3072
	v_and_b32_e32 v34, 64, v174
	v_add_u32_e32 v34, 64, v34
	v_xor_b32_e32 v35, 1, v174
	v_cmp_lt_i32_e32 vcc, v35, v34
	v_readlane_b32 s0, v253, 53
	v_and_b32_e32 v33, 63, v33
	v_cndmask_b32_e32 v35, v174, v35, vcc
	v_lshlrev_b32_e32 v49, 2, v35
	v_xor_b32_e32 v35, 2, v174
	v_cmp_lt_i32_e32 vcc, v35, v34
	v_add_u32_e32 v32, s0, v32
	v_lshlrev_b32_e32 v128, 4, v33
	v_cndmask_b32_e32 v35, v174, v35, vcc
	v_lshlrev_b32_e32 v54, 2, v35
	v_xor_b32_e32 v35, 4, v174
	v_cmp_lt_i32_e32 vcc, v35, v34
	v_ashrrev_i32_e32 v33, 31, v32
	v_lshlrev_b64 v[32:33], 12, v[32:33]
	v_cndmask_b32_e32 v35, v174, v35, vcc
	v_lshlrev_b32_e32 v55, 2, v35
	v_xor_b32_e32 v35, 8, v174
	v_cmp_lt_i32_e32 vcc, v35, v34
	v_lshl_add_u64 v[52:53], s[86:87], 0, v[32:33]
	s_mov_b64 s[42:43], 0
	v_cndmask_b32_e32 v35, v174, v35, vcc
	v_lshlrev_b32_e32 v56, 2, v35
	v_xor_b32_e32 v35, 16, v174
	v_cmp_lt_i32_e32 vcc, v35, v34
	s_nop 1
	v_cndmask_b32_e32 v35, v174, v35, vcc
	v_lshlrev_b32_e32 v57, 2, v35
	v_xor_b32_e32 v35, 32, v174
	v_cmp_lt_i32_e32 vcc, v35, v34
	s_nop 1
	v_cndmask_b32_e32 v34, v174, v35, vcc
	v_lshlrev_b32_e32 v58, 2, v34
	s_branch .LBB0_1260

; __device__ __forceinline__ void phase_final(const Params& P) {
;     ...
;     for (int r = gw; r < TL; r += NGW) { float* hr = P.out + (size_t)r * 1024; const int rn = r + NGW; f32x4 vn[4];
;         if (rn < TL) {
; #pragma unroll
;             for (int j = 0; j < 4; ++j) vn[j] = *(const f32x4*)(P.out + (size_t)rn * 1024 + 4 * lane + 256 * j); }
.LBB0_1260:
	v_add_u32_e32 v48, s96, v48
	v_cmp_gt_i32_e64 s[38:39], s25, v48
	v_cmp_lt_i32_e32 vcc, s19, v48
	s_waitcnt vmcnt(3)
	v_mov_b32_e32 v32, v28
	v_mov_b32_e32 v33, v29
	v_mov_b32_e32 v34, v30
	v_mov_b32_e32 v35, v31
	s_waitcnt vmcnt(2)
	v_mov_b32_e32 v36, v24
	v_mov_b32_e32 v37, v25
	v_mov_b32_e32 v38, v26
	v_mov_b32_e32 v39, v27
	s_waitcnt vmcnt(1)
	v_mov_b32_e32 v40, v20
	v_mov_b32_e32 v41, v21
	v_mov_b32_e32 v42, v22
	v_mov_b32_e32 v43, v23
	s_waitcnt vmcnt(0)
	v_mov_b32_e32 v44, v16
	v_mov_b32_e32 v45, v17
	v_mov_b32_e32 v46, v18
	v_mov_b32_e32 v47, v19
	s_and_saveexec_b64 s[44:45], s[38:39]
	s_cbranch_execz .LBB0_1259
	v_lshl_add_u64 v[44:45], v[52:53], 0, v[128:129]
	global_load_dwordx4 v[32:35], v[44:45], off
	global_load_dwordx4 v[36:39], v[44:45], off offset:1024
	global_load_dwordx4 v[40:43], v[44:45], off offset:2048
	global_load_dwordx4 v[44:47], v[44:45], off offset:3072
	s_branch .LBB0_1259

; __device__ __forceinline__ void phase_norm(const Params& P, int l, int sub, int addpart) {
;     int tid = threadIdx.x; asm volatile("" : "+v"(tid)); const int lane = tid & 63, wave = tid >> 6; const int rbeg = blockIdx.x * 8 + wave, rstride = gridDim.x * 8, rend = T;
;     const float* Hc = (const float*)(P.ws + OFF_HC); bf16_t* XN = (bf16_t*)(P.ws + OFF_XN); const float* MOD = (const float*)(P.ws + OFF_MOD) + (size_t)l * 9 * 9216;
;     const float* g = P.norm_g + (l * 3 + sub) * 1024; f32x4 gg[4];
; #pragma unroll
;     for (int j = 0; j < 4; ++j) gg[j] = *(const f32x4*)(g + 4 * lane + 256 * j);
;     f32x4 v[4], sc[4], sh[4];
;     if (rbeg < rend) NR_LOAD(rbeg, v, sc, sh);
;     for (int r = rbeg; r < rend; r += rstride) { const int rn = r + rstride; f32x4 vn[4], scn[4], shn[4];
;         if (rn < rend) NR_LOAD(rn, vn, scn, shn);
.LBB0_1263:
	s_and_b64 vcc, exec, s[26:27]
	s_cbranch_vccz .LBB0_1386
	s_and_b64 vcc, exec, s[8:9]
	s_cbranch_vccz .LBB0_1386
	s_waitcnt vmcnt(0)
	v_mov_b32_e32 v66, v168
	v_readlane_b32 s0, v250, 18
	v_ashrrev_i32_e32 v67, 6, v66
	s_nop 0
	v_add_u32_e32 v64, s0, v67
	s_mov_b32 s0, 0x8800
	v_cmp_gt_i32_e32 vcc, s0, v64
	s_and_saveexec_b64 s[8:9], vcc
	s_cbranch_execz .LBB0_1290
	v_add_u32_e32 v128, 0xffff8000, v64
	v_ashrrev_i32_e32 v65, 31, v64
	v_cmp_gt_i32_e32 vcc, s25, v64
	v_mov_b32_e32 v18, s31
	v_mov_b32_e32 v19, s87
	v_lshlrev_b32_e32 v0, 2, v66
	v_cndmask_b32_e32 v17, 0, v65, vcc
	v_cndmask_b32_e32 v16, v128, v64, vcc
	v_cndmask_b32_e32 v19, v18, v19, vcc
	v_mov_b32_e32 v18, s30
	v_mov_b32_e32 v20, s86
	v_and_b32_e32 v28, 0xfc, v0
	v_readlane_b32 s0, v253, 14
	v_cndmask_b32_e32 v18, v18, v20, vcc
	v_lshlrev_b64 v[16:17], 12, v[16:17]
	v_lshlrev_b32_e32 v112, 2, v28
	v_readlane_b32 s1, v253, 15
	v_lshl_add_u64 v[16:17], v[18:19], 0, v[16:17]
	v_min_i32_e32 v18, 0x8000, v64
	s_waitcnt lgkmcnt(0)
	s_nop 1
	global_load_dwordx4 v[0:3], v112, s[0:1]
	global_load_dwordx4 v[4:7], v112, s[0:1] offset:1024
	global_load_dwordx4 v[8:11], v112, s[0:1] offset:2048
	global_load_dwordx4 v[12:15], v112, s[0:1] offset:3072
	v_ashrrev_i32_e32 v18, 12, v18
	v_readlane_b32 s0, v253, 16
	v_mul_hi_i32_i24_e32 v19, 0x9000, v18
	v_mul_i32_i24_e32 v18, 0x9000, v18
	v_readlane_b32 s1, v253, 17
	v_mov_b32_e32 v113, v129
	v_lshl_add_u64 v[16:17], v[16:17], 0, v[112:113]
	v_lshl_add_u64 v[18:19], s[0:1], 0, v[18:19]
	s_mov_b64 s[0:1], 0x1000
	v_lshl_add_u64 v[20:21], v[18:19], 0, s[0:1]
	v_lshl_add_u64 v[68:69], v[18:19], 0, v[112:113]
	v_or_b32_e32 v18, 0x100, v28
	v_lshlrev_b32_e32 v114, 2, v18
	v_or_b32_e32 v18, 0x200, v28
	v_or_b32_e32 v28, 0x300, v28
	v_lshl_add_u64 v[22:23], v[20:21], 0, v[112:113]
	v_mov_b32_e32 v115, v129
	v_lshlrev_b32_e32 v116, 2, v18
	v_mov_b32_e32 v117, v129
	v_lshlrev_b32_e32 v118, 2, v28
	v_mov_b32_e32 v119, v129
	global_load_dwordx4 v[40:43], v[22:23], off
	global_load_dwordx4 v[44:47], v[68:69], off
	global_load_dwordx4 v[60:63], v[16:17], off
	global_load_dwordx4 v[56:59], v[16:17], off offset:1024
	v_lshl_add_u64 v[22:23], v[20:21], 0, v[114:115]
	v_lshl_add_u64 v[18:19], v[20:21], 0, v[116:117]
	global_load_dwordx4 v[32:35], v[68:69], off offset:1024
	global_load_dwordx4 v[24:27], v[68:69], off offset:2048
	global_load_dwordx4 v[52:55], v[16:17], off offset:2048
	global_load_dwordx4 v[36:39], v[16:17], off offset:3072
	v_lshl_add_u64 v[16:17], v[20:21], 0, v[118:119]
	global_load_dwordx4 v[28:31], v[18:19], off
	global_load_dwordx4 v[16:19], v[16:17], off
	global_load_dwordx4 v[48:51], v[22:23], off
	global_load_dwordx4 v[20:23], v[68:69], off offset:3072
	v_cmp_lt_i32_e32 vcc, s19, v64
	s_and_saveexec_b64 s[26:27], vcc
	s_cbranch_execz .LBB0_1268
	v_readlane_b32 s0, v250, 21
	v_lshlrev_b64 v[68:69], 12, v[128:129]
	v_readlane_b32 s1, v250, 22
	s_nop 1
	v_lshl_add_u64 v[68:69], s[0:1], 0, v[68:69]
	v_lshl_add_u64 v[80:81], v[68:69], 0, v[112:113]
	global_load_dwordx4 v[68:71], v[80:81], off
	global_load_dwordx4 v[72:75], v[80:81], off offset:1024
	global_load_dwordx4 v[76:79], v[80:81], off offset:2048
	global_load_dwordx4 v[80:83], v[80:81], off offset:3072
	s_waitcnt vmcnt(3)
	v_pk_add_f32 v[62:63], v[62:63], v[70:71]
	v_pk_add_f32 v[60:61], v[60:61], v[68:69]
	s_waitcnt vmcnt(2)
	v_pk_add_f32 v[58:59], v[58:59], v[74:75]
	v_pk_add_f32 v[56:57], v[56:57], v[72:73]
	s_waitcnt vmcnt(1)
	v_pk_add_f32 v[54:55], v[54:55], v[78:79]
	v_pk_add_f32 v[52:53], v[52:53], v[76:77]
	s_waitcnt vmcnt(0)
	v_pk_add_f32 v[38:39], v[38:39], v[82:83]
	v_pk_add_f32 v[36:37], v[36:37], v[80:81]

; __device__ __forceinline__ void phase_norm(const Params& P, int l, int sub, int addpart) {
;     ...
;     for (int r = rbeg; r < rend; r += rstride) { const int rn = r + rstride; f32x4 vn[4], scn[4], shn[4];
;         if (rn < rend) NR_LOAD(rn, vn, scn, shn);
.LBB0_1270:
	v_add_u32_e32 v128, s96, v138
	v_add_u32_e32 v39, 0x8000, v128
	s_mov_b32 s0, 0x8800
	v_cmp_gt_i32_e64 s[38:39], s0, v39
	s_mov_b32 s0, 0x87ff
	v_cmp_lt_i32_e32 vcc, s0, v39
	s_and_saveexec_b64 s[42:43], s[38:39]
	s_cbranch_execz .LBB0_1274
	v_ashrrev_i32_e32 v63, 31, v39
	v_cmp_gt_i32_e64 s[38:39], s25, v39
	v_mov_b32_e32 v66, s87
	v_readlane_b32 s0, v253, 16
	v_cndmask_b32_e64 v65, 0, v63, s[38:39]
	v_mov_b32_e32 v63, s31
	v_cndmask_b32_e64 v67, v63, v66, s[38:39]
	v_mov_b32_e32 v63, s30
	v_mov_b32_e32 v66, s86
	v_cndmask_b32_e64 v64, v128, v39, s[38:39]
	v_cndmask_b32_e64 v66, v63, v66, s[38:39]
	v_min_i32_e32 v63, 0x8000, v39
	v_lshlrev_b64 v[64:65], 12, v[64:65]
	v_ashrrev_i32_e32 v63, 12, v63
	v_lshl_add_u64 v[64:65], v[66:67], 0, v[64:65]
	v_mul_hi_i32_i24_e32 v67, 0x9000, v63
	v_mul_i32_i24_e32 v66, 0x9000, v63
	v_readlane_b32 s1, v253, 17
	v_mov_b32_e32 v113, v129
	v_mov_b32_e32 v115, v129
	v_lshl_add_u64 v[66:67], s[0:1], 0, v[66:67]
	s_mov_b64 s[0:1], 0x1000
	v_lshl_add_u64 v[88:89], v[66:67], 0, s[0:1]
	v_mov_b32_e32 v117, v129
	v_mov_b32_e32 v119, v129
	v_lshl_add_u64 v[90:91], v[64:65], 0, v[112:113]
	v_lshl_add_u64 v[64:65], v[88:89], 0, v[112:113]
	v_lshl_add_u64 v[100:101], v[66:67], 0, v[112:113]
	v_lshl_add_u64 v[96:97], v[88:89], 0, v[114:115]
	v_lshl_add_u64 v[92:93], v[88:89], 0, v[116:117]
	v_lshl_add_u64 v[88:89], v[88:89], 0, v[118:119]
	global_load_dwordx4 v[68:71], v[64:65], off
	global_load_dwordx4 v[72:75], v[100:101], off
	global_load_dwordx4 v[64:67], v[90:91], off
	global_load_dwordx4 v[76:79], v[90:91], off offset:1024
	global_load_dwordx4 v[80:83], v[100:101], off offset:1024
	global_load_dwordx4 v[84:87], v[100:101], off offset:2048
	global_load_dwordx4 v[104:107], v[90:91], off offset:2048
	global_load_dwordx4 v[108:111], v[90:91], off offset:3072
	global_load_dwordx4 v[92:95], v[92:93], off
	global_load_dwordx4 v[88:91], v[88:89], off
	global_load_dwordx4 v[96:99], v[96:97], off
	global_load_dwordx4 v[100:103], v[100:101], off offset:3072
	v_cmp_lt_i32_e64 s[38:39], s19, v39
	s_and_saveexec_b64 s[44:45], s[38:39]
	s_cbranch_execz .LBB0_1273
	v_lshlrev_b64 v[146:147], 12, v[128:129]
	v_lshl_add_u64 v[158:159], v[122:123], 0, v[146:147]
	global_load_dwordx4 v[146:149], v[158:159], off
	global_load_dwordx4 v[150:153], v[158:159], off offset:1024
	global_load_dwordx4 v[154:157], v[158:159], off offset:2048
	global_load_dwordx4 v[158:161], v[158:159], off offset:3072
	s_waitcnt vmcnt(3)
	v_pk_add_f32 v[66:67], v[66:67], v[148:149]
	v_pk_add_f32 v[64:65], v[64:65], v[146:147]
	s_waitcnt vmcnt(2)
	v_pk_add_f32 v[78:79], v[78:79], v[152:153]
	v_pk_add_f32 v[76:77], v[76:77], v[150:151]
	s_waitcnt vmcnt(1)
	v_pk_add_f32 v[106:107], v[106:107], v[156:157]
	v_pk_add_f32 v[104:105], v[104:105], v[154:155]
	s_waitcnt vmcnt(0)
	v_pk_add_f32 v[110:111], v[110:111], v[160:161]
	v_pk_add_f32 v[108:109], v[108:109], v[158:159]
